# e25: no 8-byte instruction straddles a 64-byte line in all latency-bound loops (B-loop, sample attention, HGRN state/output loops, skinny loops)
# baseline (speedup 1.0000x reference)
; #define SK_LOAD3() do { SK_LOAD(0, 0); if (1 < nsc) SK_LOAD(1, 1); if (2 < nsc) SK_LOAD(2, 2); } while (0)
; #define SK_WRITE(s_, b) do { LAS unsigned char* bb = lds + (b) * BUF; _Pragma("unroll") for (int i = 0; i < 4; ++i) *(LAS bf16x8*)(bb + st0 + i * 8192) = ra[s_][i]; \
;         _Pragma("unroll") for (int i = 0; i < NW2; ++i) *(LAS bf16x8*)(bb + 32768 + st0 + i * 8192) = rw[s_][i]; } while (0)
; template <class Epi, int NC>
; __device__ __forceinline__ void skinny_phase(const bf16* __restrict__ A, int lda, int a_goff, const bf16* __restrict__ Bt, int ldb, int K, int ncg, int vcu, int G, const Epi& E, LAS float* rs_tab, LAS unsigned char* lds) {
;     ...
;     int u = vcu;
;     if (u < NU) { SK_PTRS(u); SK_LOAD3(); }
; #pragma unroll 1
;     while (u < NU) {
;         const int cg = (u >> 2) * NC, rb = u & 3;
;         f32x16 acc[NC] = {};
;         SK_WRITE(0, 0);
;         asm volatile("s_waitcnt lgkmcnt(0)" ::: "memory"); __builtin_amdgcn_s_barrier(); asm volatile("" ::: "memory");
; #pragma unroll 1
;         for (int c3 = 0; c3 < nsc; c3 += 3) { SK_STEP(0); SK_STEP(1); SK_STEP(2); }
.LBB0_250:
	v_add_u32_e32 v2, 0, v192
	s_waitcnt vmcnt(8) lgkmcnt(0)
	ds_write_b128 v2, v[36:39]
	ds_write_b128 v2, v[48:51] offset:8192
	ds_write_b128 v2, v[80:83] offset:16384
	ds_write_b128 v2, v[60:63] offset:24576
	ds_write_b128 v2, v[84:87] offset:32768
	ds_write_b128 v2, v[96:99] offset:40960
	ds_write_b128 v2, v[104:107] offset:49152
	s_nop 0
	ds_write_b128 v2, v[112:115] offset:57344
	s_waitcnt lgkmcnt(0)
	s_barrier
	v_mov_b32_e32 v4, 0
	s_mov_b32 s4, s65
	s_mov_b64 s[2:3], 0
	s_mov_b32 s5, 0
	s_mov_b32 s6, 0
	v_mov_b32_e32 v5, v4
	v_mov_b32_e32 v6, v4
	v_mov_b32_e32 v7, v4
	v_mov_b32_e32 v8, v4
	v_mov_b32_e32 v9, v4
	v_mov_b32_e32 v10, v4
	v_mov_b32_e32 v11, v4
	v_mov_b32_e32 v12, v4
	v_mov_b32_e32 v13, v4
	v_mov_b32_e32 v14, v4
	v_mov_b32_e32 v15, v4
	v_mov_b32_e32 v16, v4
	v_mov_b32_e32 v17, v4
	v_mov_b32_e32 v18, v4
	v_mov_b32_e32 v19, v4
	v_mov_b32_e32 v20, v4
	v_mov_b32_e32 v21, v4
	v_mov_b32_e32 v22, v4
	v_mov_b32_e32 v23, v4
	v_mov_b32_e32 v24, v4
	v_mov_b32_e32 v25, v4
	v_mov_b32_e32 v26, v4
	v_mov_b32_e32 v27, v4
	v_mov_b32_e32 v28, v4
	v_mov_b32_e32 v29, v4
	v_mov_b32_e32 v30, v4
	v_mov_b32_e32 v31, v4
	v_mov_b32_e32 v32, v4
	v_mov_b32_e32 v33, v4
	v_mov_b32_e32 v34, v4
	v_mov_b32_e32 v35, v4
	s_branch .LBB0_253
.LBB0_251:
	v_add_u32_e32 v156, s8, v194
	v_add_u32_e32 v157, s8, v195
	v_add_u32_e32 v158, v156, v207
	ds_read_b128 v[216:219], v158
	v_add_u32_e32 v159, v157, v207
	s_nop 0
	ds_read_b128 v[232:235], v159 offset:32768
	ds_read_b128 v[244:247], v159 offset:49152
	v_add_u32_e32 v164, v156, v208
	ds_read_b128 v[220:223], v164
	v_add_u32_e32 v165, v157, v208
	ds_read_b128 v[236:239], v165 offset:32768
	ds_read_b128 v[248:251], v165 offset:49152
	v_add_u32_e32 v180, v156, v209
	ds_read_b128 v[224:227], v180
	v_add_u32_e32 v181, v157, v209
	ds_read_b128 v[240:243], v181 offset:32768
	ds_read_b128 v[176:179], v181 offset:49152
	v_add_u32_e32 v200, v156, v210
	ds_read_b128 v[228:231], v200
	v_add_u32_e32 v201, v157, v210
	s_waitcnt lgkmcnt(8)
	v_mfma_f32_32x32x16_bf16 v[4:19], v[232:235], v[216:219], v[4:19]
	s_waitcnt lgkmcnt(7)
	v_mfma_f32_32x32x16_bf16 v[20:35], v[244:247], v[216:219], v[20:35]
	ds_read_b128 v[232:235], v201 offset:32768
	ds_read_b128 v[244:247], v201 offset:49152
	s_waitcnt lgkmcnt(7)
	v_mfma_f32_32x32x16_bf16 v[4:19], v[236:239], v[220:223], v[4:19]
	s_waitcnt lgkmcnt(6)
	v_mfma_f32_32x32x16_bf16 v[20:35], v[248:251], v[220:223], v[20:35]
	s_waitcnt lgkmcnt(4)
	v_mfma_f32_32x32x16_bf16 v[4:19], v[240:243], v[224:227], v[4:19]
	s_waitcnt lgkmcnt(3)
	v_mfma_f32_32x32x16_bf16 v[20:35], v[176:179], v[224:227], v[20:35]
	s_waitcnt lgkmcnt(1)
	s_nop 0
	v_mfma_f32_32x32x16_bf16 v[4:19], v[232:235], v[228:231], v[4:19]
	s_waitcnt lgkmcnt(0)
	s_barrier
	v_mfma_f32_32x32x16_bf16 v[20:35], v[244:247], v[228:231], v[20:35]

.Lsk250_a:
	s_waitcnt vmcnt(6)
	s_cmp_gt_u32 s6, 4
	s_cselect_b64 s[12:13], -1, 0
	v_add_u32_e32 v2, s7, v192
	s_and_b64 vcc, exec, s[12:13]
	ds_write_b128 v2, v[40:43]
	ds_write_b128 v2, v[44:47] offset:8192
	s_nop 0
	ds_write_b128 v2, v[76:79] offset:16384
	ds_write_b128 v2, v[56:59] offset:24576
	ds_write_b128 v2, v[72:75] offset:32768
	ds_write_b128 v2, v[92:95] offset:40960
	ds_write_b128 v2, v[100:103] offset:49152
	ds_write_b128 v2, v[108:111] offset:57344
	s_cbranch_vccnz .LBB0_255
	v_lshl_add_u64 v[60:61], v[138:139], 0, s[2:3]
	s_nop 0
	v_add_co_u32_e32 v48, vcc, 0x10000, v60
	v_lshl_add_u64 v[84:85], v[132:133], 0, s[2:3]
	s_nop 0
	v_addc_co_u32_e32 v49, vcc, 0, v61, vcc
	v_add_co_u32_e32 v62, vcc, 0x20000, v60
	global_load_dwordx4 v[36:39], v[60:61], off offset:1536
	s_nop 0
	global_load_dwordx4 v[48:51], v[48:49], off offset:1536
	v_addc_co_u32_e32 v63, vcc, 0, v61, vcc
	v_add_co_u32_e32 v60, vcc, 0x30000, v60
	v_lshl_add_u64 v[96:97], v[136:137], 0, s[2:3]
	s_nop 0
	v_addc_co_u32_e32 v61, vcc, 0, v61, vcc
	v_lshl_add_u64 v[104:105], v[140:141], 0, s[2:3]
	v_lshl_add_u64 v[112:113], v[134:135], 0, s[2:3]
	global_load_dwordx4 v[80:83], v[62:63], off offset:1536
	s_nop 0
	global_load_dwordx4 v[60:63], v[60:61], off offset:1536
	s_nop 0
	global_load_dwordx4 v[84:87], v[84:85], off offset:1536
	s_nop 0
	global_load_dwordx4 v[96:99], v[96:97], off offset:1536
	s_nop 0
	global_load_dwordx4 v[104:107], v[104:105], off offset:1536
	s_nop 0
	global_load_dwordx4 v[112:115], v[112:113], off offset:1536
.LBB0_255:
	s_add_i32 s8, s8, 0
	v_add_u32_e32 v156, s8, v194
	v_add_u32_e32 v157, s8, v195
	s_cmp_lt_u32 s6, 6
	s_cselect_b64 s[18:19], -1, 0
	s_cmp_gt_u32 s6, 5
	v_add_u32_e32 v158, v156, v207
	ds_read_b128 v[216:219], v158
	v_add_u32_e32 v159, v157, v207
	ds_read_b128 v[232:235], v159 offset:32768
	ds_read_b128 v[244:247], v159 offset:49152
	v_add_u32_e32 v164, v156, v208
	ds_read_b128 v[220:223], v164
	v_add_u32_e32 v165, v157, v208
	ds_read_b128 v[236:239], v165 offset:32768
	ds_read_b128 v[248:251], v165 offset:49152
	v_add_u32_e32 v180, v156, v209
	ds_read_b128 v[224:227], v180
	v_add_u32_e32 v181, v157, v209
	ds_read_b128 v[240:243], v181 offset:32768
	ds_read_b128 v[152:155], v181 offset:49152
	v_add_u32_e32 v200, v156, v210
	ds_read_b128 v[228:231], v200
	v_add_u32_e32 v201, v157, v210
	s_waitcnt lgkmcnt(8)
	v_mfma_f32_32x32x16_bf16 v[4:19], v[232:235], v[216:219], v[4:19]
	s_waitcnt lgkmcnt(7)
	s_nop 0
	v_mfma_f32_32x32x16_bf16 v[20:35], v[244:247], v[216:219], v[20:35]
	ds_read_b128 v[232:235], v201 offset:32768
	ds_read_b128 v[244:247], v201 offset:49152
	s_waitcnt lgkmcnt(7)
	v_mfma_f32_32x32x16_bf16 v[4:19], v[236:239], v[220:223], v[4:19]
	s_waitcnt lgkmcnt(6)
	v_mfma_f32_32x32x16_bf16 v[20:35], v[248:251], v[220:223], v[20:35]
	s_waitcnt lgkmcnt(4)
	v_mfma_f32_32x32x16_bf16 v[4:19], v[240:243], v[224:227], v[4:19]
	s_waitcnt lgkmcnt(3)
	v_mfma_f32_32x32x16_bf16 v[20:35], v[152:155], v[224:227], v[20:35]
	s_waitcnt lgkmcnt(1)
	v_mfma_f32_32x32x16_bf16 v[4:19], v[232:235], v[228:231], v[4:19]
	s_waitcnt lgkmcnt(0)
	s_barrier
	v_mfma_f32_32x32x16_bf16 v[20:35], v[244:247], v[228:231], v[20:35]
	s_cbranch_scc1 .LBB0_257
	v_add_u32_e32 v154, s8, v192
	s_waitcnt vmcnt(8)
	ds_write_b128 v154, v[52:55]
	ds_write_b128 v154, v[64:67] offset:8192
	ds_write_b128 v154, v[68:71] offset:16384
	ds_write_b128 v154, v[88:91] offset:24576
	ds_write_b128 v154, v[116:119] offset:32768
	ds_write_b128 v154, v[120:123] offset:40960
	ds_write_b128 v154, v[124:127] offset:49152
	ds_write_b128 v154, v[128:131] offset:57344

.LBB0_259:
	v_add_u32_e32 v154, s7, v194
	v_add_u32_e32 v155, s7, v195
	s_andn2_b64 vcc, exec, s[18:19]
	v_add_u32_e32 v158, v154, v207
	ds_read_b128 v[216:219], v158
	v_add_u32_e32 v159, v155, v207
	ds_read_b128 v[232:235], v159 offset:32768
	ds_read_b128 v[244:247], v159 offset:49152
	v_add_u32_e32 v164, v154, v208
	ds_read_b128 v[220:223], v164
	v_add_u32_e32 v165, v155, v208
	ds_read_b128 v[236:239], v165 offset:32768
	ds_read_b128 v[248:251], v165 offset:49152
	v_add_u32_e32 v180, v154, v209
	ds_read_b128 v[224:227], v180
	v_add_u32_e32 v181, v155, v209
	ds_read_b128 v[240:243], v181 offset:32768
	ds_read_b128 v[176:179], v181 offset:49152
	v_add_u32_e32 v200, v154, v210
	ds_read_b128 v[228:231], v200
	v_add_u32_e32 v201, v155, v210
	s_waitcnt lgkmcnt(8)
	v_mfma_f32_32x32x16_bf16 v[4:19], v[232:235], v[216:219], v[4:19]
	s_waitcnt lgkmcnt(7)
	v_mfma_f32_32x32x16_bf16 v[20:35], v[244:247], v[216:219], v[20:35]
	ds_read_b128 v[232:235], v201 offset:32768
	ds_read_b128 v[244:247], v201 offset:49152
	s_waitcnt lgkmcnt(7)
	v_mfma_f32_32x32x16_bf16 v[4:19], v[236:239], v[220:223], v[4:19]
	s_waitcnt lgkmcnt(6)
	v_mfma_f32_32x32x16_bf16 v[20:35], v[248:251], v[220:223], v[20:35]
	s_waitcnt lgkmcnt(4)
	v_mfma_f32_32x32x16_bf16 v[4:19], v[240:243], v[224:227], v[4:19]
	s_waitcnt lgkmcnt(3)
	v_mfma_f32_32x32x16_bf16 v[20:35], v[176:179], v[224:227], v[20:35]
	s_waitcnt lgkmcnt(1)
	s_nop 0
	v_mfma_f32_32x32x16_bf16 v[4:19], v[232:235], v[228:231], v[4:19]
	s_waitcnt lgkmcnt(0)
	s_barrier
	v_mfma_f32_32x32x16_bf16 v[20:35], v[244:247], v[228:231], v[20:35]
	s_cbranch_vccnz .LBB0_252
	s_cmpk_eq_i32 s2, 0xa00
	s_cbranch_scc1 .LBB0_262
	s_waitcnt vmcnt(8)
	ds_write_b128 v2, v[36:39]
	ds_write_b128 v2, v[48:51] offset:8192
	ds_write_b128 v2, v[80:83] offset:16384
	ds_write_b128 v2, v[60:63] offset:24576
	ds_write_b128 v2, v[84:87] offset:32768
	ds_write_b128 v2, v[96:99] offset:40960
	ds_write_b128 v2, v[104:107] offset:49152
	ds_write_b128 v2, v[112:115] offset:57344

; #define LAS __attribute__((address_space(3)))
; #define SK_LOAD3() do { SK_LOAD(0, 0); if (1 < nsc) SK_LOAD(1, 1); if (2 < nsc) SK_LOAD(2, 2); } while (0)
; template <class Epi, int NC>
; __device__ __forceinline__ void skinny_phase(const bf16* __restrict__ A, int lda, int a_goff, const bf16* __restrict__ Bt, int ldb, int K, int ncg, int vcu, int G, const Epi& E, LAS float* rs_tab, LAS unsigned char* lds) {
;     ...
;         const int un = u + G;
;         if (un < NU) { SK_PTRS(un); SK_LOAD3(); }
;         LAS float* pb = (LAS float*)lds + (w * NC) * 1024 + lane;
;         asm volatile("" : "+v"(pb));
; #pragma unroll
;         for (int g = 0; g < NC; ++g)
; #pragma unroll
;             for (int r = 0; r < 16; ++r) pb[(g * 16 + r) * 64] = acc[g][r];
;         asm volatile("s_waitcnt lgkmcnt(0)" ::: "memory"); __builtin_amdgcn_s_barrier(); asm volatile("" ::: "memory");
;         if (kq == 0) {
;             const int row = 64 * rb + rrow; const float rs = Epi::NEEDS_RS ? rs_tab[row] : 1.f;
; #pragma unroll
;             for (int g = 0; g < NC; ++g) {
; #pragma unroll
;                 for (int r = 0; r < 16; ++r) { const int o_ = (g * 16 + r) * 64; acc[g][r] = ((pb[o_] + pb[o_ + 2 * NC * 1024]) + pb[o_ + 4 * NC * 1024]) + pb[o_ + 6 * NC * 1024]; }
.LBB0_264:
	s_add_i32 s65, s4, s62
	s_cmpk_gt_i32 s65, 0x17f
	s_cselect_b64 s[2:3], -1, 0
	s_cmpk_lt_i32 s65, 0x180
	s_cbranch_scc0 .LBB0_266
	s_lshl_b32 s5, s65, 6
	s_and_b32 s5, s5, 0xc0
	s_waitcnt vmcnt(0)
	v_add_u32_e32 v36, s5, v190
	s_lshl_b32 s5, s65, 4
	s_andn2_b32 s5, s5, 63
	v_add_u32_e32 v38, s5, v190
	v_ashrrev_i32_e32 v39, 31, v38
	v_lshlrev_b64 v[38:39], 12, v[38:39]
	v_lshl_add_u64 v[132:133], v[144:145], 0, v[38:39]
	v_add_u32_e32 v38, s5, v191
	v_ashrrev_i32_e32 v37, 31, v36
	v_ashrrev_i32_e32 v39, 31, v38
	s_nop 0
	v_lshlrev_b64 v[36:37], 12, v[36:37]
	v_lshlrev_b64 v[38:39], 12, v[38:39]
	s_or_b32 s5, s5, 32
	v_lshl_add_u64 v[136:137], v[144:145], 0, v[38:39]
	v_add_u32_e32 v38, s5, v190
	v_lshl_add_u64 v[138:139], v[142:143], 0, v[36:37]
	v_ashrrev_i32_e32 v39, 31, v38
	v_lshlrev_b64 v[38:39], 12, v[38:39]
	v_add_co_u32_e32 v64, vcc, s71, v138
	v_lshl_add_u64 v[140:141], v[144:145], 0, v[38:39]
	s_nop 0
	v_addc_co_u32_e32 v65, vcc, 0, v139, vcc
	v_add_u32_e32 v38, s5, v191
	v_add_co_u32_e32 v68, vcc, s81, v138
	v_ashrrev_i32_e32 v39, 31, v38
	s_nop 0
	v_addc_co_u32_e32 v69, vcc, 0, v139, vcc
	s_mov_b32 s5, 0x30000
	v_lshlrev_b64 v[38:39], 12, v[38:39]
	v_add_co_u32_e32 v88, vcc, s5, v138
	v_lshl_add_u64 v[134:135], v[144:145], 0, v[38:39]
	s_nop 0
	v_addc_co_u32_e32 v89, vcc, 0, v139, vcc
	global_load_dwordx4 v[36:39], v[138:139], off
	global_load_dwordx4 v[40:43], v[138:139], off offset:512
	global_load_dwordx4 v[48:51], v[64:65], off
	global_load_dwordx4 v[44:47], v[64:65], off offset:512
	global_load_dwordx4 v[60:63], v[88:89], off
	global_load_dwordx4 v[56:59], v[88:89], off offset:512
	global_load_dwordx4 v[84:87], v[132:133], off
	global_load_dwordx4 v[72:75], v[132:133], off offset:512
	global_load_dwordx4 v[96:99], v[136:137], off
	global_load_dwordx4 v[92:95], v[136:137], off offset:512
	global_load_dwordx4 v[104:107], v[140:141], off
	global_load_dwordx4 v[100:103], v[140:141], off offset:512
	global_load_dwordx4 v[112:115], v[134:135], off
	global_load_dwordx4 v[108:111], v[134:135], off offset:512
	global_load_dwordx4 v[52:55], v[138:139], off offset:1024
	global_load_dwordx4 v[80:83], v[68:69], off
	s_nop 0
	global_load_dwordx4 v[64:67], v[64:65], off offset:1024
	s_nop 0
	global_load_dwordx4 v[76:79], v[68:69], off offset:512
	s_nop 0
	global_load_dwordx4 v[68:71], v[68:69], off offset:1024
	s_nop 0
	global_load_dwordx4 v[88:91], v[88:89], off offset:1024
	s_nop 0
	global_load_dwordx4 v[116:119], v[132:133], off offset:1024
	s_nop 0
	global_load_dwordx4 v[120:123], v[136:137], off offset:1024
	global_load_dwordx4 v[124:127], v[140:141], off offset:1024
	global_load_dwordx4 v[128:131], v[134:135], off offset:1024
.LBB0_266:
	v_mov_b32_e32 v212, v196
	ds_write2st64_b32 v212, v4, v5 offset1:1
	ds_write2st64_b32 v212, v6, v7 offset0:2 offset1:3
	ds_write2st64_b32 v212, v8, v9 offset0:4 offset1:5
	ds_write2st64_b32 v212, v10, v11 offset0:6 offset1:7
	s_nop 0
	ds_write2st64_b32 v212, v12, v13 offset0:8 offset1:9
	ds_write2st64_b32 v212, v14, v15 offset0:10 offset1:11
	ds_write2st64_b32 v212, v16, v17 offset0:12 offset1:13
	ds_write2st64_b32 v212, v18, v19 offset0:14 offset1:15
	ds_write2st64_b32 v212, v20, v21 offset0:16 offset1:17
	ds_write2st64_b32 v212, v22, v23 offset0:18 offset1:19
	ds_write2st64_b32 v212, v24, v25 offset0:20 offset1:21
	ds_write2st64_b32 v212, v26, v27 offset0:22 offset1:23
	ds_write2st64_b32 v212, v28, v29 offset0:24 offset1:25
	ds_write2st64_b32 v212, v30, v31 offset0:26 offset1:27
	ds_write2st64_b32 v212, v32, v33 offset0:28 offset1:29
	ds_write2st64_b32 v212, v34, v35 offset0:30 offset1:31
	s_waitcnt lgkmcnt(0)
	s_barrier
	s_andn2_b64 vcc, exec, s[0:1]
	s_cbranch_vccnz .LBB0_249
	s_lshl_b32 s5, s4, 6
	s_and_b32 s5, s5, 0xc0
	s_ashr_i32 s8, s4, 1
	v_or_b32_e32 v9, s5, v193
	s_ashr_i32 s5, s4, 7
	s_ashr_i32 s4, s4, 8
	s_add_i32 s4, s5, s4
	s_mul_hi_i32 s6, s4, 0x4100000
	s_mul_i32 s4, s4, 0x4100000
	s_add_i32 s9, s5, -1
	s_add_u32 s4, s63, s4
	s_addc_u32 s5, s64, s6
	s_cmp_gt_u32 s8, 63
	s_cselect_b64 s[12:13], -1, 0
	s_cmp_lt_u32 s8, 64
	s_cselect_b64 s[6:7], -1, 0
	s_and_b64 vcc, s[6:7], exec
	s_cselect_b32 s6, 0, s9
	v_lshl_add_u32 v2, v9, 2, 0
	s_ashr_i32 s7, s6, 31
	v_add_u32_e32 v2, 0x20000, v2
	s_lshl_b64 s[6:7], s[6:7], 21
	ds_read_b32 v8, v2
	s_add_u32 s6, s10, s6
	ds_read2st64_b32 v[4:5], v212 offset1:1
	ds_read2st64_b32 v[6:7], v212 offset0:2 offset1:3
	ds_read2st64_b32 v[146:147], v212 offset0:4 offset1:5
	ds_read2st64_b32 v[148:149], v212 offset0:6 offset1:7
	ds_read2st64_b32 v[14:15], v212 offset0:64 offset1:65
	ds_read2st64_b32 v[156:157], v212 offset0:66 offset1:67
	ds_read2st64_b32 v[178:179], v212 offset0:68 offset1:69
	ds_read2st64_b32 v[152:153], v212 offset0:70 offset1:71
	ds_read2st64_b32 v[158:159], v212 offset0:128 offset1:129
	ds_read2st64_b32 v[164:165], v212 offset0:130 offset1:131
	ds_read2st64_b32 v[182:183], v212 offset0:132 offset1:133
	ds_read2st64_b32 v[172:173], v212 offset0:134 offset1:135
	ds_read2st64_b32 v[200:201], v212 offset0:192 offset1:193
	ds_read2st64_b32 v[214:215], v212 offset0:194 offset1:195
	ds_read2st64_b32 v[186:187], v212 offset0:196 offset1:197
	ds_read2st64_b32 v[176:177], v212 offset0:198 offset1:199
	ds_read2st64_b32 v[32:33], v212 offset0:8 offset1:9
	ds_read2st64_b32 v[34:35], v212 offset0:10 offset1:11
	ds_read2st64_b32 v[16:17], v212 offset0:12 offset1:13
	ds_read2st64_b32 v[18:19], v212 offset0:14 offset1:15
	ds_read2st64_b32 v[180:181], v212 offset0:72 offset1:73
	ds_read2st64_b32 v[150:151], v212 offset0:74 offset1:75
	ds_read2st64_b32 v[26:27], v212 offset0:76 offset1:77
	ds_read2st64_b32 v[20:21], v212 offset0:78 offset1:79
	ds_read2st64_b32 v[184:185], v212 offset0:136 offset1:137
	ds_read2st64_b32 v[154:155], v212 offset0:138 offset1:139
	ds_read2st64_b32 v[28:29], v212 offset0:140 offset1:141
	ds_read2st64_b32 v[22:23], v212 offset0:142 offset1:143
	ds_read2st64_b32 v[188:189], v212 offset0:200 offset1:201
	ds_read2st64_b32 v[174:175], v212 offset0:202 offset1:203
	ds_read2st64_b32 v[30:31], v212 offset0:204 offset1:205
	ds_read2st64_b32 v[24:25], v212 offset0:206 offset1:207
	s_addc_u32 s7, s20, s7
	s_lshl_b32 s8, s8, 5
	s_and_b32 s8, s8, 0x7c0
	v_lshlrev_b32_e32 v2, 12, v9
	s_waitcnt lgkmcnt(0)
; __device__ __forceinline__ u32x2 pack4(float a, float b, float c, float d) { u32x2 w; w.x = cvt_pk_bf16(a, b); w.y = cvt_pk_bf16(c, d); return w; }
; template <class Epi, int NC>
; __device__ __forceinline__ void skinny_phase(const bf16* __restrict__ A, int lda, int a_goff, const bf16* __restrict__ Bt, int ldb, int K, int ncg, int vcu, int G, const Epi& E, LAS float* rs_tab, LAS unsigned char* lds) {
;     ...
;                 for (int r = 0; r < 16; ++r) { const int o_ = (g * 16 + r) * 64; acc[g][r] = ((pb[o_] + pb[o_ + 2 * NC * 1024]) + pb[o_ + 4 * NC * 1024]) + pb[o_ + 6 * NC * 1024]; }
;                 E(acc[g], cg + g, row, hi, rs); }
;     __device__ __forceinline__ void operator()(const f32x16& acc, int u, int row, int hi, float rs) const {
;         const int seg = u >> 6;
;         bf16* dst = (bf16*)((char*)Q + (size_t)(seg + (seg >> 1)) * (65 * MiB));
;         float* fo = out + OFF_K_S + (size_t)(seg ? seg - 1 : 0) * (OFF_V_S - OFF_K_S);
; #pragma unroll
;         for (int q = 0; q < 4; ++q) { const int c = 32 * (u & 63) + 8 * q + 4 * hi;
;             const f32x4 a = {acc[4 * q] * rs, acc[4 * q + 1] * rs, acc[4 * q + 2] * rs, acc[4 * q + 3] * rs};
;             *(u32x2*)(dst + (size_t)(MP + row) * D + c) = pack4(a[0], a[1], a[2], a[3]);
;             if (seg) *(f32x4*)(fo + (size_t)row * D + c) = a; }
;     }
	v_pk_add_f32 v[4:5], v[4:5], v[14:15]
	v_or_b32_e32 v211, s8, v197
	v_lshl_add_u64 v[10:11], s[4:5], 0, v[2:3]
	s_mov_b64 s[4:5], 0x4000000
	v_lshlrev_b32_e32 v2, 13, v9
	v_pk_add_f32 v[4:5], v[4:5], v[158:159]
	v_pk_add_f32 v[6:7], v[6:7], v[156:157]
	v_lshl_add_u64 v[12:13], v[10:11], 0, s[4:5]
	v_lshl_add_u64 v[10:11], s[6:7], 0, v[2:3]
	v_pk_add_f32 v[4:5], v[4:5], v[200:201]
	v_pk_add_f32 v[6:7], v[6:7], v[164:165]
	v_lshlrev_b32_e32 v2, 1, v211
	v_pk_mul_f32 v[4:5], v[8:9], v[4:5] op_sel_hi:[0,1]
	v_pk_add_f32 v[6:7], v[6:7], v[214:215]
	v_cvt_pk_bf16_f32 v14, v4, v5
	v_lshl_add_u64 v[156:157], v[12:13], 0, v[2:3]
	v_pk_mul_f32 v[6:7], v[8:9], v[6:7] op_sel_hi:[0,1]
	s_nop 0
	v_cvt_pk_bf16_f32 v15, v6, v7
	global_store_dwordx2 v[156:157], v[14:15], off
	v_lshlrev_b32_e32 v14, 2, v211
	s_cbranch_vccnz .LBB0_269
	v_mov_b32_e32 v15, v3
	v_lshl_add_u64 v[156:157], v[10:11], 0, v[14:15]
	global_store_dwordx4 v[156:157], v[4:7], off
.LBB0_269:
	s_nop 1
	v_pk_add_f32 v[4:5], v[146:147], v[178:179]
	v_pk_add_f32 v[6:7], v[148:149], v[152:153]
	v_pk_add_f32 v[4:5], v[4:5], v[182:183]
	v_pk_add_f32 v[6:7], v[6:7], v[172:173]
	v_lshl_or_b32 v2, v211, 1, 16
	v_mov_b32_e32 v9, v8
	v_pk_add_f32 v[4:5], v[4:5], v[186:187]
	v_pk_add_f32 v[6:7], v[6:7], v[176:177]
	v_lshl_add_u64 v[148:149], v[12:13], 0, v[2:3]
	v_cndmask_b32_e64 v2, 0, 1, s[12:13]
	s_nop 0
	v_pk_mul_f32 v[4:5], v[8:9], v[4:5]
	v_pk_mul_f32 v[6:7], v[8:9], v[6:7]
	v_cmp_ne_u32_e64 s[38:39], 1, v2
	s_andn2_b64 vcc, exec, s[12:13]
	v_cvt_pk_bf16_f32 v146, v4, v5
	v_cvt_pk_bf16_f32 v147, v6, v7
	global_store_dwordx2 v[148:149], v[146:147], off
	s_cbranch_vccnz .LBB0_271
	v_mov_b32_e32 v15, v3
	s_nop 0
	v_lshl_add_u64 v[146:147], v[10:11], 0, v[14:15]
	global_store_dwordx4 v[146:147], v[4:7], off offset:32
.LBB0_271:
	s_nop 1
	v_pk_add_f32 v[4:5], v[32:33], v[180:181]
	v_pk_add_f32 v[6:7], v[34:35], v[150:151]
	v_pk_add_f32 v[4:5], v[4:5], v[184:185]
	v_pk_add_f32 v[6:7], v[6:7], v[154:155]
	v_pk_add_f32 v[4:5], v[4:5], v[188:189]
	s_nop 0
	v_pk_add_f32 v[6:7], v[6:7], v[174:175]
	v_lshl_or_b32 v2, v211, 1, 32
	v_pk_mul_f32 v[4:5], v[8:9], v[4:5]
	v_pk_mul_f32 v[6:7], v[8:9], v[6:7]
	v_lshl_add_u64 v[34:35], v[12:13], 0, v[2:3]
	s_and_b64 vcc, exec, s[38:39]
	v_cvt_pk_bf16_f32 v32, v4, v5
	v_cvt_pk_bf16_f32 v33, v6, v7
	s_nop 0
	global_store_dwordx2 v[34:35], v[32:33], off
	s_cbranch_vccnz .LBB0_273
	v_mov_b32_e32 v15, v3
	v_lshl_add_u64 v[32:33], v[10:11], 0, v[14:15]
	global_store_dwordx4 v[32:33], v[4:7], off offset:64
.LBB0_273:
	s_nop 1
	v_pk_add_f32 v[4:5], v[16:17], v[26:27]
	v_pk_add_f32 v[6:7], v[18:19], v[20:21]
	v_pk_add_f32 v[4:5], v[4:5], v[28:29]
	s_nop 0
	v_pk_add_f32 v[6:7], v[6:7], v[22:23]
	v_pk_add_f32 v[4:5], v[4:5], v[30:31]
	v_pk_add_f32 v[6:7], v[6:7], v[24:25]
	v_lshl_or_b32 v2, v211, 1, 48
	v_pk_mul_f32 v[4:5], v[8:9], v[4:5]
	v_pk_mul_f32 v[6:7], v[8:9], v[6:7]
	v_lshl_add_u64 v[18:19], v[12:13], 0, v[2:3]
	s_and_b64 vcc, exec, s[38:39]
	s_nop 0
	v_cvt_pk_bf16_f32 v16, v4, v5
	v_cvt_pk_bf16_f32 v17, v6, v7
	global_store_dwordx2 v[18:19], v[16:17], off
	s_cbranch_vccnz .LBB0_275
	v_mov_b32_e32 v15, v3
	v_lshl_add_u64 v[16:17], v[10:11], 0, v[14:15]
	global_store_dwordx4 v[16:17], v[4:7], off offset:96
; __device__ __forceinline__ u32x2 pack4(float a, float b, float c, float d) { u32x2 w; w.x = cvt_pk_bf16(a, b); w.y = cvt_pk_bf16(c, d); return w; }
; template <class Epi, int NC>
; __device__ __forceinline__ void skinny_phase(const bf16* __restrict__ A, int lda, int a_goff, const bf16* __restrict__ Bt, int ldb, int K, int ncg, int vcu, int G, const Epi& E, LAS float* rs_tab, LAS unsigned char* lds) {
;     ...
;                 for (int r = 0; r < 16; ++r) { const int o_ = (g * 16 + r) * 64; acc[g][r] = ((pb[o_] + pb[o_ + 2 * NC * 1024]) + pb[o_ + 4 * NC * 1024]) + pb[o_ + 6 * NC * 1024]; }
;                 E(acc[g], cg + g, row, hi, rs); }
;     __device__ __forceinline__ void operator()(const f32x16& acc, int u, int row, int hi, float rs) const {
;         const int seg = u >> 6;
;         bf16* dst = (bf16*)((char*)Q + (size_t)(seg + (seg >> 1)) * (65 * MiB));
;         float* fo = out + OFF_K_S + (size_t)(seg ? seg - 1 : 0) * (OFF_V_S - OFF_K_S);
; #pragma unroll
;         for (int q = 0; q < 4; ++q) { const int c = 32 * (u & 63) + 8 * q + 4 * hi;
;             const f32x4 a = {acc[4 * q] * rs, acc[4 * q + 1] * rs, acc[4 * q + 2] * rs, acc[4 * q + 3] * rs};
;             *(u32x2*)(dst + (size_t)(MP + row) * D + c) = pack4(a[0], a[1], a[2], a[3]);
;             if (seg) *(f32x4*)(fo + (size_t)row * D + c) = a; }
;     }
.LBB0_275:
	ds_read2st64_b32 v[4:5], v212 offset0:16 offset1:17
	ds_read2st64_b32 v[6:7], v212 offset0:18 offset1:19
	ds_read2st64_b32 v[146:147], v212 offset0:20 offset1:21
	ds_read2st64_b32 v[148:149], v212 offset0:22 offset1:23
	ds_read2st64_b32 v[156:157], v212 offset0:80 offset1:81
	ds_read2st64_b32 v[158:159], v212 offset0:82 offset1:83
	ds_read2st64_b32 v[178:179], v212 offset0:84 offset1:85
	ds_read2st64_b32 v[150:151], v212 offset0:86 offset1:87
	ds_read2st64_b32 v[164:165], v212 offset0:144 offset1:145
	ds_read2st64_b32 v[200:201], v212 offset0:146 offset1:147
	ds_read2st64_b32 v[180:181], v212 offset0:148 offset1:149
	ds_read2st64_b32 v[154:155], v212 offset0:150 offset1:151
	ds_read2st64_b32 v[214:215], v212 offset0:208 offset1:209
	ds_read2st64_b32 v[216:217], v212 offset0:210 offset1:211
	ds_read2st64_b32 v[184:185], v212 offset0:212 offset1:213
	ds_read2st64_b32 v[174:175], v212 offset0:214 offset1:215
	ds_read2st64_b32 v[32:33], v212 offset0:24 offset1:25
	ds_read2st64_b32 v[34:35], v212 offset0:26 offset1:27
	ds_read2st64_b32 v[16:17], v212 offset0:28 offset1:29
	ds_read2st64_b32 v[18:19], v212 offset0:30 offset1:31
	ds_read2st64_b32 v[182:183], v212 offset0:88 offset1:89
	ds_read2st64_b32 v[152:153], v212 offset0:90 offset1:91
	ds_read2st64_b32 v[26:27], v212 offset0:92 offset1:93
	ds_read2st64_b32 v[20:21], v212 offset0:94 offset1:95
	ds_read2st64_b32 v[186:187], v212 offset0:152 offset1:153
	ds_read2st64_b32 v[172:173], v212 offset0:154 offset1:155
	ds_read2st64_b32 v[28:29], v212 offset0:156 offset1:157
	ds_read2st64_b32 v[22:23], v212 offset0:158 offset1:159
	ds_read2st64_b32 v[188:189], v212 offset0:216 offset1:217
	ds_read2st64_b32 v[176:177], v212 offset0:218 offset1:219
	ds_read2st64_b32 v[30:31], v212 offset0:220 offset1:221
	ds_read2st64_b32 v[24:25], v212 offset0:222 offset1:223
	s_waitcnt lgkmcnt(0)
	v_pk_add_f32 v[4:5], v[4:5], v[156:157]
	s_nop 0
	v_pk_add_f32 v[6:7], v[6:7], v[158:159]
	v_pk_add_f32 v[4:5], v[4:5], v[164:165]
	v_pk_add_f32 v[6:7], v[6:7], v[200:201]
	v_pk_add_f32 v[4:5], v[4:5], v[214:215]
	v_pk_add_f32 v[6:7], v[6:7], v[216:217]
	v_lshl_or_b32 v2, v211, 1, 64
	v_pk_mul_f32 v[4:5], v[8:9], v[4:5]
	v_pk_mul_f32 v[6:7], v[8:9], v[6:7]
	v_lshl_add_u64 v[158:159], v[12:13], 0, v[2:3]
	s_and_b64 vcc, exec, s[38:39]
	v_cvt_pk_bf16_f32 v156, v4, v5
	v_cvt_pk_bf16_f32 v157, v6, v7
	global_store_dwordx2 v[158:159], v[156:157], off
	s_cbranch_vccnz .LBB0_277
	v_mov_b32_e32 v15, v3
	v_lshl_add_u64 v[156:157], v[10:11], 0, v[14:15]
	global_store_dwordx4 v[156:157], v[4:7], off offset:128
.LBB0_277:
	s_nop 1
	v_pk_add_f32 v[4:5], v[146:147], v[178:179]
	v_pk_add_f32 v[6:7], v[148:149], v[150:151]
	v_pk_add_f32 v[4:5], v[4:5], v[180:181]
	v_pk_add_f32 v[6:7], v[6:7], v[154:155]
	v_mov_b32_e32 v2, 0x50
	v_pk_add_f32 v[4:5], v[4:5], v[184:185]
	v_pk_add_f32 v[6:7], v[6:7], v[174:175]
	v_lshl_or_b32 v2, v211, 1, v2
	v_pk_mul_f32 v[4:5], v[8:9], v[4:5]
	v_pk_mul_f32 v[6:7], v[8:9], v[6:7]
	v_lshl_add_u64 v[148:149], v[12:13], 0, v[2:3]
	s_and_b64 vcc, exec, s[38:39]
	v_cvt_pk_bf16_f32 v146, v4, v5
	v_cvt_pk_bf16_f32 v147, v6, v7
	global_store_dwordx2 v[148:149], v[146:147], off
	s_cbranch_vccnz .LBB0_279
	v_mov_b32_e32 v15, v3
	s_nop 0
	v_lshl_add_u64 v[146:147], v[10:11], 0, v[14:15]
	global_store_dwordx4 v[146:147], v[4:7], off offset:160
.LBB0_279:
	s_nop 1
	v_pk_add_f32 v[4:5], v[32:33], v[182:183]
	v_pk_add_f32 v[6:7], v[34:35], v[152:153]
	v_pk_add_f32 v[4:5], v[4:5], v[186:187]
	v_pk_add_f32 v[6:7], v[6:7], v[172:173]
	v_mov_b32_e32 v2, 0x60
	s_nop 0
	v_pk_add_f32 v[4:5], v[4:5], v[188:189]
	v_pk_add_f32 v[6:7], v[6:7], v[176:177]
	v_lshl_or_b32 v2, v211, 1, v2
	v_pk_mul_f32 v[4:5], v[8:9], v[4:5]
	v_pk_mul_f32 v[6:7], v[8:9], v[6:7]
	v_lshl_add_u64 v[34:35], v[12:13], 0, v[2:3]
	s_and_b64 vcc, exec, s[38:39]
	v_cvt_pk_bf16_f32 v32, v4, v5
	s_nop 0
	v_cvt_pk_bf16_f32 v33, v6, v7
	global_store_dwordx2 v[34:35], v[32:33], off
	s_cbranch_vccnz .LBB0_281
	v_mov_b32_e32 v15, v3
	v_lshl_add_u64 v[32:33], v[10:11], 0, v[14:15]
	global_store_dwordx4 v[32:33], v[4:7], off offset:192
.LBB0_281:
	s_nop 1
	v_pk_add_f32 v[4:5], v[16:17], v[26:27]
	v_pk_add_f32 v[6:7], v[18:19], v[20:21]
	s_nop 0
	v_pk_add_f32 v[4:5], v[4:5], v[28:29]
	v_pk_add_f32 v[6:7], v[6:7], v[22:23]
	v_pk_add_f32 v[4:5], v[4:5], v[30:31]
	v_pk_add_f32 v[6:7], v[6:7], v[24:25]
	v_lshl_or_b32 v2, v211, 1, v202
	v_pk_mul_f32 v[4:5], v[8:9], v[4:5]
	v_pk_mul_f32 v[6:7], v[8:9], v[6:7]
	v_lshl_add_u64 v[12:13], v[12:13], 0, v[2:3]
	s_and_b64 vcc, exec, s[38:39]
	v_cvt_pk_bf16_f32 v8, v4, v5
	v_cvt_pk_bf16_f32 v9, v6, v7
	global_store_dwordx2 v[12:13], v[8:9], off
	s_cbranch_vccnz .LBB0_249
	v_mov_b32_e32 v15, v3
	v_lshl_add_u64 v[8:9], v[10:11], 0, v[14:15]
	global_store_dwordx4 v[8:9], v[4:7], off offset:224
	s_branch .LBB0_249

; __global__ void __launch_bounds__(512, 2) fwd_kernel(Args a) {
;     ...
;                 float* lut = (float*)(ldsg + 131072); float* scr = (float*)(ldsg + 131072 + 8192);
;                 for (int e = tid; e < 2048; e += 512) lut[e] = CONSTS[4608 + e];
;                 __syncthreads();
.LBB0_338:
	s_mov_b64 s[2:3], s[94:95]
	s_load_dwordx4 s[40:43], s[2:3], 0xf8
	s_mov_b32 s48, s96
	s_mov_b32 s49, s76
	s_mov_b32 s0, s93
	s_waitcnt vmcnt(0)
	v_mov_b32_e32 v4, v0
	s_movk_i32 s0, 0x800
	s_nop 0
	v_cmp_gt_i32_e32 vcc, s0, v4
	s_and_saveexec_b64 s[0:1], vcc
	s_cbranch_execz .LBB0_351
	v_max_i32_e32 v2, 0x600, v4
	v_sub_u32_e32 v2, v2, v4
	v_add_u32_e32 v2, 0x1ff, v2
	s_movk_i32 s4, 0x1ff
	v_cmp_lt_u32_e32 vcc, s4, v2
	s_mov_b64 s[18:19], -1
	s_and_saveexec_b64 s[12:13], vcc
	s_cbranch_execz .LBB0_348
	v_lshrrev_b32_e32 v2, 9, v2
	v_add_u32_e32 v6, -1, v2
	v_add_u32_e32 v5, 0x200, v4
	v_lshrrev_b32_e32 v7, 1, v6
	v_add_u32_e32 v8, 1, v7
	v_cmp_lt_u32_e32 vcc, 13, v6
	v_mov_b32_e32 v11, 0
	v_mov_b64_e32 v[6:7], v[4:5]
	s_and_saveexec_b64 s[18:19], vcc
	s_cbranch_execz .LBB0_344
	s_add_i32 s4, 0, 0x20000
	v_and_b32_e32 v9, -8, v8
	s_nop 0
	v_lshl_add_u32 v10, v4, 2, s4
	s_mov_b32 s4, 0
	s_mov_b64 s[20:21], 0
	v_mov_b64_e32 v[6:7], v[4:5]
	s_mov_b32 s5, 0x204000
.LBB0_342:
	v_ashrrev_i32_e32 v15, 31, v6
	v_mov_b32_e32 v14, v6
	s_waitcnt lgkmcnt(0)
	v_lshl_add_u64 v[14:15], v[14:15], 2, s[42:43]
	v_ashrrev_i32_e32 v13, 31, v7
	v_mov_b32_e32 v12, v7
	v_add_co_u32_e32 v14, vcc, 0x204000, v14
	v_lshl_add_u64 v[12:13], v[12:13], 2, s[42:43]
	s_nop 0
	v_addc_co_u32_e32 v15, vcc, 0, v15, vcc
	v_add_co_u32_e32 v12, vcc, 0x204000, v12
	global_load_dword v5, v[14:15], off offset:2048
	s_nop 0
	v_addc_co_u32_e32 v13, vcc, 0, v13, vcc
	global_load_dword v11, v[12:13], off offset:2048
	v_add_u32_e32 v12, 0x400, v6
	v_ashrrev_i32_e32 v13, 31, v12
	s_nop 0
	v_add_u32_e32 v14, 0x400, v7
	v_lshl_add_u64 v[12:13], v[12:13], 2, s[42:43]
	v_ashrrev_i32_e32 v15, 31, v14
	v_add_co_u32_e32 v12, vcc, s5, v12
	v_lshl_add_u64 v[14:15], v[14:15], 2, s[42:43]
	s_nop 0
	v_addc_co_u32_e32 v13, vcc, 0, v13, vcc
	v_add_u32_e32 v9, -8, v9
	s_add_i32 s4, s4, 16
	s_waitcnt vmcnt(0)
	ds_write2st64_b32 v10, v5, v11 offset1:8
	s_nop 0
	global_load_dword v5, v[12:13], off offset:2048
	v_add_co_u32_e32 v12, vcc, s5, v14
	v_add_u32_e32 v14, 0x800, v7
	s_nop 0
	v_addc_co_u32_e32 v13, vcc, 0, v15, vcc
	global_load_dword v11, v[12:13], off offset:2048
	v_add_u32_e32 v12, 0x800, v6
	v_ashrrev_i32_e32 v13, 31, v12
	v_lshl_add_u64 v[12:13], v[12:13], 2, s[42:43]
	v_ashrrev_i32_e32 v15, 31, v14
	v_add_co_u32_e32 v12, vcc, s5, v12
	v_lshl_add_u64 v[14:15], v[14:15], 2, s[42:43]
	s_nop 0
	v_addc_co_u32_e32 v13, vcc, 0, v13, vcc
	s_waitcnt vmcnt(0)
	ds_write2st64_b32 v10, v5, v11 offset0:16 offset1:24
	global_load_dword v5, v[12:13], off offset:2048
	v_add_co_u32_e32 v12, vcc, s5, v14
	v_add_u32_e32 v14, 0xc00, v7
	s_nop 0
	v_addc_co_u32_e32 v13, vcc, 0, v15, vcc
	global_load_dword v11, v[12:13], off offset:2048
	v_add_u32_e32 v12, 0xc00, v6
	v_ashrrev_i32_e32 v13, 31, v12
	v_lshl_add_u64 v[12:13], v[12:13], 2, s[42:43]
	v_ashrrev_i32_e32 v15, 31, v14
	v_add_co_u32_e32 v12, vcc, s5, v12
	v_lshl_add_u64 v[14:15], v[14:15], 2, s[42:43]
	s_nop 0
	v_addc_co_u32_e32 v13, vcc, 0, v13, vcc
	s_waitcnt vmcnt(0)
	ds_write2st64_b32 v10, v5, v11 offset0:32 offset1:40
	global_load_dword v5, v[12:13], off offset:2048
	v_add_co_u32_e32 v12, vcc, s5, v14
	v_add_u32_e32 v14, 0x1000, v7
	s_nop 0
	v_addc_co_u32_e32 v13, vcc, 0, v15, vcc
	global_load_dword v11, v[12:13], off offset:2048
	v_add_u32_e32 v12, 0x1000, v6
	v_ashrrev_i32_e32 v13, 31, v12
	v_lshl_add_u64 v[12:13], v[12:13], 2, s[42:43]
	v_ashrrev_i32_e32 v15, 31, v14
	v_add_co_u32_e32 v12, vcc, s5, v12
	v_lshl_add_u64 v[14:15], v[14:15], 2, s[42:43]
	s_nop 0
	v_addc_co_u32_e32 v13, vcc, 0, v13, vcc
	s_waitcnt vmcnt(0)
	ds_write2st64_b32 v10, v5, v11 offset0:48 offset1:56
	global_load_dword v5, v[12:13], off offset:2048
	v_add_co_u32_e32 v12, vcc, s5, v14
	v_add_u32_e32 v14, 0x1400, v7
	s_nop 0
	v_addc_co_u32_e32 v13, vcc, 0, v15, vcc
	global_load_dword v11, v[12:13], off offset:2048
	v_add_u32_e32 v12, 0x1400, v6
	v_ashrrev_i32_e32 v13, 31, v12
	v_lshl_add_u64 v[12:13], v[12:13], 2, s[42:43]
	v_ashrrev_i32_e32 v15, 31, v14
	v_add_co_u32_e32 v12, vcc, s5, v12
	v_lshl_add_u64 v[14:15], v[14:15], 2, s[42:43]
	s_nop 0
	v_addc_co_u32_e32 v13, vcc, 0, v13, vcc
	s_waitcnt vmcnt(0)
	ds_write2st64_b32 v10, v5, v11 offset0:64 offset1:72
	global_load_dword v5, v[12:13], off offset:2048
	v_add_co_u32_e32 v12, vcc, s5, v14
	s_nop 0
	v_add_u32_e32 v14, 0x1800, v7
	s_nop 0
	v_addc_co_u32_e32 v13, vcc, 0, v15, vcc
	global_load_dword v11, v[12:13], off offset:2048
	v_add_u32_e32 v12, 0x1800, v6
	v_ashrrev_i32_e32 v13, 31, v12
	v_lshl_add_u64 v[12:13], v[12:13], 2, s[42:43]
	v_ashrrev_i32_e32 v15, 31, v14
	v_add_co_u32_e32 v12, vcc, s5, v12
	v_lshl_add_u64 v[14:15], v[14:15], 2, s[42:43]
	s_nop 0
	v_addc_co_u32_e32 v13, vcc, 0, v13, vcc
	s_waitcnt vmcnt(0)
	ds_write2st64_b32 v10, v5, v11 offset0:80 offset1:88
	global_load_dword v5, v[12:13], off offset:2048
	v_add_co_u32_e32 v12, vcc, s5, v14
	v_add_u32_e32 v14, 0x1c00, v7
	s_nop 0
	v_addc_co_u32_e32 v13, vcc, 0, v15, vcc
	global_load_dword v11, v[12:13], off offset:2048
	v_add_u32_e32 v12, 0x1c00, v6
	v_ashrrev_i32_e32 v13, 31, v12
	v_lshl_add_u64 v[12:13], v[12:13], 2, s[42:43]
	v_ashrrev_i32_e32 v15, 31, v14
	v_add_co_u32_e32 v12, vcc, s5, v12
	v_lshl_add_u64 v[14:15], v[14:15], 2, s[42:43]
	s_nop 0
	v_addc_co_u32_e32 v13, vcc, 0, v13, vcc
	v_add_u32_e32 v7, 0x2000, v7
	v_add_u32_e32 v6, 0x2000, v6
	s_waitcnt vmcnt(0)
	ds_write2st64_b32 v10, v5, v11 offset0:96 offset1:104
	s_nop 0
	global_load_dword v5, v[12:13], off offset:2048
	v_add_co_u32_e32 v12, vcc, s5, v14
	s_nop 1
	v_addc_co_u32_e32 v13, vcc, 0, v15, vcc
	global_load_dword v11, v[12:13], off offset:2048
	v_cmp_eq_u32_e32 vcc, 0, v9
	s_or_b64 s[20:21], vcc, s[20:21]
	s_waitcnt vmcnt(0)
	ds_write2st64_b32 v10, v5, v11 offset0:112 offset1:120
	v_add_u32_e32 v10, 0x8000, v10
	v_mov_b32_e32 v11, s4
	s_andn2_b64 exec, exec, s[20:21]
	s_cbranch_execnz .LBB0_342
	s_or_b64 exec, exec, s[20:21]

; __global__ void __launch_bounds__(512, 2) fwd_kernel(Args a) {
;     ...
;                 for (int e = tid; e < 2048; e += 512) lut[e] = CONSTS[4608 + e];
.LBB0_346:
	v_ashrrev_i32_e32 v13, 31, v6
	v_mov_b32_e32 v12, v6
	s_waitcnt lgkmcnt(0)
	v_lshl_add_u64 v[12:13], v[12:13], 2, s[42:43]
	v_ashrrev_i32_e32 v11, 31, v7
	v_mov_b32_e32 v10, v7
	v_add_co_u32_e32 v12, vcc, 0x204000, v12
	v_lshl_add_u64 v[10:11], v[10:11], 2, s[42:43]
	s_nop 0
	v_addc_co_u32_e32 v13, vcc, 0, v13, vcc
	v_add_co_u32_e32 v10, vcc, 0x204000, v10
	v_add_u32_e32 v5, -1, v5
	s_nop 0
	v_addc_co_u32_e32 v11, vcc, 0, v11, vcc
	global_load_dword v9, v[12:13], off offset:2048
	s_nop 0
	global_load_dword v10, v[10:11], off offset:2048
	v_add_u32_e32 v11, 0xfffff800, v8
	v_cmp_eq_u32_e32 vcc, 0, v5
	v_add_u32_e32 v7, 0x400, v7
	v_add_u32_e32 v6, 0x400, v6
	s_or_b64 s[20:21], vcc, s[20:21]
	s_waitcnt vmcnt(0)
	s_nop 0
	ds_write_b32 v11, v9
	ds_write_b32 v8, v10
	v_add_u32_e32 v8, 0x1000, v8
	s_andn2_b64 exec, exec, s[20:21]
	s_cbranch_execnz .LBB0_346

; __global__ void __launch_bounds__(512, 2) fwd_kernel(Args a) {
;     ...
;                 for (int e = tid; e < 2048; e += 512) lut[e] = CONSTS[4608 + e];
.LBB0_348:
	s_or_b64 exec, exec, s[12:13]
	s_and_b64 exec, exec, s[18:19]
	s_cbranch_execz .LBB0_351
	v_ashrrev_i32_e32 v5, 31, v4
	s_waitcnt lgkmcnt(0)
	v_lshl_add_u64 v[6:7], v[4:5], 2, s[42:43]
	s_mov_b64 s[4:5], 0x204800
	v_lshl_add_u64 v[6:7], v[6:7], 0, s[4:5]
	s_add_i32 s4, 0, 0x20000
	v_add_u32_e32 v2, 0xfffffe00, v4
	s_nop 0
	v_lshl_add_u32 v4, v4, 2, s4
	s_mov_b64 s[12:13], 0

; __global__ void __launch_bounds__(512, 2) fwd_kernel(Args a) {
;     ...
;                 __syncthreads();
;                 if (SITE(15)) for (int u = vcu; u < 256; u += G) { const int b = u >> 4, h = (u >> 1) & 7, sp = u & 1;
;                     att::attn_sample_unit(b, h, sp, A0, ap->in[I_CK], ap->in[I_CV], out + OFF_K_S, out + OFF_V_S, PART, lut + h * 256, ldsg, scr); __syncthreads(); }
.LBB0_351:
	s_or_b64 exec, exec, s[0:1]
	s_cmpk_gt_i32 s48, 0xff
	s_waitcnt vmcnt(0) lgkmcnt(0)
	s_barrier
	s_cbranch_scc1 .LBB0_409
	s_add_u32 s0, s42, 0x24400000
	s_addc_u32 s1, s43, 0
	s_add_u32 s50, s42, 0x40c00000
	s_addc_u32 s51, s43, 0
	s_add_u32 s52, s40, 0x1a7fe000
	s_nop 0
	s_load_dwordx4 s[44:47], s[2:3], 0x20
	s_addc_u32 s53, s41, 0
	s_add_u32 s56, s40, 0x1a5fe000
	s_addc_u32 s57, s41, 0
	s_bitcmp1_b32 s48, 0
	s_cselect_b64 s[2:3], -1, 0
	s_bitcmp1_b32 s49, 0
	s_cselect_b64 s[12:13], -1, 0
	s_waitcnt lgkmcnt(0)
	s_add_u32 s58, s46, 0x100000
	s_addc_u32 s59, s47, 0
	s_add_u32 s62, s44, 0x100000
	s_addc_u32 s63, s45, 0
	s_branch .LBB0_355

; __device__ __forceinline__ int opaque_tid() { int t = threadIdx.x; asm volatile("" : "+v"(t)); return t; }
; __device__ __forceinline__ void attn_sample_unit(int b, int h, int split, const bf16* __restrict__ Q, const float* __restrict__ cache_k, const float* __restrict__ cache_v, ...
;   const int tid = opaque_tid(), wid = __builtin_amdgcn_readfirstlane(tid >> 6), lane = tid & 63, r32 = lane & 31, hi = lane >> 5;
;   const int nT = split ? 33 : 32;
;   if (wid >= 4) {
;     const int lw = wid - 4;
;     f32x4 kreg[16], vreg[16];
;     ...
;     SL_LOAD(0); SL_WRITE(0); SL_LOAD(1);
;     __syncthreads();
;     for (int j = 0; j < nT; ++j) {
;       if (j + 1 < nT) { SL_WRITE((j + 1) & 1); if (j + 2 < nT) SL_LOAD(j + 2); }
;       __syncthreads();
;     }
;     ...
;   } else {
;     const int c = wid & 1, vh = wid >> 1;
;     float* li_l = scr + wid * 64; float* al_l = li_l + 32;
;     float m_reg = -1e30f, l_reg = 0; f32x16 o[4] = {};
;     const bf16* Qw = Q + (size_t)(MP + b * 16 + (r32 & 15)) * LD + h * 256 + c * 128 + hi * 8;
;     __syncthreads();
;     for (int j = 0; j < nT; ++j) {
;       char* bb = lds + (j & 1) * 65536;
;       f32x16 p0, p1; float mn, al; bf16x8 pa0, pa1, pa2, pa3; bf16x8 qr[8];
;       asm volatile("" : "+v"(Qw));
; #pragma unroll
;       for (int d0 = 0; d0 < 8; ++d0) { bf16x8 v = *reinterpret_cast<const bf16x8*>(Qw + d0 * 16); if (r32 >= 16) v = (bf16x8){0, 0, 0, 0, 0, 0, 0, 0}; qr[d0] = v; }
.LBB0_355:
	v_mov_b32_e32 v104, v0
	s_bfe_u32 s5, s48, 0x30001
	s_and_b32 s64, s48, 1
	v_readfirstlane_b32 s37, v104
	s_lshl_b32 s4, s5, 8
	s_ashr_i32 s36, s37, 6
	v_and_b32_e32 v132, 63, v104
	v_and_b32_e32 v106, 31, v104
	v_bfe_u32 v107, v104, 5, 1
	s_mov_b64 s[18:19], -1
	s_cmp_lt_i32 s36, 4
	v_cndmask_b32_e64 v101, 0, 1, s[2:3]
	v_lshlrev_b32_e32 v105, 3, v132
	v_lshlrev_b32_e32 v100, 4, v132
	s_cbranch_scc0 .LBB0_368
	s_and_b32 s8, s37, 0x3fffffc0
	s_lshl_b32 s8, s8, 2
	s_and_b32 s66, s48, -16
	s_add_i32 s67, s8, 0
	s_add_i32 s8, s66, 0x4000
	v_and_or_b32 v4, v104, 15, s8
	v_readfirstlane_b32 s7, v101
	v_ashrrev_i32_e32 v5, 31, v4
	s_lshl_b32 s6, s7, 11
	s_lshl_b32 s21, s7, 16
	s_lshl_b32 s7, s4, 2
	v_lshlrev_b64 v[4:5], 12, v[4:5]
	s_add_i32 s65, s7, 0
	s_bfe_u32 s7, s37, 0x10006
	v_lshl_add_u64 v[4:5], s[0:1], 0, v[4:5]
	s_lshl_b32 s10, s4, 1
	v_lshl_add_u64 v[4:5], v[4:5], 0, s[10:11]
	s_lshl_b32 s10, s7, 8
	v_lshl_add_u64 v[4:5], v[4:5], 0, s[10:11]
	v_lshlrev_b32_e32 v2, 4, v107
	v_lshl_add_u64 v[102:103], v[4:5], 0, v[2:3]
	flat_load_dwordx4 v[208:211], v[102:103]
	flat_load_dwordx4 v[212:215], v[102:103] offset:32
	s_nop 0
	flat_load_dwordx4 v[216:219], v[102:103] offset:64
	flat_load_dwordx4 v[220:223], v[102:103] offset:96
	flat_load_dwordx4 v[224:227], v[102:103] offset:128
	flat_load_dwordx4 v[228:231], v[102:103] offset:160
	flat_load_dwordx4 v[232:235], v[102:103] offset:192
	flat_load_dwordx4 v[236:239], v[102:103] offset:224
	v_lshlrev_b32_e32 v4, 4, v106
	s_movk_i32 s8, 0x70
	v_and_b32_e32 v5, 0x70, v4
	v_bitop3_b32 v109, v2, v4, s8 bitop3:0x78
	s_movk_i32 s8, 0xa0
	v_bitop3_b32 v114, v2, v5, s8 bitop3:0x36
	s_movk_i32 s8, 0xe0
	v_bitop3_b32 v110, v2, v5, 32 bitop3:0x36
	v_bitop3_b32 v111, v2, v5, 64 bitop3:0x36
	v_bitop3_b32 v112, v2, v5, s22 bitop3:0x36
	v_bitop3_b32 v113, v2, v5, s70 bitop3:0x36
	v_bitop3_b32 v115, v2, v5, s34 bitop3:0x36
	v_bitop3_b32 v116, v2, v5, s8 bitop3:0x36
	v_and_b32_e32 v4, 0xc0, v100
	v_lshlrev_b32_e32 v5, 1, v132
	v_and_or_b32 v4, v105, 24, v4
	v_and_b32_e32 v5, 32, v5
	v_and_b32_e32 v6, 0x100, v105
	v_mov_b32_e32 v18, v3
	v_mov_b32_e32 v19, v3
	s_ashr_i32 s20, s37, 7
	s_add_i32 s67, s67, 0x22000
	s_nop 0
	v_or3_b32 v119, v4, v5, v6
	v_mov_b32_e32 v4, v3
	v_mov_b32_e32 v5, v3
	v_mov_b32_e32 v6, v3
	v_mov_b32_e32 v7, v3
	v_mov_b32_e32 v8, v3
	v_mov_b32_e32 v9, v3
	v_mov_b32_e32 v10, v3
	v_mov_b32_e32 v11, v3
	v_mov_b32_e32 v12, v3
	v_mov_b32_e32 v13, v3
	v_mov_b32_e32 v14, v3
	v_mov_b32_e32 v15, v3
	v_mov_b32_e32 v16, v3
	v_mov_b32_e32 v17, v3
	v_mov_b64_e32 v[34:35], v[18:19]
	v_mov_b64_e32 v[50:51], v[18:19]
	v_mov_b64_e32 v[66:67], v[18:19]
	s_bitset1_b32 s21, 21
	s_add_i32 s65, s65, 0x20000
	v_cmp_lt_u32_e64 s[40:41], 15, v106
	s_lshl_b32 s10, s7, 14
	v_lshlrev_b32_e32 v108, 8, v106
	v_cmp_gt_u32_e64 s[38:39], 32, v132
	v_lshl_add_u32 v117, v106, 2, s67
	s_lshl_b32 s70, s20, 14
	s_mov_b32 s71, 0
	v_mov_b32_e32 v120, 0
	v_mov_b32_e32 v118, 0xf149f2ca
	v_mov_b64_e32 v[32:33], v[16:17]
	v_mov_b64_e32 v[30:31], v[14:15]
	v_mov_b64_e32 v[28:29], v[12:13]
	v_mov_b64_e32 v[26:27], v[10:11]
	v_mov_b64_e32 v[24:25], v[8:9]
	v_mov_b64_e32 v[22:23], v[6:7]
	v_mov_b64_e32 v[20:21], v[4:5]
	v_mov_b64_e32 v[48:49], v[16:17]
	v_mov_b64_e32 v[46:47], v[14:15]
	v_mov_b64_e32 v[44:45], v[12:13]
	v_mov_b64_e32 v[42:43], v[10:11]
	v_mov_b64_e32 v[40:41], v[8:9]
	v_mov_b64_e32 v[38:39], v[6:7]
	v_mov_b64_e32 v[36:37], v[4:5]
	v_mov_b64_e32 v[64:65], v[16:17]
	v_mov_b64_e32 v[62:63], v[14:15]
	v_mov_b64_e32 v[60:61], v[12:13]
	v_mov_b64_e32 v[58:59], v[10:11]
	v_mov_b64_e32 v[56:57], v[8:9]
	v_mov_b64_e32 v[54:55], v[6:7]
	v_mov_b64_e32 v[52:53], v[4:5]
	s_waitcnt vmcnt(0) lgkmcnt(0)
	v_cndmask_b32_e64 v208, v208, 0, s[40:41]
	v_cndmask_b32_e64 v209, v209, 0, s[40:41]
	v_cndmask_b32_e64 v210, v210, 0, s[40:41]
	s_nop 0
	v_cndmask_b32_e64 v211, v211, 0, s[40:41]
	v_cndmask_b32_e64 v212, v212, 0, s[40:41]
	v_cndmask_b32_e64 v213, v213, 0, s[40:41]
	v_cndmask_b32_e64 v214, v214, 0, s[40:41]
	v_cndmask_b32_e64 v215, v215, 0, s[40:41]
	v_cndmask_b32_e64 v216, v216, 0, s[40:41]
	v_cndmask_b32_e64 v217, v217, 0, s[40:41]
	v_cndmask_b32_e64 v218, v218, 0, s[40:41]
	v_cndmask_b32_e64 v219, v219, 0, s[40:41]
	v_cndmask_b32_e64 v220, v220, 0, s[40:41]
	v_cndmask_b32_e64 v221, v221, 0, s[40:41]
	v_cndmask_b32_e64 v222, v222, 0, s[40:41]
	v_cndmask_b32_e64 v223, v223, 0, s[40:41]
	v_cndmask_b32_e64 v224, v224, 0, s[40:41]
	v_cndmask_b32_e64 v225, v225, 0, s[40:41]
	v_cndmask_b32_e64 v226, v226, 0, s[40:41]
	v_cndmask_b32_e64 v227, v227, 0, s[40:41]
	v_cndmask_b32_e64 v228, v228, 0, s[40:41]
	v_cndmask_b32_e64 v229, v229, 0, s[40:41]
	v_cndmask_b32_e64 v230, v230, 0, s[40:41]
	v_cndmask_b32_e64 v231, v231, 0, s[40:41]
	v_cndmask_b32_e64 v232, v232, 0, s[40:41]
	v_cndmask_b32_e64 v233, v233, 0, s[40:41]
	v_cndmask_b32_e64 v234, v234, 0, s[40:41]
	v_cndmask_b32_e64 v235, v235, 0, s[40:41]
	v_cndmask_b32_e64 v236, v236, 0, s[40:41]
	v_cndmask_b32_e64 v237, v237, 0, s[40:41]
	v_cndmask_b32_e64 v238, v238, 0, s[40:41]
	v_cndmask_b32_e64 v239, v239, 0, s[40:41]
	s_barrier
; __device__ __forceinline__ int crow(int r, int hi) { return (r & 3) + 8 * (r >> 2) + 4 * hi; }
; __device__ __forceinline__ int crow(int r, int hi) { return (r & 3) + 8 * (r >> 2) + 4 * hi; }
; __device__ __forceinline__ void qkt(f32x16& p0, f32x16& p1, const char* Ks, const bf16x8* qr, int r32, int hi) {
;   p0 = f32x16{}; p1 = f32x16{};
; #pragma unroll
;   for (int d0 = 0; d0 < 8; ++d0) { int cb = (d0 * 16 + hi * 8) * 2;
;     bf16x8 b0 = *reinterpret_cast<const bf16x8*>(Ks + KSWZ(r32, cb));
;     bf16x8 b1 = *reinterpret_cast<const bf16x8*>(Ks + KSWZ(32 + r32, cb));
;     p0 = __builtin_amdgcn_mfma_f32_32x32x16_bf16(b0, qr[d0], p0, 0, 0, 0);
;     p1 = __builtin_amdgcn_mfma_f32_32x32x16_bf16(b1, qr[d0], p1, 0, 0, 0); }
; }
; __device__ __forceinline__ void attn_sample_unit(int b, int h, int split, const bf16* __restrict__ Q, const float* __restrict__ cache_k, const float* __restrict__ cache_v, ...
;     ...
;     for (int j = 0; j < nT; ++j) {
;       char* bb = lds + (j & 1) * 65536;
;       f32x16 p0, p1; float mn, al; bf16x8 pa0, pa1, pa2, pa3; bf16x8 qr[8];
;       asm volatile("" : "+v"(Qw));
; #pragma unroll
;       for (int d0 = 0; d0 < 8; ++d0) { bf16x8 v = *reinterpret_cast<const bf16x8*>(Qw + d0 * 16); if (r32 >= 16) v = (bf16x8){0, 0, 0, 0, 0, 0, 0, 0}; qr[d0] = v; }
;       qkt(p0, p1, bb + c * 16384, qr, r32, hi);
;       const int kbase = (j == 32) ? 4096 : split * 2048 + j * 64;
;       if (kbase >= 3904) {
;         const float* lp = lut + (kbase - (4096 + r32) + 192);
; #pragma unroll
;         for (int r = 0; r < 16; ++r) { p0[r] += lp[crow(r, hi)]; p1[r] += lp[32 + crow(r, hi)]; }
;       }
.LBB0_357:
	v_mov_b32_e32 v68, v208
	v_mov_b32_e32 v69, v209
	v_mov_b32_e32 v70, v210
	v_mov_b32_e32 v71, v211
	v_mov_b32_e32 v122, v212
	v_mov_b32_e32 v123, v213
	v_mov_b32_e32 v124, v214
	v_mov_b32_e32 v125, v215
	s_and_b32 s8, s71, 0x10000
	s_add_i32 s77, s8, 0
	s_add_i32 s8, s77, s10
	v_add3_u32 v76, s8, v109, v108
	ds_read_b128 v[72:75], v76
	ds_read_b128 v[84:87], v76 offset:8192
	v_mov_b32_e32 v126, v216
	v_mov_b32_e32 v127, v217
	v_mov_b32_e32 v128, v218
	v_mov_b32_e32 v129, v219
	v_add3_u32 v121, s8, v110, v108
	ds_read_b128 v[134:137], v121
	ds_read_b128 v[138:141], v121 offset:8192
	v_add3_u32 v121, s8, v111, v108
	s_cmp_eq_u32 s71, 0x200000
	s_cselect_b64 vcc, -1, 0
	s_waitcnt vmcnt(0) lgkmcnt(0)
	v_cndmask_b32_e64 v91, v71, 0, s[40:41]
	s_nop 0
	v_cndmask_b32_e64 v90, v70, 0, s[40:41]
	v_cndmask_b32_e64 v89, v69, 0, s[40:41]
	v_cndmask_b32_e64 v88, v68, 0, s[40:41]
	v_cndmask_b32_e64 v125, v125, 0, s[40:41]
	v_cndmask_b32_e64 v124, v124, 0, s[40:41]
	v_mfma_f32_32x32x16_bf16 v[68:83], v[72:75], v[88:91], 0
	v_cndmask_b32_e64 v123, v123, 0, s[40:41]
	v_cndmask_b32_e64 v122, v122, 0, s[40:41]
	v_cndmask_b32_e64 v129, v129, 0, s[40:41]
	v_cndmask_b32_e64 v128, v128, 0, s[40:41]
	v_cndmask_b32_e64 v127, v127, 0, s[40:41]
	v_cndmask_b32_e64 v126, v126, 0, s[40:41]
	v_mfma_f32_32x32x16_bf16 v[68:83], v[134:137], v[122:125], v[68:83]
	v_mov_b32_e32 v134, v220
	v_mov_b32_e32 v135, v221
	v_mov_b32_e32 v136, v222
	v_mov_b32_e32 v137, v223
	s_waitcnt vmcnt(0) lgkmcnt(0)
	s_nop 0
	v_cndmask_b32_e64 v137, v137, 0, s[40:41]
	v_mfma_f32_32x32x16_bf16 v[84:99], v[84:87], v[88:91], 0
	v_cndmask_b32_e64 v136, v136, 0, s[40:41]
	v_cndmask_b32_e64 v135, v135, 0, s[40:41]
	v_cndmask_b32_e64 v134, v134, 0, s[40:41]
	v_mfma_f32_32x32x16_bf16 v[84:99], v[138:141], v[122:125], v[84:99]
	ds_read_b128 v[122:125], v121
	ds_read_b128 v[138:141], v121 offset:8192
	v_add3_u32 v121, s8, v112, v108
	s_waitcnt lgkmcnt(1)
	v_mfma_f32_32x32x16_bf16 v[68:83], v[122:125], v[126:129], v[68:83]
	v_mov_b32_e32 v122, v224
	v_mov_b32_e32 v123, v225
	v_mov_b32_e32 v124, v226
	v_mov_b32_e32 v125, v227
	s_waitcnt vmcnt(0) lgkmcnt(0)
	v_cndmask_b32_e64 v125, v125, 0, s[40:41]
	v_mfma_f32_32x32x16_bf16 v[84:99], v[138:141], v[126:129], v[84:99]
	ds_read_b128 v[126:129], v121
	ds_read_b128 v[138:141], v121 offset:8192
	v_add3_u32 v121, s8, v113, v108
	v_cndmask_b32_e64 v124, v124, 0, s[40:41]
	v_cndmask_b32_e64 v123, v123, 0, s[40:41]
	v_cndmask_b32_e64 v122, v122, 0, s[40:41]
	s_waitcnt lgkmcnt(1)
	v_mfma_f32_32x32x16_bf16 v[68:83], v[126:129], v[134:137], v[68:83]
	v_mov_b32_e32 v126, v228
	v_mov_b32_e32 v127, v229
	v_mov_b32_e32 v128, v230
	v_mov_b32_e32 v129, v231
	s_waitcnt vmcnt(0) lgkmcnt(0)
	v_cndmask_b32_e64 v129, v129, 0, s[40:41]
	v_mfma_f32_32x32x16_bf16 v[84:99], v[138:141], v[134:137], v[84:99]
	ds_read_b128 v[134:137], v121
	ds_read_b128 v[138:141], v121 offset:8192
	v_add3_u32 v121, s8, v114, v108
	v_cndmask_b32_e64 v128, v128, 0, s[40:41]
	v_cndmask_b32_e64 v127, v127, 0, s[40:41]
	v_cndmask_b32_e64 v126, v126, 0, s[40:41]
	s_waitcnt lgkmcnt(1)
	v_mfma_f32_32x32x16_bf16 v[68:83], v[134:137], v[122:125], v[68:83]
	v_mov_b32_e32 v134, v232
	v_mov_b32_e32 v135, v233
	v_mov_b32_e32 v136, v234
	v_mov_b32_e32 v137, v235
	s_waitcnt vmcnt(0) lgkmcnt(0)
	v_cndmask_b32_e64 v137, v137, 0, s[40:41]
	v_mfma_f32_32x32x16_bf16 v[84:99], v[138:141], v[122:125], v[84:99]
	ds_read_b128 v[122:125], v121
	ds_read_b128 v[138:141], v121 offset:8192
	v_add3_u32 v121, s8, v115, v108
	v_cndmask_b32_e64 v136, v136, 0, s[40:41]
	v_cndmask_b32_e64 v135, v135, 0, s[40:41]
	v_cndmask_b32_e64 v134, v134, 0, s[40:41]
	s_waitcnt lgkmcnt(1)
	v_mfma_f32_32x32x16_bf16 v[68:83], v[122:125], v[126:129], v[68:83]
	v_mov_b32_e32 v122, v236
	v_mov_b32_e32 v123, v237
	v_mov_b32_e32 v124, v238
	v_mov_b32_e32 v125, v239
	s_waitcnt vmcnt(0) lgkmcnt(0)
	v_cndmask_b32_e64 v125, v125, 0, s[40:41]
	v_mfma_f32_32x32x16_bf16 v[84:99], v[138:141], v[126:129], v[84:99]
	ds_read_b128 v[126:129], v121
	ds_read_b128 v[138:141], v121 offset:8192
	v_add3_u32 v121, s8, v116, v108
	v_cndmask_b32_e64 v124, v124, 0, s[40:41]
	v_cndmask_b32_e64 v123, v123, 0, s[40:41]
	v_cndmask_b32_e64 v122, v122, 0, s[40:41]
	s_and_b64 s[8:9], vcc, exec
	s_cselect_b32 s8, 0x1000, s6
	s_waitcnt lgkmcnt(1)
	v_mfma_f32_32x32x16_bf16 v[68:83], v[126:129], v[134:137], v[68:83]
	s_cmpk_lt_u32 s8, 0xf40
	s_waitcnt lgkmcnt(0)
	v_mfma_f32_32x32x16_bf16 v[84:99], v[138:141], v[134:137], v[84:99]
	ds_read_b128 v[126:129], v121
	ds_read_b128 v[134:137], v121 offset:8192
	s_waitcnt lgkmcnt(1)
	v_mfma_f32_32x32x16_bf16 v[68:83], v[126:129], v[122:125], v[68:83]
	s_waitcnt lgkmcnt(0)
	v_mfma_f32_32x32x16_bf16 v[84:99], v[134:137], v[122:125], v[84:99]
	s_cbranch_scc1 .LBB0_359
	v_sub_u32_e32 v121, s8, v106
	v_lshl_add_u32 v121, v121, 2, s65
	s_movk_i32 s8, 0xc300
	v_add3_u32 v121, v121, v2, s8
	ds_read2_b32 v[122:123], v121 offset1:1
	s_nop 0
	ds_read2_b32 v[124:125], v121 offset0:2 offset1:3
	ds_read2_b32 v[126:127], v121 offset0:8 offset1:9
	ds_read2_b32 v[128:129], v121 offset0:10 offset1:11
	ds_read2_b32 v[130:131], v121 offset0:16 offset1:17
	ds_read2_b32 v[134:135], v121 offset0:18 offset1:19
	ds_read2_b32 v[136:137], v121 offset0:24 offset1:25
	ds_read2_b32 v[138:139], v121 offset0:26 offset1:27
	ds_read2_b32 v[140:141], v121 offset0:32 offset1:33
	ds_read2_b32 v[142:143], v121 offset0:34 offset1:35
	ds_read2_b32 v[144:145], v121 offset0:40 offset1:41
	ds_read2_b32 v[146:147], v121 offset0:42 offset1:43
	s_waitcnt lgkmcnt(4)
	v_pk_add_f32 v[82:83], v[82:83], v[138:139]
	v_pk_add_f32 v[80:81], v[80:81], v[136:137]
	v_pk_add_f32 v[78:79], v[78:79], v[134:135]
	v_pk_add_f32 v[76:77], v[76:77], v[130:131]
	s_nop 0
	ds_read2_b32 v[130:131], v121 offset0:48 offset1:49
	ds_read2_b32 v[134:135], v121 offset0:50 offset1:51
	ds_read2_b32 v[136:137], v121 offset0:56 offset1:57
	ds_read2_b32 v[138:139], v121 offset0:58 offset1:59
	v_pk_add_f32 v[74:75], v[74:75], v[128:129]
	v_pk_add_f32 v[72:73], v[72:73], v[126:127]
	v_pk_add_f32 v[70:71], v[70:71], v[124:125]
	v_pk_add_f32 v[68:69], v[68:69], v[122:123]
	s_waitcnt lgkmcnt(0)
	v_pk_add_f32 v[98:99], v[98:99], v[138:139]
	v_pk_add_f32 v[96:97], v[96:97], v[136:137]
	v_pk_add_f32 v[94:95], v[94:95], v[134:135]
	v_pk_add_f32 v[92:93], v[92:93], v[130:131]
	v_pk_add_f32 v[90:91], v[90:91], v[146:147]
	v_pk_add_f32 v[88:89], v[88:89], v[144:145]
	v_pk_add_f32 v[86:87], v[86:87], v[142:143]
	s_nop 0
	v_pk_add_f32 v[84:85], v[84:85], v[140:141]
; __device__ __forceinline__ int crow(int r, int hi) { return (r & 3) + 8 * (r >> 2) + 4 * hi; }
; __device__ __forceinline__ int crow(int r, int hi) { return (r & 3) + 8 * (r >> 2) + 4 * hi; }
; #define RESC(a) do { if (__any((a) < 1.f)) { if (hi == 0) al_l[r32] = (a); asm volatile("s_waitcnt lgkmcnt(0)" ::: "memory"); \
;     _Pragma("unroll") for (int d = 0; d < 4; ++d) _Pragma("unroll") for (int r = 0; r < 16; ++r) o[d][r] *= al_l[crow(r, hi)]; } } while (0)
; __device__ __forceinline__ void partialSM(f32x16& p0, f32x16& p1, float& m_reg, float& mn, float& alpha) {
;   constexpr float C = SCALE * 1.4426950408889634f;
;   float pmax = fmaxf(p0[0], p1[0]);
; #pragma unroll
;   for (int r = 1; r < 16; ++r) pmax = __builtin_fmaxf(__builtin_fmaxf(pmax, p0[r]), p1[r]);
;   { auto rr = __builtin_amdgcn_permlane32_swap(__float_as_uint(pmax), __float_as_uint(pmax), false, false);
;     pmax = fmaxf(__uint_as_float(rr[0]), __uint_as_float(rr[1])); }
;   if (__builtin_expect(__all(pmax - m_reg <= THR / SCALE), 1)) { mn = m_reg; alpha = 1.f; }
;   else { mn = fmaxf(m_reg, pmax); alpha = __builtin_amdgcn_exp2f((m_reg - mn) * C); m_reg = mn; }
; __device__ __forceinline__ void attn_sample_unit(int b, int h, int split, const bf16* __restrict__ Q, const float* __restrict__ cache_k, const float* __restrict__ cache_v, ...
;     ...
;       if (j == 32) {
; #pragma unroll
;         for (int r = 0; r < 16; ++r) { if (crow(r, hi) >= 16) p0[r] = -1e30f; p1[r] = -1e30f; }
;       }
;       partialSM(p0, p1, m_reg, mn, al);
;       RESC(al);
.LBB0_359:
	s_nop 10
	v_cndmask_b32_e32 v84, v84, v203, vcc
	v_cndmask_b32_e32 v121, v76, v203, vcc
	v_max_f32_e32 v76, v84, v84
	v_max_f32_e32 v122, v68, v68
	v_cndmask_b32_e32 v85, v85, v203, vcc
	v_max_f32_e32 v76, v122, v76
	v_cndmask_b32_e32 v86, v86, v203, vcc
	v_max3_f32 v76, v76, v69, v85
	v_cndmask_b32_e32 v87, v87, v203, vcc
	v_max3_f32 v76, v76, v70, v86
	v_cndmask_b32_e32 v88, v88, v203, vcc
	v_max3_f32 v76, v76, v71, v87
	v_cndmask_b32_e32 v89, v89, v203, vcc
	v_max3_f32 v76, v76, v72, v88
	v_cndmask_b32_e32 v90, v90, v203, vcc
	v_max3_f32 v76, v76, v73, v89
	v_cndmask_b32_e32 v91, v91, v203, vcc
	v_max3_f32 v76, v76, v74, v90
	v_cndmask_b32_e32 v92, v92, v203, vcc
	v_max3_f32 v76, v76, v75, v91
	v_cndmask_b32_e32 v93, v93, v203, vcc
	v_cndmask_b32_e32 v77, v77, v203, vcc
	v_max3_f32 v76, v76, v121, v92
	v_cndmask_b32_e32 v94, v94, v203, vcc
	v_cndmask_b32_e32 v78, v78, v203, vcc
	v_max3_f32 v76, v76, v77, v93
	v_cndmask_b32_e32 v95, v95, v203, vcc
	v_cndmask_b32_e32 v79, v79, v203, vcc
	v_max3_f32 v76, v76, v78, v94
	v_cndmask_b32_e32 v96, v96, v203, vcc
	v_cndmask_b32_e32 v80, v80, v203, vcc
	v_max3_f32 v76, v76, v79, v95
	v_cndmask_b32_e32 v97, v97, v203, vcc
	v_cndmask_b32_e32 v81, v81, v203, vcc
	v_max3_f32 v76, v76, v80, v96
	v_cndmask_b32_e32 v98, v98, v203, vcc
	v_cndmask_b32_e32 v82, v82, v203, vcc
	v_max3_f32 v76, v76, v81, v97
	v_cndmask_b32_e32 v99, v99, v203, vcc
	v_cndmask_b32_e32 v83, v83, v203, vcc
	v_max3_f32 v76, v76, v82, v98
	v_max3_f32 v76, v76, v83, v99
	v_mov_b32_e32 v122, v76
	s_nop 1
	v_permlane32_swap_b32_e32 v76, v122
	v_max_f32_e32 v122, v122, v122
	v_max_f32_e32 v76, v76, v76
	v_max_f32_e32 v76, v76, v122
	v_sub_f32_e32 v122, v76, v118
	v_cmp_ge_f32_e32 vcc, s31, v122
	v_max_f32_e32 v122, v118, v118
	v_max_f32_e32 v122, v122, v76
	v_sub_f32_e32 v76, v118, v122
	v_mul_f32_e32 v76, 0x3e0293ee, v76
	v_exp_f32_e32 v76, v76
	s_cmp_eq_u64 vcc, exec
	s_cselect_b64 s[42:43], -1, 0
	v_cndmask_b32_e64 v76, v76, 1.0, s[42:43]
	v_cmp_gt_f32_e32 vcc, 1.0, v76
	s_cbranch_vccz .LBB0_363
	s_and_saveexec_b64 s[18:19], s[38:39]
	ds_write_b32 v117, v76 offset:128
	s_or_b64 exec, exec, s[18:19]
	s_waitcnt lgkmcnt(0)
	v_add_u32_e32 v123, s67, v2
	ds_read_b128 v[124:127], v123 offset:224
	ds_read_b128 v[128:131], v123 offset:192
	ds_read_b128 v[134:137], v123 offset:160
	ds_read_b128 v[138:141], v123 offset:128
	s_waitcnt lgkmcnt(3)
	s_nop 0
	v_pk_mul_f32 v[64:65], v[64:65], v[124:125]
	s_waitcnt lgkmcnt(2)
	v_pk_mul_f32 v[60:61], v[60:61], v[128:129]
	s_waitcnt lgkmcnt(1)
	v_pk_mul_f32 v[56:57], v[56:57], v[134:135]
	v_pk_mul_f32 v[66:67], v[66:67], v[126:127]
	v_pk_mul_f32 v[62:63], v[62:63], v[130:131]
	v_pk_mul_f32 v[58:59], v[58:59], v[136:137]
	s_waitcnt lgkmcnt(0)
	s_nop 0
	v_pk_mul_f32 v[54:55], v[54:55], v[140:141]
	v_pk_mul_f32 v[52:53], v[52:53], v[138:139]
	v_pk_mul_f32 v[48:49], v[48:49], v[124:125]
	v_pk_mul_f32 v[44:45], v[44:45], v[128:129]
	v_pk_mul_f32 v[40:41], v[40:41], v[134:135]
	v_pk_mul_f32 v[50:51], v[50:51], v[126:127]
	v_pk_mul_f32 v[46:47], v[46:47], v[130:131]
	v_pk_mul_f32 v[42:43], v[42:43], v[136:137]
	v_pk_mul_f32 v[38:39], v[38:39], v[140:141]
	v_pk_mul_f32 v[36:37], v[36:37], v[138:139]
	v_pk_mul_f32 v[32:33], v[32:33], v[124:125]
	v_pk_mul_f32 v[28:29], v[28:29], v[128:129]
	v_pk_mul_f32 v[24:25], v[24:25], v[134:135]
	v_pk_mul_f32 v[34:35], v[34:35], v[126:127]
	v_pk_mul_f32 v[30:31], v[30:31], v[130:131]
	v_pk_mul_f32 v[26:27], v[26:27], v[136:137]
	v_pk_mul_f32 v[22:23], v[22:23], v[140:141]
	v_pk_mul_f32 v[20:21], v[20:21], v[138:139]
	v_pk_mul_f32 v[16:17], v[16:17], v[124:125]
	v_pk_mul_f32 v[12:13], v[12:13], v[128:129]
	v_pk_mul_f32 v[8:9], v[8:9], v[134:135]
	v_pk_mul_f32 v[18:19], v[18:19], v[126:127]
	v_pk_mul_f32 v[14:15], v[14:15], v[130:131]
	v_pk_mul_f32 v[10:11], v[10:11], v[136:137]
	v_pk_mul_f32 v[6:7], v[6:7], v[140:141]
	v_pk_mul_f32 v[4:5], v[4:5], v[138:139]
; #define SBAR() __builtin_amdgcn_sched_barrier(0)
; __device__ __forceinline__ void partialSM(f32x16& p0, f32x16& p1, float& m_reg, float& mn, float& alpha) {
;     ...
;   else { mn = fmaxf(m_reg, pmax); alpha = __builtin_amdgcn_exp2f((m_reg - mn) * C); m_reg = mn; }
;   float mnC = -mn * C;
; #pragma unroll
;   for (int r = 0; r < 16; ++r) p0[r] = fmaf(p0[r], C, mnC);
; #pragma unroll
;   for (int r = 0; r < 16; ++r) p1[r] = fmaf(p1[r], C, mnC);
; #pragma unroll
;   for (int r = 0; r < 16; ++r) p0[r] = __builtin_amdgcn_exp2f(p0[r]);
; }
; __device__ __forceinline__ void finishSM(f32x16& p0, f32x16& p1, float alpha, float& l_reg, bf16x8& pa0, bf16x8& pa1, bf16x8& pa2, bf16x8& pa3) {
; #pragma unroll
;   for (int r = 0; r < 16; ++r) p1[r] = __builtin_amdgcn_exp2f(p1[r]);
;   float ps = 0;
; #pragma unroll
;   for (int r = 0; r < 16; ++r) ps += p0[r];
; #pragma unroll
;   for (int r = 0; r < 16; ++r) ps += p1[r];
;   { auto rr = __builtin_amdgcn_permlane32_swap(__float_as_uint(ps), __float_as_uint(ps), false, false);
;     ps = __uint_as_float(rr[0]) + __uint_as_float(rr[1]); }
;   l_reg = l_reg * alpha + ps;
;     ...
;   PK4(p0, 0, pa0); PK4(p0, 8, pa1); PK4(p1, 0, pa2); PK4(p1, 8, pa3);
; template <int D0> __device__ __forceinline__ void pv_one(f32x16& od, int vb, bf16x8 pa0, bf16x8 pa1, bf16x8 pa2, bf16x8 pa3) {
;   const s16x4 l0 = tr_read<v_rd_off(D0, 0, 0)>(vb), h0 = tr_read<v_rd_off(D0, 0, 1)>(vb), l1 = tr_read<v_rd_off(D0, 1, 0)>(vb), h1 = tr_read<v_rd_off(D0, 1, 1)>(vb);
;   const s16x4 l2 = tr_read<v_rd_off(D0, 2, 0)>(vb), h2 = tr_read<v_rd_off(D0, 2, 1)>(vb), l3 = tr_read<v_rd_off(D0, 3, 0)>(vb), h3 = tr_read<v_rd_off(D0, 3, 1)>(vb);
;   asm volatile("s_waitcnt lgkmcnt(0)" ::: "memory"); SBAR();
;     ...
;   od = __builtin_amdgcn_mfma_f32_32x32x16_bf16(pa0, PK(l0, h0), od, 0, 0, 0);
;   od = __builtin_amdgcn_mfma_f32_32x32x16_bf16(pa1, PK(l1, h1), od, 0, 0, 0);
;   od = __builtin_amdgcn_mfma_f32_32x32x16_bf16(pa2, PK(l2, h2), od, 0, 0, 0);
;   od = __builtin_amdgcn_mfma_f32_32x32x16_bf16(pa3, PK(l3, h3), od, 0, 0, 0);
;     ...
; }
; template <int D0> __device__ __forceinline__ void pv_two(f32x16& oa, f32x16& ob, int vb, bf16x8 pa0, bf16x8 pa1, bf16x8 pa2, bf16x8 pa3, bf16x8 pb0, bf16x8 pb1, bf16x8 pb2, bf16x8 pb3) {
;   const s16x4 l0 = tr_read<v_rd_off(D0, 0, 0)>(vb), h0 = tr_read<v_rd_off(D0, 0, 1)>(vb), l1 = tr_read<v_rd_off(D0, 1, 0)>(vb), h1 = tr_read<v_rd_off(D0, 1, 1)>(vb);
.LBB0_363:
	v_cndmask_b32_e64 v118, v122, v118, s[42:43]
	v_mul_f32_e32 v122, 0xbe0293ee, v118
	v_fmamk_f32 v68, v68, 0x3e0293ee, v122
	v_fmamk_f32 v69, v69, 0x3e0293ee, v122
	v_fmamk_f32 v70, v70, 0x3e0293ee, v122
	v_fmamk_f32 v71, v71, 0x3e0293ee, v122
	v_fmamk_f32 v72, v72, 0x3e0293ee, v122
	v_fmamk_f32 v73, v73, 0x3e0293ee, v122
	v_fmamk_f32 v74, v74, 0x3e0293ee, v122
	v_fmamk_f32 v75, v75, 0x3e0293ee, v122
	v_fmamk_f32 v121, v121, 0x3e0293ee, v122
	v_fmamk_f32 v77, v77, 0x3e0293ee, v122
	v_fmamk_f32 v78, v78, 0x3e0293ee, v122
	v_fmamk_f32 v79, v79, 0x3e0293ee, v122
	v_fmamk_f32 v80, v80, 0x3e0293ee, v122
	v_fmamk_f32 v81, v81, 0x3e0293ee, v122
	v_fmamk_f32 v82, v82, 0x3e0293ee, v122
	v_fmamk_f32 v83, v83, 0x3e0293ee, v122
	v_fmamk_f32 v84, v84, 0x3e0293ee, v122
	v_fmamk_f32 v85, v85, 0x3e0293ee, v122
	v_fmamk_f32 v86, v86, 0x3e0293ee, v122
	v_fmamk_f32 v87, v87, 0x3e0293ee, v122
	v_fmamk_f32 v88, v88, 0x3e0293ee, v122
	v_fmamk_f32 v89, v89, 0x3e0293ee, v122
	v_fmamk_f32 v90, v90, 0x3e0293ee, v122
	v_fmamk_f32 v91, v91, 0x3e0293ee, v122
	v_fmamk_f32 v92, v92, 0x3e0293ee, v122
	v_fmamk_f32 v93, v93, 0x3e0293ee, v122
	v_fmamk_f32 v94, v94, 0x3e0293ee, v122
	v_fmamk_f32 v95, v95, 0x3e0293ee, v122
	v_fmamk_f32 v96, v96, 0x3e0293ee, v122
	v_fmamk_f32 v97, v97, 0x3e0293ee, v122
	v_fmamk_f32 v98, v98, 0x3e0293ee, v122
	v_fmac_f32_e32 v122, 0x3e0293ee, v99
	v_exp_f32_e32 v99, v68
	v_exp_f32_e32 v69, v69
	v_exp_f32_e32 v123, v70
	v_exp_f32_e32 v71, v71
	v_exp_f32_e32 v72, v72
	v_add_f32_e32 v68, 0, v99
	v_exp_f32_e32 v73, v73
	v_add_f32_e32 v68, v69, v68
	v_exp_f32_e32 v74, v74
	v_add_f32_e32 v68, v123, v68
	v_exp_f32_e32 v75, v75
	v_add_f32_e32 v68, v71, v68
	v_exp_f32_e32 v121, v121
	v_add_f32_e32 v68, v72, v68
	v_exp_f32_e32 v77, v77
	v_add_f32_e32 v68, v73, v68
	v_exp_f32_e32 v78, v78
	v_add_f32_e32 v68, v74, v68
	v_exp_f32_e32 v79, v79
	v_add_f32_e32 v68, v75, v68
	v_exp_f32_e32 v80, v80
	v_add_f32_e32 v68, v121, v68
	v_exp_f32_e32 v81, v81
	v_add_f32_e32 v68, v77, v68
	v_exp_f32_e32 v82, v82
	v_add_f32_e32 v68, v78, v68
	v_exp_f32_e32 v83, v83
	v_add_f32_e32 v68, v79, v68
	v_exp_f32_e32 v84, v84
	v_add_f32_e32 v68, v80, v68
	v_exp_f32_e32 v85, v85
	v_add_f32_e32 v68, v81, v68
	v_exp_f32_e32 v86, v86
	v_add_f32_e32 v68, v82, v68
	v_exp_f32_e32 v87, v87
	v_add_f32_e32 v68, v83, v68
	v_exp_f32_e32 v88, v88
	v_add_f32_e32 v68, v84, v68
	v_exp_f32_e32 v89, v89
	v_add_f32_e32 v68, v85, v68
	v_exp_f32_e32 v90, v90
	v_add_f32_e32 v68, v86, v68
	v_exp_f32_e32 v91, v91
	v_add_f32_e32 v68, v87, v68
	v_exp_f32_e32 v92, v92
	v_add_f32_e32 v68, v88, v68
	v_exp_f32_e32 v93, v93
	v_add_f32_e32 v68, v89, v68
	v_exp_f32_e32 v94, v94
	v_add_f32_e32 v68, v90, v68
	v_exp_f32_e32 v95, v95
	v_add_f32_e32 v68, v91, v68
	v_exp_f32_e32 v96, v96
	v_add_f32_e32 v68, v92, v68
	v_exp_f32_e32 v97, v97
	v_add_f32_e32 v68, v93, v68
	v_exp_f32_e32 v98, v98
	v_add_f32_e32 v68, v94, v68
	v_exp_f32_e32 v122, v122
	v_add_f32_e32 v68, v95, v68
	v_add_f32_e32 v68, v96, v68
	v_add_f32_e32 v68, v97, v68
	v_add_f32_e32 v68, v98, v68
	v_add_f32_e32 v68, v122, v68
	v_mov_b32_e32 v70, v68
	s_nop 1
	v_permlane32_swap_b32_e32 v68, v70
	v_add_f32_e32 v68, v68, v70
	v_fmac_f32_e32 v68, v120, v76
	v_cvt_pk_bf16_f32 v70, v99, v69
	s_nop 0
	v_cvt_pk_bf16_f32 v71, v123, v71
	v_cvt_pk_bf16_f32 v72, v72, v73
	v_cvt_pk_bf16_f32 v73, v74, v75
	v_cvt_pk_bf16_f32 v74, v121, v77
	v_cvt_pk_bf16_f32 v75, v78, v79
	v_cvt_pk_bf16_f32 v76, v80, v81
	v_cvt_pk_bf16_f32 v77, v82, v83
	v_cvt_pk_bf16_f32 v78, v84, v85
	v_cvt_pk_bf16_f32 v79, v86, v87
	v_cvt_pk_bf16_f32 v80, v88, v89
	v_cvt_pk_bf16_f32 v81, v90, v91
	v_cvt_pk_bf16_f32 v82, v92, v93
	v_cvt_pk_bf16_f32 v83, v94, v95
	v_cvt_pk_bf16_f32 v84, v96, v97
	v_cvt_pk_bf16_f32 v85, v98, v122
	s_nop 0
	v_permlane32_swap_b32_e32 v70, v72
	v_permlane32_swap_b32_e32 v71, v73
	v_permlane32_swap_b32_e32 v74, v76
	v_permlane32_swap_b32_e32 v75, v77
	v_permlane32_swap_b32_e32 v78, v80
	v_permlane32_swap_b32_e32 v79, v81
	v_permlane32_swap_b32_e32 v82, v84
	v_permlane32_swap_b32_e32 v83, v85
	s_add_i32 s8, s77, s70
	s_add_i32 s8, s8, 0x8000
	v_add_u32_e32 v69, s8, v119
	ds_read_b64_tr_b16 v[86:87], v69 offset:0
	ds_read_b64_tr_b16 v[88:89], v69 offset:0x800
	s_nop 0
	ds_read_b64_tr_b16 v[90:91], v69 offset:0x1000
	ds_read_b64_tr_b16 v[92:93], v69 offset:0x1800
	ds_read_b64_tr_b16 v[94:95], v69 offset:0x2000
	ds_read_b64_tr_b16 v[96:97], v69 offset:0x2800
	ds_read_b64_tr_b16 v[120:121], v69 offset:0x3000
	ds_read_b64_tr_b16 v[122:123], v69 offset:0x3800
	s_waitcnt lgkmcnt(0)
	s_nop 0
	v_mfma_f32_32x32x16_bf16 v[52:67], v[70:73], v[86:89], v[52:67]
	ds_read_b64_tr_b16 v[86:87], v69 offset:0x200
	ds_read_b64_tr_b16 v[88:89], v69 offset:0xa00
	v_mfma_f32_32x32x16_bf16 v[52:67], v[74:77], v[90:93], v[52:67]
	ds_read_b64_tr_b16 v[90:91], v69 offset:0x1200
	ds_read_b64_tr_b16 v[92:93], v69 offset:0x1a00
	v_mfma_f32_32x32x16_bf16 v[52:67], v[78:81], v[94:97], v[52:67]
	ds_read_b64_tr_b16 v[94:95], v69 offset:0x2200
	ds_read_b64_tr_b16 v[96:97], v69 offset:0x2a00
	v_mfma_f32_32x32x16_bf16 v[52:67], v[82:85], v[120:123], v[52:67]
	ds_read_b64_tr_b16 v[120:121], v69 offset:0x3200
	ds_read_b64_tr_b16 v[122:123], v69 offset:0x3a00
	s_waitcnt lgkmcnt(0)
	v_mfma_f32_32x32x16_bf16 v[36:51], v[70:73], v[86:89], v[36:51]
	ds_read_b64_tr_b16 v[86:87], v69 offset:0x400
	ds_read_b64_tr_b16 v[88:89], v69 offset:0xc00
	v_mfma_f32_32x32x16_bf16 v[36:51], v[74:77], v[90:93], v[36:51]
	s_nop 0
	ds_read_b64_tr_b16 v[90:91], v69 offset:0x1400
	ds_read_b64_tr_b16 v[92:93], v69 offset:0x1c00
	v_mfma_f32_32x32x16_bf16 v[36:51], v[78:81], v[94:97], v[36:51]
	ds_read_b64_tr_b16 v[94:95], v69 offset:0x2400
	ds_read_b64_tr_b16 v[96:97], v69 offset:0x2c00
	v_mfma_f32_32x32x16_bf16 v[36:51], v[82:85], v[120:123], v[36:51]
	ds_read_b64_tr_b16 v[120:121], v69 offset:0x3400
	ds_read_b64_tr_b16 v[122:123], v69 offset:0x3c00
	s_waitcnt lgkmcnt(0)
	v_mfma_f32_32x32x16_bf16 v[20:35], v[70:73], v[86:89], v[20:35]
	ds_read_b64_tr_b16 v[86:87], v69 offset:0x600
	ds_read_b64_tr_b16 v[88:89], v69 offset:0xe00
	v_mfma_f32_32x32x16_bf16 v[20:35], v[74:77], v[90:93], v[20:35]
	ds_read_b64_tr_b16 v[90:91], v69 offset:0x1600
	ds_read_b64_tr_b16 v[92:93], v69 offset:0x1e00
	v_mfma_f32_32x32x16_bf16 v[20:35], v[78:81], v[94:97], v[20:35]
	s_nop 0
	ds_read_b64_tr_b16 v[94:95], v69 offset:0x2600
	ds_read_b64_tr_b16 v[96:97], v69 offset:0x2e00
	v_mfma_f32_32x32x16_bf16 v[20:35], v[82:85], v[120:123], v[20:35]
	ds_read_b64_tr_b16 v[120:121], v69 offset:0x3600
	ds_read_b64_tr_b16 v[122:123], v69 offset:0x3e00
	s_waitcnt lgkmcnt(0)
	v_mfma_f32_32x32x16_bf16 v[4:19], v[70:73], v[86:89], v[4:19]
	s_add_i32 s6, s6, 64
	s_add_i32 s71, s71, 0x10000
	s_cmp_eq_u32 s21, s71
	s_barrier
	v_mfma_f32_32x32x16_bf16 v[4:19], v[74:77], v[90:93], v[4:19]
	v_mfma_f32_32x32x16_bf16 v[4:19], v[78:81], v[94:97], v[4:19]
	v_mfma_f32_32x32x16_bf16 v[4:19], v[82:85], v[120:123], v[4:19]
	s_cbranch_scc1 .LBB0_365
	v_mov_b32_e32 v120, v68
	s_branch .LBB0_357

; __device__ __forceinline__ void attn_sample_unit(int b, int h, int split, const bf16* __restrict__ Q, const float* __restrict__ cache_k, const float* __restrict__ cache_v, ...
;     ...
;   if (wid >= 4) {
;     const int lw = wid - 4;
;     f32x4 kreg[16], vreg[16];
;     ...
;     SL_LOAD(0); SL_WRITE(0); SL_LOAD(1);
.LBB0_368:
	s_and_b64 vcc, exec, s[18:19]
	s_cbranch_vccz .LBB0_354
	v_readfirstlane_b32 s5, v101
	s_ashr_i32 s20, s48, 4
	s_lshl_b32 s38, s5, 24
	s_lshl_b32 s5, s5, 19
	s_ashr_i32 s21, s20, 31
	s_or_b32 s42, s5, 0xf00000
	s_lshl_b64 s[6:7], s[20:21], 12
	s_lshl_b32 s5, s64, 11
	s_add_i32 s10, s36, -4
	s_or_b32 s5, s6, s5
	s_add_u32 s6, s5, s10
	s_addc_u32 s7, s7, 0
	s_lshl_b64 s[18:19], s[6:7], 13
	s_add_u32 s5, s44, s18
	s_addc_u32 s6, s45, s19
	s_lshl_b32 s40, s4, 2
	s_add_u32 s4, s5, s40
	s_addc_u32 s5, s6, 0
	s_add_u32 s6, s46, s18
	s_addc_u32 s7, s47, s19
	s_add_u32 s6, s6, s40
	s_addc_u32 s7, s7, 0
	global_load_dwordx4 v[108:111], v100, s[4:5] nt
	global_load_dwordx4 v[112:115], v100, s[6:7] nt
	v_mov_b32_e32 v101, v3
	v_lshl_add_u64 v[4:5], s[4:5], 0, v[100:101]
	v_lshl_add_u64 v[6:7], s[6:7], 0, v[100:101]
	v_lshl_add_u64 v[4:5], v[4:5], 0, s[72:73]
	v_lshl_add_u64 v[6:7], v[6:7], 0, s[72:73]
	flat_load_dwordx4 v[116:119], v[4:5] nt
	flat_load_dwordx4 v[120:123], v[6:7] nt
	v_lshl_add_u64 v[4:5], v[4:5], 0, s[72:73]
	v_lshl_add_u64 v[6:7], v[6:7], 0, s[72:73]
	flat_load_dwordx4 v[124:127], v[4:5] nt
	flat_load_dwordx4 v[128:131], v[6:7] nt
	v_lshl_add_u64 v[4:5], v[4:5], 0, s[72:73]
	v_lshl_add_u64 v[6:7], v[6:7], 0, s[72:73]
	flat_load_dwordx4 v[148:151], v[4:5] nt
	flat_load_dwordx4 v[152:155], v[6:7] nt
	v_lshl_add_u64 v[4:5], v[4:5], 0, s[72:73]
	v_lshl_add_u64 v[6:7], v[6:7], 0, s[72:73]
	flat_load_dwordx4 v[172:175], v[4:5] nt
	flat_load_dwordx4 v[92:95], v[6:7] nt
	v_lshl_add_u64 v[4:5], v[4:5], 0, s[72:73]
	v_lshl_add_u64 v[6:7], v[6:7], 0, s[72:73]
	flat_load_dwordx4 v[88:91], v[4:5] nt
	flat_load_dwordx4 v[84:87], v[6:7] nt
	v_lshl_add_u64 v[4:5], v[4:5], 0, s[72:73]
	v_lshl_add_u64 v[6:7], v[6:7], 0, s[72:73]
	flat_load_dwordx4 v[80:83], v[4:5] nt
	flat_load_dwordx4 v[76:79], v[6:7] nt
	v_lshl_add_u64 v[4:5], v[4:5], 0, s[72:73]
	v_lshl_add_u64 v[6:7], v[6:7], 0, s[72:73]
	flat_load_dwordx4 v[72:75], v[4:5] nt
	flat_load_dwordx4 v[68:71], v[6:7] nt
	v_lshl_add_u64 v[4:5], v[4:5], 0, s[72:73]
	v_lshl_add_u64 v[6:7], v[6:7], 0, s[72:73]
	flat_load_dwordx4 v[64:67], v[4:5] nt
	flat_load_dwordx4 v[60:63], v[6:7] nt
	v_lshl_add_u64 v[4:5], v[4:5], 0, s[72:73]
	v_lshl_add_u64 v[6:7], v[6:7], 0, s[72:73]
	flat_load_dwordx4 v[56:59], v[4:5] nt
	flat_load_dwordx4 v[52:55], v[6:7] nt
	v_lshl_add_u64 v[4:5], v[4:5], 0, s[72:73]
	v_lshl_add_u64 v[6:7], v[6:7], 0, s[72:73]
	flat_load_dwordx4 v[48:51], v[4:5] nt
	flat_load_dwordx4 v[44:47], v[6:7] nt
	v_lshl_add_u64 v[4:5], v[4:5], 0, s[72:73]
	v_lshl_add_u64 v[6:7], v[6:7], 0, s[72:73]
	flat_load_dwordx4 v[40:43], v[4:5] nt
	flat_load_dwordx4 v[36:39], v[6:7] nt
	v_lshl_add_u64 v[4:5], v[4:5], 0, s[72:73]
	v_lshl_add_u64 v[6:7], v[6:7], 0, s[72:73]
	flat_load_dwordx4 v[32:35], v[4:5] nt
	flat_load_dwordx4 v[28:31], v[6:7] nt
	v_lshl_add_u64 v[4:5], v[4:5], 0, s[72:73]
	v_lshl_add_u64 v[6:7], v[6:7], 0, s[72:73]
	flat_load_dwordx4 v[24:27], v[4:5] nt
	flat_load_dwordx4 v[20:23], v[6:7] nt
	v_lshl_add_u64 v[4:5], v[4:5], 0, s[72:73]
	v_lshl_add_u64 v[6:7], v[6:7], 0, s[72:73]
	flat_load_dwordx4 v[16:19], v[4:5] nt
	flat_load_dwordx4 v[12:15], v[6:7] nt
	v_lshl_add_u64 v[96:97], v[4:5], 0, s[72:73]
	v_lshl_add_u64 v[98:99], v[6:7], 0, s[72:73]
	flat_load_dwordx4 v[8:11], v[96:97] nt
	flat_load_dwordx4 v[4:7], v[98:99] nt
	v_lshl_add_u64 v[96:97], v[96:97], 0, s[72:73]
	v_lshl_add_u64 v[98:99], v[98:99], 0, s[72:73]
	v_lshlrev_b32_e32 v2, 3, v106
	v_lshlrev_b32_e32 v139, 14, v107
	v_and_b32_e32 v98, 0xf0, v2
	s_lshl_b32 s5, s10, 4
	s_lshl_b32 s6, s10, 1
	v_add_u32_e32 v97, 0, v139
	s_lshl_b32 s43, s10, 8
	v_bitop3_b32 v141, s5, v98, v202 bitop3:0x6c
	s_and_b32 s5, s10, 0xfffff0
	s_and_b32 s6, s6, 8
	v_and_b32_e32 v138, 8, v2
	v_add_u32_e32 v99, s43, v97
	s_or_b32 s5, s6, s5
	s_lshr_b32 s6, s10, 1
	v_lshlrev_b32_e32 v2, 9, v132
	v_bfe_u32 v96, v104, 3, 2
	s_bfe_u32 s4, s37, 0x20006
	v_add3_u32 v99, v99, v141, v138
	s_and_b32 s6, s6, 4
	s_lshr_b32 s5, s5, 1
	v_and_b32_e32 v140, 0x4000, v2
	s_waitcnt vmcnt(0)
	v_cvt_pk_bf16_f32 v102, v108, v109
	v_cvt_pk_bf16_f32 v103, v110, v111
	ds_write_b64 v99, v[102:103]
	v_or_b32_e32 v99, s5, v96
	s_or_b32 s5, s6, s4
	v_add_u32_e32 v2, 0, v140
	v_lshlrev_b32_e32 v142, 9, v99
	s_lshl_b32 s65, s5, 6
	v_and_b32_e32 v136, 48, v105
	v_and_b32_e32 v137, 8, v105
	v_add3_u32 v99, v2, v142, s65
	s_lshl_b32 s5, s36, 4
	s_lshl_b32 s6, s36, 1
	v_add3_u32 v99, v99, v136, v137
	s_lshl_b32 s66, s36, 8
	v_bitop3_b32 v143, s5, v98, v202 bitop3:0x6c
	s_and_b32 s5, s36, 0xfffff0
	s_and_b32 s6, s6, 8
	v_cvt_pk_bf16_f32 v102, v112, v113
	v_cvt_pk_bf16_f32 v103, v114, v115
	ds_write_b64 v99, v[102:103] offset:32768
	v_add_u32_e32 v99, s66, v97
	s_or_b32 s5, s6, s5
	s_lshr_b32 s6, s36, 1
	v_add3_u32 v99, v99, v143, v138
	s_and_b32 s6, s6, 4
	s_lshr_b32 s5, s5, 1
	s_waitcnt lgkmcnt(0)
	v_cvt_pk_bf16_f32 v102, v116, v117
	v_cvt_pk_bf16_f32 v103, v118, v119
	ds_write_b64 v99, v[102:103]
	v_or_b32_e32 v99, s5, v96
	s_or_b32 s5, s6, s4
	v_lshlrev_b32_e32 v144, 9, v99
	s_lshl_b32 s41, s5, 6
	s_add_i32 s5, s36, 4
	v_add3_u32 v99, v2, v144, s41
	s_lshl_b32 s6, s5, 4
	s_lshl_b32 s7, s5, 1
	v_add3_u32 v99, v99, v136, v137
	s_lshl_b32 s67, s5, 8
	v_bitop3_b32 v145, s6, v98, v202 bitop3:0x6c
	s_and_b32 s6, s5, 0xfffff0
	s_and_b32 s7, s7, 8
	v_cvt_pk_bf16_f32 v102, v120, v121
	v_cvt_pk_bf16_f32 v103, v122, v123
	ds_write_b64 v99, v[102:103] offset:32768
	v_add_u32_e32 v99, s67, v97
	s_or_b32 s6, s7, s6
	s_lshr_b32 s5, s5, 1
	v_add3_u32 v99, v99, v145, v138
	s_and_b32 s5, s5, 4
	s_lshr_b32 s6, s6, 1
	v_cvt_pk_bf16_f32 v102, v124, v125
	v_cvt_pk_bf16_f32 v103, v126, v127
	ds_write_b64 v99, v[102:103]
	v_or_b32_e32 v99, s6, v96
	s_or_b32 s5, s5, s4
	v_lshlrev_b32_e32 v146, 9, v99
	s_lshl_b32 s77, s5, 6
	s_add_i32 s5, s36, 8
	v_add3_u32 v99, v2, v146, s77
	s_lshl_b32 s6, s5, 4
	s_lshl_b32 s7, s5, 1
	v_add3_u32 v99, v99, v136, v137
	s_lshl_b32 s78, s5, 8
	v_bitop3_b32 v147, s6, v98, v202 bitop3:0x6c
	s_and_b32 s6, s5, 0xfffff0
	s_and_b32 s7, s7, 8
	v_cvt_pk_bf16_f32 v102, v128, v129
	v_cvt_pk_bf16_f32 v103, v130, v131
	ds_write_b64 v99, v[102:103] offset:32768
	v_add_u32_e32 v99, s78, v97
	s_or_b32 s6, s7, s6
	s_lshr_b32 s5, s5, 1
	v_add3_u32 v99, v99, v147, v138
	s_and_b32 s5, s5, 4
	s_lshr_b32 s6, s6, 1
	v_cvt_pk_bf16_f32 v102, v148, v149
	v_cvt_pk_bf16_f32 v103, v150, v151
	ds_write_b64 v99, v[102:103]
	v_or_b32_e32 v99, s6, v96
	s_or_b32 s5, s5, s4
	v_lshlrev_b32_e32 v148, 9, v99
	s_lshl_b32 s79, s5, 6
	s_add_i32 s5, s36, 12
	v_add3_u32 v99, v2, v148, s79
	s_lshl_b32 s6, s5, 4
	s_lshl_b32 s7, s5, 1
	v_add3_u32 v99, v99, v136, v137
	s_lshl_b32 s80, s5, 8
	v_bitop3_b32 v149, s6, v98, v202 bitop3:0x6c
	s_and_b32 s6, s5, 0xfffff0
	s_and_b32 s7, s7, 8
	s_lshr_b32 s5, s5, 1
	v_cvt_pk_bf16_f32 v102, v152, v153
	v_cvt_pk_bf16_f32 v103, v154, v155
	ds_write_b64 v99, v[102:103] offset:32768
	v_add_u32_e32 v99, s80, v97
	s_or_b32 s6, s7, s6
	s_and_b32 s5, s5, 4
	v_add3_u32 v99, v99, v149, v138
	s_lshr_b32 s6, s6, 1
	s_or_b32 s5, s5, s4
	v_cvt_pk_bf16_f32 v102, v172, v173
	v_cvt_pk_bf16_f32 v103, v174, v175
	s_nop 0
	ds_write_b64 v99, v[102:103]
	v_cvt_pk_bf16_f32 v92, v92, v93
	v_cvt_pk_bf16_f32 v93, v94, v95
	v_or_b32_e32 v94, s6, v96
	s_lshl_b32 s81, s5, 6
	s_add_i32 s5, s36, 16
	v_lshlrev_b32_e32 v150, 9, v94
	s_lshl_b32 s6, s5, 4
	v_add3_u32 v94, v2, v150, s81
	s_lshl_b32 s82, s5, 8
	v_bitop3_b32 v151, s6, v98, v202 bitop3:0x6c
	s_and_b32 s6, s5, 0xfffff0
	s_lshl_b32 s5, s5, 1
	v_add3_u32 v94, v94, v136, v137
	s_and_b32 s5, s5, 8
	ds_write_b64 v94, v[92:93] offset:32768
	v_cvt_pk_bf16_f32 v88, v88, v89
	v_cvt_pk_bf16_f32 v89, v90, v91
	v_add_u32_e32 v90, s82, v97
	s_or_b32 s5, s5, s6
	v_add3_u32 v90, v90, v151, v138
	s_lshr_b32 s5, s5, 1
	ds_write_b64 v90, v[88:89]
	v_cvt_pk_bf16_f32 v84, v84, v85
	v_cvt_pk_bf16_f32 v85, v86, v87
	v_or_b32_e32 v86, s5, v96
	v_lshlrev_b32_e32 v152, 9, v86
	s_add_i32 s5, s36, 20
	v_add3_u32 v86, v2, v152, s41
	s_lshl_b32 s6, s5, 4
	s_lshl_b32 s7, s5, 1
	v_add3_u32 v86, v86, v136, v137
	s_lshl_b32 s83, s5, 8
	v_bitop3_b32 v153, s6, v98, v202 bitop3:0x6c
	s_and_b32 s6, s5, 0xfffff0
	s_and_b32 s7, s7, 8
	ds_write_b64 v86, v[84:85] offset:32768
	v_cvt_pk_bf16_f32 v80, v80, v81
	v_cvt_pk_bf16_f32 v81, v82, v83
	v_add_u32_e32 v82, s83, v97
	s_or_b32 s6, s7, s6
	s_lshr_b32 s5, s5, 1
	s_nop 0
	v_add3_u32 v82, v82, v153, v138
	s_and_b32 s5, s5, 4
	s_lshr_b32 s6, s6, 1
	ds_write_b64 v82, v[80:81]
	v_cvt_pk_bf16_f32 v76, v76, v77
	v_cvt_pk_bf16_f32 v77, v78, v79
	v_or_b32_e32 v78, s6, v96
	s_or_b32 s5, s5, s4
	v_lshlrev_b32_e32 v154, 9, v78
	s_lshl_b32 s84, s5, 6
	s_add_i32 s5, s36, 24
	s_nop 0
	v_add3_u32 v78, v2, v154, s84
	s_lshl_b32 s6, s5, 4
	s_lshl_b32 s7, s5, 1
	v_add3_u32 v78, v78, v136, v137
	s_lshl_b32 s85, s5, 8
	v_bitop3_b32 v155, s6, v98, v202 bitop3:0x6c
	s_and_b32 s6, s5, 0xfffff0
	s_and_b32 s7, s7, 8
	ds_write_b64 v78, v[76:77] offset:32768
	v_cvt_pk_bf16_f32 v72, v72, v73
	v_cvt_pk_bf16_f32 v73, v74, v75
	v_add_u32_e32 v74, s85, v97
	s_or_b32 s6, s7, s6
	s_lshr_b32 s5, s5, 1
	v_add3_u32 v74, v74, v155, v138
	s_and_b32 s5, s5, 4
	s_lshr_b32 s6, s6, 1
	ds_write_b64 v74, v[72:73]
	v_cvt_pk_bf16_f32 v68, v68, v69
	v_cvt_pk_bf16_f32 v69, v70, v71
	v_or_b32_e32 v70, s6, v96
	s_or_b32 s5, s5, s4
	v_lshlrev_b32_e32 v172, 9, v70
	s_lshl_b32 s86, s5, 6
	s_add_i32 s5, s36, 28
	v_add3_u32 v70, v2, v172, s86
	s_lshl_b32 s6, s5, 4
	s_lshl_b32 s7, s5, 1
	v_add3_u32 v70, v70, v136, v137
	s_lshl_b32 s87, s5, 8
	v_bitop3_b32 v173, s6, v98, v202 bitop3:0x6c
	s_and_b32 s6, s5, 0xfffff0
	s_and_b32 s7, s7, 8
	s_lshr_b32 s5, s5, 1
	ds_write_b64 v70, v[68:69] offset:32768
	v_cvt_pk_bf16_f32 v64, v64, v65
	v_cvt_pk_bf16_f32 v65, v66, v67
	v_add_u32_e32 v66, s87, v97
	s_or_b32 s6, s7, s6
	s_and_b32 s5, s5, 4
	v_add3_u32 v66, v66, v173, v138
	s_lshr_b32 s6, s6, 1
	s_or_b32 s5, s5, s4
	ds_write_b64 v66, v[64:65]
	v_cvt_pk_bf16_f32 v60, v60, v61
	v_cvt_pk_bf16_f32 v61, v62, v63
	v_or_b32_e32 v62, s6, v96
	s_lshl_b32 s88, s5, 6
	s_add_i32 s5, s36, 32
	v_lshlrev_b32_e32 v174, 9, v62
	s_lshl_b32 s6, s5, 4
	v_add3_u32 v62, v2, v174, s88
	s_lshl_b32 s89, s5, 8
	v_bitop3_b32 v175, s6, v98, v202 bitop3:0x6c
	s_and_b32 s6, s5, 0xfffff0
	s_lshl_b32 s5, s5, 1
	v_add3_u32 v62, v62, v136, v137
	s_and_b32 s5, s5, 8
	ds_write_b64 v62, v[60:61] offset:32768
	v_cvt_pk_bf16_f32 v56, v56, v57
	v_cvt_pk_bf16_f32 v57, v58, v59
	v_add_u32_e32 v58, s89, v97
	s_or_b32 s5, s5, s6
	v_add3_u32 v58, v58, v175, v138
	s_lshr_b32 s5, s5, 1
	s_nop 0
	ds_write_b64 v58, v[56:57]
	v_cvt_pk_bf16_f32 v52, v52, v53
	v_cvt_pk_bf16_f32 v53, v54, v55
	v_or_b32_e32 v54, s5, v96
	v_lshlrev_b32_e32 v176, 9, v54
	s_add_i32 s5, s36, 36
	v_add3_u32 v54, v2, v176, s41
	s_lshl_b32 s6, s5, 4
	s_lshl_b32 s7, s5, 1
	v_add3_u32 v54, v54, v136, v137
	s_lshl_b32 s90, s5, 8
	v_bitop3_b32 v177, s6, v98, v202 bitop3:0x6c
	s_and_b32 s6, s5, 0xfffff0
	s_and_b32 s7, s7, 8
	ds_write_b64 v54, v[52:53] offset:32768
	v_cvt_pk_bf16_f32 v48, v48, v49
	v_cvt_pk_bf16_f32 v49, v50, v51
	v_add_u32_e32 v50, s90, v97
	s_or_b32 s6, s7, s6
	s_lshr_b32 s5, s5, 1
	v_add3_u32 v50, v50, v177, v138
	s_and_b32 s5, s5, 4
	s_lshr_b32 s6, s6, 1
	ds_write_b64 v50, v[48:49]
	v_cvt_pk_bf16_f32 v44, v44, v45
	v_cvt_pk_bf16_f32 v45, v46, v47
	v_or_b32_e32 v46, s6, v96
	s_or_b32 s5, s5, s4
	v_lshlrev_b32_e32 v178, 9, v46
	s_lshl_b32 s91, s5, 6
	s_add_i32 s5, s36, 40
	v_add3_u32 v46, v2, v178, s91
	s_lshl_b32 s6, s5, 4
	s_lshl_b32 s7, s5, 1
	v_add3_u32 v46, v46, v136, v137
	s_lshl_b32 s92, s5, 8
	v_bitop3_b32 v179, s6, v98, v202 bitop3:0x6c
	s_and_b32 s6, s5, 0xfffff0
	s_and_b32 s7, s7, 8
	ds_write_b64 v46, v[44:45] offset:32768
	v_cvt_pk_bf16_f32 v40, v40, v41
	v_cvt_pk_bf16_f32 v41, v42, v43
	v_add_u32_e32 v42, s92, v97
	s_or_b32 s6, s7, s6
	s_lshr_b32 s5, s5, 1
	v_add3_u32 v42, v42, v179, v138
	s_and_b32 s5, s5, 4
	s_lshr_b32 s6, s6, 1
	ds_write_b64 v42, v[40:41]
	v_cvt_pk_bf16_f32 v36, v36, v37
	v_cvt_pk_bf16_f32 v37, v38, v39
	v_or_b32_e32 v38, s6, v96
	s_or_b32 s5, s5, s4
	s_mov_b32 s34, s93
	v_lshlrev_b32_e32 v180, 9, v38
	s_lshl_b32 s93, s5, 6
	s_add_i32 s5, s36, 44
	v_add3_u32 v38, v2, v180, s93
	s_lshl_b32 s6, s5, 4
	s_lshl_b32 s7, s5, 1
	s_mov_b64 s[26:27], s[94:95]
	v_add3_u32 v38, v38, v136, v137
	s_lshl_b32 s94, s5, 8
	v_bitop3_b32 v181, s6, v98, v202 bitop3:0x6c
	s_and_b32 s6, s5, 0xfffff0
	s_and_b32 s7, s7, 8
	s_lshr_b32 s5, s5, 1
	ds_write_b64 v38, v[36:37] offset:32768
	v_cvt_pk_bf16_f32 v32, v32, v33
	v_cvt_pk_bf16_f32 v33, v34, v35
	v_add_u32_e32 v34, s94, v97
	s_or_b32 s6, s7, s6
	s_and_b32 s5, s5, 4
	v_add3_u32 v34, v34, v181, v138
	s_lshr_b32 s6, s6, 1
	s_or_b32 s5, s5, s4
	ds_write_b64 v34, v[32:33]
	s_nop 0
	v_cvt_pk_bf16_f32 v28, v28, v29
	v_cvt_pk_bf16_f32 v29, v30, v31
	v_or_b32_e32 v30, s6, v96
	s_lshl_b32 s95, s5, 6
	s_add_i32 s5, s36, 48
	v_lshlrev_b32_e32 v182, 9, v30
	s_lshl_b32 s6, s5, 4
	s_mov_b32 s75, s96
	v_add3_u32 v30, v2, v182, s95
	s_lshl_b32 s96, s5, 8
	v_bitop3_b32 v183, s6, v98, v202 bitop3:0x6c
	s_nop 0
	s_and_b32 s6, s5, 0xfffff0
	s_lshl_b32 s5, s5, 1
	v_add3_u32 v30, v30, v136, v137
	s_and_b32 s5, s5, 8
	ds_write_b64 v30, v[28:29] offset:32768
	v_cvt_pk_bf16_f32 v24, v24, v25
	v_cvt_pk_bf16_f32 v25, v26, v27
	v_add_u32_e32 v26, s96, v97
	s_or_b32 s5, s5, s6
	v_add3_u32 v26, v26, v183, v138
	s_lshr_b32 s5, s5, 1
	ds_write_b64 v26, v[24:25]
	v_cvt_pk_bf16_f32 v20, v20, v21
	v_cvt_pk_bf16_f32 v21, v22, v23
	v_or_b32_e32 v22, s5, v96
	v_lshlrev_b32_e32 v184, 9, v22
	s_add_i32 s5, s36, 52
	v_add3_u32 v22, v2, v184, s41
	s_lshl_b32 s6, s5, 4
	s_lshl_b32 s7, s5, 1
	v_add3_u32 v22, v22, v136, v137
	s_lshl_b32 s97, s5, 8
	v_bitop3_b32 v185, s6, v98, v202 bitop3:0x6c
	s_and_b32 s6, s5, 0xfffff0
	s_and_b32 s7, s7, 8
	s_lshr_b32 s5, s5, 1
	ds_write_b64 v22, v[20:21] offset:32768
	v_cvt_pk_bf16_f32 v16, v16, v17
	v_cvt_pk_bf16_f32 v17, v18, v19
	v_add_u32_e32 v18, s97, v97
	s_or_b32 s6, s7, s6
	s_and_b32 s5, s5, 4
	v_add3_u32 v18, v18, v185, v138
	s_lshr_b32 s6, s6, 1
	s_or_b32 s5, s5, s4
	s_add_i32 s36, s36, 56
	ds_write_b64 v18, v[16:17]
	v_cvt_pk_bf16_f32 v12, v12, v13
	v_cvt_pk_bf16_f32 v13, v14, v15
	v_or_b32_e32 v14, s6, v96
	s_lshl_b32 s70, s5, 6
	s_lshl_b32 s5, s36, 4
	s_lshl_b32 s6, s36, 1
	v_lshlrev_b32_e32 v186, 9, v14
	v_bitop3_b32 v187, s5, v98, v202 bitop3:0x6c
	s_and_b32 s5, s36, 0xfffff0
	s_and_b32 s6, s6, 8
	v_add3_u32 v14, v2, v186, s70
	s_or_b32 s5, s6, s5
	s_lshr_b32 s6, s36, 1
	v_add3_u32 v14, v14, v136, v137
	s_lshl_b32 s71, s36, 8
	s_and_b32 s6, s6, 4
	ds_write_b64 v14, v[12:13] offset:32768
	s_nop 0
	v_cvt_pk_bf16_f32 v8, v8, v9
	v_cvt_pk_bf16_f32 v9, v10, v11
; __device__ __forceinline__ void attn_sample_unit(int b, int h, int split, const bf16* __restrict__ Q, const float* __restrict__ cache_k, const float* __restrict__ cache_v, ...
;     ...
;     SL_LOAD(0); SL_WRITE(0); SL_LOAD(1);
;     __syncthreads();
	v_add_u32_e32 v10, s71, v97
	s_or_b32 s4, s6, s4
	v_add3_u32 v10, v10, v187, v138
	s_lshr_b32 s5, s5, 1
	s_lshl_b32 s4, s4, 6
	ds_write_b64 v10, v[8:9]
	v_cvt_pk_bf16_f32 v4, v4, v5
	v_cvt_pk_bf16_f32 v5, v6, v7
	v_or_b32_e32 v6, s5, v96
	s_add_u32 s5, s18, 0x80000
	s_addc_u32 s8, s19, 0
	s_add_u32 s6, s44, s5
	s_addc_u32 s7, s45, s8
	s_add_u32 s6, s6, s40
	s_addc_u32 s7, s7, 0
	s_add_u32 s5, s46, s5
	v_lshlrev_b32_e32 v188, 9, v6
	s_addc_u32 s9, s47, s8
	v_add3_u32 v2, v2, v188, s4
	s_add_u32 s8, s5, s40
	v_add3_u32 v2, v2, v136, v137
	s_addc_u32 s9, s9, 0
	ds_write_b64 v2, v[4:5] offset:32768
	v_lshl_add_u64 v[4:5], s[6:7], 0, v[100:101]
	v_lshl_add_u64 v[6:7], s[8:9], 0, v[100:101]
	v_lshl_add_u64 v[4:5], v[4:5], 0, s[72:73]
	v_lshl_add_u64 v[6:7], v[6:7], 0, s[72:73]
	global_load_dwordx4 v[128:131], v100, s[6:7] nt
	global_load_dwordx4 v[124:127], v100, s[8:9] nt
	s_nop 0
	flat_load_dwordx4 v[120:123], v[4:5] nt
	flat_load_dwordx4 v[116:119], v[6:7] nt
	v_lshl_add_u64 v[4:5], v[4:5], 0, s[72:73]
	v_lshl_add_u64 v[6:7], v[6:7], 0, s[72:73]
	flat_load_dwordx4 v[112:115], v[4:5] nt
	flat_load_dwordx4 v[108:111], v[6:7] nt
	v_lshl_add_u64 v[4:5], v[4:5], 0, s[72:73]
	v_lshl_add_u64 v[6:7], v[6:7], 0, s[72:73]
	flat_load_dwordx4 v[104:107], v[4:5] nt
	flat_load_dwordx4 v[100:103], v[6:7] nt
	v_lshl_add_u64 v[4:5], v[4:5], 0, s[72:73]
	v_lshl_add_u64 v[6:7], v[6:7], 0, s[72:73]
	flat_load_dwordx4 v[96:99], v[4:5] nt
	flat_load_dwordx4 v[88:91], v[6:7] nt
	v_lshl_add_u64 v[4:5], v[4:5], 0, s[72:73]
	v_lshl_add_u64 v[6:7], v[6:7], 0, s[72:73]
	flat_load_dwordx4 v[92:95], v[4:5] nt
	flat_load_dwordx4 v[80:83], v[6:7] nt
	v_lshl_add_u64 v[4:5], v[4:5], 0, s[72:73]
	v_lshl_add_u64 v[6:7], v[6:7], 0, s[72:73]
	flat_load_dwordx4 v[84:87], v[4:5] nt
	flat_load_dwordx4 v[72:75], v[6:7] nt
	v_lshl_add_u64 v[4:5], v[4:5], 0, s[72:73]
	v_lshl_add_u64 v[6:7], v[6:7], 0, s[72:73]
	flat_load_dwordx4 v[76:79], v[4:5] nt
	flat_load_dwordx4 v[64:67], v[6:7] nt
	v_lshl_add_u64 v[4:5], v[4:5], 0, s[72:73]
	v_lshl_add_u64 v[6:7], v[6:7], 0, s[72:73]
	flat_load_dwordx4 v[68:71], v[4:5] nt
	flat_load_dwordx4 v[56:59], v[6:7] nt
	v_lshl_add_u64 v[4:5], v[4:5], 0, s[72:73]
	v_lshl_add_u64 v[6:7], v[6:7], 0, s[72:73]
	flat_load_dwordx4 v[60:63], v[4:5] nt
	flat_load_dwordx4 v[48:51], v[6:7] nt
	v_lshl_add_u64 v[4:5], v[4:5], 0, s[72:73]
	v_lshl_add_u64 v[6:7], v[6:7], 0, s[72:73]
	flat_load_dwordx4 v[52:55], v[4:5] nt
	flat_load_dwordx4 v[40:43], v[6:7] nt
	v_lshl_add_u64 v[4:5], v[4:5], 0, s[72:73]
	v_lshl_add_u64 v[6:7], v[6:7], 0, s[72:73]
	flat_load_dwordx4 v[44:47], v[4:5] nt
	flat_load_dwordx4 v[32:35], v[6:7] nt
	v_lshl_add_u64 v[4:5], v[4:5], 0, s[72:73]
	v_lshl_add_u64 v[6:7], v[6:7], 0, s[72:73]
	flat_load_dwordx4 v[36:39], v[4:5] nt
	flat_load_dwordx4 v[24:27], v[6:7] nt
	v_lshl_add_u64 v[4:5], v[4:5], 0, s[72:73]
	v_lshl_add_u64 v[6:7], v[6:7], 0, s[72:73]
	flat_load_dwordx4 v[28:31], v[4:5] nt
	flat_load_dwordx4 v[16:19], v[6:7] nt
	v_lshl_add_u64 v[4:5], v[4:5], 0, s[72:73]
	v_lshl_add_u64 v[6:7], v[6:7], 0, s[72:73]
	flat_load_dwordx4 v[20:23], v[4:5] nt
	flat_load_dwordx4 v[8:11], v[6:7] nt
	v_lshl_add_u64 v[134:135], v[4:5], 0, s[72:73]
	v_lshl_add_u64 v[156:157], v[6:7], 0, s[72:73]
	flat_load_dwordx4 v[12:15], v[134:135] nt
	flat_load_dwordx4 v[4:7], v[156:157] nt
	s_lshl_b64 s[6:7], s[20:21], 17
	s_add_u32 s5, s56, s6
	s_addc_u32 s14, s57, s7
	s_lshl_b64 s[8:9], s[10:11], 13
	s_add_u32 s5, s5, s8
	s_addc_u32 s10, s14, s9
	s_add_u32 s6, s52, s6
	s_addc_u32 s7, s53, s7
	s_add_u32 s6, s6, s8
	s_addc_u32 s7, s7, s9
	s_lshl_b64 s[14:15], s[20:21], 25
	s_or_b32 s14, s14, s38
	s_add_u32 s14, s14, s8
	s_addc_u32 s15, s15, s9
	s_add_u32 s8, s58, s14
	s_addc_u32 s9, s59, s15
	v_lshlrev_b32_e32 v2, 2, v132
	s_add_u32 s14, s62, s14
	s_mov_b32 s30, s76
	v_lshl_add_u64 v[132:133], v[134:135], 0, s[72:73]
	v_lshl_add_u64 v[134:135], v[156:157], 0, s[72:73]
	s_addc_u32 s15, s63, s15
	s_mov_b64 s[20:21], 0
	s_mov_b32 s76, 0x10000
	v_lshlrev_b32_e32 v2, 2, v2
	s_waitcnt lgkmcnt(0)
	s_barrier
	s_branch .LBB0_372

; __device__ __forceinline__ void attn_sample_unit(int b, int h, int split, const bf16* __restrict__ Q, const float* __restrict__ cache_k, const float* __restrict__ cache_v, ...
;     ...
;     for (int j = 0; j < nT; ++j) {
;       if (j + 1 < nT) { SL_WRITE((j + 1) & 1); if (j + 2 < nT) SL_LOAD(j + 2); }
;       __syncthreads();
.LBB0_372:
	s_and_b32 s28, s76, 0x10000
	s_add_i32 s28, s28, 0
	v_add_u32_e32 v132, s28, v139
	s_waitcnt vmcnt(0)
	v_cvt_pk_bf16_f32 v128, v128, v129
	v_cvt_pk_bf16_f32 v129, v130, v131
	v_add_u32_e32 v130, s43, v132
	v_add_u32_e32 v133, s28, v140
	s_nop 0
	v_add3_u32 v130, v130, v141, v138
	ds_write_b64 v130, v[128:129]
	v_cvt_pk_bf16_f32 v124, v124, v125
	v_cvt_pk_bf16_f32 v125, v126, v127
	v_add3_u32 v126, v133, v142, s65
	v_add3_u32 v126, v126, v136, v137
	ds_write_b64 v126, v[124:125] offset:32768
	v_cvt_pk_bf16_f32 v120, v120, v121
	v_cvt_pk_bf16_f32 v121, v122, v123
	v_add_u32_e32 v122, s66, v132
	v_add3_u32 v122, v122, v143, v138
	ds_write_b64 v122, v[120:121]
	v_cvt_pk_bf16_f32 v116, v116, v117
	v_cvt_pk_bf16_f32 v117, v118, v119
	v_add3_u32 v118, v133, v144, s41
	v_add3_u32 v118, v118, v136, v137
	s_nop 0
	ds_write_b64 v118, v[116:117] offset:32768
	v_cvt_pk_bf16_f32 v112, v112, v113
	v_cvt_pk_bf16_f32 v113, v114, v115
	v_add_u32_e32 v114, s67, v132
	v_add3_u32 v114, v114, v145, v138
	ds_write_b64 v114, v[112:113]
	v_cvt_pk_bf16_f32 v108, v108, v109
	v_cvt_pk_bf16_f32 v109, v110, v111
	s_nop 0
	v_add3_u32 v110, v133, v146, s77
	v_add3_u32 v110, v110, v136, v137
	ds_write_b64 v110, v[108:109] offset:32768
	v_cvt_pk_bf16_f32 v104, v104, v105
	v_cvt_pk_bf16_f32 v105, v106, v107
	v_add_u32_e32 v106, s78, v132
	v_add3_u32 v106, v106, v147, v138
	ds_write_b64 v106, v[104:105]
	s_nop 0
	v_cvt_pk_bf16_f32 v100, v100, v101
	v_cvt_pk_bf16_f32 v101, v102, v103
	v_add3_u32 v102, v133, v148, s79
	v_add3_u32 v102, v102, v136, v137
	ds_write_b64 v102, v[100:101] offset:32768
	v_cvt_pk_bf16_f32 v96, v96, v97
	v_cvt_pk_bf16_f32 v97, v98, v99
	v_add_u32_e32 v98, s80, v132
	s_nop 0
	v_add3_u32 v98, v98, v149, v138
	ds_write_b64 v98, v[96:97]
	v_cvt_pk_bf16_f32 v88, v88, v89
	v_cvt_pk_bf16_f32 v89, v90, v91
	v_add3_u32 v90, v133, v150, s81
	v_add3_u32 v90, v90, v136, v137
	ds_write_b64 v90, v[88:89] offset:32768
	v_add_u32_e32 v90, s82, v132
	s_nop 0
	v_add3_u32 v90, v90, v151, v138
	v_cvt_pk_bf16_f32 v88, v92, v93
	v_cvt_pk_bf16_f32 v89, v94, v95
	ds_write_b64 v90, v[88:89]
	v_cvt_pk_bf16_f32 v80, v80, v81
	v_cvt_pk_bf16_f32 v81, v82, v83
	v_add3_u32 v82, v133, v152, s41
	v_add3_u32 v82, v82, v136, v137
	ds_write_b64 v82, v[80:81] offset:32768
	v_add_u32_e32 v82, s83, v132
	v_add3_u32 v82, v82, v153, v138
	v_cvt_pk_bf16_f32 v80, v84, v85
	v_cvt_pk_bf16_f32 v81, v86, v87
	ds_write_b64 v82, v[80:81]
	v_cvt_pk_bf16_f32 v72, v72, v73
	v_cvt_pk_bf16_f32 v73, v74, v75
	s_nop 0
	v_add3_u32 v74, v133, v154, s84
	v_add3_u32 v74, v74, v136, v137
	ds_write_b64 v74, v[72:73] offset:32768
	v_add_u32_e32 v74, s85, v132
	v_add3_u32 v74, v74, v155, v138
	v_cvt_pk_bf16_f32 v72, v76, v77
	v_cvt_pk_bf16_f32 v73, v78, v79
	ds_write_b64 v74, v[72:73]
	s_nop 0
	v_cvt_pk_bf16_f32 v64, v64, v65
	v_cvt_pk_bf16_f32 v65, v66, v67
	v_add3_u32 v66, v133, v172, s86
	v_add3_u32 v66, v66, v136, v137
	ds_write_b64 v66, v[64:65] offset:32768
	v_add_u32_e32 v66, s87, v132
	v_add3_u32 v66, v66, v173, v138
	v_cvt_pk_bf16_f32 v64, v68, v69
	s_nop 0
	v_cvt_pk_bf16_f32 v65, v70, v71
	ds_write_b64 v66, v[64:65]
	v_cvt_pk_bf16_f32 v56, v56, v57
	v_cvt_pk_bf16_f32 v57, v58, v59
	v_add3_u32 v58, v133, v174, s88
	v_add3_u32 v58, v58, v136, v137
	ds_write_b64 v58, v[56:57] offset:32768
	v_add_u32_e32 v58, s89, v132
	s_nop 0
	v_add3_u32 v58, v58, v175, v138
	v_cvt_pk_bf16_f32 v56, v60, v61
	v_cvt_pk_bf16_f32 v57, v62, v63
	ds_write_b64 v58, v[56:57]
	v_cvt_pk_bf16_f32 v48, v48, v49
	v_cvt_pk_bf16_f32 v49, v50, v51
	v_add3_u32 v50, v133, v176, s41
	v_add3_u32 v50, v50, v136, v137
	ds_write_b64 v50, v[48:49] offset:32768
	v_add_u32_e32 v50, s90, v132
	v_add3_u32 v50, v50, v177, v138
	v_cvt_pk_bf16_f32 v48, v52, v53
	v_cvt_pk_bf16_f32 v49, v54, v55
	ds_write_b64 v50, v[48:49]
	v_cvt_pk_bf16_f32 v40, v40, v41
	v_cvt_pk_bf16_f32 v41, v42, v43
	s_nop 0
	v_add3_u32 v42, v133, v178, s91
	v_add3_u32 v42, v42, v136, v137
	ds_write_b64 v42, v[40:41] offset:32768
	v_add_u32_e32 v42, s92, v132
	v_add3_u32 v42, v42, v179, v138
	v_cvt_pk_bf16_f32 v40, v44, v45
	v_cvt_pk_bf16_f32 v41, v46, v47
	ds_write_b64 v42, v[40:41]
	s_nop 0
	v_cvt_pk_bf16_f32 v32, v32, v33
	v_cvt_pk_bf16_f32 v33, v34, v35
	v_add3_u32 v34, v133, v180, s93
	v_add3_u32 v34, v34, v136, v137
	ds_write_b64 v34, v[32:33] offset:32768
	v_add_u32_e32 v34, s94, v132
	v_add3_u32 v34, v34, v181, v138
	v_cvt_pk_bf16_f32 v32, v36, v37
	s_nop 0
	v_cvt_pk_bf16_f32 v33, v38, v39
	ds_write_b64 v34, v[32:33]
	v_cvt_pk_bf16_f32 v24, v24, v25
	v_cvt_pk_bf16_f32 v25, v26, v27
	v_add3_u32 v26, v133, v182, s95
	v_add3_u32 v26, v26, v136, v137
	s_cmp_lg_u32 s20, 0xf00000
	ds_write_b64 v26, v[24:25] offset:32768
	v_add_u32_e32 v26, s96, v132
	s_cselect_b64 s[36:37], -1, 0
	s_add_u32 s28, s14, s20
	v_add3_u32 v26, v26, v183, v138
	s_addc_u32 s29, s15, s21
	v_cvt_pk_bf16_f32 v24, v28, v29
	v_cvt_pk_bf16_f32 v25, v30, v31
	ds_write_b64 v26, v[24:25]
	v_cvt_pk_bf16_f32 v16, v16, v17
	v_cvt_pk_bf16_f32 v17, v18, v19
	v_add3_u32 v18, v133, v184, s41
	s_add_u32 s33, s8, s20
	v_add3_u32 v18, v18, v136, v137
	s_addc_u32 s23, s9, s21
	ds_write_b64 v18, v[16:17] offset:32768
	v_add_u32_e32 v18, s97, v132
	s_cmp_eq_u32 s20, 0xf00000
	v_add3_u32 v18, v18, v185, v138
	s_cselect_b64 s[38:39], -1, 0
	v_cvt_pk_bf16_f32 v16, v20, v21
	v_cvt_pk_bf16_f32 v17, v22, v23
	ds_write_b64 v18, v[16:17]
	v_cvt_pk_bf16_f32 v8, v8, v9
	v_cvt_pk_bf16_f32 v9, v10, v11
	v_add3_u32 v10, v133, v186, s70
	s_and_b64 vcc, s[38:39], exec
	v_add3_u32 v10, v10, v136, v137
	s_cselect_b32 s28, s5, s28
	ds_write_b64 v10, v[8:9] offset:32768
	v_add_u32_e32 v10, s71, v132
	s_cselect_b32 s29, s10, s29
	s_cselect_b32 s23, s7, s23
	s_cselect_b32 s33, s6, s33
	s_add_u32 s38, s28, s40
	v_add3_u32 v10, v10, v187, v138
	s_addc_u32 s39, s29, 0
	v_cvt_pk_bf16_f32 v8, v12, v13
	v_cvt_pk_bf16_f32 v9, v14, v15
	ds_write_b64 v10, v[8:9]
	v_cvt_pk_bf16_f32 v4, v4, v5
	v_cvt_pk_bf16_f32 v5, v6, v7
	v_add3_u32 v6, v133, v188, s4
	s_add_u32 s28, s33, s40
	v_add3_u32 v6, v6, v136, v137
	s_addc_u32 s29, s23, 0
	ds_write_b64 v6, v[4:5] offset:32768
	v_lshl_add_u64 v[4:5], s[38:39], 0, v[2:3]
	v_lshl_add_u64 v[6:7], s[28:29], 0, v[2:3]
	v_lshl_add_u64 v[4:5], v[4:5], 0, s[72:73]
	v_lshl_add_u64 v[6:7], v[6:7], 0, s[72:73]
	global_load_dwordx4 v[128:131], v2, s[38:39] nt
	global_load_dwordx4 v[124:127], v2, s[28:29] nt
	flat_load_dwordx4 v[120:123], v[4:5] nt
	flat_load_dwordx4 v[116:119], v[6:7] nt
	v_lshl_add_u64 v[4:5], v[4:5], 0, s[72:73]
	v_lshl_add_u64 v[6:7], v[6:7], 0, s[72:73]
	flat_load_dwordx4 v[112:115], v[4:5] nt
	flat_load_dwordx4 v[108:111], v[6:7] nt
	v_lshl_add_u64 v[4:5], v[4:5], 0, s[72:73]
	v_lshl_add_u64 v[6:7], v[6:7], 0, s[72:73]
	flat_load_dwordx4 v[104:107], v[4:5] nt
	flat_load_dwordx4 v[100:103], v[6:7] nt
	v_lshl_add_u64 v[4:5], v[4:5], 0, s[72:73]
	v_lshl_add_u64 v[6:7], v[6:7], 0, s[72:73]
	s_cbranch_vccnz .LBB0_374
	s_nop 0
	flat_load_dwordx4 v[96:99], v[4:5] nt
	flat_load_dwordx4 v[88:91], v[6:7] nt
	s_branch .LBB0_375

.LBB0_375:
	v_cndmask_b32_e64 v8, 0, 1, s[36:37]
	v_lshl_add_u64 v[4:5], v[4:5], 0, s[72:73]
	s_nop 0
	v_lshl_add_u64 v[6:7], v[6:7], 0, s[72:73]
	v_cmp_ne_u32_e64 s[38:39], 1, v8
	s_andn2_b64 vcc, exec, s[36:37]
	s_cbranch_vccnz .LBB0_377
	flat_load_dwordx4 v[92:95], v[4:5] nt
	flat_load_dwordx4 v[80:83], v[6:7] nt
	s_branch .LBB0_378

.LBB0_396:
	v_lshl_add_u64 v[4:5], v[4:5], 0, s[72:73]
	v_lshl_add_u64 v[6:7], v[6:7], 0, s[72:73]
	s_and_b64 vcc, exec, s[38:39]
	s_cbranch_vccnz .LBB0_398
	flat_load_dwordx4 v[36:39], v[4:5] nt
	s_nop 0
	flat_load_dwordx4 v[24:27], v[6:7] nt
	s_branch .LBB0_399

.LBB0_399:
	v_lshl_add_u64 v[4:5], v[4:5], 0, s[72:73]
	v_lshl_add_u64 v[6:7], v[6:7], 0, s[72:73]
	s_and_b64 vcc, exec, s[38:39]
	s_cbranch_vccnz .LBB0_401
	s_nop 0
	flat_load_dwordx4 v[28:31], v[4:5] nt
	flat_load_dwordx4 v[16:19], v[6:7] nt
	s_branch .LBB0_402

; __device__ __forceinline__ void attn_sample_unit(int b, int h, int split, const bf16* __restrict__ Q, const float* __restrict__ cache_k, const float* __restrict__ cache_v, ...
;     ...
;     SL_LOAD(0); SL_WRITE(0); SL_LOAD(1);
;     __syncthreads();
;     for (int j = 0; j < nT; ++j) {
;       if (j + 1 < nT) { SL_WRITE((j + 1) & 1); if (j + 2 < nT) SL_LOAD(j + 2); }
.LBB0_407:
	s_add_i32 s8, s64, -1
	s_and_b32 s8, s8, 0x10000
	s_add_i32 s8, s8, 0
	v_add_u32_e32 v132, s8, v139
	s_waitcnt vmcnt(0)
	s_nop 0
	v_cvt_pk_bf16_f32 v128, v128, v129
	v_cvt_pk_bf16_f32 v129, v130, v131
	v_add_u32_e32 v130, s43, v132
	v_add_u32_e32 v133, s8, v140
	v_add3_u32 v130, v130, v141, v138
	ds_write_b64 v130, v[128:129]
	v_cvt_pk_bf16_f32 v124, v124, v125
	v_cvt_pk_bf16_f32 v125, v126, v127
	v_add3_u32 v126, v133, v142, s65
	v_add3_u32 v126, v126, v136, v137
	ds_write_b64 v126, v[124:125] offset:32768
	v_cvt_pk_bf16_f32 v120, v120, v121
	v_cvt_pk_bf16_f32 v121, v122, v123
	v_add_u32_e32 v122, s66, v132
	v_add3_u32 v122, v122, v143, v138
	ds_write_b64 v122, v[120:121]
	v_cvt_pk_bf16_f32 v116, v116, v117
	s_nop 0
	v_cvt_pk_bf16_f32 v117, v118, v119
	v_add3_u32 v118, v133, v144, s41
	v_add3_u32 v118, v118, v136, v137
	ds_write_b64 v118, v[116:117] offset:32768
	v_cvt_pk_bf16_f32 v112, v112, v113
	v_cvt_pk_bf16_f32 v113, v114, v115
	v_add_u32_e32 v114, s67, v132
	v_add3_u32 v114, v114, v145, v138
	s_nop 0
	ds_write_b64 v114, v[112:113]
	v_cvt_pk_bf16_f32 v108, v108, v109
	v_cvt_pk_bf16_f32 v109, v110, v111
	v_add3_u32 v110, v133, v146, s77
	v_add3_u32 v110, v110, v136, v137
	ds_write_b64 v110, v[108:109] offset:32768
	v_cvt_pk_bf16_f32 v104, v104, v105
	v_cvt_pk_bf16_f32 v105, v106, v107
	v_add_u32_e32 v106, s78, v132
	v_add3_u32 v106, v106, v147, v138
	ds_write_b64 v106, v[104:105]
	v_cvt_pk_bf16_f32 v100, v100, v101
	v_cvt_pk_bf16_f32 v101, v102, v103
	v_add3_u32 v102, v133, v148, s79
	v_add3_u32 v102, v102, v136, v137
	ds_write_b64 v102, v[100:101] offset:32768
	s_nop 0
	v_cvt_pk_bf16_f32 v96, v96, v97
	v_cvt_pk_bf16_f32 v97, v98, v99
	v_add_u32_e32 v98, s80, v132
	v_add3_u32 v98, v98, v149, v138
	ds_write_b64 v98, v[96:97]
	v_cvt_pk_bf16_f32 v88, v88, v89
	v_cvt_pk_bf16_f32 v89, v90, v91
	v_add3_u32 v90, v133, v150, s81
	s_nop 0
	v_add3_u32 v90, v90, v136, v137
	ds_write_b64 v90, v[88:89] offset:32768
	v_add_u32_e32 v90, s82, v132
	v_add3_u32 v90, v90, v151, v138
	v_cvt_pk_bf16_f32 v88, v92, v93
	v_cvt_pk_bf16_f32 v89, v94, v95
	ds_write_b64 v90, v[88:89]
	v_cvt_pk_bf16_f32 v80, v80, v81
	s_nop 0
	v_cvt_pk_bf16_f32 v81, v82, v83
	v_add3_u32 v82, v133, v152, s41
	v_add3_u32 v82, v82, v136, v137
	ds_write_b64 v82, v[80:81] offset:32768
	v_add_u32_e32 v82, s83, v132
	v_add3_u32 v82, v82, v153, v138
	v_cvt_pk_bf16_f32 v80, v84, v85
	v_cvt_pk_bf16_f32 v81, v86, v87
	s_nop 0
	ds_write_b64 v82, v[80:81]
	v_cvt_pk_bf16_f32 v72, v72, v73
	v_cvt_pk_bf16_f32 v73, v74, v75
	v_add3_u32 v74, v133, v154, s84
	v_add3_u32 v74, v74, v136, v137
	ds_write_b64 v74, v[72:73] offset:32768
	v_add_u32_e32 v74, s85, v132
	v_add3_u32 v74, v74, v155, v138
	s_nop 0
	v_cvt_pk_bf16_f32 v72, v76, v77
	v_cvt_pk_bf16_f32 v73, v78, v79
	ds_write_b64 v74, v[72:73]
	v_cvt_pk_bf16_f32 v64, v64, v65
	v_cvt_pk_bf16_f32 v65, v66, v67
	v_add3_u32 v66, v133, v172, s86
	v_add3_u32 v66, v66, v136, v137
	ds_write_b64 v66, v[64:65] offset:32768
	v_add_u32_e32 v66, s87, v132
	v_add3_u32 v66, v66, v173, v138
	v_cvt_pk_bf16_f32 v64, v68, v69
	v_cvt_pk_bf16_f32 v65, v70, v71
	ds_write_b64 v66, v[64:65]
	v_cvt_pk_bf16_f32 v56, v56, v57
	v_cvt_pk_bf16_f32 v57, v58, v59
	v_add3_u32 v58, v133, v174, s88
	s_nop 0
	v_add3_u32 v58, v58, v136, v137
	ds_write_b64 v58, v[56:57] offset:32768
	v_add_u32_e32 v58, s89, v132
	v_add3_u32 v58, v58, v175, v138
	v_cvt_pk_bf16_f32 v56, v60, v61
	v_cvt_pk_bf16_f32 v57, v62, v63
	ds_write_b64 v58, v[56:57]
	v_cvt_pk_bf16_f32 v48, v48, v49
	s_nop 0
	v_cvt_pk_bf16_f32 v49, v50, v51
	v_add3_u32 v50, v133, v176, s41
	v_add3_u32 v50, v50, v136, v137
	ds_write_b64 v50, v[48:49] offset:32768
	v_add_u32_e32 v50, s90, v132
	v_add3_u32 v50, v50, v177, v138
	v_cvt_pk_bf16_f32 v48, v52, v53
	v_cvt_pk_bf16_f32 v49, v54, v55
	s_nop 0
	ds_write_b64 v50, v[48:49]
	v_cvt_pk_bf16_f32 v40, v40, v41
	v_cvt_pk_bf16_f32 v41, v42, v43
	v_add3_u32 v42, v133, v178, s91
	v_add3_u32 v42, v42, v136, v137
	ds_write_b64 v42, v[40:41] offset:32768
	v_add_u32_e32 v42, s92, v132
	v_add3_u32 v42, v42, v179, v138
	s_nop 0
	v_cvt_pk_bf16_f32 v40, v44, v45
	v_cvt_pk_bf16_f32 v41, v46, v47
	ds_write_b64 v42, v[40:41]
	v_cvt_pk_bf16_f32 v32, v32, v33
	v_cvt_pk_bf16_f32 v33, v34, v35
	v_add3_u32 v34, v133, v180, s93
	v_add3_u32 v34, v34, v136, v137
	ds_write_b64 v34, v[32:33] offset:32768
	v_add_u32_e32 v34, s94, v132
	v_add3_u32 v34, v34, v181, v138
	v_cvt_pk_bf16_f32 v32, v36, v37
	v_cvt_pk_bf16_f32 v33, v38, v39
	ds_write_b64 v34, v[32:33]
	v_cvt_pk_bf16_f32 v24, v24, v25
	v_cvt_pk_bf16_f32 v25, v26, v27
	v_add3_u32 v26, v133, v182, s95
	s_nop 0
	v_add3_u32 v26, v26, v136, v137
	ds_write_b64 v26, v[24:25] offset:32768
	v_add_u32_e32 v26, s96, v132
	v_add3_u32 v26, v26, v183, v138
	v_cvt_pk_bf16_f32 v24, v28, v29
	v_cvt_pk_bf16_f32 v25, v30, v31
	ds_write_b64 v26, v[24:25]
	v_cvt_pk_bf16_f32 v16, v16, v17
	s_nop 0
	v_cvt_pk_bf16_f32 v17, v18, v19
	v_add3_u32 v18, v133, v184, s41
	v_add3_u32 v18, v18, v136, v137
	ds_write_b64 v18, v[16:17] offset:32768
	v_add_u32_e32 v18, s97, v132
	v_add3_u32 v18, v18, v185, v138
	v_cvt_pk_bf16_f32 v16, v20, v21
	v_cvt_pk_bf16_f32 v17, v22, v23
	s_nop 0
	ds_write_b64 v18, v[16:17]
	v_cvt_pk_bf16_f32 v8, v8, v9
	v_cvt_pk_bf16_f32 v9, v10, v11
	v_add3_u32 v10, v133, v186, s70
	v_add3_u32 v10, v10, v136, v137
	ds_write_b64 v10, v[8:9] offset:32768
	v_add_u32_e32 v10, s71, v132
	v_add3_u32 v10, v10, v187, v138
	s_nop 0
	v_cvt_pk_bf16_f32 v8, v12, v13
	v_cvt_pk_bf16_f32 v9, v14, v15
	ds_write_b64 v10, v[8:9]
	v_cvt_pk_bf16_f32 v4, v4, v5
	v_cvt_pk_bf16_f32 v5, v6, v7
	v_add3_u32 v6, v133, v188, s4
	v_add3_u32 v6, v6, v136, v137
	s_movk_i32 s33, 0x5ff
	s_nop 0
	ds_write_b64 v6, v[4:5] offset:32768
	s_cbranch_execnz .LBB0_353
	s_or_b32 s4, s64, 32
	s_add_u32 s8, s44, s18
	s_addc_u32 s9, s45, s19
	s_add_u32 s14, s46, s18
	s_addc_u32 s15, s47, s19
	s_lshl_b32 s18, s4, 19
	s_add_u32 s8, s8, s18
	s_addc_u32 s9, s9, 0
	s_add_u32 s14, s14, s18
	s_addc_u32 s15, s15, 0
	s_cmp_eq_u32 s4, 32
	s_cselect_b32 s4, s5, s8
	s_cselect_b32 s9, s10, s9
	s_cselect_b32 s7, s7, s15
	s_cselect_b32 s6, s6, s14
	s_add_u32 s4, s4, s40
	s_addc_u32 s5, s9, 0
	v_lshl_add_u64 v[4:5], s[4:5], 0, v[2:3]
	s_add_u32 s4, s6, s40
	s_addc_u32 s5, s7, 0
	v_lshl_add_u64 v[6:7], s[4:5], 0, v[2:3]
	v_lshl_add_u64 v[4:5], v[4:5], 0, s[72:73]
	v_lshl_add_u64 v[6:7], v[6:7], 0, s[72:73]
	s_nop 0
	s_nop 0
	v_lshl_add_u64 v[4:5], v[4:5], 0, s[72:73]
	v_lshl_add_u64 v[6:7], v[6:7], 0, s[72:73]
	s_nop 0
	v_lshl_add_u64 v[4:5], v[4:5], 0, s[72:73]
	v_lshl_add_u64 v[6:7], v[6:7], 0, s[72:73]
	s_nop 0
	v_lshl_add_u64 v[4:5], v[4:5], 0, s[72:73]
	v_lshl_add_u64 v[6:7], v[6:7], 0, s[72:73]
	s_nop 0
	s_nop 0
	v_lshl_add_u64 v[4:5], v[4:5], 0, s[72:73]
	v_lshl_add_u64 v[6:7], v[6:7], 0, s[72:73]
	s_nop 0
	v_lshl_add_u64 v[4:5], v[4:5], 0, s[72:73]
	v_lshl_add_u64 v[6:7], v[6:7], 0, s[72:73]
	s_nop 0
	v_lshl_add_u64 v[4:5], v[4:5], 0, s[72:73]
	v_lshl_add_u64 v[6:7], v[6:7], 0, s[72:73]
	s_nop 0
	s_nop 0
	v_lshl_add_u64 v[4:5], v[4:5], 0, s[72:73]
	v_lshl_add_u64 v[6:7], v[6:7], 0, s[72:73]
	s_nop 0
	v_lshl_add_u64 v[4:5], v[4:5], 0, s[72:73]
	v_lshl_add_u64 v[6:7], v[6:7], 0, s[72:73]
	s_nop 0
	v_lshl_add_u64 v[4:5], v[4:5], 0, s[72:73]
	v_lshl_add_u64 v[6:7], v[6:7], 0, s[72:73]
	s_nop 0
	s_nop 0
	v_lshl_add_u64 v[4:5], v[4:5], 0, s[72:73]
	v_lshl_add_u64 v[6:7], v[6:7], 0, s[72:73]
	s_nop 0
	v_lshl_add_u64 v[4:5], v[4:5], 0, s[72:73]
	v_lshl_add_u64 v[6:7], v[6:7], 0, s[72:73]
	s_nop 0
	v_lshl_add_u64 v[4:5], v[4:5], 0, s[72:73]
	v_lshl_add_u64 v[6:7], v[6:7], 0, s[72:73]
	s_nop 0
	s_nop 0
	v_lshl_add_u64 v[4:5], v[4:5], 0, s[72:73]
	v_lshl_add_u64 v[6:7], v[6:7], 0, s[72:73]
	s_nop 0
	v_lshl_add_u64 v[4:5], v[4:5], 0, s[72:73]
	v_lshl_add_u64 v[6:7], v[6:7], 0, s[72:73]
	s_nop 0
	v_lshl_add_u64 v[4:5], v[4:5], 0, s[72:73]
	v_lshl_add_u64 v[6:7], v[6:7], 0, s[72:73]
	s_branch .LBB0_353

; __device__ __forceinline__ int crow(int r, int hi) { return (r & 3) + 8 * (r >> 2) + 4 * hi; }
; __device__ __forceinline__ int crow(int r, int hi) { return (r & 3) + 8 * (r >> 2) + 4 * hi; }
; #define DMA_K(j_, b_) do { const char* kb_ = (const char*)Kh + (size_t)(j_) * (64 * LD * 2); _Pragma("unroll") for (int i = 0; i < 4; ++i) \
;     __builtin_amdgcn_global_load_lds((const unsigned*)(kb_ + kgo[i]), (LAS unsigned*)(K_las + (b_) * 16384 + (4 * a + i) * 1024), 16, 0, 0); } while (0)
; #define DMA_V(j_, b_) do { const char* vb_ = (const char*)Vh + (size_t)(j_) * (64 * LD * 2); _Pragma("unroll") for (int hf = 0; hf < 2; ++hf) _Pragma("unroll") for (int i = 0; i < 4; ++i) \
;     __builtin_amdgcn_global_load_lds((const unsigned*)(vb_ + hf * 256 + vgo[i]), (LAS unsigned*)(V_las + (b_) * 32768 + hf * 16384 + (4 * a + i) * 1024), 16, 0, 0); } while (0)
; __device__ __forceinline__ void attn_unit2(const bf16* __restrict__ Qb, const bf16* __restrict__ Kh, const bf16* __restrict__ Vh, bf16* __restrict__ Ob,
;                                            int NT, int lim, int qrow0, const float* lut, char* lds, float* scr) {
;     ...
;     for (int j = 0; j <= NT; ++j) {
;       if (j + 1 < NT) DMA_K(j + 1, (j + 1) & 1);
;       if (j < NT) DMA_V(j, j & 1);
;       if (j >= 1) {
;         const float* al = al0 + ((j - 1) & 1) * 128;
;         if (__any(al[r32] < 1.f) || __any(al[32 + r32] < 1.f)) {
; #pragma unroll
;           for (int rb = 0; rb < 2; ++rb)
; #pragma unroll
;             for (int d = 0; d < 4; ++d)
; #pragma unroll
;               for (int r = 0; r < 16; ++r) o[rb][d][r] *= al[rb * 32 + crow(r, hi)]; }
.LBB0_432:
	s_and_b32 s14, s7, 0x4000
	s_add_i32 s14, s6, s14
	v_lshl_add_u64 v[156:157], v[148:149], 0, s[36:37]
	s_mov_b32 m0, s14
	s_nop 0
	global_load_lds_dwordx4 v[156:157], off
	v_lshl_add_u64 v[156:157], v[150:151], 0, s[36:37]
	s_add_i32 m0, s14, 0x400
	s_nop 0
	global_load_lds_dwordx4 v[156:157], off
	v_lshl_add_u64 v[156:157], v[152:153], 0, s[36:37]
	s_nop 0
	s_add_i32 m0, s14, 0x800
	s_nop 0
	global_load_lds_dwordx4 v[156:157], off
	v_lshl_add_u64 v[156:157], v[154:155], 0, s[36:37]
	s_add_i32 m0, s14, 0xc00
	s_nop 0
	global_load_lds_dwordx4 v[156:157], off
.LBB0_433:
	s_and_b32 s14, s10, 1
	s_lshl_b32 s15, s14, 9
	s_add_i32 s15, s4, s15
	s_nop 0
	v_lshl_add_u32 v177, v172, 2, s15
	ds_read_b32 v200, v177
	s_and_b32 s23, s9, 0x8000
	s_add_i32 s23, s6, s23
	v_lshl_add_u64 v[156:157], v[138:139], 0, s[36:37]
	s_add_i32 m0, s23, 0x8000
	v_lshl_add_u64 v[158:159], v[156:157], 0, s[54:55]
	global_load_lds_dwordx4 v[158:159], off
	s_nop 0
	v_lshl_add_u64 v[158:159], v[142:143], 0, s[36:37]
	v_lshl_add_u64 v[164:165], v[158:159], 0, s[54:55]
	s_add_i32 m0, s23, 0x8400
	v_lshl_add_u64 v[156:157], v[156:157], 0, s[68:69]
	global_load_lds_dwordx4 v[164:165], off
	v_lshl_add_u64 v[164:165], v[144:145], 0, s[36:37]
	v_lshl_add_u64 v[178:179], v[164:165], 0, s[54:55]
	s_add_i32 m0, s23, 0x8800
	s_nop 0
	global_load_lds_dwordx4 v[178:179], off
	v_lshl_add_u64 v[178:179], v[146:147], 0, s[36:37]
	v_lshl_add_u64 v[180:181], v[178:179], 0, s[54:55]
	s_add_i32 m0, s23, 0x8c00
	s_nop 0
	global_load_lds_dwordx4 v[180:181], off
	v_lshl_add_u64 v[158:159], v[158:159], 0, s[68:69]
	v_lshl_add_u64 v[164:165], v[164:165], 0, s[68:69]
	v_lshl_add_u64 v[252:253], v[178:179], 0, s[68:69]
	s_waitcnt lgkmcnt(0)
	v_cmp_gt_f32_e32 vcc, 1.0, v200
	s_cmp_lg_u64 vcc, 0
	s_cselect_b64 s[46:47], -1, 0
	s_cbranch_vccz .LBB0_438
	s_andn2_b64 vcc, exec, s[46:47]
	s_cbranch_vccnz .LBB0_436
.LBB0_435:
	v_add_u32_e32 v201, s15, v140
	ds_read_b128 v[178:181], v201
	ds_read_b128 v[182:185], v201 offset:32
	ds_read_b128 v[186:189], v201 offset:64
	ds_read_b128 v[190:193], v201 offset:96
	s_waitcnt lgkmcnt(0)
	v_pk_mul_f32 v[118:119], v[118:119], v[180:181]
	v_pk_mul_f32 v[120:121], v[120:121], v[182:183]
	v_pk_mul_f32 v[124:125], v[124:125], v[186:187]
	v_pk_mul_f32 v[128:129], v[128:129], v[190:191]
	v_pk_mul_f32 v[130:131], v[130:131], v[192:193]
	v_pk_mul_f32 v[126:127], v[126:127], v[188:189]
	s_nop 0
	v_pk_mul_f32 v[122:123], v[122:123], v[184:185]
	v_pk_mul_f32 v[116:117], v[116:117], v[178:179]
	v_pk_mul_f32 v[112:113], v[112:113], v[190:191]
	v_pk_mul_f32 v[108:109], v[108:109], v[186:187]
	v_pk_mul_f32 v[104:105], v[104:105], v[182:183]
	v_pk_mul_f32 v[114:115], v[114:115], v[192:193]
	v_pk_mul_f32 v[110:111], v[110:111], v[188:189]
	v_pk_mul_f32 v[106:107], v[106:107], v[184:185]
	v_pk_mul_f32 v[102:103], v[102:103], v[180:181]
	v_pk_mul_f32 v[100:101], v[100:101], v[178:179]
	v_pk_mul_f32 v[96:97], v[96:97], v[190:191]
	v_pk_mul_f32 v[92:93], v[92:93], v[186:187]
	v_pk_mul_f32 v[88:89], v[88:89], v[182:183]
	v_pk_mul_f32 v[98:99], v[98:99], v[192:193]
	v_pk_mul_f32 v[94:95], v[94:95], v[188:189]
	v_pk_mul_f32 v[90:91], v[90:91], v[184:185]
	v_pk_mul_f32 v[86:87], v[86:87], v[180:181]
	v_pk_mul_f32 v[84:85], v[84:85], v[178:179]
	v_pk_mul_f32 v[80:81], v[80:81], v[190:191]
	v_pk_mul_f32 v[76:77], v[76:77], v[186:187]
	v_pk_mul_f32 v[72:73], v[72:73], v[182:183]
	v_pk_mul_f32 v[82:83], v[82:83], v[192:193]
	v_pk_mul_f32 v[78:79], v[78:79], v[188:189]
	v_pk_mul_f32 v[74:75], v[74:75], v[184:185]
	v_pk_mul_f32 v[70:71], v[70:71], v[180:181]
	v_pk_mul_f32 v[68:69], v[68:69], v[178:179]
	ds_read_b128 v[178:181], v201 offset:128
	ds_read_b128 v[182:185], v201 offset:160
	ds_read_b128 v[186:189], v201 offset:192
	ds_read_b128 v[190:193], v201 offset:224
	s_waitcnt lgkmcnt(0)
	v_pk_mul_f32 v[54:55], v[54:55], v[180:181]
	s_nop 0
	v_pk_mul_f32 v[56:57], v[56:57], v[182:183]
	v_pk_mul_f32 v[60:61], v[60:61], v[186:187]
	v_pk_mul_f32 v[64:65], v[64:65], v[190:191]
	v_pk_mul_f32 v[66:67], v[66:67], v[192:193]
	v_pk_mul_f32 v[62:63], v[62:63], v[188:189]
	v_pk_mul_f32 v[58:59], v[58:59], v[184:185]
	v_pk_mul_f32 v[52:53], v[52:53], v[178:179]
	v_pk_mul_f32 v[48:49], v[48:49], v[190:191]
	v_pk_mul_f32 v[44:45], v[44:45], v[186:187]
	v_pk_mul_f32 v[40:41], v[40:41], v[182:183]
	v_pk_mul_f32 v[50:51], v[50:51], v[192:193]
	v_pk_mul_f32 v[46:47], v[46:47], v[188:189]
	v_pk_mul_f32 v[42:43], v[42:43], v[184:185]
	v_pk_mul_f32 v[38:39], v[38:39], v[180:181]
	v_pk_mul_f32 v[36:37], v[36:37], v[178:179]
	v_pk_mul_f32 v[32:33], v[32:33], v[190:191]
	v_pk_mul_f32 v[28:29], v[28:29], v[186:187]
	v_pk_mul_f32 v[24:25], v[24:25], v[182:183]
	v_pk_mul_f32 v[34:35], v[34:35], v[192:193]
	v_pk_mul_f32 v[30:31], v[30:31], v[188:189]
	v_pk_mul_f32 v[26:27], v[26:27], v[184:185]
	v_pk_mul_f32 v[22:23], v[22:23], v[180:181]
	v_pk_mul_f32 v[20:21], v[20:21], v[178:179]
	v_pk_mul_f32 v[16:17], v[16:17], v[190:191]
	v_pk_mul_f32 v[12:13], v[12:13], v[186:187]
	v_pk_mul_f32 v[8:9], v[8:9], v[182:183]
	v_pk_mul_f32 v[18:19], v[18:19], v[192:193]
	v_pk_mul_f32 v[14:15], v[14:15], v[188:189]
	v_pk_mul_f32 v[10:11], v[10:11], v[184:185]
	v_pk_mul_f32 v[6:7], v[6:7], v[180:181]
	v_pk_mul_f32 v[4:5], v[4:5], v[178:179]
; #define SBAR() __builtin_amdgcn_sched_barrier(0)
; #define VRD(D0, L) const s16x4 L##0 = tr_read<v_rd_off(D0, 0, 0)>(vb), L##1 = tr_read<v_rd_off(D0, 0, 1)>(vb), L##2 = tr_read<v_rd_off(D0, 1, 0)>(vb), L##3 = tr_read<v_rd_off(D0, 1, 1)>(vb), \
;                          L##4 = tr_read<v_rd_off(D0, 2, 0)>(vb), L##5 = tr_read<v_rd_off(D0, 2, 1)>(vb), L##6 = tr_read<v_rd_off(D0, 3, 0)>(vb), L##7 = tr_read<v_rd_off(D0, 3, 1)>(vb)
; __device__ __forceinline__ void pv_four(f32x16 (&o)[2][4], int vb, bf16x8 pa0, bf16x8 pa1, bf16x8 pa2, bf16x8 pa3, bf16x8 pb0, bf16x8 pb1, bf16x8 pb2, bf16x8 pb3) {
;     ...
;   VRD(0, x); SBAR();
;   VRD(1, y); asm volatile("s_waitcnt lgkmcnt(8)" ::: "memory"); SBAR(); MMA(0, x); SBAR();
;   VRD(2, z); asm volatile("s_waitcnt lgkmcnt(8)" ::: "memory"); SBAR(); MMA(1, y); SBAR();
;   VRD(3, w); asm volatile("s_waitcnt lgkmcnt(8)" ::: "memory"); SBAR(); MMA(2, z); SBAR();
;   asm volatile("s_waitcnt lgkmcnt(0)" ::: "memory"); SBAR(); MMA(3, w);
; __device__ __forceinline__ void attn_unit2(const bf16* __restrict__ Qb, const bf16* __restrict__ Kh, const bf16* __restrict__ Vh, bf16* __restrict__ Ob,
;                                            int NT, int lim, int qrow0, const float* lut, char* lds, float* scr) {
;     ...
;         const char* ps = P0 + ((j - 1) & 1) * 16384 + lane * 16;
;         const bf16x8 pa0 = *(const bf16x8*)(ps), pa1 = *(const bf16x8*)(ps + 1024), pa2 = *(const bf16x8*)(ps + 2048), pa3 = *(const bf16x8*)(ps + 3072);
;         const bf16x8 pb0 = *(const bf16x8*)(ps + 4096), pb1 = *(const bf16x8*)(ps + 4096 + 1024), pb2 = *(const bf16x8*)(ps + 4096 + 2048), pb3 = *(const bf16x8*)(ps + 4096 + 3072);
;         const int vb = vrb + ((j - 1) & 1) * 32768 + ch * 16384;
;         pv_four(o, vb, pa0, pa1, pa2, pa3, pb0, pb1, pb2, pb3);
;       }
;       asm volatile("s_waitcnt vmcnt(0)" ::: "memory");
;       __syncthreads();
.LBB0_436:
	v_lshl_add_u32 v201, s14, 14, v175
	ds_read_b128 v[178:181], v201
	ds_read_b128 v[182:185], v201 offset:1024
	ds_read_b128 v[186:189], v201 offset:2048
	ds_read_b128 v[190:193], v201 offset:3072
	ds_read_b128 v[194:197], v201 offset:4096
	ds_read_b128 v[208:211], v201 offset:5120
	ds_read_b128 v[212:215], v201 offset:6144
	ds_read_b128 v[216:219], v201 offset:7168
	v_lshl_add_u32 v207, s14, 15, v176
	ds_read_b64_tr_b16 v[220:221], v207 offset:0
	ds_read_b64_tr_b16 v[222:223], v207 offset:0x800
	ds_read_b64_tr_b16 v[224:225], v207 offset:0x1000
	ds_read_b64_tr_b16 v[226:227], v207 offset:0x1800
	ds_read_b64_tr_b16 v[228:229], v207 offset:0x2000
	ds_read_b64_tr_b16 v[230:231], v207 offset:0x2800
	ds_read_b64_tr_b16 v[232:233], v207 offset:0x3000
	ds_read_b64_tr_b16 v[234:235], v207 offset:0x3800
	ds_read_b64_tr_b16 v[236:237], v207 offset:0x200
	ds_read_b64_tr_b16 v[238:239], v207 offset:0xa00
	ds_read_b64_tr_b16 v[240:241], v207 offset:0x1200
	ds_read_b64_tr_b16 v[242:243], v207 offset:0x1a00
	ds_read_b64_tr_b16 v[244:245], v207 offset:0x2200
	ds_read_b64_tr_b16 v[246:247], v207 offset:0x2a00
	ds_read_b64_tr_b16 v[248:249], v207 offset:0x3200
	ds_read_b64_tr_b16 v[250:251], v207 offset:0x3a00
	s_add_i32 m0, s23, 0xc000
	s_nop 0
	global_load_lds_dwordx4 v[156:157], off
	s_add_i32 m0, s23, 0xc400
	s_nop 0
	global_load_lds_dwordx4 v[158:159], off
	s_add_i32 m0, s23, 0xc800
	s_nop 0
	s_nop 0
	global_load_lds_dwordx4 v[164:165], off
	s_add_i32 m0, s23, 0xcc00
	s_nop 0
	global_load_lds_dwordx4 v[252:253], off
	s_waitcnt lgkmcnt(8)
	s_waitcnt lgkmcnt(0)
	v_mfma_f32_32x32x16_bf16 v[116:131], v[178:181], v[220:223], v[116:131]
	v_mfma_f32_32x32x16_bf16 v[52:67], v[194:197], v[220:223], v[52:67]
	v_mfma_f32_32x32x16_bf16 v[116:131], v[182:185], v[224:227], v[116:131]
	s_nop 0
	v_mfma_f32_32x32x16_bf16 v[52:67], v[208:211], v[224:227], v[52:67]
	v_mfma_f32_32x32x16_bf16 v[116:131], v[186:189], v[228:231], v[116:131]
	v_mfma_f32_32x32x16_bf16 v[52:67], v[212:215], v[228:231], v[52:67]
	v_mfma_f32_32x32x16_bf16 v[116:131], v[190:193], v[232:235], v[116:131]
	v_mfma_f32_32x32x16_bf16 v[52:67], v[216:219], v[232:235], v[52:67]
	ds_read_b64_tr_b16 v[220:221], v207 offset:0x400
	ds_read_b64_tr_b16 v[222:223], v207 offset:0xc00
	ds_read_b64_tr_b16 v[224:225], v207 offset:0x1400
	ds_read_b64_tr_b16 v[226:227], v207 offset:0x1c00
	ds_read_b64_tr_b16 v[228:229], v207 offset:0x2400
	ds_read_b64_tr_b16 v[230:231], v207 offset:0x2c00
	ds_read_b64_tr_b16 v[232:233], v207 offset:0x3400
	ds_read_b64_tr_b16 v[234:235], v207 offset:0x3c00
	s_waitcnt lgkmcnt(8)
	v_mfma_f32_32x32x16_bf16 v[100:115], v[178:181], v[236:239], v[100:115]
	v_mfma_f32_32x32x16_bf16 v[36:51], v[194:197], v[236:239], v[36:51]
	s_nop 0
	v_mfma_f32_32x32x16_bf16 v[100:115], v[182:185], v[240:243], v[100:115]
	v_mfma_f32_32x32x16_bf16 v[36:51], v[208:211], v[240:243], v[36:51]
	v_mfma_f32_32x32x16_bf16 v[100:115], v[186:189], v[244:247], v[100:115]
	v_mfma_f32_32x32x16_bf16 v[36:51], v[212:215], v[244:247], v[36:51]
	v_mfma_f32_32x32x16_bf16 v[100:115], v[190:193], v[248:251], v[100:115]
	v_mfma_f32_32x32x16_bf16 v[36:51], v[216:219], v[248:251], v[36:51]
	ds_read_b64_tr_b16 v[236:237], v207 offset:0x600
	ds_read_b64_tr_b16 v[238:239], v207 offset:0xe00
	ds_read_b64_tr_b16 v[240:241], v207 offset:0x1600
	ds_read_b64_tr_b16 v[242:243], v207 offset:0x1e00
	ds_read_b64_tr_b16 v[244:245], v207 offset:0x2600
	ds_read_b64_tr_b16 v[246:247], v207 offset:0x2e00
	ds_read_b64_tr_b16 v[248:249], v207 offset:0x3600
	ds_read_b64_tr_b16 v[250:251], v207 offset:0x3e00
	s_waitcnt lgkmcnt(8)
	v_mfma_f32_32x32x16_bf16 v[84:99], v[178:181], v[220:223], v[84:99]
	s_nop 0
	v_mfma_f32_32x32x16_bf16 v[20:35], v[194:197], v[220:223], v[20:35]
	v_mfma_f32_32x32x16_bf16 v[84:99], v[182:185], v[224:227], v[84:99]
	v_mfma_f32_32x32x16_bf16 v[20:35], v[208:211], v[224:227], v[20:35]
	v_mfma_f32_32x32x16_bf16 v[84:99], v[186:189], v[228:231], v[84:99]
	v_mfma_f32_32x32x16_bf16 v[20:35], v[212:215], v[228:231], v[20:35]
	v_mfma_f32_32x32x16_bf16 v[84:99], v[190:193], v[232:235], v[84:99]
	v_mfma_f32_32x32x16_bf16 v[20:35], v[216:219], v[232:235], v[20:35]
	s_waitcnt lgkmcnt(0)
	s_nop 0
	v_mfma_f32_32x32x16_bf16 v[68:83], v[178:181], v[236:239], v[68:83]
	s_add_i32 s9, s9, 0x8000
	s_waitcnt vmcnt(0)
	s_add_u32 s36, s36, 0x40000
	s_addc_u32 s37, s37, 0
	s_add_i32 s14, s10, 1
	s_addk_i32 s7, 0x4000
	s_cmp_eq_u32 s8, s36
	v_mfma_f32_32x32x16_bf16 v[4:19], v[194:197], v[236:239], v[4:19]
	s_waitcnt vmcnt(0)
	s_barrier
	s_nop 0
	v_mfma_f32_32x32x16_bf16 v[68:83], v[182:185], v[240:243], v[68:83]
	v_mfma_f32_32x32x16_bf16 v[4:19], v[208:211], v[240:243], v[4:19]
	v_mfma_f32_32x32x16_bf16 v[68:83], v[186:189], v[244:247], v[68:83]
	v_mfma_f32_32x32x16_bf16 v[4:19], v[212:215], v[244:247], v[4:19]
	v_mfma_f32_32x32x16_bf16 v[68:83], v[190:193], v[248:251], v[68:83]
	v_mfma_f32_32x32x16_bf16 v[4:19], v[216:219], v[248:251], v[4:19]
	s_cbranch_scc1 .LBB0_439
	s_mov_b32 s10, s14
	s_cmp_lt_u32 s10, s5
	s_cselect_b64 s[38:39], -1, 0
	s_cmp_ge_u32 s10, s5
	s_cbranch_scc0 .LBB0_432
	s_branch .LBB0_433

.Lsk627_a:
	s_waitcnt vmcnt(4)
	ds_write_b128 v2, v[28:31]
	ds_write_b128 v2, v[40:43] offset:8192
	ds_write_b128 v2, v[56:59] offset:16384
	ds_write_b128 v2, v[60:63] offset:24576
	ds_write_b128 v2, v[68:71] offset:32768
	ds_write_b128 v2, v[72:75] offset:40960
	s_cbranch_vccnz .LBB0_630
	v_lshl_add_u64 v[32:33], v[98:99], 0, s[20:21]
	v_add_co_u32_e32 v24, vcc, 0x10000, v32
	s_nop 0
	v_lshl_add_u64 v[44:45], v[94:95], 0, s[20:21]
	s_nop 0
	v_addc_co_u32_e32 v25, vcc, 0, v33, vcc
	v_add_co_u32_e32 v34, vcc, 0x20000, v32
	v_lshl_add_u64 v[48:49], v[96:97], 0, s[20:21]
	s_nop 0
	v_addc_co_u32_e32 v35, vcc, 0, v33, vcc
	v_add_co_u32_e32 v36, vcc, 0x30000, v32
	global_load_dwordx4 v[20:23], v[32:33], off offset:1536
	s_nop 0
	s_nop 0
	global_load_dwordx4 v[24:27], v[24:25], off offset:1536
	v_addc_co_u32_e32 v37, vcc, 0, v33, vcc
	global_load_dwordx4 v[32:35], v[34:35], off offset:1536
	s_nop 0
	global_load_dwordx4 v[36:39], v[36:37], off offset:1536
	s_nop 0
	global_load_dwordx4 v[44:47], v[44:45], off offset:1536
	s_nop 0
	global_load_dwordx4 v[48:51], v[48:49], off offset:1536
.LBB0_630:
	s_cmp_eq_u32 s7, 1
	s_nop 0
	s_cselect_b32 s7, 0xc000, 0
	s_add_i32 s7, s7, 0
	v_add_u32_e32 v210, s7, v108
	v_add_u32_e32 v211, s7, v109
	s_cmpk_eq_i32 s20, 0xc00
	v_add_u32_e32 v208, v210, v112
	ds_read_b128 v[216:219], v208
	v_add_u32_e32 v209, v211, v112
	ds_read_b128 v[232:235], v209 offset:32768
	v_add_u32_e32 v208, v210, v113
	ds_read_b128 v[220:223], v208
	v_add_u32_e32 v209, v211, v113
	ds_read_b128 v[236:239], v209 offset:32768
	v_add_u32_e32 v208, v210, v114
	ds_read_b128 v[224:227], v208
	v_add_u32_e32 v209, v211, v114
	ds_read_b128 v[240:243], v209 offset:32768
	v_add_u32_e32 v208, v210, v115
	ds_read_b128 v[228:231], v208
	v_add_u32_e32 v209, v211, v115
	ds_read_b128 v[244:247], v209 offset:32768
	s_waitcnt lgkmcnt(6)
	s_nop 0
	v_mfma_f32_32x32x16_bf16 v[4:19], v[232:235], v[216:219], v[4:19]
	s_waitcnt lgkmcnt(4)
	v_mfma_f32_32x32x16_bf16 v[4:19], v[236:239], v[220:223], v[4:19]
	s_waitcnt lgkmcnt(2)
	v_mfma_f32_32x32x16_bf16 v[4:19], v[240:243], v[224:227], v[4:19]
	s_waitcnt lgkmcnt(0)
	s_barrier
	v_mfma_f32_32x32x16_bf16 v[4:19], v[244:247], v[228:231], v[4:19]
	s_cbranch_scc1 .LBB0_632
	v_add_u32_e32 v120, s7, v105
	s_waitcnt vmcnt(6)
	s_nop 0
	ds_write_b128 v120, v[52:55]
	ds_write_b128 v120, v[64:67] offset:8192
	ds_write_b128 v120, v[76:79] offset:16384
	ds_write_b128 v120, v[80:83] offset:24576
	ds_write_b128 v120, v[84:87] offset:32768
	ds_write_b128 v120, v[88:91] offset:40960

.LBB0_634:
	v_add_u32_e32 v212, s6, v108
	v_add_u32_e32 v213, s6, v109
	s_add_i32 s6, s5, 3
	s_cmp_gt_u32 s5, 5
	v_add_u32_e32 v208, v212, v112
	ds_read_b128 v[216:219], v208
	v_add_u32_e32 v209, v213, v112
	ds_read_b128 v[232:235], v209 offset:32768
	v_add_u32_e32 v208, v212, v113
	ds_read_b128 v[220:223], v208
	v_add_u32_e32 v209, v213, v113
	ds_read_b128 v[236:239], v209 offset:32768
	v_add_u32_e32 v208, v212, v114
	ds_read_b128 v[224:227], v208
	v_add_u32_e32 v209, v213, v114
	ds_read_b128 v[240:243], v209 offset:32768
	v_add_u32_e32 v208, v212, v115
	ds_read_b128 v[228:231], v208
	v_add_u32_e32 v209, v213, v115
	ds_read_b128 v[244:247], v209 offset:32768
	s_waitcnt lgkmcnt(6)
	v_mfma_f32_32x32x16_bf16 v[4:19], v[232:235], v[216:219], v[4:19]
	s_waitcnt lgkmcnt(4)
	s_nop 0
	v_mfma_f32_32x32x16_bf16 v[4:19], v[236:239], v[220:223], v[4:19]
	s_waitcnt lgkmcnt(2)
	v_mfma_f32_32x32x16_bf16 v[4:19], v[240:243], v[224:227], v[4:19]
	s_waitcnt lgkmcnt(0)
	s_barrier
	v_mfma_f32_32x32x16_bf16 v[4:19], v[244:247], v[228:231], v[4:19]
	s_cbranch_scc1 .LBB0_640
	s_andn2_b64 vcc, exec, s[40:41]
	s_cbranch_vccnz .LBB0_637
	s_bitcmp1_b32 s6, 0
	s_cselect_b32 s7, 0xc000, 0
	v_add_u32_e32 v120, s7, v107
	s_waitcnt vmcnt(6)
	ds_write_b128 v120, v[20:23]
	ds_write_b128 v120, v[24:27] offset:8192
	ds_write_b128 v120, v[32:35] offset:16384
	ds_write_b128 v120, v[36:39] offset:24576
	ds_write_b128 v120, v[44:47] offset:32768
	ds_write_b128 v120, v[48:51] offset:40960
.LBB0_637:
	s_cmp_gt_u32 s5, 2
	s_cbranch_scc1 .LBB0_639
	s_nop 0
	v_lshl_add_u64 v[76:77], v[98:99], 0, s[20:21]
	v_add_co_u32_e32 v64, vcc, 0x10000, v76
	v_lshl_add_u64 v[84:85], v[94:95], 0, s[20:21]
	s_nop 0
	v_addc_co_u32_e32 v65, vcc, 0, v77, vcc
	v_add_co_u32_e32 v78, vcc, 0x20000, v76
	v_lshl_add_u64 v[88:89], v[96:97], 0, s[20:21]
	s_nop 0
	v_addc_co_u32_e32 v79, vcc, 0, v77, vcc
	v_add_co_u32_e32 v80, vcc, 0x30000, v76
	global_load_dwordx4 v[52:55], v[76:77], off offset:2560
	s_nop 0
	global_load_dwordx4 v[64:67], v[64:65], off offset:2560
	v_addc_co_u32_e32 v81, vcc, 0, v77, vcc
	global_load_dwordx4 v[76:79], v[78:79], off offset:2560
	s_nop 0
	global_load_dwordx4 v[80:83], v[80:81], off offset:2560
	s_nop 0
	global_load_dwordx4 v[84:87], v[84:85], off offset:2560
	s_nop 0
	s_nop 0
	global_load_dwordx4 v[88:91], v[88:89], off offset:2560
.LBB0_639:
	v_add_u32_e32 v208, v210, v112
	ds_read_b128 v[216:219], v208
	v_add_u32_e32 v209, v211, v112
	ds_read_b128 v[232:235], v209 offset:32768
	v_add_u32_e32 v208, v210, v113
	ds_read_b128 v[220:223], v208
	v_add_u32_e32 v209, v211, v113
	ds_read_b128 v[236:239], v209 offset:32768
	v_add_u32_e32 v208, v210, v114
	s_nop 0
	ds_read_b128 v[224:227], v208
	v_add_u32_e32 v209, v211, v114
	ds_read_b128 v[240:243], v209 offset:32768
	v_add_u32_e32 v208, v210, v115
	ds_read_b128 v[228:231], v208
	v_add_u32_e32 v209, v211, v115
	ds_read_b128 v[244:247], v209 offset:32768
	s_waitcnt lgkmcnt(6)
	v_mfma_f32_32x32x16_bf16 v[4:19], v[232:235], v[216:219], v[4:19]
	s_waitcnt lgkmcnt(4)
	s_nop 0
	v_mfma_f32_32x32x16_bf16 v[4:19], v[236:239], v[220:223], v[4:19]
	s_waitcnt lgkmcnt(2)
	v_mfma_f32_32x32x16_bf16 v[4:19], v[240:243], v[224:227], v[4:19]
	s_waitcnt lgkmcnt(0)
	s_barrier
	v_mfma_f32_32x32x16_bf16 v[4:19], v[244:247], v[228:231], v[4:19]

; #define LAS __attribute__((address_space(3)))
; template <class Epi, int NC>
; __device__ __forceinline__ void skinny_phase(const bf16* __restrict__ A, int lda, int a_goff, const bf16* __restrict__ Bt, int ldb, int K, int ncg, int vcu, int G, const Epi& E, LAS float* rs_tab, LAS unsigned char* lds) {
;     ...
;         LAS float* pb = (LAS float*)lds + (w * NC) * 1024 + lane;
;         asm volatile("" : "+v"(pb));
; #pragma unroll
;         for (int g = 0; g < NC; ++g)
; #pragma unroll
;             for (int r = 0; r < 16; ++r) pb[(g * 16 + r) * 64] = acc[g][r];
;         asm volatile("s_waitcnt lgkmcnt(0)" ::: "memory"); __builtin_amdgcn_s_barrier(); asm volatile("" ::: "memory");
;         if (kq == 0) {
.LBB0_644:
	v_mov_b32_e32 v2, v110
	s_nop 1
	ds_write2st64_b32 v2, v4, v5 offset1:1
	ds_write2st64_b32 v2, v6, v7 offset0:2 offset1:3
	ds_write2st64_b32 v2, v8, v9 offset0:4 offset1:5
	ds_write2st64_b32 v2, v10, v11 offset0:6 offset1:7
	ds_write2st64_b32 v2, v12, v13 offset0:8 offset1:9
	ds_write2st64_b32 v2, v14, v15 offset0:10 offset1:11
	ds_write2st64_b32 v2, v16, v17 offset0:12 offset1:13
	ds_write2st64_b32 v2, v18, v19 offset0:14 offset1:15
	s_waitcnt lgkmcnt(0)
	s_barrier
	s_andn2_b64 vcc, exec, s[12:13]
	s_cbranch_vccnz .LBB0_626
; __device__ __forceinline__ u32x2 pack4(float a, float b, float c, float d) { u32x2 w; w.x = cvt_pk_bf16(a, b); w.y = cvt_pk_bf16(c, d); return w; }
; template <class Epi, int NC>
; __device__ __forceinline__ void skinny_phase(const bf16* __restrict__ A, int lda, int a_goff, const bf16* __restrict__ Bt, int ldb, int K, int ncg, int vcu, int G, const Epi& E, LAS float* rs_tab, LAS unsigned char* lds) {
;     ...
;         if (kq == 0) {
;             const int row = 64 * rb + rrow; const float rs = Epi::NEEDS_RS ? rs_tab[row] : 1.f;
; #pragma unroll
;             for (int g = 0; g < NC; ++g) {
; #pragma unroll
;                 for (int r = 0; r < 16; ++r) { const int o_ = (g * 16 + r) * 64; acc[g][r] = ((pb[o_] + pb[o_ + 2 * NC * 1024]) + pb[o_ + 4 * NC * 1024]) + pb[o_ + 6 * NC * 1024]; }
;                 E(acc[g], cg + g, row, hi, rs); }
;     __device__ __forceinline__ void operator()(const f32x16& acc, int u, int row, int hi, float) const {
;         float ss = 0.f;
; #pragma unroll
;         for (int q = 0; q < 4; ++q) { const int c = 32 * u + 8 * q + 4 * hi; bf16* xp = XB + (size_t)(MP + row) * D + c;
;             const u32x2 w0 = *(const u32x2*)xp; f32x4 xv = {__uint_as_float(w0.x << 16), __uint_as_float(w0.x & 0xffff0000u), __uint_as_float(w0.y << 16), __uint_as_float(w0.y & 0xffff0000u)};
;             f32x4 av = {acc[4 * q], acc[4 * q + 1], acc[4 * q + 2], acc[4 * q + 3]};
;             if (cs) av *= *(const f32x4*)(cs + c);
;             xv += av; const u32x2 w1 = pack4(xv[0], xv[1], xv[2], xv[3]); *(u32x2*)xp = w1;
;             xv = (f32x4){__uint_as_float(w1.x << 16), __uint_as_float(w1.x & 0xffff0000u), __uint_as_float(w1.y << 16), __uint_as_float(w1.y & 0xffff0000u)};
;             ss += (xv[0] * xv[0] + xv[1] * xv[1]) + (xv[2] * xv[2] + xv[3] * xv[3]); }
;         ss += __shfl_xor(ss, 32);
;         if (hi == 0) ssqS[(size_t)row * 64 + u] = ss;
;     }
	ds_read2st64_b32 v[4:5], v2 offset1:1
	ds_read2st64_b32 v[6:7], v2 offset0:32 offset1:33
	ds_read2st64_b32 v[8:9], v2 offset0:64 offset1:65
	ds_read2st64_b32 v[10:11], v2 offset0:96 offset1:97
	ds_read2st64_b32 v[12:13], v2 offset0:2 offset1:3
	ds_read2st64_b32 v[14:15], v2 offset0:34 offset1:35
	ds_read2st64_b32 v[16:17], v2 offset0:66 offset1:67
	ds_read2st64_b32 v[18:19], v2 offset0:98 offset1:99
	s_waitcnt lgkmcnt(0)
	v_pk_add_f32 v[4:5], v[4:5], v[6:7]
	s_ashr_i32 s36, s4, 2
	v_pk_add_f32 v[6:7], v[12:13], v[14:15]
	v_pk_add_f32 v[4:5], v[4:5], v[8:9]
	v_pk_add_f32 v[6:7], v[6:7], v[16:17]
	v_pk_add_f32 v[16:17], v[4:5], v[10:11]
	v_pk_add_f32 v[18:19], v[6:7], v[18:19]
	ds_read2st64_b32 v[4:5], v2 offset0:4 offset1:5
	ds_read2st64_b32 v[6:7], v2 offset0:36 offset1:37
	ds_read2st64_b32 v[8:9], v2 offset0:68 offset1:69
	ds_read2st64_b32 v[10:11], v2 offset0:100 offset1:101
	ds_read2st64_b32 v[12:13], v2 offset0:6 offset1:7
	ds_read2st64_b32 v[14:15], v2 offset0:38 offset1:39
	ds_read2st64_b32 v[116:117], v2 offset0:70 offset1:71
	ds_read2st64_b32 v[118:119], v2 offset0:102 offset1:103
	s_waitcnt lgkmcnt(0)
	v_pk_add_f32 v[4:5], v[4:5], v[6:7]
	s_lshl_b32 s4, s4, 6
	v_pk_add_f32 v[6:7], v[12:13], v[14:15]
	v_pk_add_f32 v[4:5], v[4:5], v[8:9]
	v_pk_add_f32 v[6:7], v[6:7], v[116:117]
	v_pk_add_f32 v[12:13], v[4:5], v[10:11]
	v_pk_add_f32 v[14:15], v[6:7], v[118:119]
	ds_read2st64_b32 v[4:5], v2 offset0:8 offset1:9
	ds_read2st64_b32 v[6:7], v2 offset0:40 offset1:41
	ds_read2st64_b32 v[8:9], v2 offset0:72 offset1:73
	ds_read2st64_b32 v[10:11], v2 offset0:104 offset1:105
	ds_read2st64_b32 v[116:117], v2 offset0:10 offset1:11
	ds_read2st64_b32 v[118:119], v2 offset0:42 offset1:43
	ds_read2st64_b32 v[120:121], v2 offset0:74 offset1:75
	ds_read2st64_b32 v[122:123], v2 offset0:106 offset1:107
	s_waitcnt lgkmcnt(0)
	v_pk_add_f32 v[4:5], v[4:5], v[6:7]
	s_and_b32 s4, s4, 0xc0
	v_pk_add_f32 v[6:7], v[116:117], v[118:119]
	v_pk_add_f32 v[4:5], v[4:5], v[8:9]
	v_pk_add_f32 v[6:7], v[6:7], v[120:121]
	v_or_b32_e32 v101, s4, v106
	v_pk_add_f32 v[8:9], v[4:5], v[10:11]
	v_pk_add_f32 v[10:11], v[6:7], v[122:123]
	ds_read2st64_b32 v[4:5], v2 offset0:12 offset1:13
	ds_read2st64_b32 v[6:7], v2 offset0:44 offset1:45
	ds_read2st64_b32 v[116:117], v2 offset0:76 offset1:77
	ds_read2st64_b32 v[118:119], v2 offset0:108 offset1:109
	ds_read2st64_b32 v[120:121], v2 offset0:14 offset1:15
	ds_read2st64_b32 v[122:123], v2 offset0:46 offset1:47
	ds_read2st64_b32 v[124:125], v2 offset0:78 offset1:79
	ds_read2st64_b32 v[126:127], v2 offset0:110 offset1:111
	v_lshl_or_b32 v102, s36, 5, v111
	s_waitcnt lgkmcnt(0)
	v_pk_add_f32 v[4:5], v[4:5], v[6:7]
	v_lshlrev_b32_e32 v2, 12, v101
	v_pk_add_f32 v[4:5], v[4:5], v[116:117]
	v_ashrrev_i32_e32 v103, 31, v102
	v_lshl_add_u64 v[116:117], s[0:1], 0, v[2:3]
	s_nop 0
	v_lshl_add_u64 v[116:117], v[102:103], 1, v[116:117]
	s_mov_b64 s[4:5], 0x4000000
	v_lshl_add_u64 v[102:103], v[116:117], 0, s[4:5]
	s_brev_b32 s4, 32
	v_add_co_u32_e32 v116, vcc, s4, v116
	v_pk_add_f32 v[4:5], v[4:5], v[118:119]
	s_nop 0
	v_addc_co_u32_e32 v117, vcc, 0, v117, vcc
	global_load_dwordx2 v[118:119], v[116:117], off
	v_pk_add_f32 v[6:7], v[120:121], v[122:123]
	s_waitcnt vmcnt(0)
	v_lshlrev_b32_e32 v120, 16, v118
	v_and_b32_e32 v121, 0xffff0000, v118
	v_pk_add_f32 v[16:17], v[16:17], v[120:121]
	v_lshlrev_b32_e32 v118, 16, v119
	v_and_b32_e32 v119, 0xffff0000, v119
	v_cvt_pk_bf16_f32 v16, v16, v17
	v_pk_add_f32 v[18:19], v[18:19], v[118:119]
	v_lshlrev_b32_e32 v2, 16, v16
	v_cvt_pk_bf16_f32 v17, v18, v19
	global_store_dwordx2 v[116:117], v[16:17], off
	v_and_b32_e32 v16, 0xffff0000, v16
	v_lshlrev_b32_e32 v18, 16, v17
	v_and_b32_e32 v17, 0xffff0000, v17
	v_mul_f32_e32 v16, v16, v16
	v_fmac_f32_e32 v16, v2, v2
	v_mul_f32_e32 v2, v17, v17
	v_fmac_f32_e32 v2, v18, v18
	v_add_f32_e32 v2, v16, v2
	global_load_dwordx2 v[16:17], v[102:103], off offset:16
	v_pk_add_f32 v[6:7], v[6:7], v[124:125]
	s_waitcnt vmcnt(0)
	v_lshlrev_b32_e32 v18, 16, v16
	v_and_b32_e32 v19, 0xffff0000, v16
	v_lshlrev_b32_e32 v16, 16, v17
	v_and_b32_e32 v17, 0xffff0000, v17
	v_pk_add_f32 v[12:13], v[12:13], v[18:19]
	v_pk_add_f32 v[14:15], v[14:15], v[16:17]
	v_cvt_pk_bf16_f32 v12, v12, v13
	v_pk_add_f32 v[6:7], v[6:7], v[126:127]
	s_nop 0
	v_cvt_pk_bf16_f32 v13, v14, v15
	global_store_dwordx2 v[102:103], v[12:13], off offset:16
	v_lshlrev_b32_e32 v14, 16, v12
	v_and_b32_e32 v12, 0xffff0000, v12
	v_lshlrev_b32_e32 v15, 16, v13
	v_and_b32_e32 v13, 0xffff0000, v13
	v_mul_f32_e32 v12, v12, v12
	v_mul_f32_e32 v13, v13, v13
	v_fmac_f32_e32 v12, v14, v14
	v_fmac_f32_e32 v13, v15, v15
	v_add_f32_e32 v12, v12, v13
	v_add_f32_e32 v2, v2, v12
	global_load_dwordx2 v[12:13], v[102:103], off offset:32
	s_waitcnt vmcnt(0)
	v_lshlrev_b32_e32 v14, 16, v12
	v_and_b32_e32 v15, 0xffff0000, v12
	v_lshlrev_b32_e32 v12, 16, v13
	v_and_b32_e32 v13, 0xffff0000, v13
	v_pk_add_f32 v[8:9], v[8:9], v[14:15]
	v_pk_add_f32 v[10:11], v[10:11], v[12:13]
	v_cvt_pk_bf16_f32 v8, v8, v9
	s_nop 0
	v_cvt_pk_bf16_f32 v9, v10, v11
	global_store_dwordx2 v[102:103], v[8:9], off offset:32
	v_lshlrev_b32_e32 v10, 16, v8
	v_and_b32_e32 v8, 0xffff0000, v8
	v_lshlrev_b32_e32 v11, 16, v9
	v_and_b32_e32 v9, 0xffff0000, v9
	v_mul_f32_e32 v8, v8, v8
	v_mul_f32_e32 v9, v9, v9
	v_fmac_f32_e32 v8, v10, v10
	v_fmac_f32_e32 v9, v11, v11
	v_add_f32_e32 v8, v8, v9
	v_add_f32_e32 v2, v2, v8
	global_load_dwordx2 v[8:9], v[102:103], off offset:48
	s_waitcnt vmcnt(0)
	v_lshlrev_b32_e32 v10, 16, v8
	v_and_b32_e32 v11, 0xffff0000, v8
	v_lshlrev_b32_e32 v8, 16, v9
	v_and_b32_e32 v9, 0xffff0000, v9
	v_pk_add_f32 v[4:5], v[4:5], v[10:11]
	v_pk_add_f32 v[6:7], v[6:7], v[8:9]
	v_cvt_pk_bf16_f32 v4, v4, v5
	s_nop 0
	v_cvt_pk_bf16_f32 v5, v6, v7
	global_store_dwordx2 v[102:103], v[4:5], off offset:48
	v_lshlrev_b32_e32 v6, 16, v4
	v_and_b32_e32 v4, 0xffff0000, v4
	v_lshlrev_b32_e32 v7, 16, v5
	v_and_b32_e32 v5, 0xffff0000, v5
	v_mul_f32_e32 v4, v4, v4
	v_mul_f32_e32 v5, v5, v5
	v_fmac_f32_e32 v4, v6, v6
	v_fmac_f32_e32 v5, v7, v7
	v_add_f32_e32 v4, v4, v5
	v_and_b32_e32 v5, 64, v204
	v_add_f32_e32 v4, v2, v4
	v_xor_b32_e32 v2, 32, v204
	v_add_u32_e32 v5, 64, v5
	v_cmp_lt_i32_e32 vcc, v2, v5
	s_nop 1
	v_cndmask_b32_e32 v2, v204, v2, vcc
	v_lshlrev_b32_e32 v2, 2, v2
	ds_bpermute_b32 v5, v2, v4
	s_and_saveexec_b64 s[40:41], s[38:39]
	s_cbranch_execz .LBB0_625
	v_lshlrev_b32_e32 v2, 8, v101
	v_lshl_add_u64 v[6:7], s[2:3], 0, v[2:3]
	s_ashr_i32 s37, s36, 31
	s_nop 0
	v_lshl_add_u64 v[6:7], s[36:37], 2, v[6:7]
	s_waitcnt lgkmcnt(0)
	v_add_f32_e32 v2, v4, v5
	global_store_dword v[6:7], v2, off
	s_branch .LBB0_625

; __device__ __forceinline__ unsigned xb_ld(unsigned* p)              { return __hip_atomic_load(p, __ATOMIC_RELAXED, __HIP_MEMORY_SCOPE_AGENT); }
; __device__ __forceinline__ void xcd_barrier_complete(unsigned* bar, unsigned x, unsigned& nloc, unsigned& nx) {
;     const unsigned G = gridDim.x * gridDim.y * gridDim.z;
;     unsigned sum, cnt, mine, sp = 0u;
;     for (;;) {
;         sum = 0u; cnt = 0u; mine = 0u;
; #pragma unroll
;         for (unsigned j = 0; j < 16; ++j) { const unsigned c = xb_ld(&bar[XB_XCNT(j)]); sum += c; cnt += (c > 0u) ? 1u : 0u; mine = (j == x) ? c : mine; }
;         if (sum == G) break;
;         __builtin_amdgcn_s_sleep(1);
;         if ((++sp & 255u) == 0u) { if (xb_ld(&bar[XB_TMO])) break; if (sp > XB_SPIN_CAP) { atomicAdd(&bar[XB_TMO], 1u); break; } }
;     }
.LBB0_655:
	v_readlane_b32 s2, v254, 6
	v_readlane_b32 s3, v254, 7
	global_load_dword v4, v3, s[82:83] sc1
	global_load_dword v2, v3, s[84:85] sc1
	s_mov_b64 s[12:13], -1
	s_waitcnt vmcnt(0)
	v_add_u32_e32 v19, v2, v4
	global_load_dword v5, v3, s[2:3] sc1
	v_readlane_b32 s2, v254, 8
	v_readlane_b32 s3, v254, 9
	s_waitcnt vmcnt(0)
	v_add_u32_e32 v19, v19, v5
	s_nop 2
	global_load_dword v6, v3, s[2:3] sc1
	v_readlane_b32 s2, v254, 10
	s_nop 0
	v_readlane_b32 s3, v254, 11
	s_waitcnt vmcnt(0)
	v_add_u32_e32 v19, v19, v6
	s_nop 2
	global_load_dword v7, v3, s[2:3] sc1
	v_readlane_b32 s2, v254, 12
	v_readlane_b32 s3, v254, 13
	s_waitcnt vmcnt(0)
	v_add_u32_e32 v19, v19, v7
	s_nop 2
	global_load_dword v8, v3, s[2:3] sc1
	v_readlane_b32 s2, v254, 14
	v_readlane_b32 s3, v254, 15
	s_waitcnt vmcnt(0)
	v_add_u32_e32 v19, v19, v8
	s_nop 2
	global_load_dword v9, v3, s[2:3] sc1
	v_readlane_b32 s2, v254, 16
	v_readlane_b32 s3, v254, 17
	s_waitcnt vmcnt(0)
	v_add_u32_e32 v19, v19, v9
	s_nop 2
	global_load_dword v10, v3, s[2:3] sc1
	v_readlane_b32 s2, v254, 18
	v_readlane_b32 s3, v254, 19
	s_waitcnt vmcnt(0)
	v_add_u32_e32 v19, v19, v10
	s_nop 2
	global_load_dword v11, v3, s[2:3] sc1
	v_readlane_b32 s2, v254, 20
	v_readlane_b32 s3, v254, 21
	s_waitcnt vmcnt(0)
	v_add_u32_e32 v19, v19, v11
	s_nop 2
	global_load_dword v12, v3, s[2:3] sc1
	v_readlane_b32 s2, v254, 22
	v_readlane_b32 s3, v254, 23
	s_waitcnt vmcnt(0)
	v_add_u32_e32 v19, v19, v12
	s_nop 2
	global_load_dword v13, v3, s[2:3] sc1
	v_readlane_b32 s2, v254, 24
	s_nop 0
	v_readlane_b32 s3, v254, 25
	s_waitcnt vmcnt(0)
	v_add_u32_e32 v19, v19, v13
	s_nop 2
	global_load_dword v14, v3, s[2:3] sc1
	v_readlane_b32 s2, v254, 26
	v_readlane_b32 s3, v254, 27
	s_waitcnt vmcnt(0)
	v_add_u32_e32 v19, v19, v14
	s_nop 2
	global_load_dword v15, v3, s[2:3] sc1
	v_readlane_b32 s2, v254, 28
	v_readlane_b32 s3, v254, 29
	s_waitcnt vmcnt(0)
	v_add_u32_e32 v19, v19, v15
	s_nop 2
	global_load_dword v16, v3, s[2:3] sc1
	v_readlane_b32 s2, v254, 30
	v_readlane_b32 s3, v254, 31
	s_waitcnt vmcnt(0)
	v_add_u32_e32 v19, v19, v16
	s_nop 2
	global_load_dword v17, v3, s[2:3] sc1
	v_readlane_b32 s2, v254, 32
	v_readlane_b32 s3, v254, 33
	s_waitcnt vmcnt(0)
	v_add_u32_e32 v19, v19, v17
	s_nop 2
	global_load_dword v18, v3, s[2:3] sc1
	s_mov_b64 s[2:3], -1
	s_waitcnt vmcnt(0)
	v_add_u32_e32 v19, v19, v18
	v_cmp_eq_u32_e32 vcc, s4, v19
	s_cbranch_vccnz .LBB0_654
	s_and_b32 s2, s5, 0xff
	s_cmp_eq_u32 s2, 0
	s_mov_b64 s[2:3], -1
	s_mov_b64 s[18:19], -1
	s_sleep 1
	s_cbranch_scc1 .LBB0_659
	s_and_b64 vcc, exec, s[18:19]
	s_cbranch_vccz .LBB0_654

; __device__ __forceinline__ unsigned xb_add(unsigned* p, unsigned v) { return __hip_atomic_fetch_add(p, v, __ATOMIC_RELAXED, __HIP_MEMORY_SCOPE_AGENT); }
; __device__ __forceinline__ void xcd_barrier_complete(unsigned* bar, unsigned x, unsigned& nloc, unsigned& nx) {
;     ...
;     nloc = mine > 0u ? mine : 1u; nx = cnt > 0u ? cnt : 1u;
; }
; __device__ __forceinline__ void xcd_barrier(const XcdBarrier& b) {
;     asm volatile("s_waitcnt vmcnt(0)" ::: "memory");
;     __syncthreads();
;     if (threadIdx.x == 0) {
;         unsigned* bar = b.bar;
;         __builtin_amdgcn_s_waitcnt(0);
;         unsigned nloc = b.st[0], nx = b.st[1];
;         if (nloc == 0u) { xcd_barrier_complete(bar, b.x, nloc, nx); b.st[0] = nloc; b.st[1] = nx; }
;         const unsigned old = xb_add(&bar[XB_XSUB(b.x)], 1u);
;         const unsigned gen = old / nloc;
;         if (old + 1u == (gen + 1u) * nloc) {
.LBB0_666:
	v_readlane_b32 s2, v255, 0
	v_readlane_b32 s3, v255, 1
	v_cmp_ne_u32_e32 vcc, 0, v4
	s_nop 0
	v_cndmask_b32_e64 v19, 0, v4, s[2:3]
	v_readlane_b32 s2, v254, 62
	v_readlane_b32 s3, v254, 63
	v_cndmask_b32_e64 v4, 0, 1, vcc
	v_cmp_ne_u32_e32 vcc, 0, v2
	v_cndmask_b32_e64 v19, v19, v2, s[2:3]
	v_readlane_b32 s2, v254, 60
	v_readlane_b32 s3, v254, 61
	v_addc_co_u32_e32 v2, vcc, 0, v4, vcc
	s_nop 0
	s_nop 0
	v_cndmask_b32_e64 v19, v19, v5, s[2:3]
	v_readlane_b32 s2, v254, 58
	v_readlane_b32 s3, v254, 59
	v_cmp_ne_u32_e32 vcc, 0, v5
	s_nop 0
	v_cndmask_b32_e64 v19, v19, v6, s[2:3]
	v_readlane_b32 s2, v254, 56
	v_readlane_b32 s3, v254, 57
	v_cndmask_b32_e64 v4, 0, 1, vcc
	v_cmp_ne_u32_e32 vcc, 0, v6
	v_cndmask_b32_e64 v19, v19, v7, s[2:3]
	v_readlane_b32 s2, v254, 54
	v_readlane_b32 s3, v254, 55
	v_addc_co_u32_e32 v2, vcc, v2, v4, vcc
	s_nop 0
	v_cndmask_b32_e64 v19, v19, v8, s[2:3]
	v_readlane_b32 s2, v254, 52
	v_readlane_b32 s3, v254, 53
	v_cmp_ne_u32_e32 vcc, 0, v7
	s_nop 0
	v_cndmask_b32_e64 v19, v19, v9, s[2:3]
	v_readlane_b32 s2, v254, 50
	v_readlane_b32 s3, v254, 51
	v_cndmask_b32_e64 v4, 0, 1, vcc
	v_cmp_ne_u32_e32 vcc, 0, v8
	v_cndmask_b32_e64 v19, v19, v10, s[2:3]
	v_readlane_b32 s2, v254, 48
	v_readlane_b32 s3, v254, 49
	v_addc_co_u32_e32 v2, vcc, v2, v4, vcc
	s_nop 0
	v_cndmask_b32_e64 v19, v19, v11, s[2:3]
	v_readlane_b32 s2, v254, 46
	v_cmp_ne_u32_e32 vcc, 0, v9
	v_readlane_b32 s3, v254, 47
	s_nop 0
	v_cndmask_b32_e64 v4, 0, 1, vcc
	v_cmp_ne_u32_e32 vcc, 0, v10
	v_cndmask_b32_e64 v19, v19, v12, s[2:3]
	s_nop 0
	v_readlane_b32 s2, v254, 44
	v_addc_co_u32_e32 v2, vcc, v2, v4, vcc
	v_readlane_b32 s3, v254, 45
	v_cmp_ne_u32_e32 vcc, 0, v11
	s_nop 0
	v_cndmask_b32_e64 v19, v19, v13, s[2:3]
	v_readlane_b32 s2, v254, 42
	v_cndmask_b32_e64 v4, 0, 1, vcc
	v_cmp_ne_u32_e32 vcc, 0, v12
	v_readlane_b32 s3, v254, 43
	s_nop 0
	v_addc_co_u32_e32 v2, vcc, v2, v4, vcc
	v_cndmask_b32_e64 v19, v19, v14, s[2:3]
	v_readlane_b32 s2, v254, 40
	v_cmp_ne_u32_e32 vcc, 0, v13
	v_readlane_b32 s3, v254, 41
	s_nop 0
	v_cndmask_b32_e64 v4, 0, 1, vcc
	v_cmp_ne_u32_e32 vcc, 0, v14
	v_cndmask_b32_e64 v19, v19, v15, s[2:3]
	s_nop 0
	v_readlane_b32 s2, v254, 38
	v_addc_co_u32_e32 v2, vcc, v2, v4, vcc
	v_readlane_b32 s3, v254, 39
	v_cmp_ne_u32_e32 vcc, 0, v15
	s_nop 0
	v_cndmask_b32_e64 v19, v19, v16, s[2:3]
	v_readlane_b32 s2, v254, 36
	v_cndmask_b32_e64 v4, 0, 1, vcc
	v_cmp_ne_u32_e32 vcc, 0, v16
	v_readlane_b32 s3, v254, 37
	s_nop 0
	v_addc_co_u32_e32 v2, vcc, v2, v4, vcc
	v_cndmask_b32_e64 v19, v19, v17, s[2:3]
	v_readlane_b32 s2, v254, 34
	v_cmp_ne_u32_e32 vcc, 0, v17
	v_readlane_b32 s3, v254, 35
	s_nop 0
	v_cndmask_b32_e64 v4, 0, 1, vcc
	v_cmp_ne_u32_e32 vcc, 0, v18
	v_cndmask_b32_e64 v19, v19, v18, s[2:3]
	s_nop 0
	v_readlane_b32 s2, v255, 10
	v_addc_co_u32_e32 v2, vcc, v2, v4, vcc
	v_max_u32_e32 v5, 1, v19
	v_max_u32_e32 v4, 1, v2
	v_mov_b32_e32 v2, s2
	v_readlane_b32 s2, v255, 11
	ds_write_b32 v2, v5
	s_nop 0
	v_mov_b32_e32 v2, s2
	ds_write_b32 v2, v4
.LBB0_667:
	s_mov_b64 s[12:13], exec
	s_nop 0
	v_mbcnt_lo_u32_b32 v2, s12, 0
	v_mbcnt_hi_u32_b32 v2, s13, v2
	v_cmp_eq_u32_e32 vcc, 0, v2
	s_and_saveexec_b64 s[2:3], vcc
	s_cbranch_execz .LBB0_669
	s_bcnt1_i32_b64 s4, s[12:13]
	v_mov_b32_e32 v6, s4
	v_readlane_b32 s4, v255, 2
	v_readlane_b32 s5, v255, 3
	s_nop 4
	global_atomic_add v6, v3, v6, s[4:5] sc0
.LBB0_669:
	s_or_b64 exec, exec, s[2:3]
	v_cvt_f32_u32_e32 v7, v5
	s_waitcnt vmcnt(0)
	v_readfirstlane_b32 s2, v6
	v_sub_u32_e32 v6, 0, v5
	v_rcp_iflag_f32_e32 v7, v7
	v_add_u32_e32 v8, s2, v2
	v_mul_f32_e32 v7, 0x4f7ffffe, v7
	v_cvt_u32_f32_e32 v7, v7
	v_mul_lo_u32 v2, v6, v7
	v_mul_hi_u32 v2, v7, v2
	v_add_u32_e32 v2, v7, v2
	s_nop 0
	v_mul_hi_u32 v2, v8, v2
	v_mul_lo_u32 v6, v2, v5
	v_sub_u32_e32 v6, v8, v6
	v_add_u32_e32 v7, 1, v2
	v_cmp_ge_u32_e32 vcc, v6, v5
	s_nop 1
	v_cndmask_b32_e32 v2, v2, v7, vcc
	v_sub_u32_e32 v7, v6, v5
	v_cndmask_b32_e32 v6, v6, v7, vcc
	v_add_u32_e32 v7, 1, v2
	v_cmp_ge_u32_e32 vcc, v6, v5
	v_add_u32_e32 v6, 1, v8
	s_nop 0
	v_cndmask_b32_e32 v2, v2, v7, vcc
	v_mul_lo_u32 v7, v5, v2
	v_add_u32_e32 v5, v7, v5
	v_cmp_ne_u32_e32 vcc, v6, v5
	s_and_saveexec_b64 s[2:3], vcc
	s_xor_b64 s[2:3], exec, s[2:3]
	s_cbranch_execz .LBB0_683
	v_readlane_b32 s4, v255, 4
	v_readlane_b32 s5, v255, 5
	s_waitcnt lgkmcnt(0)
	s_nop 3
	global_load_dword v4, v3, s[4:5] sc1
	s_waitcnt vmcnt(0)
	v_cmp_eq_u32_e32 vcc, v4, v2
	s_and_saveexec_b64 s[12:13], vcc
	s_cbranch_execz .LBB0_682
	s_mov_b32 s4, 1
	s_mov_b64 s[18:19], 0
	s_branch .LBB0_673

; __device__ __forceinline__ unsigned xb_add(unsigned* p, unsigned v) { return __hip_atomic_fetch_add(p, v, __ATOMIC_RELAXED, __HIP_MEMORY_SCOPE_AGENT); }
; __device__ __forceinline__ void xcd_barrier(const XcdBarrier& b) {
;     ...
;         const unsigned old = xb_add(&bar[XB_XSUB(b.x)], 1u);
;         const unsigned gen = old / nloc;
;         if (old + 1u == (gen + 1u) * nloc) {
;             __builtin_amdgcn_fence(__ATOMIC_RELEASE, "agent");
;             asm volatile("s_waitcnt vmcnt(0)" ::: "memory");
;             const unsigned og = xb_add(&bar[XB_TOP], 1u);
;             const unsigned tg = og / nx;
;             if (og + 1u == (tg + 1u) * nx) xb_add(&bar[XB_TOPGEN], 1u);
.LBB0_683:
	s_andn2_saveexec_b64 s[2:3], s[2:3]
	s_cbranch_execz .LBB0_703
	s_mov_b64 s[2:3], exec
	buffer_wbl2 sc1
	s_waitcnt lgkmcnt(0)
	s_waitcnt vmcnt(0)
	s_nop 0
	v_mbcnt_lo_u32_b32 v2, s2, 0
	v_mbcnt_hi_u32_b32 v2, s3, v2
	v_cmp_eq_u32_e32 vcc, 0, v2
	s_and_saveexec_b64 s[12:13], vcc
	s_cbranch_execz .LBB0_686
	s_bcnt1_i32_b64 s2, s[2:3]
	v_mov_b32_e32 v5, s2
	v_readlane_b32 s2, v255, 6
	v_readlane_b32 s3, v255, 7
	s_nop 4
	global_atomic_add v5, v3, v5, s[2:3] sc0

; __device__ __forceinline__ unsigned xb_ld(unsigned* p)              { return __hip_atomic_load(p, __ATOMIC_RELAXED, __HIP_MEMORY_SCOPE_AGENT); }
; __device__ __forceinline__ unsigned xb_add(unsigned* p, unsigned v) { return __hip_atomic_fetch_add(p, v, __ATOMIC_RELAXED, __HIP_MEMORY_SCOPE_AGENT); }
; #define XB_SPIN(cond, bar) do { unsigned _sp = 0; while (cond) { __builtin_amdgcn_s_sleep(1); \
;     if ((++_sp & 255u) == 0u) { if (xb_ld(&(bar)[XB_TMO])) break; if (_sp > XB_SPIN_CAP) { atomicAdd(&(bar)[XB_TMO], 1u); break; } } } } while (0)
; __device__ __forceinline__ void xcd_barrier(const XcdBarrier& b) {
;     ...
;             if (og + 1u == (tg + 1u) * nx) xb_add(&bar[XB_TOPGEN], 1u);
;             else XB_SPIN(xb_ld(&bar[XB_TOPGEN]) == tg, bar);
;             __builtin_amdgcn_fence(__ATOMIC_ACQUIRE, "agent");
;             xb_add(&bar[XB_XGEN(b.x)], 1u);
;             asm volatile("s_waitcnt vmcnt(0)" ::: "memory");
.LBB0_700:
	s_or_b64 exec, exec, s[2:3]
	s_mov_b64 s[2:3], exec
	v_mbcnt_lo_u32_b32 v2, s2, 0
	v_mbcnt_hi_u32_b32 v2, s3, v2
	v_cmp_eq_u32_e32 vcc, 0, v2
	s_waitcnt vmcnt(0)
	buffer_inv sc1
	s_and_saveexec_b64 s[12:13], vcc
	s_cbranch_execz .LBB0_702
	s_bcnt1_i32_b64 s2, s[2:3]
	v_mov_b32_e32 v2, s2
	v_readlane_b32 s2, v255, 4
	s_nop 0
	v_readlane_b32 s3, v255, 5
	s_nop 4
	global_atomic_add v3, v2, s[2:3]

.LBB0_2016:
	v_add_u32_e32 v156, s8, v196
	v_add_u32_e32 v157, s8, v197
	v_add_u32_e32 v158, v156, v209
	ds_read_b128 v[216:219], v158
	v_add_u32_e32 v159, v157, v209
	ds_read_b128 v[232:235], v159 offset:32768
	ds_read_b128 v[244:247], v159 offset:49152
	v_add_u32_e32 v164, v156, v210
	ds_read_b128 v[220:223], v164
	v_add_u32_e32 v165, v157, v210
	s_nop 0
	ds_read_b128 v[236:239], v165 offset:32768
	ds_read_b128 v[248:251], v165 offset:49152
	v_add_u32_e32 v180, v156, v211
	ds_read_b128 v[224:227], v180
	v_add_u32_e32 v181, v157, v211
	ds_read_b128 v[240:243], v181 offset:32768
	ds_read_b128 v[176:179], v181 offset:49152
	v_add_u32_e32 v200, v156, v212
	ds_read_b128 v[228:231], v200
	v_add_u32_e32 v201, v157, v212
	s_waitcnt lgkmcnt(8)
	v_mfma_f32_32x32x16_bf16 v[4:19], v[232:235], v[216:219], v[4:19]
	s_waitcnt lgkmcnt(7)
	v_mfma_f32_32x32x16_bf16 v[20:35], v[244:247], v[216:219], v[20:35]
	ds_read_b128 v[232:235], v201 offset:32768
	ds_read_b128 v[244:247], v201 offset:49152
	s_waitcnt lgkmcnt(7)
	v_mfma_f32_32x32x16_bf16 v[4:19], v[236:239], v[220:223], v[4:19]
	s_waitcnt lgkmcnt(6)
	v_mfma_f32_32x32x16_bf16 v[20:35], v[248:251], v[220:223], v[20:35]
	s_waitcnt lgkmcnt(4)
	v_mfma_f32_32x32x16_bf16 v[4:19], v[240:243], v[224:227], v[4:19]
	s_waitcnt lgkmcnt(3)
	v_mfma_f32_32x32x16_bf16 v[20:35], v[176:179], v[224:227], v[20:35]
	s_waitcnt lgkmcnt(1)
	v_mfma_f32_32x32x16_bf16 v[4:19], v[232:235], v[228:231], v[4:19]
	s_waitcnt lgkmcnt(0)
	s_barrier
	v_mfma_f32_32x32x16_bf16 v[20:35], v[244:247], v[228:231], v[20:35]

.LBB0_2022:
	s_cmp_gt_u32 s6, 3
	s_cbranch_scc1 .LBB0_2024
	v_lshl_add_u64 v[56:57], v[138:139], 0, s[2:3]
	v_add_co_u32_e32 v44, vcc, 0x10000, v56
	v_lshl_add_u64 v[72:73], v[132:133], 0, s[2:3]
	s_nop 0
	v_addc_co_u32_e32 v45, vcc, 0, v57, vcc
	v_add_co_u32_e32 v58, vcc, 0x20000, v56
	global_load_dwordx4 v[40:43], v[56:57], off offset:2048
	s_nop 0
	s_nop 0
	global_load_dwordx4 v[44:47], v[44:45], off offset:2048
	v_addc_co_u32_e32 v59, vcc, 0, v57, vcc
	v_add_co_u32_e32 v56, vcc, 0x30000, v56
	v_lshl_add_u64 v[92:93], v[136:137], 0, s[2:3]
	s_nop 0
	v_addc_co_u32_e32 v57, vcc, 0, v57, vcc
	v_lshl_add_u64 v[100:101], v[140:141], 0, s[2:3]
	v_lshl_add_u64 v[108:109], v[134:135], 0, s[2:3]
	global_load_dwordx4 v[76:79], v[58:59], off offset:2048
	s_nop 0
	global_load_dwordx4 v[56:59], v[56:57], off offset:2048
	s_nop 0
	global_load_dwordx4 v[72:75], v[72:73], off offset:2048
	s_nop 0
	global_load_dwordx4 v[92:95], v[92:93], off offset:2048
	s_nop 0
	global_load_dwordx4 v[100:103], v[100:101], off offset:2048
	s_nop 0
	global_load_dwordx4 v[108:111], v[108:109], off offset:2048
.LBB0_2024:
	v_add_u32_e32 v154, s7, v196
	v_add_u32_e32 v155, s7, v197
	s_andn2_b64 vcc, exec, s[20:21]
	v_add_u32_e32 v158, v154, v209
	ds_read_b128 v[216:219], v158
	v_add_u32_e32 v159, v155, v209
	ds_read_b128 v[232:235], v159 offset:32768
	ds_read_b128 v[244:247], v159 offset:49152
	v_add_u32_e32 v164, v154, v210
	ds_read_b128 v[220:223], v164
	v_add_u32_e32 v165, v155, v210
	ds_read_b128 v[236:239], v165 offset:32768
	s_nop 0
	ds_read_b128 v[248:251], v165 offset:49152
	v_add_u32_e32 v180, v154, v211
	ds_read_b128 v[224:227], v180
	v_add_u32_e32 v181, v155, v211
	ds_read_b128 v[240:243], v181 offset:32768
	ds_read_b128 v[176:179], v181 offset:49152
	v_add_u32_e32 v200, v154, v212
	ds_read_b128 v[228:231], v200
	v_add_u32_e32 v201, v155, v212
	s_waitcnt lgkmcnt(8)
	s_nop 0
	v_mfma_f32_32x32x16_bf16 v[4:19], v[232:235], v[216:219], v[4:19]
	s_waitcnt lgkmcnt(7)
	v_mfma_f32_32x32x16_bf16 v[20:35], v[244:247], v[216:219], v[20:35]
	ds_read_b128 v[232:235], v201 offset:32768
	ds_read_b128 v[244:247], v201 offset:49152
	s_waitcnt lgkmcnt(7)
	v_mfma_f32_32x32x16_bf16 v[4:19], v[236:239], v[220:223], v[4:19]
	s_waitcnt lgkmcnt(6)
	v_mfma_f32_32x32x16_bf16 v[20:35], v[248:251], v[220:223], v[20:35]
	s_waitcnt lgkmcnt(4)
	v_mfma_f32_32x32x16_bf16 v[4:19], v[240:243], v[224:227], v[4:19]
	s_waitcnt lgkmcnt(3)
	v_mfma_f32_32x32x16_bf16 v[20:35], v[176:179], v[224:227], v[20:35]
	s_waitcnt lgkmcnt(1)
	v_mfma_f32_32x32x16_bf16 v[4:19], v[232:235], v[228:231], v[4:19]
	s_waitcnt lgkmcnt(0)
	s_barrier
	v_mfma_f32_32x32x16_bf16 v[20:35], v[244:247], v[228:231], v[20:35]
	s_cbranch_vccnz .LBB0_2017
	s_cmpk_eq_i32 s2, 0xa00
	s_cbranch_scc1 .LBB0_2027
	s_waitcnt vmcnt(8)
	ds_write_b128 v2, v[36:39]
	ds_write_b128 v2, v[48:51] offset:8192
	ds_write_b128 v2, v[80:83] offset:16384
	ds_write_b128 v2, v[60:63] offset:24576
	ds_write_b128 v2, v[84:87] offset:32768
	ds_write_b128 v2, v[96:99] offset:40960
	ds_write_b128 v2, v[104:107] offset:49152
	ds_write_b128 v2, v[112:115] offset:57344

; template <class Epi, int NC>
; __device__ __forceinline__ void skinny_phase(const bf16* __restrict__ A, int lda, int a_goff, const bf16* __restrict__ Bt, int ldb, int K, int ncg, int vcu, int G, const Epi& E, LAS float* rs_tab, LAS unsigned char* lds) {
;     ...
;     int u = vcu;
;     if (u < NU) { SK_PTRS(u); SK_LOAD3(); }
; #pragma unroll 1
;     while (u < NU) {
;         const int cg = (u >> 2) * NC, rb = u & 3;
;         f32x16 acc[NC] = {};
;         SK_WRITE(0, 0);
;         asm volatile("s_waitcnt lgkmcnt(0)" ::: "memory"); __builtin_amdgcn_s_barrier(); asm volatile("" ::: "memory");
; #pragma unroll 1
;         for (int c3 = 0; c3 < nsc; c3 += 3) { SK_STEP(0); SK_STEP(1); SK_STEP(2); }
;         const int un = u + G;
;         if (un < NU) { SK_PTRS(un); SK_LOAD3(); }
;         LAS float* pb = (LAS float*)lds + (w * NC) * 1024 + lane;
;         asm volatile("" : "+v"(pb));
; #pragma unroll
;         for (int g = 0; g < NC; ++g)
; #pragma unroll
;             for (int r = 0; r < 16; ++r) pb[(g * 16 + r) * 64] = acc[g][r];
;         asm volatile("s_waitcnt lgkmcnt(0)" ::: "memory"); __builtin_amdgcn_s_barrier(); asm volatile("" ::: "memory");
;         if (kq == 0) {
;             const int row = 64 * rb + rrow; const float rs = Epi::NEEDS_RS ? rs_tab[row] : 1.f;
; #pragma unroll
;             for (int g = 0; g < NC; ++g) {
; #pragma unroll
;                 for (int r = 0; r < 16; ++r) { const int o_ = (g * 16 + r) * 64; acc[g][r] = ((pb[o_] + pb[o_ + 2 * NC * 1024]) + pb[o_ + 4 * NC * 1024]) + pb[o_ + 6 * NC * 1024]; }
;                 E(acc[g], cg + g, row, hi, rs); }
;     __device__ __forceinline__ void operator()(const f32x16& acc, int u, int row, int hi, float rs) const {
;         const int seg = u >> 6;
; #pragma unroll
;         for (int q = 0; q < 4; ++q) { const int c = 32 * (u & 63) + 8 * q + 4 * hi; const size_t off = (size_t)(MP + row) * D + c;
;             f32x4 a = {acc[4 * q] * rs, acc[4 * q + 1] * rs, acc[4 * q + 2] * rs, acc[4 * q + 3] * rs};
;             if (seg == 1) { const f32x4 l = *(const f32x4*)(lb + c);
; #pragma unroll
;                 for (int j = 0; j < 4; ++j) a[j] = __builtin_amdgcn_logf(fmaxf(l[j] + (1.f - l[j]) * sigmoidf_(a[j]), 1e-6f));
;                 u32x2 lw_; lw_.x = pk_f16(a[0], a[1]); lw_.y = pk_f16(a[2], a[3]); *(u32x2*)((unsigned short*)LOGF + off) = lw_;
;             } else {
.LBB0_2029:
	s_add_i32 s67, s4, s64
	s_cmpk_gt_i32 s67, 0x1ff
	s_cselect_b64 s[18:19], -1, 0
	s_cmpk_lt_i32 s67, 0x200
	s_cbranch_scc0 .LBB0_2031
	s_lshl_b32 s2, s67, 6
	s_and_b32 s2, s2, 0xc0
	s_waitcnt vmcnt(0)
	v_add_u32_e32 v36, s2, v192
	s_lshl_b32 s2, s67, 4
	s_andn2_b32 s2, s2, 63
	v_add_u32_e32 v38, s2, v192
	v_ashrrev_i32_e32 v39, 31, v38
	v_lshlrev_b64 v[38:39], 12, v[38:39]
	v_lshl_add_u64 v[132:133], v[144:145], 0, v[38:39]
	v_add_u32_e32 v38, s2, v193
	v_ashrrev_i32_e32 v37, 31, v36
	v_ashrrev_i32_e32 v39, 31, v38
	v_lshlrev_b64 v[36:37], 12, v[36:37]
	v_lshlrev_b64 v[38:39], 12, v[38:39]
	s_or_b32 s2, s2, 32
	v_lshl_add_u64 v[136:137], v[144:145], 0, v[38:39]
	v_add_u32_e32 v38, s2, v192
	v_lshl_add_u64 v[138:139], v[142:143], 0, v[36:37]
	v_ashrrev_i32_e32 v39, 31, v38
	v_lshlrev_b64 v[38:39], 12, v[38:39]
	v_add_co_u32_e32 v64, vcc, s71, v138
	v_lshl_add_u64 v[140:141], v[144:145], 0, v[38:39]
	s_nop 0
	v_addc_co_u32_e32 v65, vcc, 0, v139, vcc
	v_add_u32_e32 v38, s2, v193
	v_add_co_u32_e32 v68, vcc, s81, v138
	v_ashrrev_i32_e32 v39, 31, v38
	s_nop 0
	v_addc_co_u32_e32 v69, vcc, 0, v139, vcc
	s_mov_b32 s2, 0x30000
	v_lshlrev_b64 v[38:39], 12, v[38:39]
	v_add_co_u32_e32 v88, vcc, s2, v138
	v_lshl_add_u64 v[134:135], v[144:145], 0, v[38:39]
	s_nop 0
	v_addc_co_u32_e32 v89, vcc, 0, v139, vcc
	global_load_dwordx4 v[36:39], v[138:139], off
	global_load_dwordx4 v[40:43], v[138:139], off offset:512
	global_load_dwordx4 v[48:51], v[64:65], off
	global_load_dwordx4 v[44:47], v[64:65], off offset:512
	global_load_dwordx4 v[60:63], v[88:89], off
	s_nop 0
	global_load_dwordx4 v[56:59], v[88:89], off offset:512
	global_load_dwordx4 v[84:87], v[132:133], off
	global_load_dwordx4 v[72:75], v[132:133], off offset:512
	global_load_dwordx4 v[96:99], v[136:137], off
	global_load_dwordx4 v[92:95], v[136:137], off offset:512
	global_load_dwordx4 v[104:107], v[140:141], off
	global_load_dwordx4 v[100:103], v[140:141], off offset:512
	global_load_dwordx4 v[112:115], v[134:135], off
	global_load_dwordx4 v[108:111], v[134:135], off offset:512
	global_load_dwordx4 v[52:55], v[138:139], off offset:1024
	global_load_dwordx4 v[80:83], v[68:69], off
	s_nop 0
	global_load_dwordx4 v[64:67], v[64:65], off offset:1024
	s_nop 0
	global_load_dwordx4 v[76:79], v[68:69], off offset:512
	s_nop 0
	global_load_dwordx4 v[68:71], v[68:69], off offset:1024
	s_nop 0
	global_load_dwordx4 v[88:91], v[88:89], off offset:1024
	s_nop 0
	global_load_dwordx4 v[116:119], v[132:133], off offset:1024
	global_load_dwordx4 v[120:123], v[136:137], off offset:1024
	global_load_dwordx4 v[124:127], v[140:141], off offset:1024
	global_load_dwordx4 v[128:131], v[134:135], off offset:1024
.LBB0_2031:
	v_mov_b32_e32 v190, v207
	ds_write2st64_b32 v190, v4, v5 offset1:1
	ds_write2st64_b32 v190, v6, v7 offset0:2 offset1:3
	ds_write2st64_b32 v190, v8, v9 offset0:4 offset1:5
	ds_write2st64_b32 v190, v10, v11 offset0:6 offset1:7
	ds_write2st64_b32 v190, v12, v13 offset0:8 offset1:9
	ds_write2st64_b32 v190, v14, v15 offset0:10 offset1:11
	ds_write2st64_b32 v190, v16, v17 offset0:12 offset1:13
	ds_write2st64_b32 v190, v18, v19 offset0:14 offset1:15
	ds_write2st64_b32 v190, v20, v21 offset0:16 offset1:17
	ds_write2st64_b32 v190, v22, v23 offset0:18 offset1:19
	ds_write2st64_b32 v190, v24, v25 offset0:20 offset1:21
	ds_write2st64_b32 v190, v26, v27 offset0:22 offset1:23
	ds_write2st64_b32 v190, v28, v29 offset0:24 offset1:25
	ds_write2st64_b32 v190, v30, v31 offset0:26 offset1:27
	ds_write2st64_b32 v190, v32, v33 offset0:28 offset1:29
	ds_write2st64_b32 v190, v34, v35 offset0:30 offset1:31
	s_waitcnt lgkmcnt(0)
	s_barrier
	s_andn2_b64 vcc, exec, s[12:13]
	s_cbranch_vccnz .LBB0_2014
	s_lshl_b32 s2, s4, 6
	s_and_b32 s2, s2, 0xc0
	v_or_b32_e32 v191, s2, v195
	v_lshl_add_u32 v2, v191, 2, 0
	v_add_u32_e32 v2, 0x20000, v2
	ds_read_b32 v4, v2
	ds_read2st64_b32 v[156:157], v190 offset1:1
	ds_read2st64_b32 v[158:159], v190 offset0:2 offset1:3
	ds_read2st64_b32 v[148:149], v190 offset0:4 offset1:5
	ds_read2st64_b32 v[150:151], v190 offset0:6 offset1:7
	ds_read2st64_b32 v[164:165], v190 offset0:64 offset1:65
	ds_read2st64_b32 v[180:181], v190 offset0:66 offset1:67
	ds_read2st64_b32 v[174:175], v190 offset0:68 offset1:69
	ds_read2st64_b32 v[152:153], v190 offset0:70 offset1:71
	ds_read2st64_b32 v[182:183], v190 offset0:128 offset1:129
	ds_read2st64_b32 v[184:185], v190 offset0:130 offset1:131
	ds_read2st64_b32 v[176:177], v190 offset0:132 offset1:133
	ds_read2st64_b32 v[154:155], v190 offset0:134 offset1:135
	ds_read2st64_b32 v[186:187], v190 offset0:192 offset1:193
	ds_read2st64_b32 v[188:189], v190 offset0:194 offset1:195
	ds_read2st64_b32 v[178:179], v190 offset0:196 offset1:197
	ds_read2st64_b32 v[172:173], v190 offset0:198 offset1:199
	ds_read2st64_b32 v[6:7], v190 offset0:8 offset1:9
	ds_read2st64_b32 v[24:25], v190 offset0:10 offset1:11
	ds_read2st64_b32 v[8:9], v190 offset0:12 offset1:13
	ds_read2st64_b32 v[10:11], v190 offset0:14 offset1:15
	ds_read2st64_b32 v[32:33], v190 offset0:72 offset1:73
	ds_read2st64_b32 v[26:27], v190 offset0:74 offset1:75
	ds_read2st64_b32 v[18:19], v190 offset0:76 offset1:77
	ds_read2st64_b32 v[12:13], v190 offset0:78 offset1:79
	ds_read2st64_b32 v[34:35], v190 offset0:136 offset1:137
	ds_read2st64_b32 v[28:29], v190 offset0:138 offset1:139
	ds_read2st64_b32 v[20:21], v190 offset0:140 offset1:141
	ds_read2st64_b32 v[14:15], v190 offset0:142 offset1:143
	ds_read2st64_b32 v[146:147], v190 offset0:200 offset1:201
	ds_read2st64_b32 v[30:31], v190 offset0:202 offset1:203
	ds_read2st64_b32 v[22:23], v190 offset0:204 offset1:205
	ds_read2st64_b32 v[16:17], v190 offset0:206 offset1:207
	s_waitcnt lgkmcnt(0)
	v_pk_add_f32 v[156:157], v[156:157], v[164:165]
	s_ashr_i32 s10, s4, 7
	v_pk_add_f32 v[156:157], v[156:157], v[182:183]
	s_ashr_i32 s5, s4, 1
	v_pk_add_f32 v[156:157], v[156:157], v[186:187]
	s_add_i32 s2, s10, 1
	v_pk_mul_f32 v[182:183], v[4:5], v[156:157] op_sel_hi:[0,1]
	v_pk_add_f32 v[156:157], v[158:159], v[180:181]
	s_cmp_gt_u32 s5, 63
	v_pk_add_f32 v[156:157], v[156:157], v[184:185]
	s_cselect_b32 s39, s2, 0
	v_pk_add_f32 v[156:157], v[156:157], v[188:189]
	s_mov_b64 s[36:37], -1
	s_nop 0
	v_pk_mul_f32 v[180:181], v[4:5], v[156:157] op_sel_hi:[0,1]
	s_mov_b64 s[2:3], 0
	s_cmp_lt_i32 s10, 3
	s_mov_b64 s[20:21], 0
	s_cbranch_scc1 .LBB0_2036
	s_cmp_eq_u32 s10, 3
	v_mov_b32_e32 v185, v181
	v_mov_b32_e32 v184, v180
	v_mov_b32_e32 v187, v183
	v_mov_b32_e32 v186, v182
	s_cbranch_scc0 .LBB0_2035
	v_mul_f32_e32 v2, 0xbfb8aa3b, v182
	v_exp_f32_e32 v2, v2
	s_nop 0
	v_mul_f32_e32 v5, 0xbfb8aa3b, v183
	v_mul_f32_e32 v157, 0xbfb8aa3b, v181
	v_exp_f32_e32 v5, v5
	v_add_f32_e32 v2, 1.0, v2
	v_rcp_f32_e32 v156, v2
	v_mul_f32_e32 v2, 0xbfb8aa3b, v180
	v_exp_f32_e32 v2, v2
	v_exp_f32_e32 v159, v157
	v_add_f32_e32 v5, 1.0, v5
	v_rcp_f32_e32 v157, v5
	v_add_f32_e32 v2, 1.0, v2
	v_rcp_f32_e32 v158, v2
	v_add_f32_e32 v2, 1.0, v159
	v_rcp_f32_e32 v159, v2
	v_pk_mul_f32 v[186:187], v[182:183], v[156:157]
	v_pk_mul_f32 v[184:185], v[180:181], v[158:159]

; __device__ __forceinline__ float sigmoidf_(float x) { return __builtin_amdgcn_rcpf(1.0f + fast_exp(-x)); }
; __device__ __forceinline__ u32x2 pack4(float a, float b, float c, float d) { u32x2 w; w.x = cvt_pk_bf16(a, b); w.y = cvt_pk_bf16(c, d); return w; }
; template <class Epi, int NC>
; __device__ __forceinline__ void skinny_phase(const bf16* __restrict__ A, int lda, int a_goff, const bf16* __restrict__ Bt, int ldb, int K, int ncg, int vcu, int G, const Epi& E, LAS float* rs_tab, LAS unsigned char* lds) {
;     ...
;         if (kq == 0) {
;             const int row = 64 * rb + rrow; const float rs = Epi::NEEDS_RS ? rs_tab[row] : 1.f;
; #pragma unroll
;             for (int g = 0; g < NC; ++g) {
; #pragma unroll
;                 for (int r = 0; r < 16; ++r) { const int o_ = (g * 16 + r) * 64; acc[g][r] = ((pb[o_] + pb[o_ + 2 * NC * 1024]) + pb[o_ + 4 * NC * 1024]) + pb[o_ + 6 * NC * 1024]; }
;                 E(acc[g], cg + g, row, hi, rs); }
;     __device__ __forceinline__ void operator()(const f32x16& acc, int u, int row, int hi, float rs) const {
;         const int seg = u >> 6;
; #pragma unroll
;         for (int q = 0; q < 4; ++q) { const int c = 32 * (u & 63) + 8 * q + 4 * hi; const size_t off = (size_t)(MP + row) * D + c;
;             f32x4 a = {acc[4 * q] * rs, acc[4 * q + 1] * rs, acc[4 * q + 2] * rs, acc[4 * q + 3] * rs};
;             if (seg == 1) { const f32x4 l = *(const f32x4*)(lb + c);
; #pragma unroll
;                 for (int j = 0; j < 4; ++j) a[j] = __builtin_amdgcn_logf(fmaxf(l[j] + (1.f - l[j]) * sigmoidf_(a[j]), 1e-6f));
;                 u32x2 lw_; lw_.x = pk_f16(a[0], a[1]); lw_.y = pk_f16(a[2], a[3]); *(u32x2*)((unsigned short*)LOGF + off) = lw_;
;             } else {
;                 if (seg == 3) {
; #pragma unroll
;                     for (int j = 0; j < 4; ++j) a[j] = a[j] * sigmoidf_(a[j]); }
;                 bf16* dst = (bf16*)((char*)Q + (size_t)(seg ? seg + 1 : 0) * (65 * MiB));
;                 *(u32x2*)(dst + off) = pack4(a[0], a[1], a[2], a[3]); } }
.LBB0_2040:
	s_lshl_b32 s4, s5, 5
	s_nop 0
	s_and_b32 s4, s4, 0x7c0
	v_or_b32_e32 v2, s4, v208
	s_andn2_b64 vcc, exec, s[2:3]
	v_lshlrev_b32_e32 v184, 2, v2
	s_cbranch_vccnz .LBB0_2042
	global_load_dwordx4 v[186:189], v184, s[44:45]
	v_mul_f32_e32 v156, 0xbfb8aa3b, v182
	v_exp_f32_e32 v156, v156
	v_mul_f32_e32 v157, 0xbfb8aa3b, v183
	v_exp_f32_e32 v157, v157
	v_mul_f32_e32 v158, 0xbfb8aa3b, v180
	v_exp_f32_e32 v158, v158
	v_mul_f32_e32 v159, 0xbfb8aa3b, v181
	v_exp_f32_e32 v159, v159
	v_add_f32_e32 v156, 1.0, v156
	v_rcp_f32_e32 v156, v156
	v_add_f32_e32 v157, 1.0, v157
	v_rcp_f32_e32 v157, v157
	v_add_f32_e32 v158, 1.0, v158
	v_rcp_f32_e32 v158, v158
	v_add_f32_e32 v159, 1.0, v159
	v_rcp_f32_e32 v159, v159
	s_mov_b64 s[20:21], s[0:1]
	s_waitcnt vmcnt(0)
	v_sub_f32_e32 v5, 1.0, v186
	s_nop 0
	v_fma_f32 v5, v156, v5, v186
	v_sub_f32_e32 v156, 1.0, v187
	v_fma_f32 v156, v157, v156, v187
	v_sub_f32_e32 v157, 1.0, v188
	v_fma_f32 v157, v158, v157, v188
	v_sub_f32_e32 v158, 1.0, v189
	v_fmac_f32_e32 v189, v159, v158
	v_max_f32_e32 v5, 0x358637bd, v5
	v_max_f32_e32 v156, 0x358637bd, v156
	v_max_f32_e32 v157, 0x358637bd, v157
	v_max_f32_e32 v158, 0x358637bd, v189
	v_log_f32_e32 v5, v5
	v_log_f32_e32 v156, v156
	v_log_f32_e32 v157, v157
	v_log_f32_e32 v158, v158
	v_cvt_pk_f16_f32 v188, v5, v156
	v_cvt_pk_f16_f32 v189, v157, v158
.LBB0_2042:
	v_lshl_or_b32 v180, v191, 11, v205
	v_pk_add_f32 v[148:149], v[148:149], v[174:175]
	v_pk_add_f32 v[150:151], v[150:151], v[152:153]
	v_or_b32_e32 v156, v180, v2
	v_pk_add_f32 v[148:149], v[148:149], v[176:177]
	v_pk_add_f32 v[150:151], v[150:151], v[154:155]
	v_lshlrev_b32_e32 v156, 1, v156
	v_mov_b32_e32 v5, v4
	v_pk_add_f32 v[148:149], v[148:149], v[178:179]
	v_pk_add_f32 v[150:151], v[150:151], v[172:173]
	global_store_dwordx2 v156, v[188:189], s[20:21]
	v_pk_mul_f32 v[152:153], v[4:5], v[148:149]
	s_nop 0
	v_pk_mul_f32 v[148:149], v[4:5], v[150:151]
	s_cmp_lt_i32 s10, 3
	s_mov_b64 s[36:37], -1
	s_mov_b64 s[2:3], 0
	s_mov_b64 s[20:21], 0
	s_cbranch_scc1 .LBB0_2046
	s_cmp_eq_u32 s10, 3
	v_mov_b32_e32 v155, v149
	v_mov_b32_e32 v154, v148
	v_mov_b32_e32 v173, v153
	v_mov_b32_e32 v172, v152
	s_cbranch_scc0 .LBB0_2045
	v_mul_f32_e32 v150, 0xbfb8aa3b, v152
	s_nop 0
	v_mul_f32_e32 v151, 0xbfb8aa3b, v153
	v_mul_f32_e32 v154, 0xbfb8aa3b, v148
	v_mul_f32_e32 v155, 0xbfb8aa3b, v149
	v_exp_f32_e32 v150, v150
	v_exp_f32_e32 v151, v151
	v_exp_f32_e32 v154, v154
	v_exp_f32_e32 v155, v155
	v_add_f32_e32 v150, 1.0, v150
	v_add_f32_e32 v151, 1.0, v151
	v_add_f32_e32 v154, 1.0, v154
	v_add_f32_e32 v155, 1.0, v155
	v_rcp_f32_e32 v150, v150
	v_rcp_f32_e32 v151, v151
	v_rcp_f32_e32 v154, v154
	v_rcp_f32_e32 v155, v155
	v_pk_mul_f32 v[172:173], v[152:153], v[150:151]
	v_pk_mul_f32 v[154:155], v[148:149], v[154:155]

; __device__ __forceinline__ float sigmoidf_(float x) { return __builtin_amdgcn_rcpf(1.0f + fast_exp(-x)); }
;     __device__ __forceinline__ void operator()(const f32x16& acc, int u, int row, int hi, float rs) const {
;     ...
;         for (int q = 0; q < 4; ++q) { const int c = 32 * (u & 63) + 8 * q + 4 * hi; const size_t off = (size_t)(MP + row) * D + c;
;             f32x4 a = {acc[4 * q] * rs, acc[4 * q + 1] * rs, acc[4 * q + 2] * rs, acc[4 * q + 3] * rs};
;             if (seg == 1) { const f32x4 l = *(const f32x4*)(lb + c);
; #pragma unroll
;                 for (int j = 0; j < 4; ++j) a[j] = __builtin_amdgcn_logf(fmaxf(l[j] + (1.f - l[j]) * sigmoidf_(a[j]), 1e-6f));
;                 u32x2 lw_; lw_.x = pk_f16(a[0], a[1]); lw_.y = pk_f16(a[2], a[3]); *(u32x2*)((unsigned short*)LOGF + off) = lw_;
.LBB0_2051:
	s_nop 0
	global_load_dwordx4 v[172:175], v184, s[44:45] offset:32
	v_mul_f32_e32 v151, 0xbfb8aa3b, v152
	v_exp_f32_e32 v151, v151
	v_mul_f32_e32 v152, 0xbfb8aa3b, v153
	v_exp_f32_e32 v152, v152
	v_mul_f32_e32 v148, 0xbfb8aa3b, v148
	v_exp_f32_e32 v148, v148
	v_mul_f32_e32 v149, 0xbfb8aa3b, v149
	v_exp_f32_e32 v149, v149
	v_add_f32_e32 v151, 1.0, v151
	v_rcp_f32_e32 v151, v151
	v_add_f32_e32 v152, 1.0, v152
	v_rcp_f32_e32 v152, v152
	v_add_f32_e32 v148, 1.0, v148
	v_rcp_f32_e32 v148, v148
	v_add_f32_e32 v149, 1.0, v149
	v_rcp_f32_e32 v149, v149
	s_mov_b64 s[20:21], s[0:1]
	s_waitcnt vmcnt(0)
	v_sub_f32_e32 v150, 1.0, v172
	v_fma_f32 v150, v151, v150, v172
	v_sub_f32_e32 v151, 1.0, v173
	v_fma_f32 v151, v152, v151, v173
	v_sub_f32_e32 v152, 1.0, v174
	s_nop 0
	v_fma_f32 v148, v148, v152, v174
	v_sub_f32_e32 v152, 1.0, v175
	v_fmac_f32_e32 v175, v149, v152
	v_max_f32_e32 v150, 0x358637bd, v150
	v_max_f32_e32 v151, 0x358637bd, v151
	v_max_f32_e32 v148, 0x358637bd, v148
	v_max_f32_e32 v149, 0x358637bd, v175
	v_log_f32_e32 v150, v150
	v_log_f32_e32 v151, v151
	v_log_f32_e32 v148, v148
	v_log_f32_e32 v149, v149
	v_cvt_pk_f16_f32 v174, v150, v151
	v_mov_b64_e32 v[150:151], v[2:3]
	v_cvt_pk_f16_f32 v175, v148, v149

; __device__ __forceinline__ float sigmoidf_(float x) { return __builtin_amdgcn_rcpf(1.0f + fast_exp(-x)); }
; __device__ __forceinline__ u32x2 pack4(float a, float b, float c, float d) { u32x2 w; w.x = cvt_pk_bf16(a, b); w.y = cvt_pk_bf16(c, d); return w; }
;     __device__ __forceinline__ void operator()(const f32x16& acc, int u, int row, int hi, float rs) const {
;         const int seg = u >> 6;
; #pragma unroll
;         for (int q = 0; q < 4; ++q) { const int c = 32 * (u & 63) + 8 * q + 4 * hi; const size_t off = (size_t)(MP + row) * D + c;
;             f32x4 a = {acc[4 * q] * rs, acc[4 * q + 1] * rs, acc[4 * q + 2] * rs, acc[4 * q + 3] * rs};
;             if (seg == 1) { const f32x4 l = *(const f32x4*)(lb + c);
; #pragma unroll
;                 for (int j = 0; j < 4; ++j) a[j] = __builtin_amdgcn_logf(fmaxf(l[j] + (1.f - l[j]) * sigmoidf_(a[j]), 1e-6f));
;                 u32x2 lw_; lw_.x = pk_f16(a[0], a[1]); lw_.y = pk_f16(a[2], a[3]); *(u32x2*)((unsigned short*)LOGF + off) = lw_;
;             } else {
;                 if (seg == 3) {
; #pragma unroll
;                     for (int j = 0; j < 4; ++j) a[j] = a[j] * sigmoidf_(a[j]); }
;                 bf16* dst = (bf16*)((char*)Q + (size_t)(seg ? seg + 1 : 0) * (65 * MiB));
;                 *(u32x2*)(dst + off) = pack4(a[0], a[1], a[2], a[3]); } }
.LBB0_2061:
	global_load_dwordx4 v[28:31], v[6:7], off offset:64
	v_mul_f32_e32 v26, 0xbfb8aa3b, v26
	v_exp_f32_e32 v26, v26
	s_nop 0
	v_mul_f32_e32 v27, 0xbfb8aa3b, v27
	v_exp_f32_e32 v27, v27
	v_mul_f32_e32 v24, 0xbfb8aa3b, v24
	v_exp_f32_e32 v24, v24
	v_mul_f32_e32 v25, 0xbfb8aa3b, v25
	v_exp_f32_e32 v25, v25
	v_add_f32_e32 v26, 1.0, v26
	v_rcp_f32_e32 v26, v26
	v_add_f32_e32 v27, 1.0, v27
	v_rcp_f32_e32 v27, v27
	v_add_f32_e32 v24, 1.0, v24
	v_rcp_f32_e32 v24, v24
	v_add_f32_e32 v25, 1.0, v25
	v_rcp_f32_e32 v25, v25
	s_mov_b64 s[20:21], s[0:1]
	s_waitcnt vmcnt(0)
	v_sub_f32_e32 v32, 1.0, v28
	v_fma_f32 v26, v26, v32, v28
	v_sub_f32_e32 v28, 1.0, v29
	v_fma_f32 v27, v27, v28, v29
	v_sub_f32_e32 v28, 1.0, v30
	v_fma_f32 v24, v24, v28, v30
	v_sub_f32_e32 v28, 1.0, v31
	v_fmac_f32_e32 v31, v25, v28
	v_max_f32_e32 v26, 0x358637bd, v26
	v_max_f32_e32 v27, 0x358637bd, v27
	v_max_f32_e32 v24, 0x358637bd, v24
	v_max_f32_e32 v25, 0x358637bd, v31
	v_log_f32_e32 v26, v26
	v_log_f32_e32 v27, v27
	v_log_f32_e32 v24, v24
	v_log_f32_e32 v25, v25
	v_cvt_pk_f16_f32 v30, v26, v27
	v_cvt_pk_f16_f32 v31, v24, v25
.LBB0_2062:
	v_pk_add_f32 v[8:9], v[8:9], v[18:19]
	v_pk_add_f32 v[10:11], v[10:11], v[12:13]
	v_pk_add_f32 v[8:9], v[8:9], v[20:21]
	v_pk_add_f32 v[10:11], v[10:11], v[14:15]
	v_pk_add_f32 v[8:9], v[8:9], v[22:23]
	v_pk_add_f32 v[12:13], v[10:11], v[16:17]
	v_lshl_add_u64 v[24:25], v[2:3], 1, s[20:21]
	v_pk_mul_f32 v[10:11], v[4:5], v[8:9]
	v_pk_mul_f32 v[8:9], v[4:5], v[12:13]
	s_mov_b64 s[36:37], -1
	s_mov_b64 s[2:3], 0
	s_cmp_lt_i32 s10, 3
	s_mov_b64 s[20:21], 0
	global_store_dwordx2 v[24:25], v[30:31], off offset:32
	s_cbranch_scc1 .LBB0_2068
	s_cmp_eq_u32 s10, 3
	v_mov_b32_e32 v13, v9
	v_mov_b32_e32 v12, v8
	v_mov_b32_e32 v15, v11
	v_mov_b32_e32 v14, v10
	s_cbranch_scc0 .LBB0_2065
	v_mul_f32_e32 v14, 0xbfb8aa3b, v8
	s_nop 0
	v_mul_f32_e32 v12, 0xbfb8aa3b, v10
	v_mul_f32_e32 v13, 0xbfb8aa3b, v11
	v_exp_f32_e32 v14, v14
	v_mul_f32_e32 v15, 0xbfb8aa3b, v9
	v_exp_f32_e32 v12, v12
	v_exp_f32_e32 v13, v13
	v_exp_f32_e32 v15, v15
	v_add_f32_e32 v14, 1.0, v14
	v_add_f32_e32 v12, 1.0, v12
	v_add_f32_e32 v13, 1.0, v13
	v_rcp_f32_e32 v16, v14
	v_add_f32_e32 v14, 1.0, v15
	v_rcp_f32_e32 v12, v12
	v_rcp_f32_e32 v13, v13
	v_rcp_f32_e32 v17, v14
	v_pk_mul_f32 v[14:15], v[10:11], v[12:13]
	v_pk_mul_f32 v[12:13], v[8:9], v[16:17]

; __device__ __forceinline__ float sigmoidf_(float x) { return __builtin_amdgcn_rcpf(1.0f + fast_exp(-x)); }
; __device__ __forceinline__ u32x2 pack4(float a, float b, float c, float d) { u32x2 w; w.x = cvt_pk_bf16(a, b); w.y = cvt_pk_bf16(c, d); return w; }
; template <class Epi, int NC>
; __device__ __forceinline__ void skinny_phase(const bf16* __restrict__ A, int lda, int a_goff, const bf16* __restrict__ Bt, int ldb, int K, int ncg, int vcu, int G, const Epi& E, LAS float* rs_tab, LAS unsigned char* lds) {
;     ...
;         if (kq == 0) {
;             const int row = 64 * rb + rrow; const float rs = Epi::NEEDS_RS ? rs_tab[row] : 1.f;
; #pragma unroll
;             for (int g = 0; g < NC; ++g) {
; #pragma unroll
;                 for (int r = 0; r < 16; ++r) { const int o_ = (g * 16 + r) * 64; acc[g][r] = ((pb[o_] + pb[o_ + 2 * NC * 1024]) + pb[o_ + 4 * NC * 1024]) + pb[o_ + 6 * NC * 1024]; }
;                 E(acc[g], cg + g, row, hi, rs); }
;     __device__ __forceinline__ void operator()(const f32x16& acc, int u, int row, int hi, float rs) const {
;         const int seg = u >> 6;
; #pragma unroll
;         for (int q = 0; q < 4; ++q) { const int c = 32 * (u & 63) + 8 * q + 4 * hi; const size_t off = (size_t)(MP + row) * D + c;
;             f32x4 a = {acc[4 * q] * rs, acc[4 * q + 1] * rs, acc[4 * q + 2] * rs, acc[4 * q + 3] * rs};
;             if (seg == 1) { const f32x4 l = *(const f32x4*)(lb + c);
; #pragma unroll
;                 for (int j = 0; j < 4; ++j) a[j] = __builtin_amdgcn_logf(fmaxf(l[j] + (1.f - l[j]) * sigmoidf_(a[j]), 1e-6f));
;                 u32x2 lw_; lw_.x = pk_f16(a[0], a[1]); lw_.y = pk_f16(a[2], a[3]); *(u32x2*)((unsigned short*)LOGF + off) = lw_;
;             } else {
;                 if (seg == 3) {
; #pragma unroll
;                     for (int j = 0; j < 4; ++j) a[j] = a[j] * sigmoidf_(a[j]); }
;                 bf16* dst = (bf16*)((char*)Q + (size_t)(seg ? seg + 1 : 0) * (65 * MiB));
;                 *(u32x2*)(dst + off) = pack4(a[0], a[1], a[2], a[3]); } }
.LBB0_2071:
	s_nop 0
	global_load_dwordx4 v[12:15], v[6:7], off offset:96
	v_mul_f32_e32 v10, 0xbfb8aa3b, v10
	v_exp_f32_e32 v10, v10
	v_mul_f32_e32 v11, 0xbfb8aa3b, v11
	v_exp_f32_e32 v11, v11
	v_mul_f32_e32 v8, 0xbfb8aa3b, v8
	v_exp_f32_e32 v8, v8
	v_mul_f32_e32 v9, 0xbfb8aa3b, v9
	v_exp_f32_e32 v9, v9
	v_add_f32_e32 v10, 1.0, v10
	v_rcp_f32_e32 v10, v10
	v_add_f32_e32 v11, 1.0, v11
	v_rcp_f32_e32 v11, v11
	v_add_f32_e32 v8, 1.0, v8
	v_rcp_f32_e32 v8, v8
	v_add_f32_e32 v9, 1.0, v9
	v_rcp_f32_e32 v9, v9
	s_mov_b64 s[20:21], s[0:1]
	s_waitcnt vmcnt(0)
	v_sub_f32_e32 v16, 1.0, v12
	v_fma_f32 v10, v10, v16, v12
	v_sub_f32_e32 v12, 1.0, v13
	v_fma_f32 v11, v11, v12, v13
	v_sub_f32_e32 v12, 1.0, v14
	s_nop 0
	v_fma_f32 v8, v8, v12, v14
	v_sub_f32_e32 v12, 1.0, v15
	v_fmac_f32_e32 v15, v9, v12
	v_max_f32_e32 v10, 0x358637bd, v10
	v_max_f32_e32 v11, 0x358637bd, v11
	v_max_f32_e32 v8, 0x358637bd, v8
	v_max_f32_e32 v9, 0x358637bd, v15
	v_log_f32_e32 v10, v10
	v_log_f32_e32 v11, v11
	v_log_f32_e32 v8, v8
	v_log_f32_e32 v9, v9
	v_cvt_pk_f16_f32 v16, v10, v11
	v_cvt_pk_f16_f32 v17, v8, v9
.LBB0_2072:
	v_lshl_add_u64 v[8:9], v[2:3], 1, s[20:21]
	global_store_dwordx2 v[8:9], v[16:17], off offset:48
	ds_read2st64_b32 v[156:157], v190 offset0:16 offset1:17
	ds_read2st64_b32 v[158:159], v190 offset0:18 offset1:19
	ds_read2st64_b32 v[150:151], v190 offset0:20 offset1:21
	ds_read2st64_b32 v[152:153], v190 offset0:22 offset1:23
	ds_read2st64_b32 v[164:165], v190 offset0:80 offset1:81
	ds_read2st64_b32 v[182:183], v190 offset0:82 offset1:83
	ds_read2st64_b32 v[176:177], v190 offset0:84 offset1:85
	ds_read2st64_b32 v[154:155], v190 offset0:86 offset1:87
	ds_read2st64_b32 v[184:185], v190 offset0:144 offset1:145
	ds_read2st64_b32 v[186:187], v190 offset0:146 offset1:147
	ds_read2st64_b32 v[178:179], v190 offset0:148 offset1:149
	ds_read2st64_b32 v[172:173], v190 offset0:150 offset1:151
	ds_read2st64_b32 v[188:189], v190 offset0:208 offset1:209
	ds_read2st64_b32 v[200:201], v190 offset0:210 offset1:211
	ds_read2st64_b32 v[180:181], v190 offset0:212 offset1:213
	ds_read2st64_b32 v[174:175], v190 offset0:214 offset1:215
	ds_read2st64_b32 v[24:25], v190 offset0:24 offset1:25
	ds_read2st64_b32 v[26:27], v190 offset0:26 offset1:27
	ds_read2st64_b32 v[8:9], v190 offset0:28 offset1:29
	ds_read2st64_b32 v[10:11], v190 offset0:30 offset1:31
	ds_read2st64_b32 v[34:35], v190 offset0:88 offset1:89
	ds_read2st64_b32 v[28:29], v190 offset0:90 offset1:91
	ds_read2st64_b32 v[18:19], v190 offset0:92 offset1:93
	ds_read2st64_b32 v[12:13], v190 offset0:94 offset1:95
	ds_read2st64_b32 v[146:147], v190 offset0:152 offset1:153
	ds_read2st64_b32 v[30:31], v190 offset0:154 offset1:155
	ds_read2st64_b32 v[20:21], v190 offset0:156 offset1:157
	ds_read2st64_b32 v[14:15], v190 offset0:158 offset1:159
	ds_read2st64_b32 v[148:149], v190 offset0:216 offset1:217
	ds_read2st64_b32 v[32:33], v190 offset0:218 offset1:219
	ds_read2st64_b32 v[22:23], v190 offset0:220 offset1:221
	ds_read2st64_b32 v[16:17], v190 offset0:222 offset1:223
	s_waitcnt lgkmcnt(0)
	v_pk_add_f32 v[156:157], v[156:157], v[164:165]
	s_mov_b64 s[36:37], -1
	v_pk_add_f32 v[156:157], v[156:157], v[184:185]
	s_mov_b64 s[2:3], 0
	s_nop 0
	v_pk_add_f32 v[156:157], v[156:157], v[188:189]
	s_cmp_lt_i32 s10, 3
	v_pk_mul_f32 v[184:185], v[4:5], v[156:157]
	v_pk_add_f32 v[156:157], v[158:159], v[182:183]
	s_mov_b64 s[20:21], 0
	v_pk_add_f32 v[156:157], v[156:157], v[186:187]
	s_nop 0
	v_pk_add_f32 v[156:157], v[156:157], v[200:201]
	s_nop 0
	v_pk_mul_f32 v[182:183], v[4:5], v[156:157]
	s_cbranch_scc1 .LBB0_2078
	s_cmp_eq_u32 s10, 3
	v_mov_b32_e32 v187, v183
	v_mov_b32_e32 v186, v182
	v_mov_b32_e32 v189, v185
	v_mov_b32_e32 v188, v184
	s_cbranch_scc0 .LBB0_2075
	v_mul_f32_e32 v156, 0xbfb8aa3b, v184
	v_mul_f32_e32 v157, 0xbfb8aa3b, v185
	v_mul_f32_e32 v158, 0xbfb8aa3b, v182
	v_mul_f32_e32 v159, 0xbfb8aa3b, v183
	v_exp_f32_e32 v156, v156
	v_exp_f32_e32 v157, v157
	v_exp_f32_e32 v158, v158
	v_exp_f32_e32 v159, v159
	v_add_f32_e32 v156, 1.0, v156
	v_add_f32_e32 v157, 1.0, v157
	v_add_f32_e32 v158, 1.0, v158
	v_add_f32_e32 v159, 1.0, v159
	v_rcp_f32_e32 v156, v156
	v_rcp_f32_e32 v157, v157
	v_rcp_f32_e32 v158, v158
	v_rcp_f32_e32 v159, v159
	v_pk_mul_f32 v[188:189], v[184:185], v[156:157]
	v_pk_mul_f32 v[186:187], v[182:183], v[158:159]

; __device__ __forceinline__ float sigmoidf_(float x) { return __builtin_amdgcn_rcpf(1.0f + fast_exp(-x)); }
; __device__ __forceinline__ u32x2 pack4(float a, float b, float c, float d) { u32x2 w; w.x = cvt_pk_bf16(a, b); w.y = cvt_pk_bf16(c, d); return w; }
;     __device__ __forceinline__ void operator()(const f32x16& acc, int u, int row, int hi, float rs) const {
;         const int seg = u >> 6;
; #pragma unroll
;         for (int q = 0; q < 4; ++q) { const int c = 32 * (u & 63) + 8 * q + 4 * hi; const size_t off = (size_t)(MP + row) * D + c;
;             f32x4 a = {acc[4 * q] * rs, acc[4 * q + 1] * rs, acc[4 * q + 2] * rs, acc[4 * q + 3] * rs};
;             if (seg == 1) { const f32x4 l = *(const f32x4*)(lb + c);
; #pragma unroll
;                 for (int j = 0; j < 4; ++j) a[j] = __builtin_amdgcn_logf(fmaxf(l[j] + (1.f - l[j]) * sigmoidf_(a[j]), 1e-6f));
;                 u32x2 lw_; lw_.x = pk_f16(a[0], a[1]); lw_.y = pk_f16(a[2], a[3]); *(u32x2*)((unsigned short*)LOGF + off) = lw_;
;             } else {
;                 if (seg == 3) {
; #pragma unroll
;                     for (int j = 0; j < 4; ++j) a[j] = a[j] * sigmoidf_(a[j]); }
;                 bf16* dst = (bf16*)((char*)Q + (size_t)(seg ? seg + 1 : 0) * (65 * MiB));
;                 *(u32x2*)(dst + off) = pack4(a[0], a[1], a[2], a[3]); } }
.LBB0_2081:
	global_load_dwordx4 v[186:189], v[6:7], off offset:128
	v_mul_f32_e32 v157, 0xbfb8aa3b, v184
	v_exp_f32_e32 v157, v157
	v_mul_f32_e32 v158, 0xbfb8aa3b, v185
	v_exp_f32_e32 v158, v158
	v_mul_f32_e32 v159, 0xbfb8aa3b, v182
	v_exp_f32_e32 v159, v159
	v_mul_f32_e32 v164, 0xbfb8aa3b, v183
	v_exp_f32_e32 v164, v164
	v_add_f32_e32 v157, 1.0, v157
	v_rcp_f32_e32 v157, v157
	v_add_f32_e32 v158, 1.0, v158
	v_rcp_f32_e32 v158, v158
	v_add_f32_e32 v159, 1.0, v159
	v_rcp_f32_e32 v159, v159
	v_add_f32_e32 v164, 1.0, v164
	v_rcp_f32_e32 v164, v164
	s_mov_b64 s[20:21], s[0:1]
	s_waitcnt vmcnt(0)
	v_sub_f32_e32 v156, 1.0, v186
	v_fma_f32 v156, v157, v156, v186
	v_sub_f32_e32 v157, 1.0, v187
	v_fma_f32 v157, v158, v157, v187
	v_sub_f32_e32 v158, 1.0, v188
	v_fma_f32 v158, v159, v158, v188
	v_sub_f32_e32 v159, 1.0, v189
	v_fmac_f32_e32 v189, v164, v159
	v_max_f32_e32 v156, 0x358637bd, v156
	v_max_f32_e32 v157, 0x358637bd, v157
	s_nop 0
	v_max_f32_e32 v158, 0x358637bd, v158
	v_max_f32_e32 v159, 0x358637bd, v189
	v_log_f32_e32 v156, v156
	v_log_f32_e32 v157, v157
	v_log_f32_e32 v158, v158
	v_log_f32_e32 v159, v159
	v_cvt_pk_f16_f32 v190, v156, v157
	v_cvt_pk_f16_f32 v191, v158, v159
.LBB0_2082:
	v_pk_add_f32 v[150:151], v[150:151], v[176:177]
	v_pk_add_f32 v[152:153], v[152:153], v[154:155]
	v_pk_add_f32 v[150:151], v[150:151], v[178:179]
	v_pk_add_f32 v[152:153], v[152:153], v[172:173]
	v_pk_add_f32 v[150:151], v[150:151], v[180:181]
	v_pk_add_f32 v[154:155], v[152:153], v[174:175]
	v_lshl_add_u64 v[156:157], v[2:3], 1, s[20:21]
	v_pk_mul_f32 v[152:153], v[4:5], v[150:151]
	v_pk_mul_f32 v[150:151], v[4:5], v[154:155]
	s_mov_b64 s[36:37], -1
	s_mov_b64 s[2:3], 0
	s_cmp_lt_i32 s10, 3
	s_mov_b64 s[20:21], 0
	global_store_dwordx2 v[156:157], v[190:191], off offset:64
	s_cbranch_scc1 .LBB0_2088
	s_cmp_eq_u32 s10, 3
	v_mov_b32_e32 v155, v151
	v_mov_b32_e32 v154, v150
	v_mov_b32_e32 v173, v153
	v_mov_b32_e32 v172, v152
	s_cbranch_scc0 .LBB0_2085
	v_mul_f32_e32 v154, 0xbfb8aa3b, v152
	v_mul_f32_e32 v155, 0xbfb8aa3b, v153
	s_nop 0
	v_mul_f32_e32 v156, 0xbfb8aa3b, v150
	v_mul_f32_e32 v157, 0xbfb8aa3b, v151
	v_exp_f32_e32 v154, v154
	v_exp_f32_e32 v155, v155
	v_exp_f32_e32 v156, v156
	v_exp_f32_e32 v157, v157
	v_add_f32_e32 v154, 1.0, v154
	v_add_f32_e32 v155, 1.0, v155
	v_add_f32_e32 v156, 1.0, v156
	v_add_f32_e32 v157, 1.0, v157
	v_rcp_f32_e32 v154, v154
	v_rcp_f32_e32 v155, v155
	v_rcp_f32_e32 v156, v156
	v_rcp_f32_e32 v157, v157
	v_pk_mul_f32 v[172:173], v[152:153], v[154:155]
	v_pk_mul_f32 v[154:155], v[150:151], v[156:157]

; __device__ __forceinline__ float sigmoidf_(float x) { return __builtin_amdgcn_rcpf(1.0f + fast_exp(-x)); }
;     __device__ __forceinline__ void operator()(const f32x16& acc, int u, int row, int hi, float rs) const {
;     ...
;         for (int q = 0; q < 4; ++q) { const int c = 32 * (u & 63) + 8 * q + 4 * hi; const size_t off = (size_t)(MP + row) * D + c;
;             f32x4 a = {acc[4 * q] * rs, acc[4 * q + 1] * rs, acc[4 * q + 2] * rs, acc[4 * q + 3] * rs};
;             if (seg == 1) { const f32x4 l = *(const f32x4*)(lb + c);
; #pragma unroll
;                 for (int j = 0; j < 4; ++j) a[j] = __builtin_amdgcn_logf(fmaxf(l[j] + (1.f - l[j]) * sigmoidf_(a[j]), 1e-6f));
;                 u32x2 lw_; lw_.x = pk_f16(a[0], a[1]); lw_.y = pk_f16(a[2], a[3]); *(u32x2*)((unsigned short*)LOGF + off) = lw_;
.LBB0_2091:
	global_load_dwordx4 v[172:175], v[6:7], off offset:160
	s_nop 0
	v_mul_f32_e32 v152, 0xbfb8aa3b, v152
	v_exp_f32_e32 v152, v152
	v_mul_f32_e32 v153, 0xbfb8aa3b, v153
	v_exp_f32_e32 v153, v153
	v_mul_f32_e32 v150, 0xbfb8aa3b, v150
	v_exp_f32_e32 v150, v150
	v_mul_f32_e32 v151, 0xbfb8aa3b, v151
	v_exp_f32_e32 v151, v151
	v_add_f32_e32 v152, 1.0, v152
	v_rcp_f32_e32 v152, v152
	v_add_f32_e32 v153, 1.0, v153
	v_rcp_f32_e32 v153, v153
	v_add_f32_e32 v150, 1.0, v150
	v_rcp_f32_e32 v150, v150
	v_add_f32_e32 v151, 1.0, v151
	v_rcp_f32_e32 v151, v151
	s_mov_b64 s[20:21], s[0:1]
	s_waitcnt vmcnt(0)
	v_sub_f32_e32 v154, 1.0, v172
	v_fma_f32 v152, v152, v154, v172
	v_sub_f32_e32 v154, 1.0, v173
	v_fma_f32 v153, v153, v154, v173
	v_sub_f32_e32 v154, 1.0, v174
	v_fma_f32 v150, v150, v154, v174
	v_sub_f32_e32 v154, 1.0, v175
	v_fmac_f32_e32 v175, v151, v154
	v_max_f32_e32 v152, 0x358637bd, v152
	v_max_f32_e32 v153, 0x358637bd, v153
	v_max_f32_e32 v150, 0x358637bd, v150
	v_max_f32_e32 v151, 0x358637bd, v175
	v_log_f32_e32 v152, v152
	v_log_f32_e32 v153, v153
	v_log_f32_e32 v150, v150
	v_log_f32_e32 v151, v151
	v_cvt_pk_f16_f32 v174, v152, v153
	s_nop 0
	v_cvt_pk_f16_f32 v175, v150, v151

; __device__ __forceinline__ float sigmoidf_(float x) { return __builtin_amdgcn_rcpf(1.0f + fast_exp(-x)); }
; __device__ __forceinline__ u32x2 pack4(float a, float b, float c, float d) { u32x2 w; w.x = cvt_pk_bf16(a, b); w.y = cvt_pk_bf16(c, d); return w; }
;     __device__ __forceinline__ void operator()(const f32x16& acc, int u, int row, int hi, float rs) const {
;     ...
;             } else {
;                 if (seg == 3) {
; #pragma unroll
;                     for (int j = 0; j < 4; ++j) a[j] = a[j] * sigmoidf_(a[j]); }
;                 bf16* dst = (bf16*)((char*)Q + (size_t)(seg ? seg + 1 : 0) * (65 * MiB));
;                 *(u32x2*)(dst + off) = pack4(a[0], a[1], a[2], a[3]); } }
.LBB0_2097:
	s_add_u32 s20, s65, s39
	s_addc_u32 s21, s66, s38
	s_nop 0
	v_cvt_pk_bf16_f32 v32, v30, v31
	v_cvt_pk_bf16_f32 v33, v28, v29
	s_cbranch_execz .LBB0_2101
	s_branch .LBB0_2102

; __device__ __forceinline__ float sigmoidf_(float x) { return __builtin_amdgcn_rcpf(1.0f + fast_exp(-x)); }
; __device__ __forceinline__ u32x2 pack4(float a, float b, float c, float d) { u32x2 w; w.x = cvt_pk_bf16(a, b); w.y = cvt_pk_bf16(c, d); return w; }
;     __device__ __forceinline__ void operator()(const f32x16& acc, int u, int row, int hi, float rs) const {
;         const int seg = u >> 6;
; #pragma unroll
;         for (int q = 0; q < 4; ++q) { const int c = 32 * (u & 63) + 8 * q + 4 * hi; const size_t off = (size_t)(MP + row) * D + c;
;             f32x4 a = {acc[4 * q] * rs, acc[4 * q + 1] * rs, acc[4 * q + 2] * rs, acc[4 * q + 3] * rs};
;             if (seg == 1) { const f32x4 l = *(const f32x4*)(lb + c);
; #pragma unroll
;                 for (int j = 0; j < 4; ++j) a[j] = __builtin_amdgcn_logf(fmaxf(l[j] + (1.f - l[j]) * sigmoidf_(a[j]), 1e-6f));
;                 u32x2 lw_; lw_.x = pk_f16(a[0], a[1]); lw_.y = pk_f16(a[2], a[3]); *(u32x2*)((unsigned short*)LOGF + off) = lw_;
;             } else {
;                 if (seg == 3) {
; #pragma unroll
;                     for (int j = 0; j < 4; ++j) a[j] = a[j] * sigmoidf_(a[j]); }
;                 bf16* dst = (bf16*)((char*)Q + (size_t)(seg ? seg + 1 : 0) * (65 * MiB));
;                 *(u32x2*)(dst + off) = pack4(a[0], a[1], a[2], a[3]); } }
.LBB0_2101:
	global_load_dwordx4 v[28:31], v[6:7], off offset:192
	v_mul_f32_e32 v26, 0xbfb8aa3b, v26
	v_exp_f32_e32 v26, v26
	v_mul_f32_e32 v27, 0xbfb8aa3b, v27
	v_exp_f32_e32 v27, v27
	v_mul_f32_e32 v24, 0xbfb8aa3b, v24
	v_exp_f32_e32 v24, v24
	v_mul_f32_e32 v25, 0xbfb8aa3b, v25
	v_exp_f32_e32 v25, v25
	v_add_f32_e32 v26, 1.0, v26
	v_rcp_f32_e32 v26, v26
	v_add_f32_e32 v27, 1.0, v27
	v_rcp_f32_e32 v27, v27
	v_add_f32_e32 v24, 1.0, v24
	v_rcp_f32_e32 v24, v24
	v_add_f32_e32 v25, 1.0, v25
	v_rcp_f32_e32 v25, v25
	s_mov_b64 s[20:21], s[0:1]
	s_waitcnt vmcnt(0)
	v_sub_f32_e32 v32, 1.0, v28
	v_fma_f32 v26, v26, v32, v28
	v_sub_f32_e32 v28, 1.0, v29
	s_nop 0
	v_fma_f32 v27, v27, v28, v29
	v_sub_f32_e32 v28, 1.0, v30
	v_fma_f32 v24, v24, v28, v30
	v_sub_f32_e32 v28, 1.0, v31
	v_fmac_f32_e32 v31, v25, v28
	v_max_f32_e32 v26, 0x358637bd, v26
	v_max_f32_e32 v27, 0x358637bd, v27
	v_max_f32_e32 v24, 0x358637bd, v24
	v_max_f32_e32 v25, 0x358637bd, v31
	v_log_f32_e32 v26, v26
	v_log_f32_e32 v27, v27
	v_log_f32_e32 v24, v24
	v_log_f32_e32 v25, v25
	v_cvt_pk_f16_f32 v32, v26, v27
	v_cvt_pk_f16_f32 v33, v24, v25
.LBB0_2102:
	v_pk_add_f32 v[8:9], v[8:9], v[18:19]
	v_pk_add_f32 v[10:11], v[10:11], v[12:13]
	v_pk_add_f32 v[8:9], v[8:9], v[20:21]
	v_pk_add_f32 v[10:11], v[10:11], v[14:15]
	s_nop 0
	v_pk_add_f32 v[8:9], v[8:9], v[22:23]
	v_pk_add_f32 v[10:11], v[10:11], v[16:17]
	v_lshl_add_u64 v[24:25], v[2:3], 1, s[20:21]
	v_pk_mul_f32 v[8:9], v[4:5], v[8:9]
	v_pk_mul_f32 v[4:5], v[4:5], v[10:11]
	s_mov_b64 s[36:37], -1
	s_mov_b64 s[2:3], 0
	s_cmp_lt_i32 s10, 3
	s_mov_b64 s[20:21], 0
	global_store_dwordx2 v[24:25], v[32:33], off offset:96
	s_cbranch_scc1 .LBB0_2108
	s_cmp_eq_u32 s10, 3
	v_mov_b32_e32 v11, v5
	v_mov_b32_e32 v10, v4
	v_mov_b32_e32 v13, v9
	v_mov_b32_e32 v12, v8
	s_cbranch_scc0 .LBB0_2105
	v_mul_f32_e32 v12, 0xbfb8aa3b, v4
	v_mul_f32_e32 v10, 0xbfb8aa3b, v8
	v_mul_f32_e32 v11, 0xbfb8aa3b, v9
	v_exp_f32_e32 v12, v12
	v_mul_f32_e32 v13, 0xbfb8aa3b, v5
	v_exp_f32_e32 v10, v10
	v_exp_f32_e32 v11, v11
	v_exp_f32_e32 v13, v13
	v_add_f32_e32 v12, 1.0, v12
	v_add_f32_e32 v10, 1.0, v10
	v_add_f32_e32 v11, 1.0, v11
	v_rcp_f32_e32 v14, v12
	v_add_f32_e32 v12, 1.0, v13
	v_rcp_f32_e32 v10, v10
	v_rcp_f32_e32 v11, v11
	v_rcp_f32_e32 v15, v12
	v_pk_mul_f32 v[12:13], v[8:9], v[10:11]
	v_pk_mul_f32 v[10:11], v[4:5], v[14:15]

; __device__ __forceinline__ float sigmoidf_(float x) { return __builtin_amdgcn_rcpf(1.0f + fast_exp(-x)); }
;     __device__ __forceinline__ void operator()(const f32x16& acc, int u, int row, int hi, float rs) const {
;     ...
;         for (int q = 0; q < 4; ++q) { const int c = 32 * (u & 63) + 8 * q + 4 * hi; const size_t off = (size_t)(MP + row) * D + c;
;             f32x4 a = {acc[4 * q] * rs, acc[4 * q + 1] * rs, acc[4 * q + 2] * rs, acc[4 * q + 3] * rs};
;             if (seg == 1) { const f32x4 l = *(const f32x4*)(lb + c);
; #pragma unroll
;                 for (int j = 0; j < 4; ++j) a[j] = __builtin_amdgcn_logf(fmaxf(l[j] + (1.f - l[j]) * sigmoidf_(a[j]), 1e-6f));
;                 u32x2 lw_; lw_.x = pk_f16(a[0], a[1]); lw_.y = pk_f16(a[2], a[3]); *(u32x2*)((unsigned short*)LOGF + off) = lw_;
.LBB0_2111:
	global_load_dwordx4 v[10:13], v[6:7], off offset:224
	v_mul_f32_e32 v7, 0xbfb8aa3b, v8
	v_exp_f32_e32 v7, v7
	v_mul_f32_e32 v8, 0xbfb8aa3b, v9
	v_exp_f32_e32 v8, v8
	v_mul_f32_e32 v4, 0xbfb8aa3b, v4
	v_exp_f32_e32 v4, v4
	v_mul_f32_e32 v5, 0xbfb8aa3b, v5
	v_exp_f32_e32 v5, v5
	v_add_f32_e32 v7, 1.0, v7
	v_rcp_f32_e32 v7, v7
	v_add_f32_e32 v8, 1.0, v8
	v_rcp_f32_e32 v8, v8
	v_add_f32_e32 v4, 1.0, v4
	v_rcp_f32_e32 v4, v4
	v_add_f32_e32 v5, 1.0, v5
	v_rcp_f32_e32 v5, v5
	s_mov_b64 s[20:21], s[0:1]
	s_waitcnt vmcnt(0)
	v_sub_f32_e32 v6, 1.0, v10
	v_fma_f32 v6, v7, v6, v10
	v_sub_f32_e32 v7, 1.0, v11
	v_fma_f32 v7, v8, v7, v11
	v_sub_f32_e32 v8, 1.0, v12
	v_fma_f32 v4, v4, v8, v12
	v_sub_f32_e32 v8, 1.0, v13
	v_fmac_f32_e32 v13, v5, v8
	v_max_f32_e32 v6, 0x358637bd, v6
	v_max_f32_e32 v7, 0x358637bd, v7
	s_nop 0
	v_max_f32_e32 v4, 0x358637bd, v4
	v_max_f32_e32 v5, 0x358637bd, v13
	v_log_f32_e32 v6, v6
	v_log_f32_e32 v7, v7
	v_log_f32_e32 v4, v4
	v_log_f32_e32 v5, v5
	v_cvt_pk_f16_f32 v14, v6, v7
	v_cvt_pk_f16_f32 v15, v4, v5
	s_branch .LBB0_2013

; #define LAS __attribute__((address_space(3)))
; __device__ __forceinline__ float h2f(unsigned short u) { return (float)__builtin_bit_cast(_Float16, u); }
; __device__ __forceinline__ int opaque_tid() { int t = threadIdx.x; asm volatile("" : "+v"(t)); return t; }
; __device__ __forceinline__ void hgrn_prep64(char* lds, int s, int w, int kc, int tq, float& gsum, bf16x8 (&vf)[2]) {
;     const int buf = s & 1; const char* raw = lds + buf * 49152; char* KDT = lds + 98304 + buf * 16384; float* DL = (float*)(lds + 131072 + buf * 512);
;     const int ch = 16 * w + kc;
;     float lf[2][8];
; #pragma unroll
;     for (int hf = 0; hf < 2; ++hf)
; #pragma unroll
;         for (int jj = 0; jj < 8; ++jj) { const int t = 32 * hf + 8 * tq + jj; lf[hf][jj] = h2f(*(const unsigned short*)(raw + (t * 128 + ch) * 2));
;             vf[hf][jj] = (short)*(const unsigned short*)(raw + 32768 + (t * 128 + ch) * 2); }
;     float c[2][8];
; #pragma unroll
;     for (int hf = 0; hf < 2; ++hf) { c[hf][0] = lf[hf][0];
; #pragma unroll
;         for (int jj = 1; jj < 8; ++jj) c[hf][jj] = c[hf][jj - 1] + lf[hf][jj]; }
;     const float R0 = c[0][7], R1 = c[1][7];
;     float P0, T0, p1_, t1_; row_prefix4(R0, tq, P0, T0); row_prefix4(R1, tq, p1_, t1_);
; __device__ __forceinline__ void hgrn_state_item64(const float* __restrict__ LOGF, const bf16* __restrict__ V, int row0, int nsteps, int h, bf16* __restrict__ Sout, float* __restrict__ Dout, char* lds) {
;     const int tid = opaque_tid(), w = __builtin_amdgcn_readfirstlane(tid >> 6), lane = tid & 63, kc = lane & 15, tq = lane >> 4;
;     f32x4 S[8];
; #pragma unroll
;     for (int kb = 0; kb < 8; ++kb) S[kb] = (f32x4){0.f, 0.f, 0.f, 0.f};
;     float gsum = 0.f;
;     const char* glf = (const char*)((const unsigned short*)LOGF + (size_t)(row0 + 8 * w + (lane >> 4)) * D + h * 128 + 8 * (lane & 15));
;     const char* gv = (const char*)(V + (size_t)(row0 + 8 * w + (lane >> 4)) * D + h * 128 + 8 * (lane & 15));
;     LAS char* ll = (LAS char*)lds;
;     ...
;     bf16x8 vf_cur[2], vf_nxt[2];
;     HG_DMA(0, 0); if (1 < nsteps) HG_DMA(1, 1);
;     asm volatile("s_waitcnt vmcnt(0)" ::: "memory"); __builtin_amdgcn_s_barrier(); asm volatile("" ::: "memory");
;     hgrn_prep64(lds, 0, w, kc, tq, gsum, vf_cur);
;     LDS_WAIT(); __builtin_amdgcn_s_barrier(); asm volatile("" ::: "memory");
.LBB0_2170:
	v_mov_b32_e32 v13, v0
	s_ashr_i32 s47, s46, 4
	s_lshl_b32 s4, s47, 10
	v_readfirstlane_b32 s5, v13
	s_ashr_i32 s6, s5, 6
	v_bfe_u32 v53, v13, 4, 2
	s_lshl_b32 s5, s6, 3
	v_or_b32_e32 v2, s4, v53
	v_add_u32_e32 v4, s5, v2
	v_ashrrev_i32_e32 v5, 31, v4
	s_and_b32 s19, s46, 15
	v_lshlrev_b64 v[4:5], 12, v[4:5]
	v_and_b32_e32 v56, 15, v13
	v_lshl_add_u64 v[6:7], s[12:13], 0, v[4:5]
	s_lshl_b32 s10, s19, 8
	v_lshl_add_u64 v[4:5], s[2:3], 0, v[4:5]
	s_lshl_b32 s7, s6, 11
	v_lshl_add_u64 v[6:7], v[6:7], 0, s[10:11]
	v_lshlrev_b32_e32 v2, 4, v56
	v_lshl_add_u64 v[4:5], v[4:5], 0, s[10:11]
	s_add_i32 s10, s7, 0
	v_lshl_add_u64 v[6:7], v[6:7], 0, v[2:3]
	s_mov_b32 m0, s10
	s_mov_b64 s[8:9], 0x4000
	global_load_lds_dwordx4 v[6:7], off
	v_lshl_add_u64 v[8:9], v[6:7], 0, s[8:9]
	s_add_i32 m0, s10, 0x400
	s_nop 0
	v_lshl_add_u64 v[4:5], v[4:5], 0, v[2:3]
	global_load_lds_dwordx4 v[8:9], off
	s_add_i32 m0, s10, 0x8000
	v_lshl_add_u64 v[8:9], v[4:5], 0, s[8:9]
	global_load_lds_dwordx4 v[4:5], off
	s_add_i32 m0, s10, 0x8400
	s_mov_b64 s[8:9], 0x44000
	global_load_lds_dwordx4 v[8:9], off
	s_add_i32 m0, s10, 0xc000
	v_lshl_add_u64 v[8:9], v[6:7], 0, s[60:61]
	global_load_lds_dwordx4 v[8:9], off
	v_lshl_add_u64 v[6:7], v[6:7], 0, s[8:9]
	s_add_i32 m0, s10, 0xc400
	s_lshl_b32 s18, s6, 4
	global_load_lds_dwordx4 v[6:7], off
	s_add_i32 m0, s10, 0x14000
	s_nop 0
	v_lshl_add_u64 v[6:7], v[4:5], 0, s[60:61]
	global_load_lds_dwordx4 v[6:7], off
	v_lshl_add_u64 v[4:5], v[4:5], 0, s[8:9]
	s_add_i32 m0, s10, 0x14400
	v_or_b32_e32 v52, s18, v56
	global_load_lds_dwordx4 v[4:5], off
	v_lshlrev_b32_e32 v4, 11, v53
	v_lshlrev_b32_e32 v5, 1, v52
	s_waitcnt vmcnt(0)
	s_barrier
	s_nop 0
	v_add3_u32 v57, v5, v4, 0
	ds_read_u16 v4, v57
	ds_read_u16 v5, v57 offset:256
	ds_read_u16 v6, v57 offset:512
	ds_read_u16 v7, v57 offset:768
	ds_read_u16 v8, v57 offset:1024
	ds_read_u16 v9, v57 offset:1280
	ds_read_u16 v10, v57 offset:1536
	ds_read_u16 v11, v57 offset:1792
	s_waitcnt lgkmcnt(0)
	v_cvt_f32_f16_e32 v46, v4
	v_cvt_f32_f16_e32 v48, v5
	v_cvt_f32_f16_e32 v45, v6
	v_cvt_f32_f16_e32 v40, v7
	v_cvt_f32_f16_e32 v30, v11
	ds_read_u16 v14, v57 offset:32768
	ds_read_u16 v15, v57 offset:33024
	ds_read_u16 v16, v57 offset:33280
	ds_read_u16 v17, v57 offset:33536
	ds_read_u16 v18, v57 offset:33792
	ds_read_u16 v19, v57 offset:34048
	ds_read_u16 v20, v57 offset:34304
	ds_read_u16 v21, v57 offset:34560
	ds_read_u16 v11, v57 offset:8192
	ds_read_u16 v12, v57 offset:8448
	ds_read_u16 v32, v57 offset:8704
	ds_read_u16 v34, v57 offset:8960
	ds_read_u16 v35, v57 offset:9216
	ds_read_u16 v36, v57 offset:9472
	ds_read_u16 v44, v57 offset:9728
	ds_read_u16 v47, v57 offset:9984
	ds_read_u16 v22, v57 offset:40960
	ds_read_u16 v23, v57 offset:41216
	ds_read_u16 v24, v57 offset:41472
	ds_read_u16 v25, v57 offset:41728
	ds_read_u16 v26, v57 offset:41984
	ds_read_u16 v27, v57 offset:42240
	ds_read_u16 v28, v57 offset:42496
	ds_read_u16 v29, v57 offset:42752
	v_cvt_f32_f16_e32 v38, v8
	v_cvt_f32_f16_e32 v6, v9
	v_add_f32_e32 v49, v46, v48
	v_cvt_f32_f16_e32 v4, v10
	v_add_f32_e32 v42, v49, v45
	v_add_f32_e32 v41, v42, v40
	v_add_f32_e32 v39, v41, v38
	v_add_f32_e32 v33, v39, v6
	v_add_f32_e32 v5, v33, v4
	v_add_f32_e32 v31, v5, v30
	v_mov_b32_e32 v9, v31
	v_mov_b32_e32 v7, v31
	s_nop 1
	v_permlane16_swap_b32_e32 v9, v7
	v_add_f32_e32 v8, v9, v7
	v_mov_b32_e32 v10, v8
	s_nop 1
	v_permlane32_swap_b32_e32 v8, v10
	v_cmp_lt_i32_e32 vcc, 0, v53
	v_mov_b32_e32 v7, 0
	s_and_saveexec_b64 s[20:21], vcc
	s_cbranch_execz .LBB0_2176
	v_cmp_ne_u32_e32 vcc, 1, v53
	s_and_saveexec_b64 s[6:7], vcc
	s_xor_b64 s[36:37], exec, s[6:7]
	v_add_f32_e32 v7, v9, v8
	v_cmp_eq_u32_e32 vcc, 2, v53
	s_nop 1
	v_cndmask_b32_e32 v7, v7, v8, vcc
	s_andn2_saveexec_b64 s[36:37], s[36:37]
	v_mov_b32_e32 v7, v9
	s_or_b64 exec, exec, s[36:37]

; #define LAS __attribute__((address_space(3)))
; __device__ __forceinline__ unsigned cvt_pk_bf16(float lo, float hi) { unsigned r; asm volatile("v_cvt_pk_bf16_f32 %0, %1, %2" : "=v"(r) : "v"(lo), "v"(hi)); return r; }
; #define LDS_WAIT() asm volatile("s_waitcnt lgkmcnt(0)" ::: "memory")
; __device__ __forceinline__ void hgrn_prep64(char* lds, int s, int w, int kc, int tq, float& gsum, bf16x8 (&vf)[2]) {
;     ...
;     float P0, T0, p1_, t1_; row_prefix4(R0, tq, P0, T0); row_prefix4(R1, tq, p1_, t1_);
;     const float P1 = T0 + p1_, glast = T0 + t1_;
; #pragma unroll
;     for (int hf = 0; hf < 2; ++hf) { const float P = hf ? P1 : P0; float kd[8];
; #pragma unroll
;         for (int jj = 0; jj < 8; ++jj) kd[jj] = (1.f - __builtin_amdgcn_exp2f(lf[hf][jj])) * __builtin_amdgcn_exp2f(glast - (P + c[hf][jj]));
;         u32x4 kw; kw.x = cvt_pk_bf16(kd[0], kd[1]); kw.y = cvt_pk_bf16(kd[2], kd[3]); kw.z = cvt_pk_bf16(kd[4], kd[5]); kw.w = cvt_pk_bf16(kd[6], kd[7]);
;         *(u32x4*)(KDT + ch * 128 + (((4 * hf + tq) ^ (ch & 7)) << 4)) = kw; }
;     DL[ch] = __builtin_amdgcn_exp2f(glast);
;     gsum += glast;
; __device__ __forceinline__ void hgrn_state_item64(const float* __restrict__ LOGF, const bf16* __restrict__ V, int row0, int nsteps, int h, bf16* __restrict__ Sout, float* __restrict__ Dout, char* lds) {
;     ...
;     f32x4 S[8];
; #pragma unroll
;     for (int kb = 0; kb < 8; ++kb) S[kb] = (f32x4){0.f, 0.f, 0.f, 0.f};
;     float gsum = 0.f;
;     const char* glf = (const char*)((const unsigned short*)LOGF + (size_t)(row0 + 8 * w + (lane >> 4)) * D + h * 128 + 8 * (lane & 15));
;     const char* gv = (const char*)(V + (size_t)(row0 + 8 * w + (lane >> 4)) * D + h * 128 + 8 * (lane & 15));
;     LAS char* ll = (LAS char*)lds;
;     ...
;     bf16x8 vf_cur[2], vf_nxt[2];
;     HG_DMA(0, 0); if (1 < nsteps) HG_DMA(1, 1);
;     asm volatile("s_waitcnt vmcnt(0)" ::: "memory"); __builtin_amdgcn_s_barrier(); asm volatile("" ::: "memory");
;     hgrn_prep64(lds, 0, w, kc, tq, gsum, vf_cur);
;     LDS_WAIT(); __builtin_amdgcn_s_barrier(); asm volatile("" ::: "memory");
; #pragma unroll 1
.LBB0_2182:
	s_or_b64 exec, exec, s[20:21]
	v_pk_add_f32 v[8:9], v[8:9], v[10:11]
	v_exp_f32_e32 v60, v6
	v_exp_f32_e32 v64, v4
	v_mov_b32_e32 v4, v8
	v_mov_b32_e32 v6, v9
	v_add_f32_e32 v10, v8, v59
	v_exp_f32_e32 v11, v46
	v_add_f32_e32 v46, v7, v46
	v_pk_add_f32 v[8:9], v[4:5], v[6:7]
	v_add_f32_e32 v6, v33, v7
	v_sub_f32_e32 v4, v8, v46
	v_exp_f32_e32 v4, v4
	v_add_f32_e32 v49, v49, v7
	v_add_f32_e32 v42, v42, v7
	v_add_f32_e32 v41, v41, v7
	v_add_f32_e32 v39, v39, v7
	v_sub_f32_e32 v6, v8, v6
	v_add_f32_e32 v7, v31, v7
	v_sub_f32_e32 v11, 1.0, v11
	v_exp_f32_e32 v6, v6
	v_sub_f32_e32 v9, v8, v9
	v_exp_f32_e32 v30, v30
	v_sub_f32_e32 v7, v8, v7
	v_exp_f32_e32 v48, v48
	v_exp_f32_e32 v45, v45
	v_exp_f32_e32 v40, v40
	v_exp_f32_e32 v38, v38
	v_mul_f32_e32 v4, v11, v4
	v_sub_f32_e32 v11, v8, v49
	v_sub_f32_e32 v42, v8, v42
	v_sub_f32_e32 v41, v8, v41
	v_sub_f32_e32 v39, v8, v39
	v_exp_f32_e32 v9, v9
	v_exp_f32_e32 v7, v7
	v_exp_f32_e32 v11, v11
	v_exp_f32_e32 v42, v42
	v_exp_f32_e32 v41, v41
	v_exp_f32_e32 v39, v39
	v_sub_f32_e32 v5, 1.0, v60
	v_sub_f32_e32 v33, 1.0, v64
	v_mul_f32_e32 v6, v5, v6
	v_sub_f32_e32 v5, 1.0, v30
	v_sub_f32_e32 v48, 1.0, v48
	v_sub_f32_e32 v45, 1.0, v45
	v_sub_f32_e32 v40, 1.0, v40
	v_sub_f32_e32 v38, 1.0, v38
	v_mul_f32_e32 v9, v33, v9
	v_mul_f32_e32 v7, v5, v7
	s_add_i32 s7, 0, 0x18000
	v_mul_f32_e32 v11, v48, v11
	v_mul_f32_e32 v42, v45, v42
	v_mul_f32_e32 v40, v40, v41
	v_mul_f32_e32 v38, v38, v39
	v_cvt_pk_bf16_f32 v4, v4, v11
	v_cvt_pk_bf16_f32 v5, v42, v40
	v_cvt_pk_bf16_f32 v6, v38, v6
	s_nop 0
	v_cvt_pk_bf16_f32 v7, v9, v7
	v_bitop3_b32 v9, v53, v13, 7 bitop3:0x78
	v_lshl_add_u32 v59, v52, 7, s7
	v_lshlrev_b32_e32 v60, 4, v9
	v_add_u32_e32 v9, v59, v60
	ds_write_b128 v9, v[4:7]
	v_add_f32_e32 v5, v10, v61
	v_exp_f32_e32 v4, v61
	v_sub_f32_e32 v5, v8, v5
	v_add_f32_e32 v7, v62, v10
	v_exp_f32_e32 v5, v5
	v_exp_f32_e32 v6, v58
	v_sub_f32_e32 v7, v8, v7
	v_exp_f32_e32 v7, v7
	v_sub_f32_e32 v4, 1.0, v4
	v_mul_f32_e32 v4, v4, v5
	v_sub_f32_e32 v5, 1.0, v6
	v_mul_f32_e32 v5, v5, v7
	v_add_f32_e32 v7, v55, v10
	v_exp_f32_e32 v6, v51
	v_sub_f32_e32 v7, v8, v7
	v_add_f32_e32 v11, v54, v10
	v_exp_f32_e32 v7, v7
	v_exp_f32_e32 v9, v50
	v_sub_f32_e32 v11, v8, v11
	v_exp_f32_e32 v11, v11
	v_sub_f32_e32 v6, 1.0, v6
	v_mul_f32_e32 v6, v6, v7
	v_sub_f32_e32 v7, 1.0, v9
	v_mul_f32_e32 v7, v7, v11
	v_add_f32_e32 v11, v47, v10
	v_exp_f32_e32 v9, v43
	v_sub_f32_e32 v11, v8, v11
	v_add_f32_e32 v30, v44, v10
	v_and_b32_e32 v63, 7, v13
	v_exp_f32_e32 v11, v11
	v_exp_f32_e32 v13, v37
	v_sub_f32_e32 v30, v8, v30
	v_exp_f32_e32 v30, v30
	v_sub_f32_e32 v9, 1.0, v9
	v_mul_f32_e32 v9, v9, v11
	v_sub_f32_e32 v11, 1.0, v13
	v_mul_f32_e32 v11, v11, v30
	v_add_f32_e32 v30, v36, v10
	v_exp_f32_e32 v13, v34
	v_sub_f32_e32 v30, v8, v30
	v_add_f32_e32 v10, v35, v10
	v_exp_f32_e32 v30, v30
	v_exp_f32_e32 v31, v32
	v_sub_f32_e32 v10, v8, v10
	v_exp_f32_e32 v10, v10
	v_sub_f32_e32 v13, 1.0, v13
	v_mul_f32_e32 v13, v13, v30
	v_sub_f32_e32 v30, 1.0, v31
	v_cvt_pk_bf16_f32 v4, v4, v5
	v_cvt_pk_bf16_f32 v5, v6, v7
	v_cvt_pk_bf16_f32 v6, v9, v11
	v_bitop3_b32 v9, v53, v63, 4 bitop3:0x36
	v_mul_f32_e32 v10, v30, v10
	v_lshlrev_b32_e32 v61, 4, v9
	v_cvt_pk_bf16_f32 v7, v13, v10
	v_add_u32_e32 v9, v59, v61
	v_exp_f32_e32 v10, v8
	s_add_i32 s4, s4, s5
	ds_write_b128 v9, v[4:7]
	v_add_u32_e32 v4, s4, v53
	s_and_b32 s6, s40, 15
	s_add_i32 s8, 0, 0x20000
	v_ashrrev_i32_e32 v5, 31, v4
	s_lshl_b32 s6, s6, 8
	v_lshl_add_u32 v62, v52, 2, s8
	v_lshlrev_b64 v[4:5], 12, v[4:5]
	ds_write_b32 v62, v10
	v_or3_b32 v4, v4, s6, v2
	v_add_f32_e32 v58, 0, v8
	s_waitcnt lgkmcnt(0)
	s_barrier
	v_lshl_add_u64 v[54:55], s[0:1], 0, v[4:5]
	v_mov_b32_e32 v4, v3
	v_mov_b32_e32 v5, v3
	v_mov_b32_e32 v6, v3
	v_mov_b32_e32 v7, v3
	v_mov_b32_e32 v8, v3
	v_mov_b32_e32 v9, v3
	v_mov_b32_e32 v2, v3
	v_mov_b64_e32 v[10:11], v[8:9]
	v_lshl_add_u32 v63, v53, 4, s8
	v_lshl_add_u32 v64, v56, 7, s7
	v_cmp_eq_u32_e32 vcc, 2, v53
	v_perm_b32 v44, v15, v14, s35
	v_perm_b32 v45, v17, v16, s35
	s_nop 0
	v_perm_b32 v46, v19, v18, s35
	v_perm_b32 v47, v21, v20, s35
	v_perm_b32 v48, v23, v22, s35
	v_perm_b32 v49, v25, v24, s35
	v_perm_b32 v50, v27, v26, s35
	v_perm_b32 v51, v29, v28, s35
	s_mov_b32 s4, 0
	s_mov_b64 s[20:21], 0
	v_mov_b64_e32 v[8:9], v[6:7]
	v_mov_b64_e32 v[6:7], v[4:5]
	v_mov_b64_e32 v[4:5], v[2:3]
	v_mov_b32_e32 v13, v12
	v_mov_b32_e32 v14, v12
	v_mov_b32_e32 v15, v12
	v_mov_b32_e32 v40, v12
	v_mov_b32_e32 v41, v12
	v_mov_b32_e32 v42, v12
	v_mov_b32_e32 v43, v12
	v_mov_b32_e32 v36, v12
	v_mov_b32_e32 v37, v12
	v_mov_b32_e32 v38, v12
	v_mov_b32_e32 v39, v12
	v_mov_b32_e32 v32, v12
	v_mov_b32_e32 v33, v12
	v_mov_b32_e32 v34, v12
	v_mov_b32_e32 v35, v12
	v_mov_b32_e32 v28, v12
	v_mov_b32_e32 v29, v12
	v_mov_b32_e32 v30, v12
	v_mov_b32_e32 v31, v12
	v_mov_b32_e32 v24, v12
	v_mov_b32_e32 v25, v12
	v_mov_b32_e32 v26, v12
	v_mov_b32_e32 v27, v12
	v_mov_b32_e32 v20, v12
	v_mov_b32_e32 v21, v12
	v_mov_b32_e32 v22, v12
	v_mov_b32_e32 v23, v12
	v_mov_b32_e32 v16, v12
	v_mov_b32_e32 v17, v12
	v_mov_b32_e32 v18, v12
	v_mov_b32_e32 v19, v12
	s_cmp_gt_u32 s4, 13
	s_cbranch_scc1 .LBB0_2185
	s_branch .LBB0_2184

; __device__ __forceinline__ float h2f(unsigned short u) { return (float)__builtin_bit_cast(_Float16, u); }
; __device__ __forceinline__ void hgrn_prep64(char* lds, int s, int w, int kc, int tq, float& gsum, bf16x8 (&vf)[2]) {
;     const int buf = s & 1; const char* raw = lds + buf * 49152; char* KDT = lds + 98304 + buf * 16384; float* DL = (float*)(lds + 131072 + buf * 512);
;     const int ch = 16 * w + kc;
;     float lf[2][8];
; #pragma unroll
;     for (int hf = 0; hf < 2; ++hf)
; #pragma unroll
;         for (int jj = 0; jj < 8; ++jj) { const int t = 32 * hf + 8 * tq + jj; lf[hf][jj] = h2f(*(const unsigned short*)(raw + (t * 128 + ch) * 2));
;             vf[hf][jj] = (short)*(const unsigned short*)(raw + 32768 + (t * 128 + ch) * 2); }
;     float c[2][8];
; #pragma unroll
;     for (int hf = 0; hf < 2; ++hf) { c[hf][0] = lf[hf][0];
; #pragma unroll
;         for (int jj = 1; jj < 8; ++jj) c[hf][jj] = c[hf][jj - 1] + lf[hf][jj]; }
;     const float R0 = c[0][7], R1 = c[1][7];
;     float P0, T0, p1_, t1_; row_prefix4(R0, tq, P0, T0); row_prefix4(R1, tq, p1_, t1_);
; __device__ __forceinline__ void hgrn_mma64(char* lds, int s, int kc, int tq, const bf16x8 (&vf)[2], f32x4 (&S)[8]) {
;     const int buf = s & 1; const char* KDT = lds + 98304 + buf * 16384; const float* DL = (const float*)(lds + 131072 + buf * 512);
; #pragma unroll
;     for (int kb = 0; kb < 8; ++kb) { const f32x4 dlv = *(const f32x4*)(DL + 16 * kb + 4 * tq); const int kr = 16 * kb + kc;
;         const bf16x8 k0 = *(const bf16x8*)(KDT + kr * 128 + ((tq ^ (kr & 7)) << 4)), k1 = *(const bf16x8*)(KDT + kr * 128 + (((4 + tq) ^ (kr & 7)) << 4));
;         f32x4 acc = S[kb] * dlv;
;         acc = __builtin_amdgcn_mfma_f32_16x16x32_bf16(k0, vf[0], acc, 0, 0, 0);
;         S[kb] = __builtin_amdgcn_mfma_f32_16x16x32_bf16(k1, vf[1], acc, 0, 0, 0); }
; }
.LBB0_2185:
	s_and_b32 s5, s4, 1
	v_lshl_add_u32 v65, s5, 14, v64
	v_add_u32_e32 v78, v65, v60
	ds_read_b128 v[70:73], v78
	v_lshl_add_u32 v2, s5, 9, v63
	ds_read_b128 v[66:69], v2
	v_add_u32_e32 v65, v65, v61
	ds_read_b128 v[74:77], v65
	s_add_i32 s4, s4, 1
	s_cmp_eq_u32 s20, 0x3c0000
	s_waitcnt lgkmcnt(0)
	v_pk_mul_f32 v[12:13], v[12:13], v[66:67]
	v_pk_mul_f32 v[14:15], v[14:15], v[68:69]
	s_nop 1
	v_mfma_f32_16x16x32_bf16 v[12:15], v[70:73], v[44:47], v[12:15]
	v_mfma_f32_16x16x32_bf16 v[12:15], v[74:77], v[48:51], v[12:15]
	ds_read_b128 v[66:69], v2 offset:64
	s_nop 0
	ds_read_b128 v[70:73], v78 offset:2048
	ds_read_b128 v[74:77], v65 offset:2048
	s_waitcnt lgkmcnt(0)
	v_pk_mul_f32 v[40:41], v[40:41], v[66:67]
	v_pk_mul_f32 v[42:43], v[42:43], v[68:69]
	s_nop 1
	v_mfma_f32_16x16x32_bf16 v[40:43], v[70:73], v[44:47], v[40:43]
	v_mfma_f32_16x16x32_bf16 v[40:43], v[74:77], v[48:51], v[40:43]
	ds_read_b128 v[66:69], v2 offset:128
	ds_read_b128 v[70:73], v78 offset:4096
	ds_read_b128 v[74:77], v65 offset:4096
	s_waitcnt lgkmcnt(0)
	v_pk_mul_f32 v[36:37], v[36:37], v[66:67]
	v_pk_mul_f32 v[38:39], v[38:39], v[68:69]
	s_nop 1
	v_mfma_f32_16x16x32_bf16 v[36:39], v[70:73], v[44:47], v[36:39]
	v_mfma_f32_16x16x32_bf16 v[36:39], v[74:77], v[48:51], v[36:39]
	ds_read_b128 v[66:69], v2 offset:192
	ds_read_b128 v[70:73], v78 offset:6144
	ds_read_b128 v[74:77], v65 offset:6144
	s_waitcnt lgkmcnt(0)
	v_pk_mul_f32 v[32:33], v[32:33], v[66:67]
	v_pk_mul_f32 v[34:35], v[34:35], v[68:69]
	s_nop 1
	v_mfma_f32_16x16x32_bf16 v[32:35], v[70:73], v[44:47], v[32:35]
	v_mfma_f32_16x16x32_bf16 v[32:35], v[74:77], v[48:51], v[32:35]
	ds_read_b128 v[66:69], v2 offset:256
	ds_read_b128 v[70:73], v78 offset:8192
	ds_read_b128 v[74:77], v65 offset:8192
	s_waitcnt lgkmcnt(0)
	v_pk_mul_f32 v[28:29], v[28:29], v[66:67]
	v_pk_mul_f32 v[30:31], v[30:31], v[68:69]
	s_nop 1
	v_mfma_f32_16x16x32_bf16 v[28:31], v[70:73], v[44:47], v[28:31]
	v_mfma_f32_16x16x32_bf16 v[28:31], v[74:77], v[48:51], v[28:31]
	ds_read_b128 v[66:69], v2 offset:320
	ds_read_b128 v[70:73], v78 offset:10240
	ds_read_b128 v[74:77], v65 offset:10240
	s_waitcnt lgkmcnt(0)
	v_pk_mul_f32 v[24:25], v[24:25], v[66:67]
	v_pk_mul_f32 v[26:27], v[26:27], v[68:69]
	s_nop 1
	v_mfma_f32_16x16x32_bf16 v[24:27], v[70:73], v[44:47], v[24:27]
	v_mfma_f32_16x16x32_bf16 v[24:27], v[74:77], v[48:51], v[24:27]
	ds_read_b128 v[66:69], v2 offset:384
	ds_read_b128 v[70:73], v78 offset:12288
	ds_read_b128 v[74:77], v65 offset:12288
	s_waitcnt lgkmcnt(0)
	v_pk_mul_f32 v[20:21], v[20:21], v[66:67]
	v_pk_mul_f32 v[22:23], v[22:23], v[68:69]
	s_nop 1
	v_mfma_f32_16x16x32_bf16 v[20:23], v[70:73], v[44:47], v[20:23]
	v_mfma_f32_16x16x32_bf16 v[20:23], v[74:77], v[48:51], v[20:23]
	ds_read_b128 v[66:69], v2 offset:448
	ds_read_b128 v[70:73], v78 offset:14336
	ds_read_b128 v[74:77], v65 offset:14336
	s_waitcnt lgkmcnt(0)
	v_pk_mul_f32 v[16:17], v[16:17], v[66:67]
	v_pk_mul_f32 v[18:19], v[18:19], v[68:69]
	s_nop 1
	v_mfma_f32_16x16x32_bf16 v[16:19], v[70:73], v[44:47], v[16:19]
	v_mfma_f32_16x16x32_bf16 v[16:19], v[74:77], v[48:51], v[16:19]
	s_cbranch_scc1 .LBB0_2199
	s_and_b32 s5, s4, 1
	s_mul_i32 s6, s5, 0xc000
	v_add_u32_e32 v47, s6, v57
	ds_read_u16 v2, v47
	ds_read_u16 v4, v47 offset:256
	ds_read_u16 v5, v47 offset:512
	ds_read_u16 v6, v47 offset:768
	ds_read_u16 v7, v47 offset:1024
	ds_read_u16 v8, v47 offset:1280
	s_nop 0
	ds_read_u16 v9, v47 offset:1536
	ds_read_u16 v10, v47 offset:1792
	s_waitcnt lgkmcnt(0)
	v_cvt_f32_f16_e32 v80, v2
	v_cvt_f32_f16_e32 v82, v4
	v_cvt_f32_f16_e32 v79, v5
	v_cvt_f32_f16_e32 v74, v6
	v_cvt_f32_f16_e32 v71, v7
	v_cvt_f32_f16_e32 v46, v8
	v_add_f32_e32 v83, v80, v82
	v_cvt_f32_f16_e32 v44, v9
	v_add_f32_e32 v76, v83, v79
	v_cvt_f32_f16_e32 v2, v10
	v_add_f32_e32 v75, v76, v74
	v_add_f32_e32 v73, v75, v71
	v_add_f32_e32 v67, v73, v46
	v_add_f32_e32 v45, v67, v44
	v_add_f32_e32 v65, v45, v2
	v_mov_b32_e32 v49, v65
	v_mov_b32_e32 v4, v65
	s_nop 1
	v_permlane16_swap_b32_e32 v49, v4
	v_add_f32_e32 v48, v49, v4
	ds_read_u16 v4, v47 offset:32768
	ds_read_u16 v91, v47 offset:33024
	ds_read_u16 v5, v47 offset:33280
	s_nop 0
	ds_read_u16 v92, v47 offset:33536
	ds_read_u16 v6, v47 offset:33792
	ds_read_u16 v93, v47 offset:34048
	ds_read_u16 v7, v47 offset:34304
	ds_read_u16 v94, v47 offset:34560
	ds_read_u16 v51, v47 offset:8192
	ds_read_u16 v66, v47 offset:8448
	ds_read_u16 v68, v47 offset:8704
	ds_read_u16 v69, v47 offset:8960
	ds_read_u16 v70, v47 offset:9216
	ds_read_u16 v72, v47 offset:9472
	ds_read_u16 v78, v47 offset:9728
	ds_read_u16 v81, v47 offset:9984
	ds_read_u16 v8, v47 offset:40960
	ds_read_u16 v95, v47 offset:41216
	ds_read_u16 v9, v47 offset:41472
	ds_read_u16 v96, v47 offset:41728
	ds_read_u16 v10, v47 offset:41984
	ds_read_u16 v97, v47 offset:42240
	ds_read_u16 v11, v47 offset:42496
	ds_read_u16 v98, v47 offset:42752
	v_mov_b32_e32 v50, v48
	s_nop 1
	v_permlane32_swap_b32_e32 v48, v50
	v_cmp_lt_i32_e64 s[38:39], 0, v53
	v_mov_b32_e32 v47, 0
	s_and_saveexec_b64 s[36:37], s[38:39]
	s_cbranch_execz .LBB0_2192
	v_cmp_ne_u32_e64 s[38:39], 1, v53
	s_and_saveexec_b64 s[6:7], s[38:39]
	s_xor_b64 s[38:39], exec, s[6:7]
	v_add_f32_e32 v47, v49, v48
	v_cndmask_b32_e32 v47, v47, v48, vcc
	s_andn2_saveexec_b64 s[38:39], s[38:39]
	v_mov_b32_e32 v47, v49
	s_or_b64 exec, exec, s[38:39]

; __device__ __forceinline__ unsigned cvt_pk_bf16(float lo, float hi) { unsigned r; asm volatile("v_cvt_pk_bf16_f32 %0, %1, %2" : "=v"(r) : "v"(lo), "v"(hi)); return r; }
; __device__ __forceinline__ void hgrn_state_item64(const float* __restrict__ LOGF, const bf16* __restrict__ V, int row0, int nsteps, int h, bf16* __restrict__ Sout, float* __restrict__ Dout, char* lds) {
;     ...
;         asm volatile("s_waitcnt vmcnt(0) lgkmcnt(0)" ::: "memory"); __builtin_amdgcn_s_barrier(); asm volatile("" ::: "memory");
;         vf_cur[0] = vf_nxt[0]; vf_cur[1] = vf_nxt[1];
;     }
;     ...
; #pragma unroll
;     for (int kb = 0; kb < 8; ++kb)
; #pragma unroll
;         for (int i = 0; i < 4; ++i) Sout[(size_t)(16 * kb + 4 * tq + i) * 128 + 16 * w + kc] = (bf16)(cvt_pk_bf16(S[kb][i], 0.f) & 0xffffu);
;     if (tq == 0) Dout[16 * w + kc] = __builtin_amdgcn_exp2f(gsum);
.LBB0_2199:
	s_waitcnt vmcnt(0) lgkmcnt(0)
	s_barrier
	s_add_u32 s20, s20, 0x40000
	s_addc_u32 s21, s21, 0
	s_cmp_eq_u32 s20, 0x400000
	s_cbranch_scc0 .LBB0_2183
	s_lshl_b32 s4, s19, 4
	s_add_i32 s20, s4, s47
	s_ashr_i32 s21, s20, 31
	s_lshl_b64 s[4:5], s[20:21], 15
	s_add_u32 s6, s42, s4
	s_addc_u32 s7, s43, s5
	s_ashr_i32 s19, s18, 31
	s_lshl_b64 s[4:5], s[18:19], 1
	s_add_u32 s4, s6, s4
	s_addc_u32 s5, s7, s5
	v_lshlrev_b32_e32 v2, 1, v56
	v_lshl_add_u64 v[4:5], s[4:5], 0, v[2:3]
	v_lshlrev_b32_e32 v2, 10, v53
	v_cvt_pk_bf16_f32 v6, v12, v3
	s_nop 0
	v_lshl_add_u64 v[4:5], v[4:5], 0, v[2:3]
	global_store_short v[4:5], v6, off
	v_cvt_pk_bf16_f32 v2, v13, v3
	v_add_co_u32_e32 v6, vcc, s97, v4
	global_store_short v[4:5], v2, off offset:256
	v_cvt_pk_bf16_f32 v2, v14, v3
	s_nop 0
	v_addc_co_u32_e32 v7, vcc, 0, v5, vcc
	global_store_short v[4:5], v2, off offset:512
	s_nop 0
	v_cvt_pk_bf16_f32 v2, v15, v3
	v_add_co_u32_e32 v8, vcc, s75, v4
	global_store_short v[4:5], v2, off offset:768
	v_cvt_pk_bf16_f32 v2, v40, v3
	s_nop 0
	v_addc_co_u32_e32 v9, vcc, 0, v5, vcc
	global_store_short v[8:9], v2, off offset:-4096
	v_cvt_pk_bf16_f32 v2, v41, v3
	global_store_short v[6:7], v2, off offset:256
	s_nop 0
	v_cvt_pk_bf16_f32 v2, v42, v3
	global_store_short v[6:7], v2, off offset:512
	v_cvt_pk_bf16_f32 v2, v43, v3
	global_store_short v[6:7], v2, off offset:768
	v_cvt_pk_bf16_f32 v2, v36, v3
	s_movk_i32 s4, 0x3000
	global_store_short v[8:9], v2, off
	v_cvt_pk_bf16_f32 v2, v37, v3
	v_add_co_u32_e32 v6, vcc, s4, v4
	global_store_short v[8:9], v2, off offset:256
	v_cvt_pk_bf16_f32 v2, v38, v3
	s_nop 0
	v_addc_co_u32_e32 v7, vcc, 0, v5, vcc
	s_movk_i32 s4, 0x4000
	global_store_short v[8:9], v2, off offset:512
	v_cvt_pk_bf16_f32 v2, v39, v3
	global_store_short v[8:9], v2, off offset:768
	v_add_co_u32_e32 v8, vcc, s4, v4
	v_cvt_pk_bf16_f32 v2, v32, v3
	s_movk_i32 s4, 0x5000
	s_nop 0
	v_addc_co_u32_e32 v9, vcc, 0, v5, vcc
	global_store_short v[8:9], v2, off offset:-4096
	v_cvt_pk_bf16_f32 v2, v33, v3
	global_store_short v[6:7], v2, off offset:256
	v_cvt_pk_bf16_f32 v2, v34, v3
	global_store_short v[6:7], v2, off offset:512
	v_cvt_pk_bf16_f32 v2, v35, v3
	s_nop 0
	global_store_short v[6:7], v2, off offset:768
	v_cvt_pk_bf16_f32 v2, v28, v3
	global_store_short v[8:9], v2, off
	v_cvt_pk_bf16_f32 v2, v29, v3
	v_add_co_u32_e32 v6, vcc, s4, v4
	global_store_short v[8:9], v2, off offset:256
	v_cvt_pk_bf16_f32 v2, v30, v3
	s_nop 0
	v_addc_co_u32_e32 v7, vcc, 0, v5, vcc
	s_movk_i32 s4, 0x6000
	global_store_short v[8:9], v2, off offset:512
	v_cvt_pk_bf16_f32 v2, v31, v3
	global_store_short v[8:9], v2, off offset:768
	v_add_co_u32_e32 v8, vcc, s4, v4
	v_cvt_pk_bf16_f32 v2, v24, v3
	s_nop 1
	v_addc_co_u32_e32 v9, vcc, 0, v5, vcc
	global_store_short v[8:9], v2, off offset:-4096
	v_cvt_pk_bf16_f32 v2, v25, v3
	s_nop 0
	global_store_short v[6:7], v2, off offset:256
	v_cvt_pk_bf16_f32 v2, v26, v3
	global_store_short v[6:7], v2, off offset:512
	v_cvt_pk_bf16_f32 v2, v27, v3
	global_store_short v[6:7], v2, off offset:768
	v_cvt_pk_bf16_f32 v2, v20, v3
	global_store_short v[8:9], v2, off
	v_cvt_pk_bf16_f32 v2, v21, v3
	global_store_short v[8:9], v2, off offset:256
	v_cvt_pk_bf16_f32 v2, v22, v3
	global_store_short v[8:9], v2, off offset:512
	v_cvt_pk_bf16_f32 v2, v23, v3
	v_add_co_u32_e32 v4, vcc, 0x7000, v4
	global_store_short v[8:9], v2, off offset:768
	v_cvt_pk_bf16_f32 v2, v16, v3
	s_nop 0
	v_addc_co_u32_e32 v5, vcc, 0, v5, vcc
	global_store_short v[4:5], v2, off
	v_cvt_pk_bf16_f32 v2, v17, v3
	global_store_short v[4:5], v2, off offset:256
	v_cvt_pk_bf16_f32 v2, v18, v3
	v_cmp_eq_u32_e32 vcc, 0, v53
	global_store_short v[4:5], v2, off offset:512
	v_cvt_pk_bf16_f32 v2, v19, v3
	global_store_short v[4:5], v2, off offset:768
	s_and_saveexec_b64 s[18:19], vcc
	s_cbranch_execz .LBB0_2169
	s_lshl_b64 s[4:5], s[20:21], 9
	v_exp_f32_e32 v2, v58
	s_add_u32 s4, s44, s4
	s_addc_u32 s5, s45, s5
	v_ashrrev_i32_e32 v53, 31, v52
	v_lshl_add_u64 v[4:5], v[52:53], 2, s[4:5]
	global_store_dword v[4:5], v2, off
	s_branch .LBB0_2169

; __device__ __forceinline__ unsigned cvt_pk_bf16(float lo, float hi) { unsigned r; asm volatile("v_cvt_pk_bf16_f32 %0, %1, %2" : "=v"(r) : "v"(lo), "v"(hi)); return r; }
; #define LDS_WAIT() asm volatile("s_waitcnt lgkmcnt(0)" ::: "memory")
; __device__ __forceinline__ void hgrn_fin(char* lds, int s, int w, int kc, int tq, int ch, int row0, float gn, const f32x4 o, const u32x2 gvp, bf16* __restrict__ O) {
;     const float* SSQP = (const float*)(lds + SSQP_OFF + (s & 1) * 512);
; #pragma unroll
;     for (int i = 0; i < 4; ++i) { const float part = SSQP[(4 * tq + i) * 8 + (kc & 7)];
;         const float tot = row16_sum(kc < 8 ? part : 0.f);
;         const float rs = __builtin_amdgcn_rsqf(tot * (1.f / 128.f) + EPS);
;         const unsigned gw_ = i < 2 ? gvp.x : gvp.y; const float gate = __uint_as_float((i & 1) ? (gw_ & 0xffff0000u) : (gw_ << 16));
;         const float ov = o[i] * rs * gn * gate;
;         O[(size_t)(row0 + 16 * s + 4 * tq + i) * D + ch] = (bf16)(cvt_pk_bf16(ov, 0.f) & 0xffffu); }
; }
; template <bool FULL, bool SBF> ...
;     ...
;     if (FULL) hgrn_fin(lds, nsteps - 1, w, kc, tq, ch, row0, gn, o_prev, gv_prev, O);
;     if (Sout) {
; #pragma unroll
;         for (int kb = 0; kb < 8; ++kb)
; #pragma unroll
;             for (int i = 0; i < 4; ++i) { const size_t so = (size_t)(16 * kb + 4 * tq + i) * 128 + 16 * w + kc; if (SBF) ((bf16*)Sout)[so] = (bf16)(cvt_pk_bf16(S[kb][i], 0.f) & 0xffffu); else ((float*)Sout)[so] = S[kb][i]; } }
;     if (!FULL && Dout && tq == 0) Dout[16 * w + kc] = __builtin_amdgcn_exp2f(gsum);
;     LDS_WAIT(); __builtin_amdgcn_s_barrier(); asm volatile("" ::: "memory");
.LBB0_2320:
	s_waitcnt vmcnt(0)
	ds_read_b32 v5, v103 offset:27136
	v_or_b32_e32 v2, s85, v104
	v_lshlrev_b32_e32 v6, 16, v64
	v_or_b32_e32 v4, 0x3f0, v2
	s_add_i32 s84, s84, s64
	s_waitcnt lgkmcnt(0)
	v_cndmask_b32_e64 v5, 0, v5, s[40:41]
	s_add_i32 s83, s83, s64
	s_cmpk_gt_i32 s84, 0xff
	v_add_f32_dpp v5, v5, v5 row_ror:8 row_mask:0xf bank_mask:0xf bound_ctrl:1
	s_nop 1
	v_add_f32_dpp v5, v5, v5 row_ror:4 row_mask:0xf bank_mask:0xf bound_ctrl:1
	s_nop 1
	v_add_f32_dpp v5, v5, v5 row_ror:2 row_mask:0xf bank_mask:0xf bound_ctrl:1
	s_nop 1
	v_add_f32_dpp v5, v5, v5 row_ror:1 row_mask:0xf bank_mask:0xf bound_ctrl:1
	v_fmamk_f32 v5, v5, 0x3c000000, v198
	v_rsq_f32_e32 v5, v5
	s_nop 0
	v_mul_f32_e32 v5, v60, v5
	v_mul_f32_e32 v5, v98, v5
	v_mul_f32_e32 v5, v5, v6
	v_cvt_pk_bf16_f32 v6, v5, v3
	v_ashrrev_i32_e32 v5, 31, v4
	v_lshlrev_b64 v[4:5], 12, v[4:5]
	v_lshl_add_u64 v[4:5], v[72:73], 0, v[4:5]
	global_store_short v[4:5], v6, off
	ds_read_b32 v4, v103 offset:27168
	v_and_b32_e32 v5, 0xffff0000, v64
	s_waitcnt lgkmcnt(0)
	v_cndmask_b32_e64 v4, 0, v4, s[40:41]
	s_nop 1
	v_add_f32_dpp v4, v4, v4 row_ror:8 row_mask:0xf bank_mask:0xf bound_ctrl:1
	s_nop 1
	v_add_f32_dpp v4, v4, v4 row_ror:4 row_mask:0xf bank_mask:0xf bound_ctrl:1
	s_nop 1
	v_add_f32_dpp v4, v4, v4 row_ror:2 row_mask:0xf bank_mask:0xf bound_ctrl:1
	s_nop 1
	v_add_f32_dpp v4, v4, v4 row_ror:1 row_mask:0xf bank_mask:0xf bound_ctrl:1
	v_fmamk_f32 v4, v4, 0x3c000000, v198
	v_rsq_f32_e32 v4, v4
	s_nop 0
	v_mul_f32_e32 v4, v61, v4
	v_mul_f32_e32 v4, v98, v4
	v_mul_f32_e32 v4, v4, v5
	v_cvt_pk_bf16_f32 v6, v4, v3
	v_or_b32_e32 v4, 0x3f1, v2
	v_ashrrev_i32_e32 v5, 31, v4
	s_nop 0
	v_lshlrev_b64 v[4:5], 12, v[4:5]
	v_lshl_add_u64 v[4:5], v[72:73], 0, v[4:5]
	global_store_short v[4:5], v6, off
	ds_read_b32 v4, v103 offset:27200
	v_lshlrev_b32_e32 v5, 16, v65
	s_waitcnt lgkmcnt(0)
	v_cndmask_b32_e64 v4, 0, v4, s[40:41]
	s_nop 1
	v_add_f32_dpp v4, v4, v4 row_ror:8 row_mask:0xf bank_mask:0xf bound_ctrl:1
	s_nop 1
	v_add_f32_dpp v4, v4, v4 row_ror:4 row_mask:0xf bank_mask:0xf bound_ctrl:1
	s_nop 1
	v_add_f32_dpp v4, v4, v4 row_ror:2 row_mask:0xf bank_mask:0xf bound_ctrl:1
	s_nop 1
	v_add_f32_dpp v4, v4, v4 row_ror:1 row_mask:0xf bank_mask:0xf bound_ctrl:1
	v_fmamk_f32 v4, v4, 0x3c000000, v198
	v_rsq_f32_e32 v4, v4
	s_nop 0
	v_mul_f32_e32 v4, v62, v4
	v_mul_f32_e32 v4, v98, v4
	v_mul_f32_e32 v4, v4, v5
	s_nop 0
	v_cvt_pk_bf16_f32 v6, v4, v3
	v_or_b32_e32 v4, 0x3f2, v2
	v_ashrrev_i32_e32 v5, 31, v4
	v_lshlrev_b64 v[4:5], 12, v[4:5]
	v_lshl_add_u64 v[4:5], v[72:73], 0, v[4:5]
	global_store_short v[4:5], v6, off
	ds_read_b32 v4, v103 offset:27232
	v_and_b32_e32 v5, 0xffff0000, v65
	s_waitcnt lgkmcnt(0)
	v_cndmask_b32_e64 v4, 0, v4, s[40:41]
	s_nop 1
	v_add_f32_dpp v4, v4, v4 row_ror:8 row_mask:0xf bank_mask:0xf bound_ctrl:1
	s_nop 1
	v_add_f32_dpp v4, v4, v4 row_ror:4 row_mask:0xf bank_mask:0xf bound_ctrl:1
	s_nop 1
	v_add_f32_dpp v4, v4, v4 row_ror:2 row_mask:0xf bank_mask:0xf bound_ctrl:1
	s_nop 1
	v_add_f32_dpp v4, v4, v4 row_ror:1 row_mask:0xf bank_mask:0xf bound_ctrl:1
	v_fmamk_f32 v4, v4, 0x3c000000, v198
	v_rsq_f32_e32 v4, v4
	s_nop 0
	v_mul_f32_e32 v4, v63, v4
	v_mul_f32_e32 v4, v98, v4
	v_mul_f32_e32 v4, v4, v5
	v_cvt_pk_bf16_f32 v6, v4, v3
	v_or_b32_e32 v4, 0x3f3, v2
	v_ashrrev_i32_e32 v5, 31, v4
	v_lshlrev_b64 v[4:5], 12, v[4:5]
	v_lshl_add_u64 v[4:5], v[72:73], 0, v[4:5]
	global_store_short v[4:5], v6, off
	s_waitcnt lgkmcnt(0)
	s_barrier
	s_cbranch_scc1 .LBB0_2399
; __device__ __forceinline__ float bf2f(unsigned short b) { return __uint_as_float(((unsigned)b) << 16); }
; __device__ __forceinline__ int opaque_tid() { int t = threadIdx.x; asm volatile("" : "+v"(t)); return t; }
; #define HG_LOAD(j, s_) do { rl[j] = *(const u32x2*)(plf + (size_t)(s_) * 16 * D); if (FULL || !lo4) rb0[j] = *(const bf16x8*)(pb0 + (size_t)(s_) * 16 * D); if (FULL && lo4) rb1[j] = *(const bf16x8*)(pb1 + (size_t)(s_) * 16 * D); } while (0)
; #define HG_WRITE(j, slot) do { char* rb = lds + RAW_OFF + (slot) * RAW_SLOT; *(u32x2*)(rb + tid * 8) = rl[j]; \
;         if (lo4) { if (FULL) { *(bf16x8*)(rb + 8192 + t2 * 16) = rb0[j]; *(bf16x8*)(rb + 16384 + t2 * 16) = rb1[j]; } } else *(bf16x8*)(rb + 12288 + t2 * 16) = rb0[j]; } while (0)
; template <bool FULL, bool SBF> ...
;     const int tid = opaque_tid(), w = __builtin_amdgcn_readfirstlane(tid >> 6), lane = tid & 63, kc = lane & 15, tq = lane >> 4;
;     const int ch = h * 128 + 16 * w + kc;
;     const int kpos = 32 * (w >> 1) + 8 * (kc >> 2) + 4 * (w & 1) + (kc & 3);
;     f32x4 S[8];
; #pragma unroll
;     for (int kb = 0; kb < 8; ++kb)
; #pragma unroll
;         for (int i = 0; i < 4; ++i) { const size_t so = (size_t)(16 * kb + 4 * tq + i) * 128 + 16 * w + kc; S[kb][i] = Sin ? (SBF ? bf2f(((const bf16*)Sin)[so]) : ((const float*)Sin)[so]) : 0.f; }
;     float gsum = 0.f;
;     const int t2 = tid & 255; const bool lo4 = tid < 256;
;     const unsigned short* plf = (const unsigned short*)LOGF + (size_t)(row0 + (tid >> 5)) * D + h * 128 + 4 * (tid & 31);
;     const size_t boff = (size_t)(row0 + (t2 >> 4)) * D + h * 128 + 8 * (t2 & 15);
;     const bf16* pb0 = (lo4 ? Q : V) + boff; const bf16* pb1 = GS + boff;
;     u32x2 rl[3]; bf16x8 rb0[3], rb1[3];
;     ...
;     const float gn = FULL ? gain[16 * w + kc] : 0.f;
;     s16x4 vf_cur, vf_nxt; u32x2 gv_cur = {0u, 0u}, gv_nxt = {0u, 0u}, gv_prev = {0u, 0u}; f32x4 o_prev = {0.f, 0.f, 0.f, 0.f};
;     HG_LOAD(0, 0); if (1 < nsteps) HG_LOAD(1, 1); if (2 < nsteps) HG_LOAD(2, 2);
;     HG_WRITE(0, 0); if (1 < nsteps) HG_WRITE(1, 1);
;     if (3 < nsteps) HG_LOAD(0, 3); if (4 < nsteps) HG_LOAD(1, 4);
.LBB0_2321:
	s_and_b32 s7, s84, 15
	s_ashr_i32 s2, s84, 4
	s_lshl_b32 s3, s7, 4
	s_lshl_b32 s85, s2, 10
	s_add_i32 s2, s3, s2
	s_ashr_i32 s3, s2, 31
	s_lshl_b64 s[2:3], s[2:3], 15
	s_waitcnt vmcnt(0)
	v_mov_b32_e32 v80, v0
	s_add_u32 s10, s81, s2
	s_addc_u32 s14, s82, s3
	v_readfirstlane_b32 s5, v80
	s_ashr_i32 s4, s5, 6
	s_lshl_b32 s2, s4, 4
	s_ashr_i32 s3, s2, 31
	s_lshl_b32 s6, s7, 7
	s_lshl_b64 s[8:9], s[2:3], 1
	v_and_b32_e32 v84, 15, v80
	s_add_u32 s8, s10, s8
	v_bfe_u32 v99, v80, 4, 2
	s_addc_u32 s9, s14, s9
	v_lshlrev_b32_e32 v28, 1, v84
	v_mov_b32_e32 v29, v3
	v_lshl_add_u64 v[4:5], s[8:9], 0, v[28:29]
	v_lshlrev_b32_e32 v30, 10, v99
	v_mov_b32_e32 v31, v3
	s_nop 0
	v_lshl_add_u64 v[4:5], v[4:5], 0, v[30:31]
	v_add_co_u32_e32 v6, vcc, s97, v4
	s_movk_i32 s3, 0x3000
	s_nop 0
	v_addc_co_u32_e32 v7, vcc, 0, v5, vcc
	v_add_co_u32_e32 v8, vcc, s75, v4
	v_ashrrev_i32_e32 v2, 5, v80
	s_nop 0
	v_addc_co_u32_e32 v9, vcc, 0, v5, vcc
	v_add_co_u32_e32 v10, vcc, s3, v4
	s_movk_i32 s3, 0x4000
	s_nop 0
	v_addc_co_u32_e32 v11, vcc, 0, v5, vcc
	v_add_co_u32_e32 v12, vcc, s3, v4
	s_movk_i32 s3, 0x5000
	s_nop 0
	v_addc_co_u32_e32 v13, vcc, 0, v5, vcc
	global_load_ushort v44, v[4:5], off
	global_load_ushort v45, v[4:5], off offset:256
	global_load_ushort v46, v[4:5], off offset:512
	global_load_ushort v47, v[4:5], off offset:768
	global_load_ushort v29, v[6:7], off offset:256
	global_load_ushort v31, v[6:7], off offset:512
	global_load_ushort v43, v[6:7], off offset:768
	global_load_ushort v42, v[10:11], off offset:256
	global_load_ushort v59, v[8:9], off offset:-4096
	global_load_ushort v50, v[8:9], off
	global_load_ushort v51, v[8:9], off offset:256
	global_load_ushort v56, v[8:9], off offset:512
	global_load_ushort v57, v[8:9], off offset:768
	global_load_ushort v58, v[12:13], off offset:-4096
	global_load_ushort v48, v[12:13], off
	global_load_ushort v49, v[12:13], off offset:256
	v_add_co_u32_e32 v6, vcc, s3, v4
	s_movk_i32 s3, 0x6000
	s_nop 0
	v_addc_co_u32_e32 v7, vcc, 0, v5, vcc
	v_add_co_u32_e32 v8, vcc, s3, v4
	s_movk_i32 s3, 0x7000
	s_nop 0
	v_addc_co_u32_e32 v9, vcc, 0, v5, vcc
	v_add_co_u32_e32 v4, vcc, s3, v4
	global_load_ushort v81, v[12:13], off offset:512
	global_load_ushort v82, v[12:13], off offset:768
	s_nop 0
	global_load_ushort v83, v[8:9], off offset:-4096
	global_load_ushort v85, v[8:9], off
	global_load_ushort v86, v[8:9], off offset:256
	global_load_ushort v87, v[8:9], off offset:512
	global_load_ushort v88, v[8:9], off offset:768
	v_addc_co_u32_e32 v5, vcc, 0, v5, vcc
	global_load_ushort v96, v[10:11], off offset:512
	global_load_ushort v97, v[10:11], off offset:768
	s_nop 0
	global_load_ushort v93, v[6:7], off offset:256
	global_load_ushort v94, v[6:7], off offset:512
	global_load_ushort v95, v[6:7], off offset:768
	global_load_ushort v89, v[4:5], off
	global_load_ushort v90, v[4:5], off offset:256
	global_load_ushort v91, v[4:5], off offset:512
	global_load_ushort v92, v[4:5], off offset:768
	v_add_u32_e32 v4, s85, v2
	v_ashrrev_i32_e32 v5, 31, v4
	v_lshlrev_b64 v[60:61], 12, v[4:5]
	v_lshl_add_u64 v[4:5], s[18:19], 0, v[60:61]
	s_lshl_b32 s10, s7, 8
	v_lshlrev_b32_e32 v100, 3, v80
	v_lshl_add_u64 v[4:5], v[4:5], 0, s[10:11]
	v_and_b32_e32 v2, 0xf8, v100
	v_lshl_add_u64 v[32:33], v[4:5], 0, v[2:3]
	v_bfe_u32 v2, v80, 4, 4
	v_or_b32_e32 v62, s85, v2
	v_ashrrev_i32_e32 v63, 31, v62
	s_movk_i32 s3, 0x100
	v_lshlrev_b64 v[64:65], 11, v[62:63]
	v_and_b32_e32 v2, 0x78, v100
	v_mov_b32_e32 v6, s80
	v_mov_b32_e32 v7, s78
	v_cmp_gt_i32_e64 s[38:39], s3, v80
	v_or_b32_e32 v68, s2, v84
	v_or3_b32 v4, v64, v2, s6
	v_mov_b32_e32 v5, v65
	v_cndmask_b32_e64 v67, v6, v7, s[38:39]
	v_mov_b32_e32 v6, s79
	v_mov_b32_e32 v7, s77
	v_ashrrev_i32_e32 v69, 31, v68
	v_cndmask_b32_e64 v66, v6, v7, s[38:39]
	v_lshlrev_b64 v[4:5], 1, v[4:5]
	v_lshl_add_u64 v[6:7], v[68:69], 2, s[20:21]
	v_lshl_add_u64 v[36:37], v[66:67], 0, v[4:5]
	global_load_dword v98, v[6:7], off
	global_load_dwordx2 v[40:41], v[32:33], off
	global_load_dwordx4 v[20:23], v[36:37], off
	v_cmp_lt_i32_e64 s[40:41], s30, v80
	v_lshl_add_u64 v[34:35], s[0:1], 0, v[4:5]
	s_and_saveexec_b64 s[36:37], s[38:39]
	s_cbranch_execz .LBB0_2323
	global_load_dwordx4 v[4:7], v[34:35], off
.LBB0_2323:
	s_or_b64 exec, exec, s[36:37]
	v_add_co_u32_e32 v8, vcc, 0x10000, v32
	s_nop 1
	v_addc_co_u32_e32 v9, vcc, 0, v33, vcc
	global_load_dwordx2 v[38:39], v[8:9], off
	s_nop 0
	v_add_co_u32_e32 v8, vcc, 0x10000, v36
	s_nop 1
	v_addc_co_u32_e32 v9, vcc, 0, v37, vcc
	global_load_dwordx4 v[24:27], v[8:9], off
	s_and_saveexec_b64 s[36:37], s[38:39]
	s_cbranch_execz .LBB0_2325
	v_add_co_u32_e32 v8, vcc, 0x10000, v34
	s_nop 1
	v_addc_co_u32_e32 v9, vcc, 0, v35, vcc
	global_load_dwordx4 v[8:11], v[8:9], off
.LBB0_2325:
	s_or_b64 exec, exec, s[36:37]
	s_nop 0
	v_add_co_u32_e32 v12, vcc, 0x20000, v32
	s_nop 1
	v_addc_co_u32_e32 v13, vcc, 0, v33, vcc
	global_load_dwordx2 v[74:75], v[12:13], off
	v_add_co_u32_e32 v12, vcc, 0x20000, v36
	s_nop 1
	v_addc_co_u32_e32 v13, vcc, 0, v37, vcc
	global_load_dwordx4 v[12:15], v[12:13], off
	s_and_saveexec_b64 s[36:37], s[38:39]
	s_cbranch_execz .LBB0_2327
	v_add_co_u32_e32 v16, vcc, 0x20000, v34
	s_nop 1
	v_addc_co_u32_e32 v17, vcc, 0, v35, vcc
	global_load_dwordx4 v[16:19], v[16:17], off

; #define HG_WRITE(j, slot) do { char* rb = lds + RAW_OFF + (slot) * RAW_SLOT; *(u32x2*)(rb + tid * 8) = rl[j]; \
;         if (lo4) { if (FULL) { *(bf16x8*)(rb + 8192 + t2 * 16) = rb0[j]; *(bf16x8*)(rb + 16384 + t2 * 16) = rb1[j]; } } else *(bf16x8*)(rb + 12288 + t2 * 16) = rb0[j]; } while (0)
; template <bool FULL, bool SBF> ...
;     ...
;     HG_WRITE(0, 0); if (1 < nsteps) HG_WRITE(1, 1);
.LBB0_2329:
	s_or_saveexec_b64 s[36:37], s[36:37]
	v_mov_b32_e32 v41, s23
	s_xor_b64 exec, exec, s[36:37]
	s_cbranch_execz .LBB0_2331
	s_waitcnt vmcnt(4)
	ds_write_b128 v40, v[20:23] offset:36864
	ds_write_b128 v40, v[4:7] offset:45056
	s_waitcnt vmcnt(3)
	s_nop 0
	ds_write_b64 v52, v[38:39] offset:49152
	s_waitcnt vmcnt(2)
	ds_write_b128 v40, v[24:27] offset:57344
	s_add_i32 s3, 0, 0x10000
	v_mov_b64_e32 v[26:27], v[10:11]
	v_mov_b32_e32 v41, s3
	v_mov_b64_e32 v[24:25], v[8:9]

; #define LDS_WAIT() asm volatile("s_waitcnt lgkmcnt(0)" ::: "memory")
; template <bool FULL>
; __device__ __forceinline__ void hgrn_prep(char* lds, int s, int w, int kc, int tq, int kpos, float& gsum, s16x4& vfrag, u32x2& gvp) {
;     const int buf = s & 1;
;     char* QG = lds + QG_OFF + buf * 4352; char* KG = lds + KG_OFF + buf * 4352; char* KDT = lds + KDT_OFF + buf * 4096;
;     float* DL = (float*)(lds + DL_OFF + buf * 512);
;     const char* raw = lds + RAW_OFF + buf * RAW_SLOT;
;     float lf[4]; unsigned short qv[4], vv[4], gv[4];
; #pragma unroll
;     for (int j = 0; j < 4; ++j) { const int e = (4 * tq + j) * 128 + 16 * w + kc; lf[j] = h2f(*(const unsigned short*)(raw + e * 2)); vv[j] = *(const unsigned short*)(raw + 12288 + e * 2);
;         if (FULL) { qv[j] = *(const unsigned short*)(raw + 8192 + e * 2); gv[j] = *(const unsigned short*)(raw + 16384 + e * 2); } }
;     float G[4], glast;
;     { const float c0 = lf[0], c1 = c0 + lf[1], c2 = c1 + lf[2], c3 = c2 + lf[3];
;       float pre; row_prefix4(c3, tq, pre, glast);
;       G[0] = pre + c0; G[1] = pre + c1; G[2] = pre + c2; G[3] = pre + c3; }
;     float kd[4];
; #pragma unroll
;     for (int j = 0; j < 4; ++j) { const float kk = 1.f - __builtin_amdgcn_exp2f(lf[j]);
;         kd[j] = kk * __builtin_amdgcn_exp2f(glast - G[j]);
;         if (FULL) { const float qg = bf2f(qv[j]) * __builtin_amdgcn_exp2f(G[j]), kg = kk * __builtin_amdgcn_exp2f(fminf(-G[j], 115.f));
;             const unsigned qk = cvt_pk_bf16(qg, kg);
;             *(bf16*)(QG + (4 * tq + j) * ROWB + kpos * 2) = (bf16)(qk & 0xffffu);
;             *(bf16*)(KG + (4 * tq + j) * ROWB + kpos * 2) = (bf16)(qk >> 16); }
;         vfrag[j] = (short)vv[j]; }
;     { u32x2 kw; kw.x = cvt_pk_bf16(kd[0], kd[1]); kw.y = cvt_pk_bf16(kd[2], kd[3]); *(u32x2*)(KDT + ((16 * w + kc) * 16 + 4 * tq) * 2) = kw; }
;     DL[16 * w + kc] = __builtin_amdgcn_exp2f(glast);
;     gsum += glast;
;     if (FULL) { gvp.x = (unsigned)gv[0] | ((unsigned)gv[1] << 16); gvp.y = (unsigned)gv[2] | ((unsigned)gv[3] << 16); }
; }
; template <bool FULL, bool SBF> ...
;     ...
;     if (3 < nsteps) HG_LOAD(0, 3); if (4 < nsteps) HG_LOAD(1, 4);
;     LDS_WAIT(); __builtin_amdgcn_s_barrier(); asm volatile("" ::: "memory");
;     hgrn_prep<FULL>(lds, 0, w, kc, tq, kpos, gsum, vf_cur, gv_cur);
;     LDS_WAIT(); __builtin_amdgcn_s_barrier(); asm volatile("" ::: "memory");
.LBB0_2333:
	s_or_b64 exec, exec, s[36:37]
	v_add_co_u32_e32 v24, vcc, 0x40000, v32
	s_nop 1
	v_addc_co_u32_e32 v25, vcc, 0, v33, vcc
	global_load_dwordx2 v[78:79], v[24:25], off
	v_add_co_u32_e32 v24, vcc, 0x40000, v36
	s_nop 1
	v_addc_co_u32_e32 v25, vcc, 0, v37, vcc
	s_nop 0
	global_load_dwordx4 v[24:27], v[24:25], off
	s_and_saveexec_b64 s[36:37], s[38:39]
	s_cbranch_execz .LBB0_2335
	v_add_co_u32_e32 v8, vcc, 0x40000, v34
	s_nop 1
	v_addc_co_u32_e32 v9, vcc, 0, v35, vcc
	global_load_dwordx4 v[8:11], v[8:9], off
.LBB0_2335:
	s_or_b64 exec, exec, s[36:37]
	v_lshl_or_b32 v32, s4, 5, v28
	s_waitcnt lgkmcnt(0)
	s_barrier
	s_nop 0
	v_add3_u32 v102, v32, v30, 0
	ds_read_u16 v30, v102 offset:28672
	ds_read_u16 v32, v102 offset:28928
	ds_read_u16 v33, v102 offset:29184
	ds_read_u16 v34, v102 offset:29440
	ds_read_u16 v69, v102 offset:40960
	ds_read_u16 v114, v102 offset:36864
	ds_read_u16 v111, v102 offset:41216
	ds_read_u16 v109, v102 offset:37120
	ds_read_u16 v112, v102 offset:41472
	ds_read_u16 v108, v102 offset:37376
	ds_read_u16 v113, v102 offset:41728
	ds_read_u16 v106, v102 offset:37632
	ds_read_u16 v117, v102 offset:45056
	ds_read_u16 v118, v102 offset:45312
	ds_read_u16 v119, v102 offset:45568
	ds_read_u16 v120, v102 offset:45824
	s_waitcnt lgkmcnt(14)
	v_cvt_f32_f16_e32 v110, v30
	v_cvt_f32_f16_e32 v105, v32
	s_waitcnt lgkmcnt(13)
	v_cvt_f32_f16_e32 v107, v33
	s_waitcnt lgkmcnt(12)
	v_cvt_f32_f16_e32 v103, v34
	v_cmp_lt_i32_e32 vcc, 0, v99
	v_add_f32_e32 v116, v110, v105
	v_add_f32_e32 v71, v116, v107
	v_add_f32_e32 v115, v71, v103
	v_mov_b32_e32 v30, v115
	v_mov_b32_e32 v32, v115
	s_nop 1
	v_permlane16_swap_b32_e32 v30, v32
	v_add_f32_e32 v70, v30, v32
	v_mov_b32_e32 v72, v70
	s_nop 1
	v_permlane32_swap_b32_e32 v70, v72
	v_mov_b32_e32 v73, 0
	s_and_saveexec_b64 s[36:37], vcc
	s_cbranch_execz .LBB0_2341
	v_cmp_ne_u32_e32 vcc, 1, v99
	s_and_saveexec_b64 s[8:9], vcc
	s_xor_b64 s[40:41], exec, s[8:9]
	v_add_f32_e32 v30, v30, v70
	v_cmp_eq_u32_e32 vcc, 2, v99
	s_nop 1
	v_cndmask_b32_e32 v73, v30, v70, vcc
	s_andn2_saveexec_b64 s[40:41], s[40:41]
	v_mov_b32_e32 v73, v30
	s_or_b64 exec, exec, s[40:41]
.LBB0_2341:
	s_or_b64 exec, exec, s[36:37]
	s_and_b32 s3, s83, 15
	s_lshl_b32 s10, s3, 8
	s_lshl_b32 s36, s3, 7
	s_ashr_i32 s3, s5, 2
	v_lshlrev_b32_e32 v53, 16, v45
	v_lshlrev_b32_e32 v45, 16, v86
	v_exp_f32_e32 v86, v110
	s_and_b32 s3, s3, 0x7fffffe0
	v_and_b32_e32 v28, 24, v28
	v_and_b32_e32 v30, 3, v80
	s_lshl_b32 s4, s4, 2
	s_nop 0
	v_or3_b32 v121, v28, v30, s3
	v_lshlrev_b32_e32 v36, 16, v58
	v_lshlrev_b32_e32 v58, 16, v81
	v_lshlrev_b32_e32 v40, 16, v83
	v_and_or_b32 v81, s4, 4, v121
	v_add_f32_e32 v83, v73, v110
	v_pk_add_f32 v[70:71], v[70:71], v[72:73]
	v_lshlrev_b32_e32 v52, 16, v44
	v_lshlrev_b32_e32 v54, 16, v46
	v_lshlrev_b32_e32 v44, 16, v85
	v_lshlrev_b32_e32 v46, 16, v87
	v_add_f32_e32 v85, v116, v73
	v_add_f32_e32 v72, v115, v73
	v_lshlrev_b32_e32 v73, 1, v81
	v_sub_f32_e32 v81, 1.0, v86
	v_sub_f32_e32 v86, v70, v83
	v_exp_f32_e32 v87, v83
	v_min_f32_e64 v83, -v83, s74
	v_exp_f32_e32 v86, v86
	v_exp_f32_e32 v83, v83
	v_lshlrev_b32_e32 v55, 16, v47
	v_lshlrev_b32_e32 v47, 16, v88
	s_waitcnt lgkmcnt(10)
	v_lshlrev_b32_e32 v88, 16, v114
	v_mul_f32_e32 v86, v81, v86
	v_mul_f32_e32 v87, v87, v88
	v_mul_f32_e32 v81, v81, v83
	s_nop 0
	v_mul_u32_u24_e32 v83, 0x440, v99
	v_cvt_pk_bf16_f32 v81, v87, v81
	v_exp_f32_e32 v87, v105
	v_add3_u32 v105, 0, v73, v83
	ds_write_b16 v105, v81
	ds_write_b16_d16_hi v105, v81 offset:8704
	v_sub_f32_e32 v81, v70, v85
	v_exp_f32_e32 v83, v85
	v_min_f32_e64 v85, -v85, s74
	v_exp_f32_e32 v81, v81
	v_exp_f32_e32 v85, v85
	v_sub_f32_e32 v73, 1.0, v87
	s_waitcnt lgkmcnt(10)
	v_lshlrev_b32_e32 v87, 16, v109
	v_mul_f32_e32 v81, v73, v81
	v_mul_f32_e32 v73, v73, v85
	v_exp_f32_e32 v85, v107
	v_mul_f32_e32 v83, v83, v87
	v_cvt_pk_bf16_f32 v73, v83, v73
	ds_write_b16 v105, v73 offset:272
	ds_write_b16_d16_hi v105, v73 offset:8976
	v_sub_f32_e32 v73, 1.0, v85
	v_sub_f32_e32 v83, v70, v71
	v_exp_f32_e32 v85, v71
	v_min_f32_e64 v71, -v71, s74
	v_exp_f32_e32 v83, v83
	v_exp_f32_e32 v71, v71
	s_waitcnt lgkmcnt(10)
	v_lshlrev_b32_e32 v87, 16, v108
	v_mul_f32_e32 v85, v85, v87
	v_mul_f32_e32 v83, v73, v83
	v_mul_f32_e32 v71, v73, v71
	v_exp_f32_e32 v73, v103
	v_cvt_pk_bf16_f32 v71, v85, v71
	ds_write_b16 v105, v71 offset:544
	s_nop 0
	ds_write_b16_d16_hi v105, v71 offset:9248
	v_exp_f32_e32 v85, v72
	v_sub_f32_e32 v71, 1.0, v73
	v_sub_f32_e32 v73, v70, v72
	v_min_f32_e64 v72, -v72, s74
	v_exp_f32_e32 v73, v73
	v_exp_f32_e32 v72, v72
	s_waitcnt lgkmcnt(10)
	v_lshlrev_b32_e32 v87, 16, v106
	v_exp_f32_e32 v70, v70
	v_mul_f32_e32 v73, v71, v73
	v_mul_f32_e32 v71, v71, v72
	v_mul_f32_e32 v85, v85, v87
	s_nop 0
	v_cvt_pk_bf16_f32 v71, v85, v71
	ds_write_b16 v105, v71 offset:816
	ds_write_b16_d16_hi v105, v71 offset:9520
	v_cvt_pk_bf16_f32 v72, v86, v81
	v_lshlrev_b32_e32 v71, 5, v68
	v_lshlrev_b32_e32 v81, 3, v99
	v_lshlrev_b32_e32 v104, 2, v99
	v_add3_u32 v106, 0, v71, v81
	v_lshl_add_u32 v107, v68, 2, 0
	s_nop 0
	v_lshl_add_u32 v108, v99, 4, 0
	v_cvt_pk_bf16_f32 v73, v83, v73
	ds_write_b64 v106, v[72:73] offset:17408
	ds_write_b32 v107, v70 offset:25600
	v_sub_u32_e32 v68, v108, v81
	v_or_b32_e32 v70, 2, v104
	v_mul_u32_u24_e32 v71, 0x78, v99
	v_cmp_gt_u32_e64 s[46:47], v70, v84
	v_or_b32_e32 v70, 3, v104
	s_nop 0
	v_lshl_add_u32 v109, v84, 5, v68
	v_add3_u32 v110, v68, v71, s4
	v_and_b32_e32 v68, 7, v80
	v_cmp_gt_u32_e64 s[48:49], v70, v84
	v_lshlrev_b32_e32 v70, 7, v99
	v_lshlrev_b32_e32 v68, 2, v68
	v_add3_u32 v103, 0, v68, v70
	v_and_b32_e32 v68, 31, v80
	v_perm_b32 v88, v111, v69, s35
	v_lshl_add_u64 v[60:61], v[60:61], 0, s[10:11]
	v_lshlrev_b32_e32 v68, 3, v68
	v_mov_b32_e32 v69, v3
	s_mov_b32 s37, s11
	v_lshl_add_u64 v[60:61], v[60:61], 0, v[68:69]
	s_add_i32 s2, s2, s6
	v_lshl_add_u64 v[80:81], s[58:59], 0, v[60:61]
	v_lshl_add_u64 v[60:61], v[64:65], 0, s[36:37]
	v_lshlrev_b32_e32 v28, 16, v59
	v_lshlrev_b32_e32 v59, 16, v82
	v_or_b32_e32 v82, s2, v84
	s_waitcnt lgkmcnt(0)
	s_barrier
; __device__ __forceinline__ unsigned cvt_pk_bf16(float lo, float hi) { unsigned r; asm volatile("v_cvt_pk_bf16_f32 %0, %1, %2" : "=v"(r) : "v"(lo), "v"(hi)); return r; }
; __device__ __forceinline__ float bf2f(unsigned short b) { return __uint_as_float(((unsigned)b) << 16); }
; template <bool FULL>
; __device__ __forceinline__ void hgrn_mma(char* lds, int s, int w, int kc, int tq, const s16x4 vfrag, f32x4 (&S)[8], f32x4& o) {
;     const int buf = s & 1;
;     const char* QG = lds + QG_OFF + buf * 4352; const char* KG = lds + KG_OFF + buf * 4352; const char* KDT = lds + KDT_OFF + buf * 4096;
;     const float* DL = (const float*)(lds + DL_OFF + buf * 512); float* SSQP = (float*)(lds + SSQP_OFF + buf * 512);
;     o = (f32x4){0.f, 0.f, 0.f, 0.f};
;     if (FULL) {
;         f32x4 st = {0.f, 0.f, 0.f, 0.f};
; #pragma unroll
;         for (int ks = 0; ks < 4; ++ks) {
;             const bf16x8 qa = *(const bf16x8*)(QG + kc * ROWB + (32 * ks + 8 * tq) * 2), ka = *(const bf16x8*)(KG + kc * ROWB + (32 * ks + 8 * tq) * 2);
;             u32x4 sw; sw.x = cvt_pk_bf16(S[2 * ks][0], S[2 * ks][1]); sw.y = cvt_pk_bf16(S[2 * ks][2], S[2 * ks][3]);
;             sw.z = cvt_pk_bf16(S[2 * ks + 1][0], S[2 * ks + 1][1]); sw.w = cvt_pk_bf16(S[2 * ks + 1][2], S[2 * ks + 1][3]);
;             o = __builtin_amdgcn_mfma_f32_16x16x32_bf16(qa, *reinterpret_cast<bf16x8*>(&sw), o, 0, 0, 0);
;             st = __builtin_amdgcn_mfma_f32_16x16x32_bf16(ka, qa, st, 0, 0, 0); }
; #pragma unroll
;         for (int i = 0; i < 4; ++i) st[i] = (4 * tq + i <= kc) ? st[i] : 0.f;
;         u32x2 sp; sp.x = cvt_pk_bf16(st[0], st[1]); sp.y = cvt_pk_bf16(st[2], st[3]);
;         o = __builtin_amdgcn_mfma_f32_16x16x16bf16_1k(*reinterpret_cast<s16x4*>(&sp), vfrag, o, 0, 0, 0);
;     }
; #pragma unroll
;     for (int kb = 0; kb < 8; ++kb) { const f32x4 dlv = *(const f32x4*)(DL + 16 * kb + 4 * tq);
;         const s16x4 ka = *(const s16x4*)(KDT + ((16 * kb + kc) * 16 + 4 * tq) * 2);
;         S[kb] = __builtin_amdgcn_mfma_f32_16x16x16bf16_1k(ka, vfrag, S[kb] * dlv, 0, 0, 0); }
; template <bool FULL, bool SBF> ...
;     ...
;         for (int i = 0; i < 4; ++i) { const size_t so = (size_t)(16 * kb + 4 * tq + i) * 128 + 16 * w + kc; S[kb][i] = Sin ? (SBF ? bf2f(((const bf16*)Sin)[so]) : ((const float*)Sin)[so]) : 0.f; }
	s_nop 0
	v_lshl_add_u64 v[60:61], v[60:61], 0, v[2:3]
	v_lshlrev_b64 v[62:63], 12, v[62:63]
	v_lshlrev_b32_e32 v2, 4, v84
	v_ashrrev_i32_e32 v83, 31, v82
	s_movk_i32 s2, 0x110
	v_lshlrev_b64 v[60:61], 1, v[60:61]
	v_or3_b32 v62, v62, s10, v2
	v_mov_b32_e32 v2, v3
	v_lshlrev_b32_e32 v29, 16, v29
	v_lshlrev_b32_e32 v30, 16, v31
	v_lshlrev_b32_e32 v31, 16, v43
	v_lshlrev_b32_e32 v32, 16, v50
	v_lshlrev_b32_e32 v33, 16, v51
	v_lshlrev_b32_e32 v34, 16, v56
	v_lshlrev_b32_e32 v35, 16, v57
	v_lshlrev_b32_e32 v37, 16, v42
	v_lshlrev_b32_e32 v38, 16, v96
	v_lshlrev_b32_e32 v39, 16, v97
	v_lshlrev_b32_e32 v56, 16, v48
	v_lshlrev_b32_e32 v57, 16, v49
	v_lshlrev_b32_e32 v41, 16, v93
	v_lshlrev_b32_e32 v42, 16, v94
	v_lshlrev_b32_e32 v43, 16, v95
	v_lshlrev_b32_e32 v48, 16, v89
	v_lshlrev_b32_e32 v49, 16, v90
	v_lshlrev_b32_e32 v50, 16, v91
	v_lshlrev_b32_e32 v51, 16, v92
	s_waitcnt lgkmcnt(10)
	v_perm_b32 v91, v120, v119, s35
	v_perm_b32 v90, v118, v117, s35
	v_cmp_gt_u32_e64 s[42:43], v104, v84
	v_cmp_lt_u32_e64 s[44:45], v104, v84
	v_cmp_eq_u32_e64 s[50:51], 2, v99
	v_cmp_gt_u32_e64 s[40:41], 8, v84
	v_lshl_add_u64 v[72:73], v[82:83], 1, s[12:13]
	v_perm_b32 v89, v113, v112, s35
	v_mad_u32_u24 v111, v84, s2, v108
	v_lshl_add_u64 v[82:83], v[66:67], 0, v[60:61]
	v_lshl_add_u64 v[84:85], s[58:59], 0, v[62:63]
	v_lshl_add_u64 v[86:87], s[58:59], 0, v[60:61]
	v_add_u32_e32 v112, s85, v104
	s_mov_b32 s10, 0
	v_mov_b32_e32 v60, v3
	v_mov_b32_e32 v61, v3
	v_mov_b32_e32 v62, v3
	v_mov_b32_e32 v63, v3
	s_mov_b64 s[2:3], 0
	s_mov_b32 s86, 0
	s_mov_b32 s87, 0
	v_mov_b64_e32 v[64:65], v[2:3]
	v_mov_b64_e32 v[92:93], v[2:3]
.LBB0_2342:
	s_and_b32 s88, s87, 1
	s_mul_i32 s89, s88, 0x1100
	v_add_u32_e32 v114, s89, v111
	ds_read_b128 v[66:69], v114
	ds_read_b128 v[94:97], v114 offset:8704
	v_cvt_pk_bf16_f32 v116, v52, v53
	v_cvt_pk_bf16_f32 v117, v54, v55
	s_nop 0
	v_cvt_pk_bf16_f32 v118, v28, v29
	v_cvt_pk_bf16_f32 v119, v30, v31
	ds_read_b128 v[120:123], v114 offset:64
	ds_read_b128 v[124:127], v114 offset:8768
	s_waitcnt lgkmcnt(3)
	v_mfma_f32_16x16x32_bf16 v[116:119], v[66:69], v[116:119], 0
	s_lshl_b32 s91, s88, 12
	s_lshl_b32 s90, s88, 9
	v_add_u32_e32 v113, s91, v109
	s_waitcnt lgkmcnt(2)
	s_nop 0
	v_mfma_f32_16x16x32_bf16 v[66:69], v[94:97], v[66:69], 0
	v_cvt_pk_bf16_f32 v94, v32, v33
	v_cvt_pk_bf16_f32 v95, v34, v35
	v_cvt_pk_bf16_f32 v96, v36, v37
	v_cvt_pk_bf16_f32 v97, v38, v39
	s_waitcnt lgkmcnt(0)
	v_mfma_f32_16x16x32_bf16 v[66:69], v[124:127], v[120:123], v[66:69]
	s_cmpk_lg_i32 s86, 0x3f0
	s_cselect_b64 s[36:37], -1, 0
	s_cmpk_eq_i32 s86, 0x3f0
	v_mfma_f32_16x16x32_bf16 v[94:97], v[120:123], v[94:97], v[116:119]
	ds_read_b128 v[120:123], v114 offset:8832
	s_mov_b64 s[52:53], -1
	s_nop 0
	ds_read_b128 v[116:119], v114 offset:128
	v_cvt_pk_bf16_f32 v124, v56, v57
	v_cvt_pk_bf16_f32 v125, v58, v59
	v_cvt_pk_bf16_f32 v126, v40, v41
	v_cvt_pk_bf16_f32 v127, v42, v43
	s_waitcnt lgkmcnt(0)
	v_mfma_f32_16x16x32_bf16 v[66:69], v[120:123], v[116:119], v[66:69]
	v_mfma_f32_16x16x32_bf16 v[94:97], v[116:119], v[124:127], v[94:97]
	ds_read_b128 v[124:127], v114 offset:192
	ds_read_b128 v[116:119], v114 offset:8896
	v_cvt_pk_bf16_f32 v120, v44, v45
	s_waitcnt lgkmcnt(0)
	v_mfma_f32_16x16x32_bf16 v[66:69], v[116:119], v[124:127], v[66:69]
	v_cvt_pk_bf16_f32 v121, v46, v47
	v_cvt_pk_bf16_f32 v122, v48, v49
	v_cvt_pk_bf16_f32 v123, v50, v51
	s_nop 7
	v_cndmask_b32_e64 v2, v66, 0, s[42:43]
	v_mfma_f32_16x16x32_bf16 v[94:97], v[124:127], v[120:123], v[94:97]
	v_cndmask_b32_e64 v66, 0, v67, s[44:45]
	v_cndmask_b32_e64 v67, v68, 0, s[46:47]
	v_cndmask_b32_e64 v68, v69, 0, s[48:49]
	s_nop 0
	v_cvt_pk_bf16_f32 v66, v2, v66
	v_add_u32_e32 v2, s90, v108
	v_cvt_pk_bf16_f32 v67, v67, v68
	ds_read2st64_b64 v[116:119], v113 offset0:34 offset1:35
	ds_read_b128 v[120:123], v2 offset:25600
	v_mfma_f32_16x16x16_bf16 v[68:71], v[66:67], v[88:89], v[94:97]
	ds_read_b128 v[124:127], v2 offset:25728
	v_mov_b32_e32 v67, v3
	s_waitcnt lgkmcnt(1)
	s_nop 0
	v_pk_mul_f32 v[52:53], v[52:53], v[120:121]
	ds_read_b128 v[94:97], v2 offset:25664
	v_pk_mul_f32 v[54:55], v[54:55], v[122:123]
	ds_read2st64_b64 v[120:123], v113 offset0:36 offset1:37
	s_waitcnt lgkmcnt(2)
	v_pk_mul_f32 v[32:33], v[32:33], v[124:125]
	v_mfma_f32_16x16x16_bf16 v[52:55], v[116:117], v[88:89], v[52:55]
	s_waitcnt lgkmcnt(1)
; __device__ __forceinline__ float h2f(unsigned short u) { return (float)__builtin_bit_cast(_Float16, u); }
; template <bool FULL>
; __device__ __forceinline__ void hgrn_prep(char* lds, int s, int w, int kc, int tq, int kpos, float& gsum, s16x4& vfrag, u32x2& gvp) {
;     ...
;     float lf[4]; unsigned short qv[4], vv[4], gv[4];
; #pragma unroll
;     for (int j = 0; j < 4; ++j) { const int e = (4 * tq + j) * 128 + 16 * w + kc; lf[j] = h2f(*(const unsigned short*)(raw + e * 2)); vv[j] = *(const unsigned short*)(raw + 12288 + e * 2);
;         if (FULL) { qv[j] = *(const unsigned short*)(raw + 8192 + e * 2); gv[j] = *(const unsigned short*)(raw + 16384 + e * 2); } }
;     float G[4], glast;
;     { const float c0 = lf[0], c1 = c0 + lf[1], c2 = c1 + lf[2], c3 = c2 + lf[3];
;       float pre; row_prefix4(c3, tq, pre, glast);
;       G[0] = pre + c0; G[1] = pre + c1; G[2] = pre + c2; G[3] = pre + c3; }
; template <bool FULL>
; __device__ __forceinline__ void hgrn_mma(char* lds, int s, int w, int kc, int tq, const s16x4 vfrag, f32x4 (&S)[8], f32x4& o) {
;     ...
; #pragma unroll
;     for (int kb = 0; kb < 8; ++kb) { const f32x4 dlv = *(const f32x4*)(DL + 16 * kb + 4 * tq);
;         const s16x4 ka = *(const s16x4*)(KDT + ((16 * kb + kc) * 16 + 4 * tq) * 2);
;         S[kb] = __builtin_amdgcn_mfma_f32_16x16x16bf16_1k(ka, vfrag, S[kb] * dlv, 0, 0, 0); }
;     if (FULL) {
;         float ss[4];
; #pragma unroll
;         for (int i = 0; i < 4; ++i) ss[i] = row16_sum(o[i] * o[i]);
; #pragma unroll
;         for (int i = 0; i < 4; ++i) SSQP[(4 * tq + i) * 8 + w] = ss[i];
;     }
	v_pk_mul_f32 v[28:29], v[28:29], v[94:95]
	v_pk_mul_f32 v[30:31], v[30:31], v[96:97]
	ds_read_b128 v[94:97], v2 offset:25792
	v_pk_mul_f32 v[34:35], v[34:35], v[126:127]
	v_mfma_f32_16x16x16_bf16 v[28:31], v[118:119], v[88:89], v[28:31]
	ds_read2st64_b64 v[116:119], v113 offset0:38 offset1:39
	ds_read_b128 v[124:127], v2 offset:25856
	v_mul_f32_e32 v66, v68, v68
	s_waitcnt lgkmcnt(2)
	v_pk_mul_f32 v[36:37], v[36:37], v[94:95]
	v_pk_mul_f32 v[38:39], v[38:39], v[96:97]
	ds_read_b128 v[94:97], v2 offset:25920
	s_waitcnt lgkmcnt(1)
	v_pk_mul_f32 v[56:57], v[56:57], v[124:125]
	v_pk_mul_f32 v[58:59], v[58:59], v[126:127]
	ds_read_b128 v[124:127], v2 offset:25984
	v_mfma_f32_16x16x16_bf16 v[32:35], v[120:121], v[88:89], v[32:35]
	s_waitcnt lgkmcnt(1)
	v_pk_mul_f32 v[40:41], v[40:41], v[94:95]
	v_pk_mul_f32 v[42:43], v[42:43], v[96:97]
	ds_read_b128 v[94:97], v2 offset:26048
	v_mfma_f32_16x16x16_bf16 v[36:39], v[122:123], v[88:89], v[36:39]
	ds_read2st64_b64 v[120:123], v113 offset0:40 offset1:41
	v_mov_b32_dpp v67, v66 row_ror:8 row_mask:0xf bank_mask:0xf
	v_fmac_f32_e32 v67, v68, v68
	s_waitcnt lgkmcnt(1)
	v_pk_mul_f32 v[48:49], v[48:49], v[94:95]
	v_mov_b32_e32 v94, v3
	s_nop 0
	v_add_f32_dpp v66, v67, v67 row_ror:4 row_mask:0xf bank_mask:0xf bound_ctrl:1
	v_mul_f32_e32 v67, v69, v69
	v_mov_b32_e32 v95, v3
	v_pk_mul_f32 v[44:45], v[44:45], v[124:125]
	v_mov_b32_dpp v94, v67 row_ror:8 row_mask:0xf bank_mask:0xf
	v_fmac_f32_e32 v94, v69, v69
	v_pk_mul_f32 v[46:47], v[46:47], v[126:127]
	v_pk_mul_f32 v[50:51], v[50:51], v[96:97]
	v_add_f32_dpp v67, v94, v94 row_ror:4 row_mask:0xf bank_mask:0xf bound_ctrl:1
	v_mul_f32_e32 v94, v70, v70
	v_mov_b32_e32 v96, v3
	v_mfma_f32_16x16x16_bf16 v[56:59], v[116:117], v[88:89], v[56:59]
	v_mov_b32_dpp v95, v94 row_ror:8 row_mask:0xf bank_mask:0xf
	v_fmac_f32_e32 v95, v70, v70
	v_add_f32_dpp v66, v66, v66 row_ror:2 row_mask:0xf bank_mask:0xf bound_ctrl:1
	v_mfma_f32_16x16x16_bf16 v[40:43], v[118:119], v[88:89], v[40:43]
	v_add_f32_dpp v94, v95, v95 row_ror:4 row_mask:0xf bank_mask:0xf bound_ctrl:1
	v_mul_f32_e32 v95, v71, v71
	v_add_f32_dpp v67, v67, v67 row_ror:2 row_mask:0xf bank_mask:0xf bound_ctrl:1
	s_waitcnt lgkmcnt(0)
	v_mfma_f32_16x16x16_bf16 v[44:47], v[120:121], v[88:89], v[44:47]
	v_mov_b32_dpp v96, v95 row_ror:8 row_mask:0xf bank_mask:0xf
	v_fmac_f32_e32 v96, v71, v71
	v_add_f32_dpp v66, v66, v66 row_ror:1 row_mask:0xf bank_mask:0xf bound_ctrl:1
	v_mfma_f32_16x16x16_bf16 v[48:51], v[122:123], v[88:89], v[48:51]
	v_add_f32_dpp v95, v96, v96 row_ror:4 row_mask:0xf bank_mask:0xf bound_ctrl:1
	v_add_u32_e32 v96, s90, v110
	v_add_f32_dpp v67, v67, v67 row_ror:1 row_mask:0xf bank_mask:0xf bound_ctrl:1
	v_add_f32_dpp v94, v94, v94 row_ror:2 row_mask:0xf bank_mask:0xf bound_ctrl:1
	v_add_f32_dpp v95, v95, v95 row_ror:2 row_mask:0xf bank_mask:0xf bound_ctrl:1
	v_add_u32_e32 v115, 0x6800, v96
	v_add_f32_dpp v94, v94, v94 row_ror:1 row_mask:0xf bank_mask:0xf bound_ctrl:1
	v_add_f32_dpp v95, v95, v95 row_ror:1 row_mask:0xf bank_mask:0xf bound_ctrl:1
	ds_write2_b32 v115, v66, v67 offset1:8
	ds_write2_b32 v115, v94, v95 offset0:16 offset1:24
	s_cbranch_scc1 .LBB0_2354
	s_xor_b32 s4, s88, 1
	s_mul_i32 s5, s4, 0x5000
	v_add_u32_e32 v89, s5, v102
	ds_read_u16 v66, v89 offset:28672
	ds_read_u16 v67, v89 offset:28928
	ds_read_u16 v88, v89 offset:29184
	ds_read_u16 v92, v89 offset:29440
	ds_read_u16 v94, v89 offset:40960
	ds_read_u16 v125, v89 offset:36864
	ds_read_u16 v95, v89 offset:41216
	s_nop 0
	ds_read_u16 v121, v89 offset:37120
	ds_read_u16 v96, v89 offset:41472
	ds_read_u16 v119, v89 offset:37376
	ds_read_u16 v97, v89 offset:41728
	ds_read_u16 v117, v89 offset:37632
	ds_read_u16 v126, v89 offset:45056
	ds_read_u16 v127, v89 offset:45312
	ds_read_u16 v93, v89 offset:45568
	ds_read_u16 v128, v89 offset:45824
	s_waitcnt lgkmcnt(14)
	v_cvt_f32_f16_e32 v122, v66
	v_cvt_f32_f16_e32 v120, v67
	s_waitcnt lgkmcnt(13)
	v_cvt_f32_f16_e32 v118, v88
	s_waitcnt lgkmcnt(12)
	v_cvt_f32_f16_e32 v116, v92
	v_cmp_lt_i32_e32 vcc, 0, v99
	v_add_f32_e32 v123, v122, v120
	v_add_f32_e32 v67, v123, v118
	v_add_f32_e32 v124, v67, v116
	v_mov_b32_e32 v92, v124
	v_mov_b32_e32 v66, v124
	s_nop 1
	v_permlane16_swap_b32_e32 v92, v66
	v_add_f32_e32 v66, v92, v66
	v_mov_b32_e32 v88, v66
	s_nop 1
	v_permlane32_swap_b32_e32 v66, v88
	v_mov_b32_e32 v89, 0
	s_and_saveexec_b64 s[52:53], vcc
	s_cbranch_execz .LBB0_2349
	v_cmp_ne_u32_e32 vcc, 1, v99
	s_and_saveexec_b64 s[6:7], vcc
	s_xor_b64 s[62:63], exec, s[6:7]
	v_add_f32_e32 v89, v92, v66
	v_cndmask_b32_e64 v89, v89, v66, s[50:51]
	s_andn2_saveexec_b64 s[62:63], s[62:63]
	v_mov_b32_e32 v89, v92
	s_or_b64 exec, exec, s[62:63]

; __device__ __forceinline__ unsigned cvt_pk_bf16(float lo, float hi) { unsigned r; asm volatile("v_cvt_pk_bf16_f32 %0, %1, %2" : "=v"(r) : "v"(lo), "v"(hi)); return r; }
; __device__ __forceinline__ void hgrn_fin(char* lds, int s, int w, int kc, int tq, int ch, int row0, float gn, const f32x4 o, const u32x2 gvp, bf16* __restrict__ O) {
;     const float* SSQP = (const float*)(lds + SSQP_OFF + (s & 1) * 512);
; #pragma unroll
;     for (int i = 0; i < 4; ++i) { const float part = SSQP[(4 * tq + i) * 8 + (kc & 7)];
;         const float tot = row16_sum(kc < 8 ? part : 0.f);
;         const float rs = __builtin_amdgcn_rsqf(tot * (1.f / 128.f) + EPS);
;         const unsigned gw_ = i < 2 ? gvp.x : gvp.y; const float gate = __uint_as_float((i & 1) ? (gw_ & 0xffff0000u) : (gw_ << 16));
;         const float ov = o[i] * rs * gn * gate;
;         O[(size_t)(row0 + 16 * s + 4 * tq + i) * D + ch] = (bf16)(cvt_pk_bf16(ov, 0.f) & 0xffffu); }
; }
.LBB0_2355:
	s_add_i32 s4, s10, 0xfffffe00
	s_and_b32 s4, s4, 0x200
	v_add_u32_e32 v95, s4, v103
	ds_read_b32 v67, v95 offset:26624
	v_add_u32_e32 v66, -16, v94
	v_lshlrev_b32_e32 v96, 16, v64
	v_and_b32_e32 v64, 0xffff0000, v64
	s_waitcnt lgkmcnt(0)
	v_cndmask_b32_e64 v67, 0, v67, s[40:41]
	s_nop 1
	v_add_f32_dpp v67, v67, v67 row_ror:8 row_mask:0xf bank_mask:0xf bound_ctrl:1
	s_nop 1
	v_add_f32_dpp v67, v67, v67 row_ror:4 row_mask:0xf bank_mask:0xf bound_ctrl:1
	s_nop 1
	v_add_f32_dpp v67, v67, v67 row_ror:2 row_mask:0xf bank_mask:0xf bound_ctrl:1
	s_nop 1
	v_add_f32_dpp v67, v67, v67 row_ror:1 row_mask:0xf bank_mask:0xf bound_ctrl:1
	v_fmamk_f32 v67, v67, 0x3c000000, v198
	v_rsq_f32_e32 v67, v67
	s_nop 0
	v_mul_f32_e32 v60, v60, v67
	v_mul_f32_e32 v60, v98, v60
	v_ashrrev_i32_e32 v67, 31, v66
	v_mul_f32_e32 v60, v60, v96
	v_lshlrev_b64 v[66:67], 12, v[66:67]
	v_cvt_pk_bf16_f32 v60, v60, v3
	v_lshl_add_u64 v[66:67], v[72:73], 0, v[66:67]
	global_store_short v[66:67], v60, off
	ds_read_b32 v60, v95 offset:26656
	s_waitcnt lgkmcnt(0)
	s_nop 0
	v_cndmask_b32_e64 v60, 0, v60, s[40:41]
	s_nop 1
	v_add_f32_dpp v60, v60, v60 row_ror:8 row_mask:0xf bank_mask:0xf bound_ctrl:1
	s_nop 1
	v_add_f32_dpp v60, v60, v60 row_ror:4 row_mask:0xf bank_mask:0xf bound_ctrl:1
	s_nop 1
	v_add_f32_dpp v60, v60, v60 row_ror:2 row_mask:0xf bank_mask:0xf bound_ctrl:1
	s_nop 1
	v_add_f32_dpp v60, v60, v60 row_ror:1 row_mask:0xf bank_mask:0xf bound_ctrl:1
	v_fmamk_f32 v60, v60, 0x3c000000, v198
	v_rsq_f32_e32 v60, v60
	s_nop 0
	v_mul_f32_e32 v60, v61, v60
	v_mul_f32_e32 v60, v98, v60
	v_mul_f32_e32 v60, v60, v64
	v_cvt_pk_bf16_f32 v64, v60, v3
	v_add_u32_e32 v60, -15, v94
	v_ashrrev_i32_e32 v61, 31, v60
	v_lshlrev_b64 v[60:61], 12, v[60:61]
	v_lshl_add_u64 v[60:61], v[72:73], 0, v[60:61]
	global_store_short v[60:61], v64, off
	s_nop 0
	ds_read_b32 v60, v95 offset:26688
	v_lshlrev_b32_e32 v61, 16, v65
	s_waitcnt lgkmcnt(0)
	v_cndmask_b32_e64 v60, 0, v60, s[40:41]
	s_nop 1
	v_add_f32_dpp v60, v60, v60 row_ror:8 row_mask:0xf bank_mask:0xf bound_ctrl:1
	s_nop 1
	v_add_f32_dpp v60, v60, v60 row_ror:4 row_mask:0xf bank_mask:0xf bound_ctrl:1
	s_nop 1
	v_add_f32_dpp v60, v60, v60 row_ror:2 row_mask:0xf bank_mask:0xf bound_ctrl:1
	s_nop 1
	v_add_f32_dpp v60, v60, v60 row_ror:1 row_mask:0xf bank_mask:0xf bound_ctrl:1
	v_fmamk_f32 v60, v60, 0x3c000000, v198
	v_rsq_f32_e32 v60, v60
	s_nop 0
	v_mul_f32_e32 v60, v62, v60
	v_mul_f32_e32 v60, v98, v60
	v_mul_f32_e32 v60, v60, v61
	v_cvt_pk_bf16_f32 v62, v60, v3
	v_add_u32_e32 v60, -14, v94
	v_ashrrev_i32_e32 v61, 31, v60
	v_lshlrev_b64 v[60:61], 12, v[60:61]
	s_nop 0
	v_lshl_add_u64 v[60:61], v[72:73], 0, v[60:61]
	global_store_short v[60:61], v62, off
	ds_read_b32 v60, v95 offset:26720
	v_and_b32_e32 v61, 0xffff0000, v65
	s_waitcnt lgkmcnt(0)
	v_cndmask_b32_e64 v60, 0, v60, s[40:41]
	s_nop 1
	v_add_f32_dpp v60, v60, v60 row_ror:8 row_mask:0xf bank_mask:0xf bound_ctrl:1
	s_nop 1
	s_nop 0
	v_add_f32_dpp v60, v60, v60 row_ror:4 row_mask:0xf bank_mask:0xf bound_ctrl:1
	s_nop 1
	v_add_f32_dpp v60, v60, v60 row_ror:2 row_mask:0xf bank_mask:0xf bound_ctrl:1
	s_nop 1
	v_add_f32_dpp v60, v60, v60 row_ror:1 row_mask:0xf bank_mask:0xf bound_ctrl:1
	v_fmamk_f32 v60, v60, 0x3c000000, v198
	v_rsq_f32_e32 v60, v60
	s_nop 0
	v_mul_f32_e32 v60, v63, v60
	v_mul_f32_e32 v60, v98, v60
	v_mul_f32_e32 v60, v60, v61
	s_nop 0
	v_cvt_pk_bf16_f32 v62, v60, v3
	v_add_u32_e32 v60, -13, v94
	v_ashrrev_i32_e32 v61, 31, v60
	v_lshlrev_b64 v[60:61], 12, v[60:61]
	v_lshl_add_u64 v[60:61], v[72:73], 0, v[60:61]
	global_store_short v[60:61], v62, off
	s_cmp_lt_u32 s87, 62
	s_cselect_b64 s[52:53], -1, 0
	s_cmp_gt_u32 s87, 61
	s_cbranch_scc0 .LBB0_2351

.LBB0_2357:
	s_waitcnt vmcnt(0)
	v_lshl_add_u64 v[12:13], v[80:81], 0, s[2:3]
	v_add_co_u32_e32 v12, vcc, 0x28550000, v12
	s_nop 1
	v_addc_co_u32_e32 v13, vcc, 0, v13, vcc
	global_load_dwordx2 v[74:75], v[12:13], off
	v_lshl_add_u64 v[12:13], v[82:83], 0, s[2:3]
	v_add_co_u32_e32 v12, vcc, 0x50000, v12
	s_nop 1
	v_addc_co_u32_e32 v13, vcc, 0, v13, vcc
	s_nop 0
	global_load_dwordx4 v[12:15], v[12:13], off
	s_and_saveexec_b64 s[62:63], s[38:39]
	s_cbranch_execz .LBB0_2359
	v_lshl_add_u64 v[16:17], v[86:87], 0, s[2:3]
	v_add_co_u32_e32 v16, vcc, 0x34850000, v16
	s_nop 1
	v_addc_co_u32_e32 v17, vcc, 0, v17, vcc
	global_load_dwordx4 v[16:19], v[16:17], off

; __device__ __forceinline__ unsigned cvt_pk_bf16(float lo, float hi) { unsigned r; asm volatile("v_cvt_pk_bf16_f32 %0, %1, %2" : "=v"(r) : "v"(lo), "v"(hi)); return r; }
; template <bool FULL>
; __device__ __forceinline__ void hgrn_mma(char* lds, int s, int w, int kc, int tq, const s16x4 vfrag, f32x4 (&S)[8], f32x4& o) {
;     const int buf = s & 1;
;     const char* QG = lds + QG_OFF + buf * 4352; const char* KG = lds + KG_OFF + buf * 4352; const char* KDT = lds + KDT_OFF + buf * 4096;
;     const float* DL = (const float*)(lds + DL_OFF + buf * 512); float* SSQP = (float*)(lds + SSQP_OFF + buf * 512);
;     o = (f32x4){0.f, 0.f, 0.f, 0.f};
;     if (FULL) {
;         f32x4 st = {0.f, 0.f, 0.f, 0.f};
; #pragma unroll
;         for (int ks = 0; ks < 4; ++ks) {
;             const bf16x8 qa = *(const bf16x8*)(QG + kc * ROWB + (32 * ks + 8 * tq) * 2), ka = *(const bf16x8*)(KG + kc * ROWB + (32 * ks + 8 * tq) * 2);
;             u32x4 sw; sw.x = cvt_pk_bf16(S[2 * ks][0], S[2 * ks][1]); sw.y = cvt_pk_bf16(S[2 * ks][2], S[2 * ks][3]);
;             sw.z = cvt_pk_bf16(S[2 * ks + 1][0], S[2 * ks + 1][1]); sw.w = cvt_pk_bf16(S[2 * ks + 1][2], S[2 * ks + 1][3]);
;             o = __builtin_amdgcn_mfma_f32_16x16x32_bf16(qa, *reinterpret_cast<bf16x8*>(&sw), o, 0, 0, 0);
;             st = __builtin_amdgcn_mfma_f32_16x16x32_bf16(ka, qa, st, 0, 0, 0); }
; #pragma unroll
;         for (int i = 0; i < 4; ++i) st[i] = (4 * tq + i <= kc) ? st[i] : 0.f;
;         u32x2 sp; sp.x = cvt_pk_bf16(st[0], st[1]); sp.y = cvt_pk_bf16(st[2], st[3]);
;         o = __builtin_amdgcn_mfma_f32_16x16x16bf16_1k(*reinterpret_cast<s16x4*>(&sp), vfrag, o, 0, 0, 0);
;     }
; #pragma unroll
;     for (int kb = 0; kb < 8; ++kb) { const f32x4 dlv = *(const f32x4*)(DL + 16 * kb + 4 * tq);
;         const s16x4 ka = *(const s16x4*)(KDT + ((16 * kb + kc) * 16 + 4 * tq) * 2);
;         S[kb] = __builtin_amdgcn_mfma_f32_16x16x16bf16_1k(ka, vfrag, S[kb] * dlv, 0, 0, 0); }
;     if (FULL) {
;         float ss[4];
; #pragma unroll
;         for (int i = 0; i < 4; ++i) ss[i] = row16_sum(o[i] * o[i]);
; #pragma unroll
;         for (int i = 0; i < 4; ++i) SSQP[(4 * tq + i) * 8 + w] = ss[i];
;     }
.LBB0_2360:
	s_waitcnt lgkmcnt(0)
	s_barrier
	s_nop 0
	v_cndmask_b32_e64 v60, 0, 1, s[52:53]
	s_andn2_b64 vcc, exec, s[36:37]
	v_cmp_ne_u32_e64 s[52:53], 1, v60
	s_cbranch_vccnz .LBB0_2379
	s_add_i32 s4, s87, 1
	s_and_b32 s5, s4, 1
	s_mul_i32 s6, s5, 0x1100
	v_add_u32_e32 v95, s6, v111
	ds_read_b128 v[60:63], v95
	ds_read_b128 v[64:67], v95 offset:8704
	s_nop 0
	v_cvt_pk_bf16_f32 v116, v52, v53
	v_cvt_pk_bf16_f32 v117, v54, v55
	v_cvt_pk_bf16_f32 v118, v28, v29
	v_cvt_pk_bf16_f32 v119, v30, v31
	ds_read_b128 v[120:123], v95 offset:64
	ds_read_b128 v[124:127], v95 offset:8768
	s_waitcnt lgkmcnt(3)
	v_mfma_f32_16x16x32_bf16 v[116:119], v[60:63], v[116:119], 0
	s_lshl_b32 s6, s5, 9
	v_lshl_add_u32 v128, s5, 12, v109
	s_and_b64 vcc, exec, s[52:53]
	s_waitcnt lgkmcnt(2)
	v_mfma_f32_16x16x32_bf16 v[60:63], v[64:67], v[60:63], 0
	v_cvt_pk_bf16_f32 v64, v32, v33
	v_cvt_pk_bf16_f32 v65, v34, v35
	v_cvt_pk_bf16_f32 v66, v36, v37
	v_cvt_pk_bf16_f32 v67, v38, v39
	s_waitcnt lgkmcnt(0)
	s_nop 0
	v_mfma_f32_16x16x32_bf16 v[60:63], v[124:127], v[120:123], v[60:63]
	v_mfma_f32_16x16x32_bf16 v[64:67], v[120:123], v[64:67], v[116:119]
	ds_read_b128 v[120:123], v95 offset:8832
	s_nop 1
	ds_read_b128 v[116:119], v95 offset:128
	v_cvt_pk_bf16_f32 v124, v56, v57
	v_cvt_pk_bf16_f32 v125, v58, v59
	v_cvt_pk_bf16_f32 v126, v40, v41
	s_nop 0
	v_cvt_pk_bf16_f32 v127, v42, v43
	s_waitcnt lgkmcnt(0)
	v_mfma_f32_16x16x32_bf16 v[60:63], v[120:123], v[116:119], v[60:63]
	v_mfma_f32_16x16x32_bf16 v[64:67], v[116:119], v[124:127], v[64:67]
	ds_read_b128 v[124:127], v95 offset:192
	ds_read_b128 v[116:119], v95 offset:8896
	v_cvt_pk_bf16_f32 v120, v44, v45
	s_waitcnt lgkmcnt(0)
	v_mfma_f32_16x16x32_bf16 v[60:63], v[116:119], v[124:127], v[60:63]
	v_cvt_pk_bf16_f32 v121, v46, v47
	v_cvt_pk_bf16_f32 v122, v48, v49
	v_cvt_pk_bf16_f32 v123, v50, v51
	s_nop 7
	v_cndmask_b32_e64 v60, v60, 0, s[42:43]
	v_cndmask_b32_e64 v61, 0, v61, s[44:45]
	v_cndmask_b32_e64 v62, v62, 0, s[46:47]
	v_cndmask_b32_e64 v63, v63, 0, s[48:49]
	v_add_u32_e32 v95, s6, v108
	v_mfma_f32_16x16x32_bf16 v[64:67], v[124:127], v[120:123], v[64:67]
	v_cvt_pk_bf16_f32 v96, v60, v61
	v_cvt_pk_bf16_f32 v97, v62, v63
	ds_read2st64_b64 v[60:63], v128 offset0:34 offset1:35
	ds_read_b128 v[116:119], v95 offset:25600
	ds_read_b128 v[120:123], v95 offset:25664
	ds_read_b128 v[124:127], v95 offset:25728
	v_mfma_f32_16x16x16_bf16 v[64:67], v[96:97], v[88:89], v[64:67]
	v_mov_b64_e32 v[96:97], v[92:93]
	s_waitcnt lgkmcnt(2)
	v_pk_mul_f32 v[54:55], v[54:55], v[118:119]
	v_pk_mul_f32 v[52:53], v[52:53], v[116:117]
	s_waitcnt lgkmcnt(1)
	v_pk_mul_f32 v[30:31], v[30:31], v[122:123]
	v_pk_mul_f32 v[28:29], v[28:29], v[120:121]
	v_mfma_f32_16x16x16_bf16 v[52:55], v[60:61], v[88:89], v[52:55]
	ds_read2st64_b64 v[116:119], v128 offset0:36 offset1:37
	s_waitcnt lgkmcnt(1)
	v_pk_mul_f32 v[34:35], v[34:35], v[126:127]
	v_pk_mul_f32 v[32:33], v[32:33], v[124:125]
	v_mfma_f32_16x16x16_bf16 v[28:31], v[62:63], v[88:89], v[28:31]
	ds_read_b128 v[60:63], v95 offset:25792
	ds_read2st64_b64 v[120:123], v128 offset0:38 offset1:39
	ds_read_b128 v[124:127], v95 offset:25856
	s_waitcnt lgkmcnt(2)
	v_pk_mul_f32 v[38:39], v[38:39], v[62:63]
	s_nop 0
	v_pk_mul_f32 v[36:37], v[36:37], v[60:61]
	ds_read_b128 v[60:63], v95 offset:25920
	s_waitcnt lgkmcnt(1)
	v_pk_mul_f32 v[58:59], v[58:59], v[126:127]
	v_pk_mul_f32 v[56:57], v[56:57], v[124:125]
	ds_read_b128 v[124:127], v95 offset:25984
	v_mfma_f32_16x16x16_bf16 v[32:35], v[116:117], v[88:89], v[32:35]
	s_waitcnt lgkmcnt(1)
	v_pk_mul_f32 v[42:43], v[42:43], v[62:63]
	v_pk_mul_f32 v[40:41], v[40:41], v[60:61]
	ds_read_b128 v[60:63], v95 offset:26048
	v_mfma_f32_16x16x16_bf16 v[36:39], v[118:119], v[88:89], v[36:39]
	ds_read2st64_b64 v[116:119], v128 offset0:40 offset1:41
	s_waitcnt lgkmcnt(2)
	v_pk_mul_f32 v[46:47], v[46:47], v[126:127]
	v_pk_mul_f32 v[44:45], v[44:45], v[124:125]
	s_waitcnt lgkmcnt(1)
	v_pk_mul_f32 v[48:49], v[48:49], v[60:61]
	v_mul_f32_e32 v60, v64, v64
	v_mov_b32_e32 v61, v3
	v_pk_mul_f32 v[50:51], v[50:51], v[62:63]
	v_mov_b32_e32 v62, v3
	v_mov_b32_dpp v61, v60 row_ror:8 row_mask:0xf bank_mask:0xf
	v_fmac_f32_e32 v61, v64, v64
	v_mov_b32_e32 v63, v3
	v_mov_b32_e32 v95, v3
	v_add_f32_dpp v60, v61, v61 row_ror:4 row_mask:0xf bank_mask:0xf bound_ctrl:1
	v_mul_f32_e32 v61, v65, v65
	v_mfma_f32_16x16x16_bf16 v[56:59], v[120:121], v[88:89], v[56:59]
	s_nop 0
	v_add_f32_dpp v60, v60, v60 row_ror:2 row_mask:0xf bank_mask:0xf bound_ctrl:1
	v_mov_b32_dpp v62, v61 row_ror:8 row_mask:0xf bank_mask:0xf
	v_fmac_f32_e32 v62, v65, v65
	v_mfma_f32_16x16x16_bf16 v[40:43], v[122:123], v[88:89], v[40:43]
	v_add_f32_dpp v60, v60, v60 row_ror:1 row_mask:0xf bank_mask:0xf bound_ctrl:1
	v_add_f32_dpp v61, v62, v62 row_ror:4 row_mask:0xf bank_mask:0xf bound_ctrl:1
	v_mul_f32_e32 v62, v66, v66
	s_waitcnt lgkmcnt(0)
	v_mfma_f32_16x16x16_bf16 v[44:47], v[116:117], v[88:89], v[44:47]
	s_nop 0
	v_add_f32_dpp v61, v61, v61 row_ror:2 row_mask:0xf bank_mask:0xf bound_ctrl:1
	v_mov_b32_dpp v63, v62 row_ror:8 row_mask:0xf bank_mask:0xf
	v_fmac_f32_e32 v63, v66, v66
	v_mfma_f32_16x16x16_bf16 v[48:51], v[118:119], v[88:89], v[48:51]
	v_add_f32_dpp v61, v61, v61 row_ror:1 row_mask:0xf bank_mask:0xf bound_ctrl:1
	v_add_f32_dpp v62, v63, v63 row_ror:4 row_mask:0xf bank_mask:0xf bound_ctrl:1
	v_mul_f32_e32 v63, v67, v67
	s_nop 0
	v_add_f32_dpp v62, v62, v62 row_ror:2 row_mask:0xf bank_mask:0xf bound_ctrl:1
	s_nop 0
	v_mov_b32_dpp v95, v63 row_ror:8 row_mask:0xf bank_mask:0xf
	v_fmac_f32_e32 v95, v67, v67
	v_add_f32_dpp v62, v62, v62 row_ror:1 row_mask:0xf bank_mask:0xf bound_ctrl:1
	s_nop 0
	v_add_f32_dpp v63, v95, v95 row_ror:4 row_mask:0xf bank_mask:0xf bound_ctrl:1
	v_add_u32_e32 v95, s6, v110
	v_add_u32_e32 v95, 0x6800, v95
	v_add_f32_dpp v63, v63, v63 row_ror:2 row_mask:0xf bank_mask:0xf bound_ctrl:1
	s_nop 1
	v_add_f32_dpp v63, v63, v63 row_ror:1 row_mask:0xf bank_mask:0xf bound_ctrl:1
	ds_write2_b32 v95, v60, v61 offset1:8
	ds_write2_b32 v95, v62, v63 offset0:16 offset1:24
	s_cbranch_vccnz .LBB0_2369
; __device__ __forceinline__ unsigned cvt_pk_bf16(float lo, float hi) { unsigned r; asm volatile("v_cvt_pk_bf16_f32 %0, %1, %2" : "=v"(r) : "v"(lo), "v"(hi)); return r; }
; __device__ __forceinline__ float bf2f(unsigned short b) { return __uint_as_float(((unsigned)b) << 16); }
; __device__ __forceinline__ float h2f(unsigned short u) { return (float)__builtin_bit_cast(_Float16, u); }
; template <bool FULL>
; __device__ __forceinline__ void hgrn_prep(char* lds, int s, int w, int kc, int tq, int kpos, float& gsum, s16x4& vfrag, u32x2& gvp) {
;     const int buf = s & 1;
;     char* QG = lds + QG_OFF + buf * 4352; char* KG = lds + KG_OFF + buf * 4352; char* KDT = lds + KDT_OFF + buf * 4096;
;     float* DL = (float*)(lds + DL_OFF + buf * 512);
;     const char* raw = lds + RAW_OFF + buf * RAW_SLOT;
;     float lf[4]; unsigned short qv[4], vv[4], gv[4];
; #pragma unroll
;     for (int j = 0; j < 4; ++j) { const int e = (4 * tq + j) * 128 + 16 * w + kc; lf[j] = h2f(*(const unsigned short*)(raw + e * 2)); vv[j] = *(const unsigned short*)(raw + 12288 + e * 2);
;         if (FULL) { qv[j] = *(const unsigned short*)(raw + 8192 + e * 2); gv[j] = *(const unsigned short*)(raw + 16384 + e * 2); } }
;     float G[4], glast;
;     { const float c0 = lf[0], c1 = c0 + lf[1], c2 = c1 + lf[2], c3 = c2 + lf[3];
;       float pre; row_prefix4(c3, tq, pre, glast);
;       G[0] = pre + c0; G[1] = pre + c1; G[2] = pre + c2; G[3] = pre + c3; }
;     float kd[4];
; #pragma unroll
;     for (int j = 0; j < 4; ++j) { const float kk = 1.f - __builtin_amdgcn_exp2f(lf[j]);
;         kd[j] = kk * __builtin_amdgcn_exp2f(glast - G[j]);
;         if (FULL) { const float qg = bf2f(qv[j]) * __builtin_amdgcn_exp2f(G[j]), kg = kk * __builtin_amdgcn_exp2f(fminf(-G[j], 115.f));
;             const unsigned qk = cvt_pk_bf16(qg, kg);
;             *(bf16*)(QG + (4 * tq + j) * ROWB + kpos * 2) = (bf16)(qk & 0xffffu);
;             *(bf16*)(KG + (4 * tq + j) * ROWB + kpos * 2) = (bf16)(qk >> 16); }
;         vfrag[j] = (short)vv[j]; }
;     { u32x2 kw; kw.x = cvt_pk_bf16(kd[0], kd[1]); kw.y = cvt_pk_bf16(kd[2], kd[3]); *(u32x2*)(KDT + ((16 * w + kc) * 16 + 4 * tq) * 2) = kw; }
;     DL[16 * w + kc] = __builtin_amdgcn_exp2f(glast);
;     gsum += glast;
;     if (FULL) { gvp.x = (unsigned)gv[0] | ((unsigned)gv[1] << 16); gvp.y = (unsigned)gv[2] | ((unsigned)gv[3] << 16); }
; }
	s_mul_i32 s5, s88, 0x5000
	v_add_u32_e32 v63, s5, v102
	ds_read_u16 v60, v63 offset:28672
	ds_read_u16 v61, v63 offset:28928
	ds_read_u16 v62, v63 offset:29184
	ds_read_u16 v88, v63 offset:29440
	v_cmp_lt_i32_e32 vcc, 0, v99
	s_waitcnt lgkmcnt(3)
	v_cvt_f32_f16_e32 v123, v60
	s_waitcnt lgkmcnt(2)
	v_cvt_f32_f16_e32 v121, v61
	s_waitcnt lgkmcnt(1)
	v_cvt_f32_f16_e32 v119, v62
	s_waitcnt lgkmcnt(0)
	v_cvt_f32_f16_e32 v117, v88
	ds_read_u16 v88, v63 offset:40960
	ds_read_u16 v126, v63 offset:36864
	ds_read_u16 v89, v63 offset:41216
	s_nop 0
	ds_read_u16 v122, v63 offset:37120
	ds_read_u16 v95, v63 offset:41472
	ds_read_u16 v120, v63 offset:37376
	ds_read_u16 v116, v63 offset:41728
	ds_read_u16 v118, v63 offset:37632
	ds_read_u16 v127, v63 offset:45056
	ds_read_u16 v128, v63 offset:45312
	ds_read_u16 v97, v63 offset:45568
	ds_read_u16 v129, v63 offset:45824
	v_add_f32_e32 v124, v123, v121
	v_add_f32_e32 v61, v124, v119
	v_add_f32_e32 v125, v61, v117
	v_mov_b32_e32 v96, v125
	v_mov_b32_e32 v60, v125
	s_nop 1
	v_permlane16_swap_b32_e32 v96, v60
	v_add_f32_e32 v60, v96, v60
	v_mov_b32_e32 v62, v60
	s_nop 1
	v_permlane32_swap_b32_e32 v60, v62
	v_mov_b32_e32 v63, 0
	s_and_saveexec_b64 s[36:37], vcc
	s_cbranch_execz .LBB0_2368
	v_cmp_ne_u32_e32 vcc, 1, v99
	s_and_saveexec_b64 s[6:7], vcc
	s_xor_b64 s[62:63], exec, s[6:7]
	v_add_f32_e32 v63, v96, v60
	v_cndmask_b32_e64 v63, v63, v60, s[50:51]
	s_andn2_saveexec_b64 s[62:63], s[62:63]
	v_mov_b32_e32 v63, v96
	s_or_b64 exec, exec, s[62:63]
.LBB0_2368:
	s_or_b64 exec, exec, s[36:37]
	s_waitcnt lgkmcnt(2)
	v_perm_b32 v96, v128, v127, s35
	v_add_f32_e32 v127, v63, v123
	v_exp_f32_e32 v123, v123
	s_nop 0
	v_pk_add_f32 v[60:61], v[60:61], v[62:63]
	v_add_f32_e32 v124, v124, v63
	v_add_f32_e32 v62, v125, v63
	v_sub_f32_e32 v63, 1.0, v123
	v_sub_f32_e32 v123, v60, v127
	v_exp_f32_e32 v125, v127
	v_min_f32_e64 v127, -v127, s74
	v_exp_f32_e32 v123, v123
	v_exp_f32_e32 v127, v127
	v_exp_f32_e32 v121, v121
	v_lshlrev_b32_e32 v126, 16, v126
	v_mul_f32_e32 v123, v63, v123
	v_mul_f32_e32 v125, v125, v126
	v_mul_f32_e32 v63, v63, v127
	v_cvt_pk_bf16_f32 v63, v125, v63
	v_add_u32_e32 v125, s89, v105
	ds_write_b16 v125, v63
	ds_write_b16_d16_hi v125, v63 offset:8704
	v_sub_f32_e32 v63, 1.0, v121
	v_sub_f32_e32 v121, v60, v124
	v_exp_f32_e32 v126, v124
	v_min_f32_e64 v124, -v124, s74
	v_exp_f32_e32 v121, v121
	v_exp_f32_e32 v124, v124
	v_exp_f32_e32 v119, v119
	v_lshlrev_b32_e32 v122, 16, v122
	v_mul_f32_e32 v121, v63, v121
	v_mul_f32_e32 v63, v63, v124
	v_mul_f32_e32 v122, v126, v122
	v_cvt_pk_bf16_f32 v63, v122, v63
	ds_write_b16 v125, v63 offset:272
	ds_write_b16_d16_hi v125, v63 offset:8976
	v_sub_f32_e32 v63, 1.0, v119
	v_sub_f32_e32 v119, v60, v61
	v_exp_f32_e32 v122, v61
	v_min_f32_e64 v61, -v61, s74
	v_exp_f32_e32 v119, v119
	v_exp_f32_e32 v61, v61
	v_lshlrev_b32_e32 v120, 16, v120
	v_mul_f32_e32 v120, v122, v120
	v_mul_f32_e32 v119, v63, v119
	v_mul_f32_e32 v61, v63, v61
	v_exp_f32_e32 v63, v117
	v_cvt_pk_bf16_f32 v61, v120, v61
	ds_write_b16 v125, v61 offset:544
	ds_write_b16_d16_hi v125, v61 offset:9248
	v_exp_f32_e32 v117, v62
	v_sub_f32_e32 v61, 1.0, v63
	v_sub_f32_e32 v63, v60, v62
	v_min_f32_e64 v62, -v62, s74
	v_exp_f32_e32 v63, v63
	v_exp_f32_e32 v62, v62
	v_lshlrev_b32_e32 v118, 16, v118
	v_exp_f32_e32 v60, v60
	v_mul_f32_e32 v63, v61, v63
	v_mul_f32_e32 v61, v61, v62
	v_mul_f32_e32 v117, v117, v118
	v_cvt_pk_bf16_f32 v61, v117, v61
	ds_write_b16 v125, v61 offset:816
	ds_write_b16_d16_hi v125, v61 offset:9520
	v_add_u32_e32 v61, s91, v106
	s_waitcnt lgkmcnt(8)
	s_nop 0
	v_perm_b32 v97, v129, v97, s35
	v_cvt_pk_bf16_f32 v62, v123, v121
	v_cvt_pk_bf16_f32 v63, v119, v63
	ds_write_b64 v61, v[62:63] offset:17408
	v_add_u32_e32 v61, s90, v107
	v_perm_b32 v88, v89, v88, s35
	v_perm_b32 v89, v116, v95, s35
	ds_write_b32 v61, v60 offset:25600
; __device__ __forceinline__ unsigned cvt_pk_bf16(float lo, float hi) { unsigned r; asm volatile("v_cvt_pk_bf16_f32 %0, %1, %2" : "=v"(r) : "v"(lo), "v"(hi)); return r; }
; __device__ __forceinline__ void hgrn_fin(char* lds, int s, int w, int kc, int tq, int ch, int row0, float gn, const f32x4 o, const u32x2 gvp, bf16* __restrict__ O) {
;     const float* SSQP = (const float*)(lds + SSQP_OFF + (s & 1) * 512);
; #pragma unroll
;     for (int i = 0; i < 4; ++i) { const float part = SSQP[(4 * tq + i) * 8 + (kc & 7)];
;         const float tot = row16_sum(kc < 8 ? part : 0.f);
;         const float rs = __builtin_amdgcn_rsqf(tot * (1.f / 128.f) + EPS);
;         const unsigned gw_ = i < 2 ? gvp.x : gvp.y; const float gate = __uint_as_float((i & 1) ? (gw_ & 0xffff0000u) : (gw_ << 16));
;         const float ov = o[i] * rs * gn * gate;
;         O[(size_t)(row0 + 16 * s + 4 * tq + i) * D + ch] = (bf16)(cvt_pk_bf16(ov, 0.f) & 0xffffu); }
; }
.LBB0_2369:
	s_nop 0
	s_and_b32 s5, s10, 0x200
	v_add_u32_e32 v62, s5, v103
	ds_read_b32 v60, v62 offset:26624
	v_lshlrev_b32_e32 v61, 16, v90
	v_ashrrev_i32_e32 v95, 31, v94
	s_cmp_gt_u32 s87, 60
	s_waitcnt lgkmcnt(0)
	v_cndmask_b32_e64 v60, 0, v60, s[40:41]
	s_nop 1
	v_add_f32_dpp v60, v60, v60 row_ror:8 row_mask:0xf bank_mask:0xf bound_ctrl:1
	s_nop 1
	s_nop 0
	v_add_f32_dpp v60, v60, v60 row_ror:4 row_mask:0xf bank_mask:0xf bound_ctrl:1
	s_nop 1
	v_add_f32_dpp v60, v60, v60 row_ror:2 row_mask:0xf bank_mask:0xf bound_ctrl:1
	s_nop 1
	v_add_f32_dpp v60, v60, v60 row_ror:1 row_mask:0xf bank_mask:0xf bound_ctrl:1
	v_fmamk_f32 v60, v60, 0x3c000000, v198
	v_rsq_f32_e32 v60, v60
	s_nop 0
	v_mul_f32_e32 v60, v68, v60
	v_mul_f32_e32 v60, v98, v60
	v_mul_f32_e32 v60, v60, v61
	s_nop 0
	v_cvt_pk_bf16_f32 v63, v60, v3
	v_lshlrev_b64 v[60:61], 12, v[94:95]
	v_lshl_add_u64 v[60:61], v[72:73], 0, v[60:61]
	global_store_short v[60:61], v63, off
	ds_read_b32 v60, v62 offset:26656
	v_and_b32_e32 v61, 0xffff0000, v90
	s_waitcnt lgkmcnt(0)
	v_cndmask_b32_e64 v60, 0, v60, s[40:41]
	s_nop 1
	v_add_f32_dpp v60, v60, v60 row_ror:8 row_mask:0xf bank_mask:0xf bound_ctrl:1
	s_nop 1
	v_add_f32_dpp v60, v60, v60 row_ror:4 row_mask:0xf bank_mask:0xf bound_ctrl:1
	s_nop 1
	v_add_f32_dpp v60, v60, v60 row_ror:2 row_mask:0xf bank_mask:0xf bound_ctrl:1
	s_nop 1
	v_add_f32_dpp v60, v60, v60 row_ror:1 row_mask:0xf bank_mask:0xf bound_ctrl:1
	v_fmamk_f32 v60, v60, 0x3c000000, v198
	v_rsq_f32_e32 v60, v60
	s_nop 0
	v_mul_f32_e32 v60, v69, v60
	v_mul_f32_e32 v60, v98, v60
	v_mul_f32_e32 v60, v60, v61
	v_cvt_pk_bf16_f32 v63, v60, v3
	v_add_u32_e32 v60, 1, v94
	v_ashrrev_i32_e32 v61, 31, v60
	v_lshlrev_b64 v[60:61], 12, v[60:61]
	v_lshl_add_u64 v[60:61], v[72:73], 0, v[60:61]
	global_store_short v[60:61], v63, off
	ds_read_b32 v60, v62 offset:26688
	v_lshlrev_b32_e32 v61, 16, v91
	s_waitcnt lgkmcnt(0)
	v_cndmask_b32_e64 v60, 0, v60, s[40:41]
	s_nop 1
	v_add_f32_dpp v60, v60, v60 row_ror:8 row_mask:0xf bank_mask:0xf bound_ctrl:1
	s_nop 1
	v_add_f32_dpp v60, v60, v60 row_ror:4 row_mask:0xf bank_mask:0xf bound_ctrl:1
	s_nop 1
	v_add_f32_dpp v60, v60, v60 row_ror:2 row_mask:0xf bank_mask:0xf bound_ctrl:1
	s_nop 1
	v_add_f32_dpp v60, v60, v60 row_ror:1 row_mask:0xf bank_mask:0xf bound_ctrl:1
	v_fmamk_f32 v60, v60, 0x3c000000, v198
	v_rsq_f32_e32 v60, v60
	s_nop 0
	v_mul_f32_e32 v60, v70, v60
	v_mul_f32_e32 v60, v98, v60
	v_mul_f32_e32 v60, v60, v61
	v_cvt_pk_bf16_f32 v63, v60, v3
	v_add_u32_e32 v60, 2, v94
	v_ashrrev_i32_e32 v61, 31, v60
	v_lshlrev_b64 v[60:61], 12, v[60:61]
	v_lshl_add_u64 v[60:61], v[72:73], 0, v[60:61]
	global_store_short v[60:61], v63, off
	s_nop 0
	ds_read_b32 v60, v62 offset:26720
	v_and_b32_e32 v61, 0xffff0000, v91
	s_waitcnt lgkmcnt(0)
	v_cndmask_b32_e64 v60, 0, v60, s[40:41]
	s_nop 1
	v_add_f32_dpp v60, v60, v60 row_ror:8 row_mask:0xf bank_mask:0xf bound_ctrl:1
	s_nop 1
	v_add_f32_dpp v60, v60, v60 row_ror:4 row_mask:0xf bank_mask:0xf bound_ctrl:1
	s_nop 1
	v_add_f32_dpp v60, v60, v60 row_ror:2 row_mask:0xf bank_mask:0xf bound_ctrl:1
	s_nop 1
	v_add_f32_dpp v60, v60, v60 row_ror:1 row_mask:0xf bank_mask:0xf bound_ctrl:1
	v_fmamk_f32 v60, v60, 0x3c000000, v198
	v_rsq_f32_e32 v60, v60
	s_nop 0
	v_mul_f32_e32 v60, v71, v60
	v_mul_f32_e32 v60, v98, v60
	v_mul_f32_e32 v60, v60, v61
	v_cvt_pk_bf16_f32 v62, v60, v3
	v_add_u32_e32 v60, 3, v94
	v_ashrrev_i32_e32 v61, 31, v60
	v_lshlrev_b64 v[60:61], 12, v[60:61]
	v_lshl_add_u64 v[60:61], v[72:73], 0, v[60:61]
	global_store_short v[60:61], v62, off
	s_cbranch_scc1 .LBB0_2373
	s_bitcmp1_b32 s4, 0
	s_cselect_b32 s4, 0x5000, 0
	s_add_i32 s4, s4, 0
	v_add_u32_e32 v60, s4, v100
	s_waitcnt vmcnt(5)
	ds_write_b64 v60, v[76:77] offset:28672
	s_waitcnt vmcnt(4)
	v_mov_b64_e32 v[62:63], v[22:23]
	s_nop 0
	v_mov_b32_e32 v68, 0x3000
	v_mov_b64_e32 v[60:61], v[20:21]
	s_and_saveexec_b64 s[36:37], s[38:39]
	v_add_u32_e32 v60, s4, v101
	ds_write_b128 v60, v[20:23] offset:36864
	v_mov_b64_e32 v[62:63], v[6:7]
	v_mov_b32_e32 v68, 0x4000
	v_mov_b64_e32 v[60:61], v[4:5]
	s_or_b64 exec, exec, s[36:37]
	v_add3_u32 v68, s4, v68, v101
	ds_write_b128 v68, v[60:63] offset:28672

; __device__ __forceinline__ unsigned cvt_pk_bf16(float lo, float hi) { unsigned r; asm volatile("v_cvt_pk_bf16_f32 %0, %1, %2" : "=v"(r) : "v"(lo), "v"(hi)); return r; }
; template <bool FULL>
; __device__ __forceinline__ void hgrn_mma(char* lds, int s, int w, int kc, int tq, const s16x4 vfrag, f32x4 (&S)[8], f32x4& o) {
;     const int buf = s & 1;
;     const char* QG = lds + QG_OFF + buf * 4352; const char* KG = lds + KG_OFF + buf * 4352; const char* KDT = lds + KDT_OFF + buf * 4096;
;     const float* DL = (const float*)(lds + DL_OFF + buf * 512); float* SSQP = (float*)(lds + SSQP_OFF + buf * 512);
;     o = (f32x4){0.f, 0.f, 0.f, 0.f};
;     if (FULL) {
;         f32x4 st = {0.f, 0.f, 0.f, 0.f};
; #pragma unroll
;         for (int ks = 0; ks < 4; ++ks) {
;             const bf16x8 qa = *(const bf16x8*)(QG + kc * ROWB + (32 * ks + 8 * tq) * 2), ka = *(const bf16x8*)(KG + kc * ROWB + (32 * ks + 8 * tq) * 2);
;             u32x4 sw; sw.x = cvt_pk_bf16(S[2 * ks][0], S[2 * ks][1]); sw.y = cvt_pk_bf16(S[2 * ks][2], S[2 * ks][3]);
;             sw.z = cvt_pk_bf16(S[2 * ks + 1][0], S[2 * ks + 1][1]); sw.w = cvt_pk_bf16(S[2 * ks + 1][2], S[2 * ks + 1][3]);
;             o = __builtin_amdgcn_mfma_f32_16x16x32_bf16(qa, *reinterpret_cast<bf16x8*>(&sw), o, 0, 0, 0);
;             st = __builtin_amdgcn_mfma_f32_16x16x32_bf16(ka, qa, st, 0, 0, 0); }
; #pragma unroll
;         for (int i = 0; i < 4; ++i) st[i] = (4 * tq + i <= kc) ? st[i] : 0.f;
;         u32x2 sp; sp.x = cvt_pk_bf16(st[0], st[1]); sp.y = cvt_pk_bf16(st[2], st[3]);
;         o = __builtin_amdgcn_mfma_f32_16x16x16bf16_1k(*reinterpret_cast<s16x4*>(&sp), vfrag, o, 0, 0, 0);
;     }
; #pragma unroll
;     for (int kb = 0; kb < 8; ++kb) { const f32x4 dlv = *(const f32x4*)(DL + 16 * kb + 4 * tq);
;         const s16x4 ka = *(const s16x4*)(KDT + ((16 * kb + kc) * 16 + 4 * tq) * 2);
;         S[kb] = __builtin_amdgcn_mfma_f32_16x16x16bf16_1k(ka, vfrag, S[kb] * dlv, 0, 0, 0); }
;     if (FULL) {
;         float ss[4];
; #pragma unroll
;         for (int i = 0; i < 4; ++i) ss[i] = row16_sum(o[i] * o[i]);
; #pragma unroll
;         for (int i = 0; i < 4; ++i) SSQP[(4 * tq + i) * 8 + w] = ss[i];
;     }
.LBB0_2380:
	s_nop 0
	ds_read_b128 v[60:63], v114
	ds_read_b128 v[68:71], v114 offset:8704
	v_cvt_pk_bf16_f32 v116, v52, v53
	v_cvt_pk_bf16_f32 v117, v54, v55
	v_cvt_pk_bf16_f32 v118, v28, v29
	v_cvt_pk_bf16_f32 v119, v30, v31
	ds_read_b128 v[120:123], v114 offset:64
	ds_read_b128 v[124:127], v114 offset:8768
	s_waitcnt lgkmcnt(3)
	v_mfma_f32_16x16x32_bf16 v[116:119], v[60:63], v[116:119], 0
	s_cmpk_eq_i32 s86, 0x3d0
	v_mov_b64_e32 v[92:93], v[96:97]
	s_waitcnt lgkmcnt(2)
	v_mfma_f32_16x16x32_bf16 v[60:63], v[68:71], v[60:63], 0
	v_cvt_pk_bf16_f32 v68, v32, v33
	v_cvt_pk_bf16_f32 v69, v34, v35
	v_cvt_pk_bf16_f32 v70, v36, v37
	v_cvt_pk_bf16_f32 v71, v38, v39
	s_waitcnt lgkmcnt(0)
	v_mfma_f32_16x16x32_bf16 v[60:63], v[124:127], v[120:123], v[60:63]
	v_mfma_f32_16x16x32_bf16 v[68:71], v[120:123], v[68:71], v[116:119]
	ds_read_b128 v[120:123], v114 offset:8832
	s_nop 1
	ds_read_b128 v[116:119], v114 offset:128
	v_cvt_pk_bf16_f32 v124, v56, v57
	v_cvt_pk_bf16_f32 v125, v58, v59
	v_cvt_pk_bf16_f32 v126, v40, v41
	v_cvt_pk_bf16_f32 v127, v42, v43
	s_waitcnt lgkmcnt(0)
	v_mfma_f32_16x16x32_bf16 v[60:63], v[120:123], v[116:119], v[60:63]
	v_mfma_f32_16x16x32_bf16 v[68:71], v[116:119], v[124:127], v[68:71]
	ds_read_b128 v[124:127], v114 offset:192
	ds_read_b128 v[116:119], v114 offset:8896
	v_cvt_pk_bf16_f32 v120, v44, v45
	s_waitcnt lgkmcnt(0)
	v_mfma_f32_16x16x32_bf16 v[60:63], v[116:119], v[124:127], v[60:63]
	v_cvt_pk_bf16_f32 v121, v46, v47
	v_cvt_pk_bf16_f32 v122, v48, v49
	v_cvt_pk_bf16_f32 v123, v50, v51
	s_nop 7
	v_cndmask_b32_e64 v60, v60, 0, s[42:43]
	v_mfma_f32_16x16x32_bf16 v[68:71], v[124:127], v[120:123], v[68:71]
	v_cndmask_b32_e64 v61, 0, v61, s[44:45]
	v_cndmask_b32_e64 v62, v62, 0, s[46:47]
	s_nop 0
	v_cndmask_b32_e64 v63, v63, 0, s[48:49]
	v_cvt_pk_bf16_f32 v60, v60, v61
	v_cvt_pk_bf16_f32 v61, v62, v63
	ds_read2st64_b64 v[116:119], v113 offset0:34 offset1:35
	ds_read_b128 v[120:123], v2 offset:25600
	v_mfma_f32_16x16x16_bf16 v[60:63], v[60:61], v[88:89], v[68:71]
	ds_read_b128 v[124:127], v2 offset:25728
	s_waitcnt lgkmcnt(1)
	s_nop 0
	v_pk_mul_f32 v[52:53], v[52:53], v[120:121]
	ds_read_b128 v[68:71], v2 offset:25664
	v_pk_mul_f32 v[54:55], v[54:55], v[122:123]
	ds_read2st64_b64 v[120:123], v113 offset0:36 offset1:37
	s_waitcnt lgkmcnt(2)
	v_pk_mul_f32 v[32:33], v[32:33], v[124:125]
	v_mfma_f32_16x16x16_bf16 v[52:55], v[116:117], v[88:89], v[52:55]
	s_waitcnt lgkmcnt(1)
	v_pk_mul_f32 v[28:29], v[28:29], v[68:69]
	v_pk_mul_f32 v[30:31], v[30:31], v[70:71]
	ds_read_b128 v[68:71], v2 offset:25792
	v_pk_mul_f32 v[34:35], v[34:35], v[126:127]
	v_mfma_f32_16x16x16_bf16 v[28:31], v[118:119], v[88:89], v[28:31]
	ds_read2st64_b64 v[116:119], v113 offset0:38 offset1:39
	ds_read_b128 v[124:127], v2 offset:25856
	s_waitcnt lgkmcnt(2)
	v_pk_mul_f32 v[36:37], v[36:37], v[68:69]
	s_nop 0
	v_pk_mul_f32 v[38:39], v[38:39], v[70:71]
	ds_read_b128 v[68:71], v2 offset:25920
	s_waitcnt lgkmcnt(1)
	v_pk_mul_f32 v[56:57], v[56:57], v[124:125]
	v_pk_mul_f32 v[58:59], v[58:59], v[126:127]
	ds_read_b128 v[124:127], v2 offset:25984
	v_mfma_f32_16x16x16_bf16 v[32:35], v[120:121], v[88:89], v[32:35]
	s_waitcnt lgkmcnt(1)
	v_pk_mul_f32 v[40:41], v[40:41], v[68:69]
	v_pk_mul_f32 v[42:43], v[42:43], v[70:71]
	ds_read_b128 v[68:71], v2 offset:26048
	v_mul_f32_e32 v2, v60, v60
	v_mfma_f32_16x16x16_bf16 v[36:39], v[122:123], v[88:89], v[36:39]
	ds_read2st64_b64 v[120:123], v113 offset0:40 offset1:41
	s_waitcnt lgkmcnt(2)
	v_pk_mul_f32 v[44:45], v[44:45], v[124:125]
	s_waitcnt lgkmcnt(1)
	v_pk_mul_f32 v[48:49], v[48:49], v[68:69]
	v_mov_b32_e32 v68, v3
	v_mov_b32_e32 v69, v3
	v_pk_mul_f32 v[50:51], v[50:51], v[70:71]
	v_mov_b32_dpp v68, v2 row_ror:8 row_mask:0xf bank_mask:0xf
	v_fmac_f32_e32 v68, v60, v60
	v_mov_b32_e32 v70, v3
	v_pk_mul_f32 v[46:47], v[46:47], v[126:127]
	v_add_f32_dpp v2, v68, v68 row_ror:4 row_mask:0xf bank_mask:0xf bound_ctrl:1
	v_mul_f32_e32 v68, v61, v61
	v_mov_b32_e32 v71, v3
	v_mfma_f32_16x16x16_bf16 v[56:59], v[116:117], v[88:89], v[56:59]
	s_nop 0
	v_mov_b32_dpp v69, v68 row_ror:8 row_mask:0xf bank_mask:0xf
	v_fmac_f32_e32 v69, v61, v61
	v_add_f32_dpp v2, v2, v2 row_ror:2 row_mask:0xf bank_mask:0xf bound_ctrl:1
	v_mfma_f32_16x16x16_bf16 v[40:43], v[118:119], v[88:89], v[40:43]
	v_add_f32_dpp v68, v69, v69 row_ror:4 row_mask:0xf bank_mask:0xf bound_ctrl:1
	v_mul_f32_e32 v69, v62, v62
	v_add_f32_dpp v2, v2, v2 row_ror:1 row_mask:0xf bank_mask:0xf bound_ctrl:1
	s_waitcnt lgkmcnt(0)
	v_mfma_f32_16x16x16_bf16 v[44:47], v[120:121], v[88:89], v[44:47]
	s_nop 0
	v_mov_b32_dpp v70, v69 row_ror:8 row_mask:0xf bank_mask:0xf
	v_fmac_f32_e32 v70, v62, v62
	v_add_f32_dpp v68, v68, v68 row_ror:2 row_mask:0xf bank_mask:0xf bound_ctrl:1
	v_mfma_f32_16x16x16_bf16 v[48:51], v[122:123], v[88:89], v[48:51]
	v_add_f32_dpp v69, v70, v70 row_ror:4 row_mask:0xf bank_mask:0xf bound_ctrl:1
	v_mul_f32_e32 v70, v63, v63
	v_add_f32_dpp v68, v68, v68 row_ror:1 row_mask:0xf bank_mask:0xf bound_ctrl:1
	v_add_f32_dpp v69, v69, v69 row_ror:2 row_mask:0xf bank_mask:0xf bound_ctrl:1
	v_mov_b32_dpp v71, v70 row_ror:8 row_mask:0xf bank_mask:0xf
	v_fmac_f32_e32 v71, v63, v63
	v_add_f32_dpp v69, v69, v69 row_ror:1 row_mask:0xf bank_mask:0xf bound_ctrl:1
	s_nop 0
	v_add_f32_dpp v70, v71, v71 row_ror:4 row_mask:0xf bank_mask:0xf bound_ctrl:1
	s_nop 1
	v_add_f32_dpp v70, v70, v70 row_ror:2 row_mask:0xf bank_mask:0xf bound_ctrl:1
	s_nop 1
	v_add_f32_dpp v70, v70, v70 row_ror:1 row_mask:0xf bank_mask:0xf bound_ctrl:1
	ds_write2_b32 v115, v2, v68 offset1:8
	ds_write2_b32 v115, v69, v70 offset0:16 offset1:24
	s_cbranch_scc1 .LBB0_2388
; __device__ __forceinline__ unsigned cvt_pk_bf16(float lo, float hi) { unsigned r; asm volatile("v_cvt_pk_bf16_f32 %0, %1, %2" : "=v"(r) : "v"(lo), "v"(hi)); return r; }
; __device__ __forceinline__ float bf2f(unsigned short b) { return __uint_as_float(((unsigned)b) << 16); }
; __device__ __forceinline__ float h2f(unsigned short u) { return (float)__builtin_bit_cast(_Float16, u); }
; template <bool FULL>
; __device__ __forceinline__ void hgrn_prep(char* lds, int s, int w, int kc, int tq, int kpos, float& gsum, s16x4& vfrag, u32x2& gvp) {
;     const int buf = s & 1;
;     char* QG = lds + QG_OFF + buf * 4352; char* KG = lds + KG_OFF + buf * 4352; char* KDT = lds + KDT_OFF + buf * 4096;
;     float* DL = (float*)(lds + DL_OFF + buf * 512);
;     const char* raw = lds + RAW_OFF + buf * RAW_SLOT;
;     float lf[4]; unsigned short qv[4], vv[4], gv[4];
; #pragma unroll
;     for (int j = 0; j < 4; ++j) { const int e = (4 * tq + j) * 128 + 16 * w + kc; lf[j] = h2f(*(const unsigned short*)(raw + e * 2)); vv[j] = *(const unsigned short*)(raw + 12288 + e * 2);
;         if (FULL) { qv[j] = *(const unsigned short*)(raw + 8192 + e * 2); gv[j] = *(const unsigned short*)(raw + 16384 + e * 2); } }
;     float G[4], glast;
;     { const float c0 = lf[0], c1 = c0 + lf[1], c2 = c1 + lf[2], c3 = c2 + lf[3];
;       float pre; row_prefix4(c3, tq, pre, glast);
;       G[0] = pre + c0; G[1] = pre + c1; G[2] = pre + c2; G[3] = pre + c3; }
;     float kd[4];
; #pragma unroll
;     for (int j = 0; j < 4; ++j) { const float kk = 1.f - __builtin_amdgcn_exp2f(lf[j]);
;         kd[j] = kk * __builtin_amdgcn_exp2f(glast - G[j]);
;         if (FULL) { const float qg = bf2f(qv[j]) * __builtin_amdgcn_exp2f(G[j]), kg = kk * __builtin_amdgcn_exp2f(fminf(-G[j], 115.f));
;             const unsigned qk = cvt_pk_bf16(qg, kg);
;             *(bf16*)(QG + (4 * tq + j) * ROWB + kpos * 2) = (bf16)(qk & 0xffffu);
;             *(bf16*)(KG + (4 * tq + j) * ROWB + kpos * 2) = (bf16)(qk >> 16); }
;         vfrag[j] = (short)vv[j]; }
;     { u32x2 kw; kw.x = cvt_pk_bf16(kd[0], kd[1]); kw.y = cvt_pk_bf16(kd[2], kd[3]); *(u32x2*)(KDT + ((16 * w + kc) * 16 + 4 * tq) * 2) = kw; }
;     DL[16 * w + kc] = __builtin_amdgcn_exp2f(glast);
;     gsum += glast;
;     if (FULL) { gvp.x = (unsigned)gv[0] | ((unsigned)gv[1] << 16); gvp.y = (unsigned)gv[2] | ((unsigned)gv[3] << 16); }
; }
	s_xor_b32 s4, s88, 1
	s_mul_i32 s5, s4, 0x5000
	v_add_u32_e32 v71, s5, v102
	ds_read_u16 v2, v71 offset:28672
	ds_read_u16 v68, v71 offset:28928
	ds_read_u16 v69, v71 offset:29184
	ds_read_u16 v70, v71 offset:29440
	v_cmp_lt_i32_e32 vcc, 0, v99
	s_waitcnt lgkmcnt(3)
	v_cvt_f32_f16_e32 v119, v2
	s_waitcnt lgkmcnt(2)
	v_cvt_f32_f16_e32 v117, v68
	s_waitcnt lgkmcnt(1)
	v_cvt_f32_f16_e32 v115, v69
	s_waitcnt lgkmcnt(0)
	v_cvt_f32_f16_e32 v113, v70
	v_add_f32_e32 v120, v119, v117
	v_add_f32_e32 v69, v120, v115
	v_add_f32_e32 v121, v69, v113
	v_mov_b32_e32 v92, v121
	v_mov_b32_e32 v2, v121
	s_nop 1
	v_permlane16_swap_b32_e32 v92, v2
	v_add_f32_e32 v68, v92, v2
	ds_read_u16 v2, v71 offset:40960
	ds_read_u16 v122, v71 offset:36864
	ds_read_u16 v88, v71 offset:41216
	ds_read_u16 v118, v71 offset:37120
	ds_read_u16 v89, v71 offset:41472
	ds_read_u16 v116, v71 offset:37376
	ds_read_u16 v95, v71 offset:41728
	ds_read_u16 v114, v71 offset:37632
	ds_read_u16 v123, v71 offset:45056
	ds_read_u16 v124, v71 offset:45312
	ds_read_u16 v93, v71 offset:45568
	ds_read_u16 v125, v71 offset:45824
	v_mov_b32_e32 v70, v68
	s_nop 1
	v_permlane32_swap_b32_e32 v68, v70
	v_mov_b32_e32 v71, 0
	s_and_saveexec_b64 s[36:37], vcc
	s_cbranch_execz .LBB0_2387
	v_cmp_ne_u32_e32 vcc, 1, v99
	s_and_saveexec_b64 s[6:7], vcc
	s_xor_b64 s[52:53], exec, s[6:7]
	v_add_f32_e32 v71, v92, v68
	v_cndmask_b32_e64 v71, v71, v68, s[50:51]
	s_andn2_saveexec_b64 s[52:53], s[52:53]
	v_mov_b32_e32 v71, v92
	s_or_b64 exec, exec, s[52:53]
.LBB0_2387:
	s_or_b64 exec, exec, s[36:37]
	s_waitcnt lgkmcnt(2)
	v_perm_b32 v92, v124, v123, s35
	v_add_f32_e32 v123, v71, v119
	v_exp_f32_e32 v119, v119
	v_pk_add_f32 v[68:69], v[68:69], v[70:71]
	v_add_f32_e32 v120, v120, v71
	v_add_f32_e32 v70, v121, v71
	v_sub_f32_e32 v71, 1.0, v119
	v_sub_f32_e32 v119, v68, v123
	v_exp_f32_e32 v121, v123
	v_min_f32_e64 v123, -v123, s74
	v_exp_f32_e32 v119, v119
	v_exp_f32_e32 v123, v123
	v_exp_f32_e32 v117, v117
	v_lshlrev_b32_e32 v122, 16, v122
	s_mul_i32 s5, s4, 0x1100
	v_mul_f32_e32 v119, v71, v119
	v_mul_f32_e32 v121, v121, v122
	v_mul_f32_e32 v71, v71, v123
	v_cvt_pk_bf16_f32 v71, v121, v71
	v_add_u32_e32 v121, s5, v105
	ds_write_b16 v121, v71
	ds_write_b16_d16_hi v121, v71 offset:8704
	v_sub_f32_e32 v71, 1.0, v117
	v_sub_f32_e32 v117, v68, v120
	v_exp_f32_e32 v122, v120
	v_min_f32_e64 v120, -v120, s74
	v_exp_f32_e32 v117, v117
	v_exp_f32_e32 v120, v120
	v_exp_f32_e32 v115, v115
	v_lshlrev_b32_e32 v118, 16, v118
	v_mul_f32_e32 v117, v71, v117
	v_mul_f32_e32 v71, v71, v120
	v_mul_f32_e32 v118, v122, v118
	v_cvt_pk_bf16_f32 v71, v118, v71
	ds_write_b16 v121, v71 offset:272
	ds_write_b16_d16_hi v121, v71 offset:8976
	v_sub_f32_e32 v71, 1.0, v115
	v_sub_f32_e32 v115, v68, v69
	v_exp_f32_e32 v118, v69
	v_min_f32_e64 v69, -v69, s74
	v_exp_f32_e32 v115, v115
	v_exp_f32_e32 v69, v69
	v_lshlrev_b32_e32 v116, 16, v116
	v_mul_f32_e32 v116, v118, v116
	v_mul_f32_e32 v115, v71, v115
	v_mul_f32_e32 v69, v71, v69
	v_exp_f32_e32 v71, v113
	v_cvt_pk_bf16_f32 v69, v116, v69
	ds_write_b16 v121, v69 offset:544
	ds_write_b16_d16_hi v121, v69 offset:9248
	v_exp_f32_e32 v113, v70
	v_sub_f32_e32 v69, 1.0, v71
	v_sub_f32_e32 v71, v68, v70
	v_min_f32_e64 v70, -v70, s74
	v_exp_f32_e32 v71, v71
	v_exp_f32_e32 v70, v70
	v_lshlrev_b32_e32 v114, 16, v114
	v_exp_f32_e32 v68, v68
	v_mul_f32_e32 v71, v69, v71
	v_mul_f32_e32 v69, v69, v70
	v_mul_f32_e32 v113, v113, v114
	v_cvt_pk_bf16_f32 v69, v113, v69
	ds_write_b16 v121, v69 offset:816
	ds_write_b16_d16_hi v121, v69 offset:9520
	v_lshl_add_u32 v69, s4, 12, v106
	s_waitcnt lgkmcnt(8)
	v_perm_b32 v93, v125, v93, s35
	s_nop 0
	v_cvt_pk_bf16_f32 v70, v119, v117
	v_cvt_pk_bf16_f32 v71, v115, v71
	ds_write_b64 v69, v[70:71] offset:17408
	v_lshl_add_u32 v69, s4, 9, v107
	v_perm_b32 v88, v88, v2, s35
	v_perm_b32 v89, v95, v89, s35
	ds_write_b32 v69, v68 offset:25600
; __device__ __forceinline__ unsigned cvt_pk_bf16(float lo, float hi) { unsigned r; asm volatile("v_cvt_pk_bf16_f32 %0, %1, %2" : "=v"(r) : "v"(lo), "v"(hi)); return r; }
; __device__ __forceinline__ void hgrn_fin(char* lds, int s, int w, int kc, int tq, int ch, int row0, float gn, const f32x4 o, const u32x2 gvp, bf16* __restrict__ O) {
;     const float* SSQP = (const float*)(lds + SSQP_OFF + (s & 1) * 512);
; #pragma unroll
;     for (int i = 0; i < 4; ++i) { const float part = SSQP[(4 * tq + i) * 8 + (kc & 7)];
;         const float tot = row16_sum(kc < 8 ? part : 0.f);
;         const float rs = __builtin_amdgcn_rsqf(tot * (1.f / 128.f) + EPS);
;         const unsigned gw_ = i < 2 ? gvp.x : gvp.y; const float gate = __uint_as_float((i & 1) ? (gw_ & 0xffff0000u) : (gw_ << 16));
;         const float ov = o[i] * rs * gn * gate;
;         O[(size_t)(row0 + 16 * s + 4 * tq + i) * D + ch] = (bf16)(cvt_pk_bf16(ov, 0.f) & 0xffffu); }
; }
.LBB0_2388:
	s_add_i32 s4, s10, 0x200
	s_and_b32 s4, s4, 0x200
	v_add_u32_e32 v2, s4, v103
	ds_read_b32 v69, v2 offset:26624
	v_add_u32_e32 v68, 16, v94
	v_lshlrev_b32_e32 v70, 16, v90
	s_cmp_gt_u32 s87, 59
	s_mov_b64 s[88:89], 0x800
	s_waitcnt lgkmcnt(0)
	v_cndmask_b32_e64 v69, 0, v69, s[40:41]
	s_nop 1
	v_add_f32_dpp v69, v69, v69 row_ror:8 row_mask:0xf bank_mask:0xf bound_ctrl:1
	s_nop 1
	v_add_f32_dpp v69, v69, v69 row_ror:4 row_mask:0xf bank_mask:0xf bound_ctrl:1
	s_nop 1
	v_add_f32_dpp v69, v69, v69 row_ror:2 row_mask:0xf bank_mask:0xf bound_ctrl:1
	s_nop 1
	v_add_f32_dpp v69, v69, v69 row_ror:1 row_mask:0xf bank_mask:0xf bound_ctrl:1
	v_fmamk_f32 v69, v69, 0x3c000000, v198
	v_rsq_f32_e32 v69, v69
	s_nop 0
	v_mul_f32_e32 v64, v64, v69
	v_mul_f32_e32 v64, v98, v64
	v_ashrrev_i32_e32 v69, 31, v68
	v_mul_f32_e32 v64, v64, v70
	v_lshlrev_b64 v[68:69], 12, v[68:69]
	v_cvt_pk_bf16_f32 v64, v64, v3
	v_lshl_add_u64 v[68:69], v[72:73], 0, v[68:69]
	global_store_short v[68:69], v64, off
	ds_read_b32 v64, v2 offset:26656
	v_and_b32_e32 v68, 0xffff0000, v90
	s_waitcnt lgkmcnt(0)
	v_cndmask_b32_e64 v64, 0, v64, s[40:41]
	s_nop 1
	v_add_f32_dpp v64, v64, v64 row_ror:8 row_mask:0xf bank_mask:0xf bound_ctrl:1
	s_nop 1
	v_add_f32_dpp v64, v64, v64 row_ror:4 row_mask:0xf bank_mask:0xf bound_ctrl:1
	s_nop 1
	v_add_f32_dpp v64, v64, v64 row_ror:2 row_mask:0xf bank_mask:0xf bound_ctrl:1
	s_nop 1
	v_add_f32_dpp v64, v64, v64 row_ror:1 row_mask:0xf bank_mask:0xf bound_ctrl:1
	v_fmamk_f32 v64, v64, 0x3c000000, v198
	v_rsq_f32_e32 v64, v64
	s_nop 0
	v_mul_f32_e32 v64, v65, v64
	v_mul_f32_e32 v64, v98, v64
	v_mul_f32_e32 v64, v64, v68
	v_cvt_pk_bf16_f32 v68, v64, v3
	v_add_u32_e32 v64, 17, v94
	v_ashrrev_i32_e32 v65, 31, v64
	v_lshlrev_b64 v[64:65], 12, v[64:65]
	v_lshl_add_u64 v[64:65], v[72:73], 0, v[64:65]
	global_store_short v[64:65], v68, off
	ds_read_b32 v64, v2 offset:26688
	v_lshlrev_b32_e32 v65, 16, v91
	s_waitcnt lgkmcnt(0)
	v_cndmask_b32_e64 v64, 0, v64, s[40:41]
	s_nop 1
	v_add_f32_dpp v64, v64, v64 row_ror:8 row_mask:0xf bank_mask:0xf bound_ctrl:1
	s_nop 1
	v_add_f32_dpp v64, v64, v64 row_ror:4 row_mask:0xf bank_mask:0xf bound_ctrl:1
	s_nop 1
	v_add_f32_dpp v64, v64, v64 row_ror:2 row_mask:0xf bank_mask:0xf bound_ctrl:1
	s_nop 1
	v_add_f32_dpp v64, v64, v64 row_ror:1 row_mask:0xf bank_mask:0xf bound_ctrl:1
	s_nop 0
	v_fmamk_f32 v64, v64, 0x3c000000, v198
	v_rsq_f32_e32 v64, v64
	s_nop 0
	v_mul_f32_e32 v64, v66, v64
	v_mul_f32_e32 v64, v98, v64
	v_mul_f32_e32 v64, v64, v65
	v_cvt_pk_bf16_f32 v66, v64, v3
	ds_read_b32 v2, v2 offset:26720
	v_add_u32_e32 v64, 18, v94
	v_ashrrev_i32_e32 v65, 31, v64
	v_lshlrev_b64 v[64:65], 12, v[64:65]
	s_nop 0
	v_lshl_add_u64 v[64:65], v[72:73], 0, v[64:65]
	s_waitcnt lgkmcnt(0)
	v_cndmask_b32_e64 v2, 0, v2, s[40:41]
	global_store_short v[64:65], v66, off
	v_and_b32_e32 v64, 0xffff0000, v91
	v_add_f32_dpp v2, v2, v2 row_ror:8 row_mask:0xf bank_mask:0xf bound_ctrl:1
	s_nop 1
	v_add_f32_dpp v2, v2, v2 row_ror:4 row_mask:0xf bank_mask:0xf bound_ctrl:1
	s_nop 1
	s_nop 0
	v_add_f32_dpp v2, v2, v2 row_ror:2 row_mask:0xf bank_mask:0xf bound_ctrl:1
	s_nop 1
	v_add_f32_dpp v2, v2, v2 row_ror:1 row_mask:0xf bank_mask:0xf bound_ctrl:1
	v_fmamk_f32 v2, v2, 0x3c000000, v198
	v_rsq_f32_e32 v2, v2
	s_nop 0
	v_mul_f32_e32 v2, v67, v2
	v_mul_f32_e32 v2, v98, v2
	v_mul_f32_e32 v2, v2, v64
	v_add_u32_e32 v64, 19, v94
	v_ashrrev_i32_e32 v65, 31, v64
	v_lshlrev_b64 v[64:65], 12, v[64:65]
	v_lshl_add_u64 v[64:65], v[72:73], 0, v[64:65]
	v_cvt_pk_bf16_f32 v2, v2, v3
	global_store_short v[64:65], v2, off
	s_cbranch_scc1 .LBB0_2392
	s_bitcmp1_b32 s87, 0
	s_cselect_b32 s4, 0x5000, 0
	s_add_i32 s4, s4, 0
	v_add_u32_e32 v2, s4, v100
	s_waitcnt vmcnt(4)
	v_mov_b64_e32 v[66:67], v[26:27]
	ds_write_b64 v2, v[78:79] offset:28672
	v_mov_b32_e32 v2, 0x3000
	v_mov_b64_e32 v[64:65], v[24:25]
	s_and_saveexec_b64 s[36:37], s[38:39]
	v_add_u32_e32 v2, s4, v101
	v_mov_b64_e32 v[66:67], v[10:11]
	ds_write_b128 v2, v[24:27] offset:36864
	v_mov_b32_e32 v2, 0x4000
	v_mov_b64_e32 v[64:65], v[8:9]
	s_or_b64 exec, exec, s[36:37]
	v_add3_u32 v2, s4, v2, v101
	ds_write_b128 v2, v[64:67] offset:28672

; template <bool FULL>
; __device__ __forceinline__ void hgrn_prep(char* lds, int s, int w, int kc, int tq, int kpos, float& gsum, s16x4& vfrag, u32x2& gvp) {
;     ...
;     float kd[4];
; #pragma unroll
;     for (int j = 0; j < 4; ++j) { const float kk = 1.f - __builtin_amdgcn_exp2f(lf[j]);
;         kd[j] = kk * __builtin_amdgcn_exp2f(glast - G[j]);
;         if (FULL) { const float qg = bf2f(qv[j]) * __builtin_amdgcn_exp2f(G[j]), kg = kk * __builtin_amdgcn_exp2f(fminf(-G[j], 115.f));
;             const unsigned qk = cvt_pk_bf16(qg, kg);
;             *(bf16*)(QG + (4 * tq + j) * ROWB + kpos * 2) = (bf16)(qk & 0xffffu);
;             *(bf16*)(KG + (4 * tq + j) * ROWB + kpos * 2) = (bf16)(qk >> 16); }
;         vfrag[j] = (short)vv[j]; }
;     { u32x2 kw; kw.x = cvt_pk_bf16(kd[0], kd[1]); kw.y = cvt_pk_bf16(kd[2], kd[3]); *(u32x2*)(KDT + ((16 * w + kc) * 16 + 4 * tq) * 2) = kw; }
;     DL[16 * w + kc] = __builtin_amdgcn_exp2f(glast);
;     gsum += glast;
;     if (FULL) { gvp.x = (unsigned)gv[0] | ((unsigned)gv[1] << 16); gvp.y = (unsigned)gv[2] | ((unsigned)gv[3] << 16); }
; }
; template <bool FULL>
; __device__ __forceinline__ void hgrn_mma(char* lds, int s, int w, int kc, int tq, const s16x4 vfrag, f32x4 (&S)[8], f32x4& o) {
;     const int buf = s & 1;
;     const char* QG = lds + QG_OFF + buf * 4352; const char* KG = lds + KG_OFF + buf * 4352; const char* KDT = lds + KDT_OFF + buf * 4096;
;     const float* DL = (const float*)(lds + DL_OFF + buf * 512); float* SSQP = (float*)(lds + SSQP_OFF + buf * 512);
;     o = (f32x4){0.f, 0.f, 0.f, 0.f};
;     if (FULL) {
;         f32x4 st = {0.f, 0.f, 0.f, 0.f};
; #pragma unroll
;         for (int ks = 0; ks < 4; ++ks) {
;             const bf16x8 qa = *(const bf16x8*)(QG + kc * ROWB + (32 * ks + 8 * tq) * 2), ka = *(const bf16x8*)(KG + kc * ROWB + (32 * ks + 8 * tq) * 2);
;             u32x4 sw; sw.x = cvt_pk_bf16(S[2 * ks][0], S[2 * ks][1]); sw.y = cvt_pk_bf16(S[2 * ks][2], S[2 * ks][3]);
;             sw.z = cvt_pk_bf16(S[2 * ks + 1][0], S[2 * ks + 1][1]); sw.w = cvt_pk_bf16(S[2 * ks + 1][2], S[2 * ks + 1][3]);
;             o = __builtin_amdgcn_mfma_f32_16x16x32_bf16(qa, *reinterpret_cast<bf16x8*>(&sw), o, 0, 0, 0);
;             st = __builtin_amdgcn_mfma_f32_16x16x32_bf16(ka, qa, st, 0, 0, 0); }
; #pragma unroll
;         for (int i = 0; i < 4; ++i) st[i] = (4 * tq + i <= kc) ? st[i] : 0.f;
.LBB0_2401:
	s_or_b64 exec, exec, s[38:39]
	s_ashr_i32 s5, s5, 2
	s_and_b32 s5, s5, 0x7fffffe0
	v_and_b32_e32 v71, 24, v71
	v_and_b32_e32 v73, 3, v64
	s_lshl_b32 s7, s4, 2
	v_or3_b32 v71, v71, v73, s5
	v_and_or_b32 v71, s7, 4, v71
	v_add_f32_e32 v73, v7, v68
	v_pk_add_f32 v[4:5], v[4:5], v[6:7]
	v_add_f32_e32 v72, v72, v7
	v_exp_f32_e32 v68, v68
	v_add_f32_e32 v6, v70, v7
	v_lshlrev_b32_e32 v7, 1, v71
	v_sub_f32_e32 v70, v4, v73
	v_exp_f32_e32 v71, v73
	v_min_f32_e64 v73, -v73, s74
	v_exp_f32_e32 v70, v70
	v_exp_f32_e32 v73, v73
	v_sub_f32_e32 v68, 1.0, v68
	s_waitcnt lgkmcnt(10)
	v_lshlrev_b32_e32 v69, 16, v69
	v_mul_f32_e32 v70, v68, v70
	v_mul_f32_e32 v69, v71, v69
	v_mul_f32_e32 v68, v68, v73
	v_cvt_pk_bf16_f32 v68, v69, v68
	v_mul_u32_u24_e32 v69, 0x440, v66
	v_add3_u32 v7, 0, v7, v69
	v_exp_f32_e32 v62, v62
	ds_write_b16 v7, v68
	ds_write_b16_d16_hi v7, v68 offset:8704
	v_sub_f32_e32 v68, v4, v72
	v_min_f32_e64 v71, -v72, s74
	v_exp_f32_e32 v68, v68
	v_exp_f32_e32 v71, v71
	v_exp_f32_e32 v69, v72
	v_sub_f32_e32 v62, 1.0, v62
	v_mul_f32_e32 v68, v62, v68
	s_waitcnt lgkmcnt(10)
	v_lshlrev_b32_e32 v67, 16, v67
	v_mul_f32_e32 v62, v62, v71
	v_mul_f32_e32 v67, v69, v67
	v_cvt_pk_bf16_f32 v62, v67, v62
	v_exp_f32_e32 v60, v60
	ds_write_b16 v7, v62 offset:272
	ds_write_b16_d16_hi v7, v62 offset:8976
	v_sub_f32_e32 v62, v4, v5
	v_exp_f32_e32 v67, v5
	v_min_f32_e64 v5, -v5, s74
	v_exp_f32_e32 v5, v5
	v_exp_f32_e32 v62, v62
	v_exp_f32_e32 v37, v37
	v_sub_f32_e32 v60, 1.0, v60
	s_waitcnt lgkmcnt(10)
	v_lshlrev_b32_e32 v61, 16, v61
	v_mul_f32_e32 v5, v60, v5
	v_mul_f32_e32 v61, v67, v61
	v_cvt_pk_bf16_f32 v5, v61, v5
	v_mul_f32_e32 v62, v60, v62
	ds_write_b16 v7, v5 offset:544
	ds_write_b16_d16_hi v7, v5 offset:9248
	v_sub_f32_e32 v5, 1.0, v37
	v_sub_f32_e32 v37, v4, v6
	v_exp_f32_e32 v60, v6
	v_min_f32_e64 v6, -v6, s74
	v_exp_f32_e32 v37, v37
	v_exp_f32_e32 v6, v6
	s_waitcnt lgkmcnt(10)
	v_lshlrev_b32_e32 v39, 16, v39
	v_mul_f32_e32 v39, v60, v39
	v_mul_f32_e32 v37, v5, v37
	v_mul_f32_e32 v5, v5, v6
	v_cvt_pk_bf16_f32 v5, v39, v5
	v_exp_f32_e32 v4, v4
	ds_write_b16 v7, v5 offset:816
	ds_write_b16_d16_hi v7, v5 offset:9520
	v_cvt_pk_bf16_f32 v6, v70, v68
	v_cvt_pk_bf16_f32 v7, v62, v37
	v_lshlrev_b32_e32 v5, 5, v16
	v_lshlrev_b32_e32 v37, 3, v66
	v_add3_u32 v5, 0, v5, v37
	ds_write_b64 v5, v[6:7] offset:17408
	v_lshl_add_u32 v5, v16, 2, 0
	ds_write_b32 v5, v4 offset:25600
	v_lshl_add_u32 v39, v66, 4, 0
	s_movk_i32 s4, 0x110
	s_waitcnt lgkmcnt(0)
	s_barrier
	v_mad_u32_u24 v16, v63, s4, v39
	ds_read_b128 v[4:7], v16
	ds_read_b128 v[68:71], v16 offset:8704
	v_cvt_pk_bf16_f32 v72, v8, v9
	v_cvt_pk_bf16_f32 v73, v10, v11
	v_cvt_pk_bf16_f32 v74, v12, v13
	v_cvt_pk_bf16_f32 v75, v14, v15
	s_nop 0
	ds_read_b128 v[76:79], v16 offset:64
	s_waitcnt lgkmcnt(2)
	v_mfma_f32_16x16x32_bf16 v[72:75], v[4:7], v[72:75], 0
	v_perm_b32 v61, v27, v19, s35
	v_perm_b32 v60, v18, v17, s35
	v_cmp_le_u32_e32 vcc, v65, v63
	s_waitcnt lgkmcnt(1)
	v_mfma_f32_16x16x32_bf16 v[4:7], v[68:71], v[4:7], 0
	ds_read_b128 v[68:71], v16 offset:8768
	s_nop 0
	v_cvt_pk_bf16_f32 v80, v20, v21
	v_cvt_pk_bf16_f32 v81, v22, v23
	v_cvt_pk_bf16_f32 v82, v40, v41
	v_cvt_pk_bf16_f32 v83, v42, v43
	s_waitcnt lgkmcnt(0)
	v_mfma_f32_16x16x32_bf16 v[4:7], v[68:71], v[76:79], v[4:7]
	ds_read_b128 v[68:71], v16 offset:8832
	v_or_b32_e32 v27, 2, v65
	v_perm_b32 v33, v35, v33, s35
	v_mfma_f32_16x16x32_bf16 v[72:75], v[76:79], v[80:83], v[72:75]
	ds_read_b128 v[80:83], v16 offset:128
	v_cvt_pk_bf16_f32 v76, v44, v45
	v_cvt_pk_bf16_f32 v77, v46, v47
	v_cvt_pk_bf16_f32 v78, v50, v51
	v_cvt_pk_bf16_f32 v79, v56, v57
	s_waitcnt lgkmcnt(0)
	v_mfma_f32_16x16x32_bf16 v[4:7], v[68:71], v[80:83], v[4:7]
	s_nop 0
	v_perm_b32 v29, v31, v29, s35
	v_or_b32_e32 v31, 3, v65
	v_sub_u32_e32 v35, v39, v37
	v_mfma_f32_16x16x32_bf16 v[72:75], v[80:83], v[76:79], v[72:75]
	ds_read_b128 v[76:79], v16 offset:192
	ds_read_b128 v[16:19], v16 offset:8896
	v_cvt_pk_bf16_f32 v68, v48, v49
	s_waitcnt lgkmcnt(0)
	v_mfma_f32_16x16x32_bf16 v[4:7], v[16:19], v[76:79], v[4:7]
	s_nop 0
	v_cvt_pk_bf16_f32 v69, v54, v55
	v_cvt_pk_bf16_f32 v70, v52, v53
	v_cvt_pk_bf16_f32 v71, v58, v59
	s_nop 7
	v_cndmask_b32_e32 v4, 0, v4, vcc
	v_cmp_lt_u32_e32 vcc, v65, v63
	v_mfma_f32_16x16x32_bf16 v[68:71], v[76:79], v[68:71], v[72:75]
	v_lshl_add_u32 v35, v63, 5, v35
	v_cndmask_b32_e32 v5, 0, v5, vcc
	v_cmp_le_u32_e32 vcc, v27, v63
	s_nop 0
	v_cvt_pk_bf16_f32 v4, v4, v5
	v_lshlrev_b32_e32 v27, 7, v66
	v_mov_b32_e32 v37, v3
	v_cndmask_b32_e32 v6, 0, v6, vcc
	v_cmp_le_u32_e32 vcc, v31, v63
	s_add_i32 s4, s44, s8
	v_or_b32_e32 v62, s4, v63
	v_cndmask_b32_e32 v7, 0, v7, vcc
	v_cvt_pk_bf16_f32 v5, v6, v7
	ds_read2st64_b64 v[72:75], v35 offset0:34 offset1:35
	ds_read_b128 v[16:19], v39 offset:25600
	s_nop 0
	v_mfma_f32_16x16x16_bf16 v[4:7], v[4:5], v[60:61], v[68:71]
	ds_read2st64_b64 v[76:79], v35 offset0:36 offset1:37
	s_add_u32 s4, s49, s42
	s_addc_u32 s5, s50, s43
	ds_read_b128 v[66:69], v39 offset:25664
	s_waitcnt lgkmcnt(2)
	v_pk_mul_f32 v[10:11], v[10:11], v[18:19]
	v_pk_mul_f32 v[8:9], v[8:9], v[16:17]
	s_add_i32 s7, s7, 0
	v_add_u32_e32 v31, s7, v27
	s_nop 0
	v_mfma_f32_16x16x16_bf16 v[16:19], v[72:73], v[60:61], v[8:11]
	ds_read_b128 v[70:73], v39 offset:25728
	v_add_u32_e32 v31, 0x6800, v31
	v_cmp_gt_u32_e32 vcc, 8, v63
	s_waitcnt lgkmcnt(1)
	v_pk_mul_f32 v[10:11], v[14:15], v[68:69]
	v_pk_mul_f32 v[8:9], v[12:13], v[66:67]
	ds_read_b128 v[66:69], v39 offset:25792
	s_waitcnt lgkmcnt(1)
	s_nop 0
	v_pk_mul_f32 v[14:15], v[22:23], v[72:73]
	v_pk_mul_f32 v[12:13], v[20:21], v[70:71]
	v_mfma_f32_16x16x16_bf16 v[8:11], v[74:75], v[60:61], v[8:11]
	v_ashrrev_i32_e32 v63, 31, v62
	s_waitcnt lgkmcnt(0)
; template <bool FULL>
; __device__ __forceinline__ void hgrn_mma(char* lds, int s, int w, int kc, int tq, const s16x4 vfrag, f32x4 (&S)[8], f32x4& o) {
;     ...
; #pragma unroll
;     for (int kb = 0; kb < 8; ++kb) { const f32x4 dlv = *(const f32x4*)(DL + 16 * kb + 4 * tq);
;         const s16x4 ka = *(const s16x4*)(KDT + ((16 * kb + kc) * 16 + 4 * tq) * 2);
;         S[kb] = __builtin_amdgcn_mfma_f32_16x16x16bf16_1k(ka, vfrag, S[kb] * dlv, 0, 0, 0); }
;     if (FULL) {
;         float ss[4];
; #pragma unroll
;         for (int i = 0; i < 4; ++i) ss[i] = row16_sum(o[i] * o[i]);
; #pragma unroll
;         for (int i = 0; i < 4; ++i) SSQP[(4 * tq + i) * 8 + w] = ss[i];
;     }
; __global__ void __launch_bounds__(512, 2) fwd_kernel(Args a) {
;     ...
;                 for (int u = vcu; u < 256; u += G) { const int b = u >> 4, h = u & 15; const size_t so = ((size_t)(j * 16 + b) * 16 + h) * 16384;
;                     hg::hgrn_item<true, false>(A0, LOGF, A2, A3, A4, MP + b * 16, 1, h, ap->in[I_SHG] + so, out + OFF_HG_S + so, nullptr, gain, ldsg); } }
	v_pk_mul_f32 v[22:23], v[42:43], v[68:69]
	v_pk_mul_f32 v[20:21], v[40:41], v[66:67]
	v_mfma_f32_16x16x16_bf16 v[12:15], v[76:77], v[60:61], v[12:15]
	ds_read2st64_b64 v[70:73], v35 offset0:38 offset1:39
	ds_read_b128 v[74:77], v39 offset:25856
	ds_read_b128 v[40:43], v39 offset:25920
	ds_read2st64_b64 v[66:69], v35 offset0:40 offset1:41
	v_mul_f32_e32 v35, v4, v4
	s_add_u32 s4, s4, s40
	s_waitcnt lgkmcnt(2)
	v_pk_mul_f32 v[46:47], v[46:47], v[76:77]
	v_mov_b32_dpp v37, v35 row_ror:8 row_mask:0xf bank_mask:0xf
	v_pk_mul_f32 v[44:45], v[44:45], v[74:75]
	s_waitcnt lgkmcnt(1)
	v_pk_mul_f32 v[42:43], v[56:57], v[42:43]
	v_pk_mul_f32 v[40:41], v[50:51], v[40:41]
	v_fmac_f32_e32 v37, v4, v4
	v_mfma_f32_16x16x16_bf16 v[44:47], v[70:71], v[60:61], v[44:47]
	v_mov_b32_e32 v50, v3
	v_add_f32_dpp v35, v37, v37 row_ror:4 row_mask:0xf bank_mask:0xf bound_ctrl:1
	v_mul_f32_e32 v37, v5, v5
	v_mfma_f32_16x16x16_bf16 v[40:43], v[72:73], v[60:61], v[40:43]
	ds_read_b128 v[70:73], v39 offset:25984
	s_nop 0
	ds_read_b128 v[74:77], v39 offset:26048
	v_mov_b32_e32 v39, v3
	v_mov_b32_e32 v51, v3
	v_add_f32_dpp v35, v35, v35 row_ror:2 row_mask:0xf bank_mask:0xf bound_ctrl:1
	v_mov_b32_dpp v39, v37 row_ror:8 row_mask:0xf bank_mask:0xf
	v_fmac_f32_e32 v39, v5, v5
	v_add_f32_dpp v35, v35, v35 row_ror:1 row_mask:0xf bank_mask:0xf bound_ctrl:1
	v_or_b32_e32 v56, s6, v65
	v_add_f32_dpp v37, v39, v39 row_ror:4 row_mask:0xf bank_mask:0xf bound_ctrl:1
	v_mul_f32_e32 v39, v6, v6
	v_ashrrev_i32_e32 v57, 31, v56
	v_add_f32_dpp v37, v37, v37 row_ror:2 row_mask:0xf bank_mask:0xf bound_ctrl:1
	v_mov_b32_dpp v50, v39 row_ror:8 row_mask:0xf bank_mask:0xf
	v_fmac_f32_e32 v50, v6, v6
	v_add_f32_dpp v37, v37, v37 row_ror:1 row_mask:0xf bank_mask:0xf bound_ctrl:1
	s_addc_u32 s5, s5, s41
	v_add_f32_dpp v39, v50, v50 row_ror:4 row_mask:0xf bank_mask:0xf bound_ctrl:1
	v_mul_f32_e32 v50, v7, v7
	v_mfma_f32_16x16x16_bf16 v[20:23], v[78:79], v[60:61], v[20:23]
	v_add_f32_dpp v39, v39, v39 row_ror:2 row_mask:0xf bank_mask:0xf bound_ctrl:1
	s_nop 0
	v_mov_b32_dpp v51, v50 row_ror:8 row_mask:0xf bank_mask:0xf
	v_fmac_f32_e32 v51, v7, v7
	v_add_f32_dpp v39, v39, v39 row_ror:1 row_mask:0xf bank_mask:0xf bound_ctrl:1
	s_waitcnt lgkmcnt(1)
	v_pk_mul_f32 v[48:49], v[48:49], v[70:71]
	v_add_f32_dpp v50, v51, v51 row_ror:4 row_mask:0xf bank_mask:0xf bound_ctrl:1
	s_waitcnt lgkmcnt(0)
	v_pk_mul_f32 v[52:53], v[52:53], v[74:75]
	s_add_i32 s65, s65, s64
	v_add_f32_dpp v50, v50, v50 row_ror:2 row_mask:0xf bank_mask:0xf bound_ctrl:1
	s_cmpk_lt_i32 s65, 0x100
	s_nop 0
	v_add_f32_dpp v50, v50, v50 row_ror:1 row_mask:0xf bank_mask:0xf bound_ctrl:1
	ds_write2_b32 v31, v35, v37 offset1:8
	ds_write2_b32 v31, v39, v50 offset0:16 offset1:24
	v_and_b32_e32 v31, 7, v64
	v_lshlrev_b32_e32 v31, 2, v31
	s_waitcnt lgkmcnt(0)
	s_barrier
; __device__ __forceinline__ unsigned cvt_pk_bf16(float lo, float hi) { unsigned r; asm volatile("v_cvt_pk_bf16_f32 %0, %1, %2" : "=v"(r) : "v"(lo), "v"(hi)); return r; }
; #define LDS_WAIT() asm volatile("s_waitcnt lgkmcnt(0)" ::: "memory")
; __device__ __forceinline__ void hgrn_fin(char* lds, int s, int w, int kc, int tq, int ch, int row0, float gn, const f32x4 o, const u32x2 gvp, bf16* __restrict__ O) {
;     const float* SSQP = (const float*)(lds + SSQP_OFF + (s & 1) * 512);
; #pragma unroll
;     for (int i = 0; i < 4; ++i) { const float part = SSQP[(4 * tq + i) * 8 + (kc & 7)];
;         const float tot = row16_sum(kc < 8 ? part : 0.f);
;         const float rs = __builtin_amdgcn_rsqf(tot * (1.f / 128.f) + EPS);
;         const unsigned gw_ = i < 2 ? gvp.x : gvp.y; const float gate = __uint_as_float((i & 1) ? (gw_ & 0xffff0000u) : (gw_ << 16));
;         const float ov = o[i] * rs * gn * gate;
;         O[(size_t)(row0 + 16 * s + 4 * tq + i) * D + ch] = (bf16)(cvt_pk_bf16(ov, 0.f) & 0xffffu); }
; }
; template <bool FULL, bool SBF> ...
;     ...
;     if (FULL) hgrn_fin(lds, nsteps - 1, w, kc, tq, ch, row0, gn, o_prev, gv_prev, O);
;     if (Sout) {
; #pragma unroll
;         for (int kb = 0; kb < 8; ++kb)
; #pragma unroll
;             for (int i = 0; i < 4; ++i) { const size_t so = (size_t)(16 * kb + 4 * tq + i) * 128 + 16 * w + kc; if (SBF) ((bf16*)Sout)[so] = (bf16)(cvt_pk_bf16(S[kb][i], 0.f) & 0xffffu); else ((float*)Sout)[so] = S[kb][i]; } }
;     if (!FULL && Dout && tq == 0) Dout[16 * w + kc] = __builtin_amdgcn_exp2f(gsum);
;     LDS_WAIT(); __builtin_amdgcn_s_barrier(); asm volatile("" ::: "memory");
	v_add3_u32 v27, 0, v31, v27
	ds_read_b32 v31, v27 offset:26624
	v_lshlrev_b32_e32 v35, 16, v33
	v_pk_mul_f32 v[50:51], v[54:55], v[72:73]
	v_pk_mul_f32 v[54:55], v[58:59], v[76:77]
	v_lshl_add_u64 v[58:59], v[62:63], 1, s[12:13]
	s_waitcnt lgkmcnt(0)
	v_cndmask_b32_e32 v31, 0, v31, vcc
	v_lshlrev_b64 v[62:63], 12, v[56:57]
	v_lshl_add_u64 v[62:63], v[58:59], 0, v[62:63]
	v_add_f32_dpp v31, v31, v31 row_ror:8 row_mask:0xf bank_mask:0xf bound_ctrl:1
	s_nop 0
	v_mfma_f32_16x16x16_bf16 v[48:51], v[66:67], v[60:61], v[48:51]
	v_mov_b32_e32 v37, v3
	v_add_f32_dpp v31, v31, v31 row_ror:4 row_mask:0xf bank_mask:0xf bound_ctrl:1
	v_mov_b32_e32 v39, v3
	v_mfma_f32_16x16x16_bf16 v[52:55], v[68:69], v[60:61], v[52:55]
	v_add_f32_dpp v31, v31, v31 row_ror:2 row_mask:0xf bank_mask:0xf bound_ctrl:1
	s_nop 1
	v_add_f32_dpp v31, v31, v31 row_ror:1 row_mask:0xf bank_mask:0xf bound_ctrl:1
	v_fmamk_f32 v31, v31, 0x3c000000, v198
	v_rsq_f32_e32 v31, v31
	s_nop 0
	v_mul_f32_e32 v4, v4, v31
	v_mul_f32_e32 v4, v25, v4
	v_mul_f32_e32 v4, v4, v35
	v_cvt_pk_bf16_f32 v4, v4, v3
	ds_read_b32 v31, v27 offset:26656
	global_store_short v[62:63], v4, off
	v_and_b32_e32 v4, 0xffff0000, v33
	v_mov_b32_e32 v35, v3
	s_waitcnt lgkmcnt(0)
	v_cndmask_b32_e32 v31, 0, v31, vcc
	s_nop 1
	v_add_f32_dpp v31, v31, v31 row_ror:8 row_mask:0xf bank_mask:0xf bound_ctrl:1
	s_nop 1
	v_add_f32_dpp v31, v31, v31 row_ror:4 row_mask:0xf bank_mask:0xf bound_ctrl:1
	s_nop 1
	v_add_f32_dpp v31, v31, v31 row_ror:2 row_mask:0xf bank_mask:0xf bound_ctrl:1
	s_nop 1
	v_add_f32_dpp v31, v31, v31 row_ror:1 row_mask:0xf bank_mask:0xf bound_ctrl:1
	v_fmamk_f32 v31, v31, 0x3c000000, v198
	v_rsq_f32_e32 v31, v31
	s_nop 0
	v_mul_f32_e32 v5, v5, v31
	v_mul_f32_e32 v5, v25, v5
	v_mul_f32_e32 v4, v5, v4
	v_cvt_pk_bf16_f32 v31, v4, v3
	ds_read_b32 v33, v27 offset:26688
	v_or_b32_e32 v4, 1, v56
	v_ashrrev_i32_e32 v5, 31, v4
	v_lshlrev_b64 v[4:5], 12, v[4:5]
	v_lshl_add_u64 v[4:5], v[58:59], 0, v[4:5]
	s_waitcnt lgkmcnt(0)
	v_cndmask_b32_e32 v33, 0, v33, vcc
	global_store_short v[4:5], v31, off
	v_lshlrev_b32_e32 v4, 16, v29
	v_add_f32_dpp v33, v33, v33 row_ror:8 row_mask:0xf bank_mask:0xf bound_ctrl:1
	v_mov_b32_e32 v31, v3
	s_nop 0
	v_add_f32_dpp v33, v33, v33 row_ror:4 row_mask:0xf bank_mask:0xf bound_ctrl:1
	s_nop 1
	v_add_f32_dpp v33, v33, v33 row_ror:2 row_mask:0xf bank_mask:0xf bound_ctrl:1
	s_nop 1
	v_add_f32_dpp v33, v33, v33 row_ror:1 row_mask:0xf bank_mask:0xf bound_ctrl:1
	v_fmamk_f32 v33, v33, 0x3c000000, v198
	v_rsq_f32_e32 v33, v33
	s_nop 0
	v_mul_f32_e32 v5, v6, v33
	v_mul_f32_e32 v5, v25, v5
	v_mul_f32_e32 v4, v5, v4
	v_cvt_pk_bf16_f32 v6, v4, v3
	ds_read_b32 v27, v27 offset:26720
	v_or_b32_e32 v4, 2, v56
	v_ashrrev_i32_e32 v5, 31, v4
	v_lshlrev_b64 v[4:5], 12, v[4:5]
	v_lshl_add_u64 v[4:5], v[58:59], 0, v[4:5]
	s_waitcnt lgkmcnt(0)
	v_cndmask_b32_e32 v27, 0, v27, vcc
	global_store_short v[4:5], v6, off
	v_and_b32_e32 v4, 0xffff0000, v29
	v_add_f32_dpp v27, v27, v27 row_ror:8 row_mask:0xf bank_mask:0xf bound_ctrl:1
	v_mov_b32_e32 v29, v3
	v_mov_b32_e32 v33, v3
	v_add_f32_dpp v27, v27, v27 row_ror:4 row_mask:0xf bank_mask:0xf bound_ctrl:1
	s_nop 1
	v_add_f32_dpp v27, v27, v27 row_ror:2 row_mask:0xf bank_mask:0xf bound_ctrl:1
	s_nop 1
	v_add_f32_dpp v27, v27, v27 row_ror:1 row_mask:0xf bank_mask:0xf bound_ctrl:1
	v_fmamk_f32 v27, v27, 0x3c000000, v198
	v_rsq_f32_e32 v27, v27
	s_nop 0
	v_mul_f32_e32 v5, v7, v27
	v_mul_f32_e32 v5, v25, v5
	v_mul_f32_e32 v4, v5, v4
	v_cvt_pk_bf16_f32 v6, v4, v3
	v_or_b32_e32 v4, 3, v56
	v_ashrrev_i32_e32 v5, 31, v4
	v_lshlrev_b64 v[4:5], 12, v[4:5]
	v_lshl_add_u64 v[4:5], v[58:59], 0, v[4:5]
	s_nop 0
	global_store_short v[4:5], v6, off
	v_lshl_add_u64 v[4:5], s[4:5], 0, v[2:3]
	v_mov_b32_e32 v25, v3
	v_lshl_add_u64 v[6:7], v[4:5], 0, v[24:25]
	v_mov_b32_e32 v27, v3
	global_store_dword v[6:7], v16, off
	global_store_dword v[6:7], v17, off offset:512
	global_store_dword v[6:7], v18, off offset:1024
	global_store_dword v[6:7], v19, off offset:1536
	v_lshl_add_u64 v[16:17], v[4:5], 0, v[26:27]
	global_store_dword v[16:17], v8, off
	v_add_co_u32_e32 v16, vcc, s75, v6
	s_movk_i32 s4, 0x4000
	s_nop 0
	v_addc_co_u32_e32 v17, vcc, 0, v7, vcc
	global_store_dword v[16:17], v9, off offset:512
	global_store_dword v[16:17], v10, off offset:1024
	global_store_dword v[16:17], v11, off offset:1536
	v_lshl_add_u64 v[8:9], v[4:5], 0, v[28:29]
	global_store_dword v[8:9], v12, off
	v_add_co_u32_e32 v8, vcc, s4, v6
	s_movk_i32 s4, 0x6000
	s_nop 0
	v_addc_co_u32_e32 v9, vcc, 0, v7, vcc
	global_store_dword v[8:9], v13, off offset:512
	global_store_dword v[8:9], v14, off offset:1024
	global_store_dword v[8:9], v15, off offset:1536
	v_lshl_add_u64 v[8:9], v[4:5], 0, v[30:31]
	global_store_dword v[8:9], v20, off
	v_add_co_u32_e32 v8, vcc, s4, v6
	s_mov_b32 s4, 0xa000
	s_nop 0
	v_addc_co_u32_e32 v9, vcc, 0, v7, vcc
	global_store_dword v[8:9], v21, off offset:512
	global_store_dword v[8:9], v22, off offset:1024
	global_store_dword v[8:9], v23, off offset:1536
	v_lshl_add_u64 v[8:9], v[4:5], 0, v[32:33]
	global_store_dword v[8:9], v44, off
	v_add_co_u32_e32 v8, vcc, s23, v6
	s_nop 1
	v_addc_co_u32_e32 v9, vcc, 0, v7, vcc
	global_store_dword v[8:9], v45, off offset:512
	global_store_dword v[8:9], v46, off offset:1024
	global_store_dword v[8:9], v47, off offset:1536
	v_lshl_add_u64 v[8:9], v[4:5], 0, v[34:35]
	global_store_dword v[8:9], v40, off
	v_add_co_u32_e32 v8, vcc, s4, v6
	s_mov_b32 s4, 0xc000
	s_nop 0
	v_addc_co_u32_e32 v9, vcc, 0, v7, vcc
	global_store_dword v[8:9], v41, off offset:512
	global_store_dword v[8:9], v42, off offset:1024
	global_store_dword v[8:9], v43, off offset:1536
	v_lshl_add_u64 v[8:9], v[4:5], 0, v[36:37]
	global_store_dword v[8:9], v48, off
	v_add_co_u32_e32 v8, vcc, s4, v6
	v_lshl_add_u64 v[4:5], v[4:5], 0, v[38:39]
	s_nop 0
	v_addc_co_u32_e32 v9, vcc, 0, v7, vcc
	global_store_dword v[8:9], v49, off offset:512
	global_store_dword v[8:9], v50, off offset:1024
	global_store_dword v[8:9], v51, off offset:1536
	global_store_dword v[4:5], v52, off
	v_add_co_u32_e32 v4, vcc, 0xe000, v6
	s_nop 1
	v_addc_co_u32_e32 v5, vcc, 0, v7, vcc
	global_store_dword v[4:5], v53, off offset:512
	global_store_dword v[4:5], v54, off offset:1024
	global_store_dword v[4:5], v55, off offset:1536
	s_waitcnt lgkmcnt(0)
	s_barrier
	s_cbranch_scc0 .LBB0_2475

; __device__ __forceinline__ float bf2f(unsigned short b) { return __uint_as_float(((unsigned)b) << 16); }
; template <bool FULL, bool SBF> ...
;     ...
;     for (int kb = 0; kb < 8; ++kb)
; #pragma unroll
;         for (int i = 0; i < 4; ++i) { const size_t so = (size_t)(16 * kb + 4 * tq + i) * 128 + 16 * w + kc; S[kb][i] = Sin ? (SBF ? bf2f(((const bf16*)Sin)[so]) : ((const float*)Sin)[so]) : 0.f; }
.LBB0_2416:
	s_and_b64 vcc, exec, s[38:39]
	s_cbranch_vccnz .LBB0_2418
	v_mov_b32_e32 v25, v3
	v_lshl_add_u64 v[6:7], v[4:5], 0, v[24:25]
	v_add_co_u32_e32 v6, vcc, 0x2000, v6
	s_nop 1
	v_addc_co_u32_e32 v7, vcc, 0, v7, vcc
	s_nop 0
	global_load_dword v15, v[6:7], off offset:1536

; __device__ __forceinline__ float bf2f(unsigned short b) { return __uint_as_float(((unsigned)b) << 16); }
; template <bool FULL, bool SBF> ...
;     ...
;     for (int kb = 0; kb < 8; ++kb)
; #pragma unroll
;         for (int i = 0; i < 4; ++i) { const size_t so = (size_t)(16 * kb + 4 * tq + i) * 128 + 16 * w + kc; S[kb][i] = Sin ? (SBF ? bf2f(((const bf16*)Sin)[so]) : ((const float*)Sin)[so]) : 0.f; }
.LBB0_2422:
	v_mov_b32_e32 v23, 0
	s_and_b64 vcc, exec, s[38:39]
	v_mov_b32_e32 v22, 0
	s_cbranch_vccnz .LBB0_2424
	v_mov_b32_e32 v25, v3
	v_lshl_add_u64 v[6:7], v[4:5], 0, v[24:25]
	s_nop 0
	v_add_co_u32_e32 v6, vcc, 0x4000, v6
	s_nop 1
	v_addc_co_u32_e32 v7, vcc, 0, v7, vcc
	global_load_dword v22, v[6:7], off offset:1024
.LBB0_2424:
	s_and_b64 vcc, exec, s[38:39]
	s_cbranch_vccnz .LBB0_2426
	v_mov_b32_e32 v25, v3
	v_lshl_add_u64 v[6:7], v[4:5], 0, v[24:25]
	v_add_co_u32_e32 v6, vcc, 0x4000, v6
	s_nop 1
	v_addc_co_u32_e32 v7, vcc, 0, v7, vcc
	s_nop 0
	global_load_dword v23, v[6:7], off offset:1536

; __device__ __forceinline__ float bf2f(unsigned short b) { return __uint_as_float(((unsigned)b) << 16); }
; template <bool FULL, bool SBF> ...
;     ...
;     for (int kb = 0; kb < 8; ++kb)
; #pragma unroll
;         for (int i = 0; i < 4; ++i) { const size_t so = (size_t)(16 * kb + 4 * tq + i) * 128 + 16 * w + kc; S[kb][i] = Sin ? (SBF ? bf2f(((const bf16*)Sin)[so]) : ((const float*)Sin)[so]) : 0.f; }
.LBB0_2430:
	v_mov_b32_e32 v43, 0
	s_and_b64 vcc, exec, s[38:39]
	v_mov_b32_e32 v42, 0
	s_cbranch_vccnz .LBB0_2432
	v_mov_b32_e32 v25, v3
	v_lshl_add_u64 v[6:7], v[4:5], 0, v[24:25]
	s_nop 0
	v_add_co_u32_e32 v6, vcc, 0x6000, v6
	s_nop 1
	v_addc_co_u32_e32 v7, vcc, 0, v7, vcc
	global_load_dword v42, v[6:7], off offset:1024
.LBB0_2432:
	s_and_b64 vcc, exec, s[38:39]
	s_cbranch_vccnz .LBB0_2434
	v_mov_b32_e32 v25, v3
	v_lshl_add_u64 v[6:7], v[4:5], 0, v[24:25]
	v_add_co_u32_e32 v6, vcc, 0x6000, v6
	s_nop 1
	v_addc_co_u32_e32 v7, vcc, 0, v7, vcc
	s_nop 0
	global_load_dword v43, v[6:7], off offset:1536

; __device__ __forceinline__ float bf2f(unsigned short b) { return __uint_as_float(((unsigned)b) << 16); }
; template <bool FULL, bool SBF> ...
;     ...
;     for (int kb = 0; kb < 8; ++kb)
; #pragma unroll
;         for (int i = 0; i < 4; ++i) { const size_t so = (size_t)(16 * kb + 4 * tq + i) * 128 + 16 * w + kc; S[kb][i] = Sin ? (SBF ? bf2f(((const bf16*)Sin)[so]) : ((const float*)Sin)[so]) : 0.f; }
.LBB0_2438:
	v_mov_b32_e32 v47, 0
	s_and_b64 vcc, exec, s[38:39]
	v_mov_b32_e32 v46, 0
	s_cbranch_vccnz .LBB0_2440
	v_mov_b32_e32 v25, v3
	v_lshl_add_u64 v[6:7], v[4:5], 0, v[24:25]
	s_nop 0
	v_add_co_u32_e32 v6, vcc, 0x8000, v6
	s_nop 1
	v_addc_co_u32_e32 v7, vcc, 0, v7, vcc
	global_load_dword v46, v[6:7], off offset:1024
.LBB0_2440:
	s_and_b64 vcc, exec, s[38:39]
	s_cbranch_vccnz .LBB0_2442
	v_mov_b32_e32 v25, v3
	v_lshl_add_u64 v[6:7], v[4:5], 0, v[24:25]
	v_add_co_u32_e32 v6, vcc, 0x8000, v6
	s_nop 1
	v_addc_co_u32_e32 v7, vcc, 0, v7, vcc
	s_nop 0
	global_load_dword v47, v[6:7], off offset:1536

; __device__ __forceinline__ float bf2f(unsigned short b) { return __uint_as_float(((unsigned)b) << 16); }
; template <bool FULL, bool SBF> ...
;     ...
;     for (int kb = 0; kb < 8; ++kb)
; #pragma unroll
;         for (int i = 0; i < 4; ++i) { const size_t so = (size_t)(16 * kb + 4 * tq + i) * 128 + 16 * w + kc; S[kb][i] = Sin ? (SBF ? bf2f(((const bf16*)Sin)[so]) : ((const float*)Sin)[so]) : 0.f; }
.LBB0_2448:
	s_and_b64 vcc, exec, s[38:39]
	s_cbranch_vccnz .LBB0_2450
	v_mov_b32_e32 v25, v3
	v_lshl_add_u64 v[6:7], v[4:5], 0, v[24:25]
	v_add_co_u32_e32 v6, vcc, 0xa000, v6
	s_nop 1
	v_addc_co_u32_e32 v7, vcc, 0, v7, vcc
	s_nop 0
	global_load_dword v57, v[6:7], off offset:1536

; __device__ __forceinline__ float bf2f(unsigned short b) { return __uint_as_float(((unsigned)b) << 16); }
; template <bool FULL, bool SBF> ...
;     ...
;     for (int kb = 0; kb < 8; ++kb)
; #pragma unroll
;         for (int i = 0; i < 4; ++i) { const size_t so = (size_t)(16 * kb + 4 * tq + i) * 128 + 16 * w + kc; S[kb][i] = Sin ? (SBF ? bf2f(((const bf16*)Sin)[so]) : ((const float*)Sin)[so]) : 0.f; }
.LBB0_2456:
	s_and_b64 vcc, exec, s[38:39]
	s_cbranch_vccnz .LBB0_2458
	v_mov_b32_e32 v25, v3
	v_lshl_add_u64 v[6:7], v[4:5], 0, v[24:25]
	v_add_co_u32_e32 v6, vcc, 0xc000, v6
	s_nop 1
	v_addc_co_u32_e32 v7, vcc, 0, v7, vcc
	s_nop 0
	global_load_dword v55, v[6:7], off offset:1536

; __device__ __forceinline__ float bf2f(unsigned short b) { return __uint_as_float(((unsigned)b) << 16); }
; #define HG_LOAD(j, s_) do { rl[j] = *(const u32x2*)(plf + (size_t)(s_) * 16 * D); if (FULL || !lo4) rb0[j] = *(const bf16x8*)(pb0 + (size_t)(s_) * 16 * D); if (FULL && lo4) rb1[j] = *(const bf16x8*)(pb1 + (size_t)(s_) * 16 * D); } while (0)
; #define HG_WRITE(j, slot) do { char* rb = lds + RAW_OFF + (slot) * RAW_SLOT; *(u32x2*)(rb + tid * 8) = rl[j]; \
;         if (lo4) { if (FULL) { *(bf16x8*)(rb + 8192 + t2 * 16) = rb0[j]; *(bf16x8*)(rb + 16384 + t2 * 16) = rb1[j]; } } else *(bf16x8*)(rb + 12288 + t2 * 16) = rb0[j]; } while (0)
; template <bool FULL, bool SBF> ...
;     ...
;         for (int i = 0; i < 4; ++i) { const size_t so = (size_t)(16 * kb + 4 * tq + i) * 128 + 16 * w + kc; S[kb][i] = Sin ? (SBF ? bf2f(((const bf16*)Sin)[so]) : ((const float*)Sin)[so]) : 0.f; }
;     float gsum = 0.f;
;     const int t2 = tid & 255; const bool lo4 = tid < 256;
;     const unsigned short* plf = (const unsigned short*)LOGF + (size_t)(row0 + (tid >> 5)) * D + h * 128 + 4 * (tid & 31);
;     const size_t boff = (size_t)(row0 + (t2 >> 4)) * D + h * 128 + 8 * (t2 & 15);
;     const bf16* pb0 = (lo4 ? Q : V) + boff; const bf16* pb1 = GS + boff;
;     u32x2 rl[3]; bf16x8 rb0[3], rb1[3];
;     ...
;     const float gn = FULL ? gain[16 * w + kc] : 0.f;
;     s16x4 vf_cur, vf_nxt; u32x2 gv_cur = {0u, 0u}, gv_nxt = {0u, 0u}, gv_prev = {0u, 0u}; f32x4 o_prev = {0.f, 0.f, 0.f, 0.f};
;     HG_LOAD(0, 0); if (1 < nsteps) HG_LOAD(1, 1); if (2 < nsteps) HG_LOAD(2, 2);
;     HG_WRITE(0, 0); if (1 < nsteps) HG_WRITE(1, 1);
.LBB0_2464:
	s_and_b64 vcc, exec, s[38:39]
	s_cbranch_vccnz .LBB0_2466
	v_mov_b32_e32 v25, v3
	v_lshl_add_u64 v[4:5], v[4:5], 0, v[24:25]
	v_add_co_u32_e32 v4, vcc, 0xe000, v4
	s_nop 1
	v_addc_co_u32_e32 v5, vcc, 0, v5, vcc
	s_nop 0
	global_load_dword v59, v[4:5], off offset:1536
.LBB0_2466:
	s_and_b32 s6, s65, -16
	s_addk_i32 s6, 0x4000
	v_ashrrev_i32_e32 v4, 5, v64
	v_add_u32_e32 v4, s6, v4
	v_ashrrev_i32_e32 v5, 31, v4
	v_lshlrev_b64 v[4:5], 12, v[4:5]
	v_lshl_add_u64 v[4:5], s[18:19], 0, v[4:5]
	s_lshl_b32 s10, s7, 8
	v_lshlrev_b32_e32 v27, 3, v64
	v_lshl_add_u64 v[4:5], v[4:5], 0, s[10:11]
	s_nop 0
	v_and_b32_e32 v6, 0xf8, v27
	v_mov_b32_e32 v7, v3
	v_lshl_add_u64 v[4:5], v[4:5], 0, v[6:7]
	v_bfe_u32 v6, v64, 4, 4
	v_or_b32_e32 v6, s6, v6
	v_ashrrev_i32_e32 v7, 31, v6
	s_lshl_b32 s8, s7, 7
	v_lshlrev_b64 v[18:19], 11, v[6:7]
	v_and_b32_e32 v6, 0x78, v27
	s_movk_i32 s7, 0x100
	s_nop 0
	v_or3_b32 v18, v18, v6, s8
	v_mov_b32_e32 v6, s80
	v_mov_b32_e32 v7, s78
	v_cmp_gt_i32_e32 vcc, s7, v64
	v_mov_b32_e32 v16, s77
	v_and_b32_e32 v29, 0xff, v64
	v_cndmask_b32_e32 v7, v6, v7, vcc
	v_mov_b32_e32 v6, s79
	v_cndmask_b32_e32 v6, v6, v16, vcc
	v_or_b32_e32 v16, s44, v63
	v_ashrrev_i32_e32 v17, 31, v16
	v_lshl_add_u64 v[6:7], v[18:19], 1, v[6:7]
	s_nop 0
	v_lshl_add_u64 v[60:61], v[16:17], 2, s[20:21]
	global_load_dword v25, v[60:61], off
	s_nop 0
	global_load_dwordx2 v[60:61], v[4:5], off
	s_nop 0
	global_load_dwordx4 v[4:7], v[6:7], off
	v_cmp_lt_i32_e32 vcc, s30, v64
	v_add_u32_e32 v17, 0, v27
	v_lshl_add_u32 v27, v29, 4, 0
	s_and_saveexec_b64 s[14:15], vcc
	s_xor_b64 s[38:39], exec, s[14:15]
	s_cbranch_execz .LBB0_2468
	s_waitcnt vmcnt(1)
	ds_write_b64 v17, v[60:61] offset:28672
	s_waitcnt vmcnt(0)
	ds_write_b128 v27, v[4:7] offset:40960

; __device__ __forceinline__ float h2f(unsigned short u) { return (float)__builtin_bit_cast(_Float16, u); }
; __device__ __forceinline__ void row_prefix4(float x, int tq, float& pre, float& tot) {
;     const auto s16 = __builtin_amdgcn_permlane16_swap(__float_as_uint(x), __float_as_uint(x), false, false);
;     const float ev = __uint_as_float(s16[0]), od = __uint_as_float(s16[1]), pr = ev + od;
;     const auto s32 = __builtin_amdgcn_permlane32_swap(__float_as_uint(pr), __float_as_uint(pr), false, false);
;     const float lo = __uint_as_float(s32[0]), hi = __uint_as_float(s32[1]);
;     tot = lo + hi; pre = tq == 0 ? 0.f : tq == 1 ? ev : tq == 2 ? lo : lo + ev;
; }
; template <bool FULL>
; __device__ __forceinline__ void hgrn_prep(char* lds, int s, int w, int kc, int tq, int kpos, float& gsum, s16x4& vfrag, u32x2& gvp) {
;     ...
;     float lf[4]; unsigned short qv[4], vv[4], gv[4];
; #pragma unroll
;     for (int j = 0; j < 4; ++j) { const int e = (4 * tq + j) * 128 + 16 * w + kc; lf[j] = h2f(*(const unsigned short*)(raw + e * 2)); vv[j] = *(const unsigned short*)(raw + 12288 + e * 2);
;         if (FULL) { qv[j] = *(const unsigned short*)(raw + 8192 + e * 2); gv[j] = *(const unsigned short*)(raw + 16384 + e * 2); } }
;     float G[4], glast;
;     { const float c0 = lf[0], c1 = c0 + lf[1], c2 = c1 + lf[2], c3 = c2 + lf[3];
;       float pre; row_prefix4(c3, tq, pre, glast);
;       G[0] = pre + c0; G[1] = pre + c1; G[2] = pre + c2; G[3] = pre + c3; }
.LBB0_2470:
	s_or_b64 exec, exec, s[38:39]
	v_lshlrev_b32_e32 v71, 1, v63
	s_waitcnt vmcnt(0)
	v_lshlrev_b32_e32 v4, 10, v66
	v_lshl_or_b32 v5, s4, 5, v71
	s_waitcnt lgkmcnt(0)
	s_barrier
	v_add3_u32 v7, v5, v4, 0
	ds_read_u16 v4, v7 offset:28672
	ds_read_u16 v5, v7 offset:28928
	ds_read_u16 v6, v7 offset:29184
	ds_read_u16 v17, v7 offset:29440
	v_cmp_lt_i32_e32 vcc, 0, v66
	s_waitcnt lgkmcnt(3)
	v_cvt_f32_f16_e32 v68, v4
	s_waitcnt lgkmcnt(2)
	v_cvt_f32_f16_e32 v62, v5
	s_waitcnt lgkmcnt(1)
	v_cvt_f32_f16_e32 v60, v6
	s_waitcnt lgkmcnt(0)
	v_cvt_f32_f16_e32 v37, v17
	ds_read_u16 v17, v7 offset:40960
	ds_read_u16 v69, v7 offset:36864
	ds_read_u16 v18, v7 offset:41216
	ds_read_u16 v67, v7 offset:37120
	ds_read_u16 v19, v7 offset:41472
	ds_read_u16 v61, v7 offset:37376
	ds_read_u16 v27, v7 offset:41728
	s_nop 0
	ds_read_u16 v39, v7 offset:37632
	ds_read_u16 v33, v7 offset:45056
	ds_read_u16 v35, v7 offset:45312
	ds_read_u16 v29, v7 offset:45568
	ds_read_u16 v31, v7 offset:45824
	v_add_f32_e32 v72, v68, v62
	v_add_f32_e32 v5, v72, v60
	v_add_f32_e32 v70, v5, v37
	v_mov_b32_e32 v73, v70
	v_mov_b32_e32 v4, v70
	s_nop 1
	v_permlane16_swap_b32_e32 v73, v4
	v_add_f32_e32 v4, v73, v4
	v_mov_b32_e32 v6, v4
	s_nop 1
	v_permlane32_swap_b32_e32 v4, v6
	v_mov_b32_e32 v7, 0
	s_and_saveexec_b64 s[38:39], vcc
	s_cbranch_execz .LBB0_2401
	v_cmp_ne_u32_e32 vcc, 1, v66
	s_and_saveexec_b64 s[14:15], vcc
	s_xor_b64 s[46:47], exec, s[14:15]
	v_add_f32_e32 v7, v73, v4
	v_cmp_eq_u32_e32 vcc, 2, v66
	s_nop 1
	v_cndmask_b32_e32 v7, v7, v4, vcc
	s_andn2_saveexec_b64 s[46:47], s[46:47]
	s_cbranch_execz .LBB0_2400
	v_mov_b32_e32 v7, v73
	s_branch .LBB0_2400

.Lsk2578_a:
	s_waitcnt vmcnt(4)
	ds_write_b128 v2, v[28:31]
	ds_write_b128 v2, v[40:43] offset:8192
	ds_write_b128 v2, v[56:59] offset:16384
	ds_write_b128 v2, v[60:63] offset:24576
	ds_write_b128 v2, v[68:71] offset:32768
	ds_write_b128 v2, v[72:75] offset:40960
	s_cbranch_vccnz .LBB0_2581
	v_lshl_add_u64 v[32:33], v[98:99], 0, s[20:21]
	v_add_co_u32_e32 v24, vcc, 0x10000, v32
	v_lshl_add_u64 v[44:45], v[94:95], 0, s[20:21]
	s_nop 0
	v_addc_co_u32_e32 v25, vcc, 0, v33, vcc
	s_nop 0
	v_add_co_u32_e32 v34, vcc, 0x20000, v32
	v_lshl_add_u64 v[48:49], v[96:97], 0, s[20:21]
	s_nop 0
	v_addc_co_u32_e32 v35, vcc, 0, v33, vcc
	v_add_co_u32_e32 v36, vcc, 0x30000, v32
	global_load_dwordx4 v[20:23], v[32:33], off offset:1536
	s_nop 0
	global_load_dwordx4 v[24:27], v[24:25], off offset:1536
	v_addc_co_u32_e32 v37, vcc, 0, v33, vcc
	global_load_dwordx4 v[32:35], v[34:35], off offset:1536
	s_nop 0
	global_load_dwordx4 v[36:39], v[36:37], off offset:1536
	s_nop 0
	global_load_dwordx4 v[44:47], v[44:45], off offset:1536
	s_nop 0
	global_load_dwordx4 v[48:51], v[48:49], off offset:1536
.LBB0_2581:
	s_cmp_eq_u32 s7, 1
	s_cselect_b32 s7, 0xc000, 0
	s_add_i32 s7, s7, 0
	v_add_u32_e32 v210, s7, v108
	v_add_u32_e32 v211, s7, v109
	s_cmpk_eq_i32 s20, 0xc00
	v_add_u32_e32 v208, v210, v112
	ds_read_b128 v[216:219], v208
	v_add_u32_e32 v209, v211, v112
	ds_read_b128 v[232:235], v209 offset:32768
	v_add_u32_e32 v208, v210, v113
	ds_read_b128 v[220:223], v208
	v_add_u32_e32 v209, v211, v113
	ds_read_b128 v[236:239], v209 offset:32768
	v_add_u32_e32 v208, v210, v114
	ds_read_b128 v[224:227], v208
	v_add_u32_e32 v209, v211, v114
	ds_read_b128 v[240:243], v209 offset:32768
	v_add_u32_e32 v208, v210, v115
	ds_read_b128 v[228:231], v208
	v_add_u32_e32 v209, v211, v115
	ds_read_b128 v[244:247], v209 offset:32768
	s_waitcnt lgkmcnt(6)
	v_mfma_f32_32x32x16_bf16 v[4:19], v[232:235], v[216:219], v[4:19]
	s_waitcnt lgkmcnt(4)
	v_mfma_f32_32x32x16_bf16 v[4:19], v[236:239], v[220:223], v[4:19]
	s_waitcnt lgkmcnt(2)
	s_nop 0
	v_mfma_f32_32x32x16_bf16 v[4:19], v[240:243], v[224:227], v[4:19]
	s_waitcnt lgkmcnt(0)
	s_barrier
	v_mfma_f32_32x32x16_bf16 v[4:19], v[244:247], v[228:231], v[4:19]
	s_cbranch_scc1 .LBB0_2583
	v_add_u32_e32 v120, s7, v105
	s_waitcnt vmcnt(6)
	ds_write_b128 v120, v[52:55]
	ds_write_b128 v120, v[64:67] offset:8192
	ds_write_b128 v120, v[76:79] offset:16384
	s_nop 0
	ds_write_b128 v120, v[80:83] offset:24576
	ds_write_b128 v120, v[84:87] offset:32768
	ds_write_b128 v120, v[88:91] offset:40960

; #define LAS __attribute__((address_space(3)))
; #define SK_LOAD3() do { SK_LOAD(0, 0); if (1 < nsc) SK_LOAD(1, 1); if (2 < nsc) SK_LOAD(2, 2); } while (0)
; #define SK_WRITE(s_, b) do { LAS unsigned char* bb = lds + (b) * BUF; _Pragma("unroll") for (int i = 0; i < 4; ++i) *(LAS bf16x8*)(bb + st0 + i * 8192) = ra[s_][i]; \
;         _Pragma("unroll") for (int i = 0; i < NW2; ++i) *(LAS bf16x8*)(bb + 32768 + st0 + i * 8192) = rw[s_][i]; } while (0)
; template <class Epi, int NC>
; __device__ __forceinline__ void skinny_phase(const bf16* __restrict__ A, int lda, int a_goff, const bf16* __restrict__ Bt, int ldb, int K, int ncg, int vcu, int G, const Epi& E, LAS float* rs_tab, LAS unsigned char* lds) {
;     ...
;     int u = vcu;
;     if (u < NU) { SK_PTRS(u); SK_LOAD3(); }
; #pragma unroll 1
;     while (u < NU) {
;         const int cg = (u >> 2) * NC, rb = u & 3;
;         f32x16 acc[NC] = {};
;         SK_WRITE(0, 0);
;         asm volatile("s_waitcnt lgkmcnt(0)" ::: "memory"); __builtin_amdgcn_s_barrier(); asm volatile("" ::: "memory");
; #pragma unroll 1
;         for (int c3 = 0; c3 < nsc; c3 += 3) { SK_STEP(0); SK_STEP(1); SK_STEP(2); }
;         const int un = u + G;
;         if (un < NU) { SK_PTRS(un); SK_LOAD3(); }
;         LAS float* pb = (LAS float*)lds + (w * NC) * 1024 + lane;
;         asm volatile("" : "+v"(pb));
; #pragma unroll
;         for (int g = 0; g < NC; ++g)
; #pragma unroll
;             for (int r = 0; r < 16; ++r) pb[(g * 16 + r) * 64] = acc[g][r];
;         asm volatile("s_waitcnt lgkmcnt(0)" ::: "memory"); __builtin_amdgcn_s_barrier(); asm volatile("" ::: "memory");
.LBB0_2590:
	v_add_u32_e32 v208, v210, v112
	ds_read_b128 v[216:219], v208
	v_add_u32_e32 v209, v211, v112
	ds_read_b128 v[232:235], v209 offset:32768
	v_add_u32_e32 v208, v210, v113
	ds_read_b128 v[220:223], v208
	v_add_u32_e32 v209, v211, v113
	ds_read_b128 v[236:239], v209 offset:32768
	v_add_u32_e32 v208, v210, v114
	ds_read_b128 v[224:227], v208
	v_add_u32_e32 v209, v211, v114
	ds_read_b128 v[240:243], v209 offset:32768
	v_add_u32_e32 v208, v210, v115
	ds_read_b128 v[228:231], v208
	v_add_u32_e32 v209, v211, v115
	s_nop 0
	ds_read_b128 v[244:247], v209 offset:32768
	s_waitcnt lgkmcnt(6)
	v_mfma_f32_32x32x16_bf16 v[4:19], v[232:235], v[216:219], v[4:19]
	s_waitcnt lgkmcnt(4)
	v_mfma_f32_32x32x16_bf16 v[4:19], v[236:239], v[220:223], v[4:19]
	s_waitcnt lgkmcnt(2)
	v_mfma_f32_32x32x16_bf16 v[4:19], v[240:243], v[224:227], v[4:19]
	s_waitcnt lgkmcnt(0)
	s_barrier
	v_mfma_f32_32x32x16_bf16 v[4:19], v[244:247], v[228:231], v[4:19]
.LBB0_2591:
	s_nop 0
	s_add_u32 s20, s20, 0x600
	s_addc_u32 s21, s21, 0
	s_and_b64 vcc, exec, s[36:37]
	s_cbranch_vccnz .LBB0_2593
	s_mov_b32 s5, s6
	s_branch .LBB0_2579
.LBB0_2593:
	s_add_i32 s65, s4, s64
	s_cmpk_gt_i32 s65, 0xff
	s_cselect_b64 s[20:21], -1, 0
	s_cmpk_lt_i32 s65, 0x100
	s_cbranch_scc0 .LBB0_2595
	s_lshl_b32 s5, s65, 6
	s_and_b32 s5, s5, 0xc0
	s_waitcnt vmcnt(0)
	v_add_u32_e32 v20, s5, v104
	v_ashrrev_i32_e32 v21, 31, v20
	v_lshlrev_b64 v[20:21], 12, v[20:21]
	v_lshl_add_u64 v[20:21], s[18:19], 0, v[20:21]
	s_lshl_b32 s5, s65, 3
	v_mov_b32_e32 v101, v3
	s_andn2_b32 s5, s5, 31
	v_lshl_add_u64 v[98:99], v[20:21], 0, v[100:101]
	v_add_u32_e32 v22, s5, v104
	v_ashrrev_i32_e32 v23, 31, v22
	v_add_co_u32_e32 v56, vcc, s71, v98
	v_lshlrev_b64 v[24:25], 12, v[22:23]
	s_nop 0
	v_addc_co_u32_e32 v57, vcc, 0, v99, vcc
	v_add_u32_e32 v22, 16, v22
	v_add_co_u32_e32 v76, vcc, s81, v98
	v_ashrrev_i32_e32 v23, 31, v22
	s_nop 0
	v_addc_co_u32_e32 v77, vcc, 0, v99, vcc
	s_mov_b32 s5, 0x30000
	v_lshlrev_b64 v[22:23], 12, v[22:23]
	v_add_co_u32_e32 v80, vcc, s5, v98
	v_lshl_add_u64 v[94:95], v[92:93], 0, v[24:25]
	v_lshl_add_u64 v[96:97], v[92:93], 0, v[22:23]
	v_addc_co_u32_e32 v81, vcc, 0, v99, vcc
	global_load_dwordx4 v[20:23], v[98:99], off
	global_load_dwordx4 v[28:31], v[98:99], off offset:512
	global_load_dwordx4 v[24:27], v[56:57], off
	global_load_dwordx4 v[40:43], v[56:57], off offset:512
	global_load_dwordx4 v[36:39], v[80:81], off
	global_load_dwordx4 v[60:63], v[80:81], off offset:512
	global_load_dwordx4 v[44:47], v[94:95], off
	s_nop 0
	global_load_dwordx4 v[68:71], v[94:95], off offset:512
	global_load_dwordx4 v[48:51], v[96:97], off
	global_load_dwordx4 v[72:75], v[96:97], off offset:512
	global_load_dwordx4 v[52:55], v[98:99], off offset:1024
	global_load_dwordx4 v[32:35], v[76:77], off
	global_load_dwordx4 v[64:67], v[56:57], off offset:1024
	s_nop 0
	global_load_dwordx4 v[56:59], v[76:77], off offset:512
	s_nop 0
	global_load_dwordx4 v[76:79], v[76:77], off offset:1024
	s_nop 0
	global_load_dwordx4 v[80:83], v[80:81], off offset:1024
	s_nop 0
	global_load_dwordx4 v[84:87], v[94:95], off offset:1024
	global_load_dwordx4 v[88:91], v[96:97], off offset:1024
.LBB0_2595:
	v_mov_b32_e32 v2, v110
	s_nop 1
	ds_write2st64_b32 v2, v4, v5 offset1:1
	ds_write2st64_b32 v2, v6, v7 offset0:2 offset1:3
	ds_write2st64_b32 v2, v8, v9 offset0:4 offset1:5
	ds_write2st64_b32 v2, v10, v11 offset0:6 offset1:7
	ds_write2st64_b32 v2, v12, v13 offset0:8 offset1:9
	ds_write2st64_b32 v2, v14, v15 offset0:10 offset1:11
	ds_write2st64_b32 v2, v16, v17 offset0:12 offset1:13
	ds_write2st64_b32 v2, v18, v19 offset0:14 offset1:15
	s_waitcnt lgkmcnt(0)
	s_barrier
	s_andn2_b64 vcc, exec, s[12:13]
	s_cbranch_vccnz .LBB0_2577
; __device__ __forceinline__ u32x2 pack4(float a, float b, float c, float d) { u32x2 w; w.x = cvt_pk_bf16(a, b); w.y = cvt_pk_bf16(c, d); return w; }
; template <class Epi, int NC>
; __device__ __forceinline__ void skinny_phase(const bf16* __restrict__ A, int lda, int a_goff, const bf16* __restrict__ Bt, int ldb, int K, int ncg, int vcu, int G, const Epi& E, LAS float* rs_tab, LAS unsigned char* lds) {
;     ...
;         if (kq == 0) {
;             const int row = 64 * rb + rrow; const float rs = Epi::NEEDS_RS ? rs_tab[row] : 1.f;
; #pragma unroll
;             for (int g = 0; g < NC; ++g) {
; #pragma unroll
;                 for (int r = 0; r < 16; ++r) { const int o_ = (g * 16 + r) * 64; acc[g][r] = ((pb[o_] + pb[o_ + 2 * NC * 1024]) + pb[o_ + 4 * NC * 1024]) + pb[o_ + 6 * NC * 1024]; }
;                 E(acc[g], cg + g, row, hi, rs); }
;         }
;         asm volatile("s_waitcnt lgkmcnt(0)" ::: "memory"); __builtin_amdgcn_s_barrier(); asm volatile("" ::: "memory");
;     __device__ __forceinline__ void operator()(const f32x16& acc, int u, int row, int hi, float) const {
;         float ss = 0.f;
; #pragma unroll
;         for (int q = 0; q < 4; ++q) { const int c = 32 * u + 8 * q + 4 * hi; bf16* xp = XB + (size_t)(MP + row) * D + c;
;             const u32x2 w0 = *(const u32x2*)xp; f32x4 xv = {__uint_as_float(w0.x << 16), __uint_as_float(w0.x & 0xffff0000u), __uint_as_float(w0.y << 16), __uint_as_float(w0.y & 0xffff0000u)};
;             f32x4 av = {acc[4 * q], acc[4 * q + 1], acc[4 * q + 2], acc[4 * q + 3]};
;             if (cs) av *= *(const f32x4*)(cs + c);
;             xv += av; const u32x2 w1 = pack4(xv[0], xv[1], xv[2], xv[3]); *(u32x2*)xp = w1;
;             xv = (f32x4){__uint_as_float(w1.x << 16), __uint_as_float(w1.x & 0xffff0000u), __uint_as_float(w1.y << 16), __uint_as_float(w1.y & 0xffff0000u)};
;             ss += (xv[0] * xv[0] + xv[1] * xv[1]) + (xv[2] * xv[2] + xv[3] * xv[3]); }
;         ss += __shfl_xor(ss, 32);
;         if (hi == 0) ssqS[(size_t)row * 64 + u] = ss;
;     }
	ds_read2st64_b32 v[4:5], v2 offset1:1
	ds_read2st64_b32 v[6:7], v2 offset0:32 offset1:33
	ds_read2st64_b32 v[8:9], v2 offset0:64 offset1:65
	ds_read2st64_b32 v[10:11], v2 offset0:96 offset1:97
	ds_read2st64_b32 v[12:13], v2 offset0:2 offset1:3
	ds_read2st64_b32 v[14:15], v2 offset0:34 offset1:35
	ds_read2st64_b32 v[16:17], v2 offset0:66 offset1:67
	ds_read2st64_b32 v[18:19], v2 offset0:98 offset1:99
	s_waitcnt lgkmcnt(0)
	v_pk_add_f32 v[4:5], v[4:5], v[6:7]
	s_ashr_i32 s36, s4, 2
	v_pk_add_f32 v[6:7], v[12:13], v[14:15]
	v_pk_add_f32 v[4:5], v[4:5], v[8:9]
	v_pk_add_f32 v[6:7], v[6:7], v[16:17]
	v_pk_add_f32 v[16:17], v[4:5], v[10:11]
	v_pk_add_f32 v[18:19], v[6:7], v[18:19]
	ds_read2st64_b32 v[4:5], v2 offset0:4 offset1:5
	ds_read2st64_b32 v[6:7], v2 offset0:36 offset1:37
	ds_read2st64_b32 v[8:9], v2 offset0:68 offset1:69
	ds_read2st64_b32 v[10:11], v2 offset0:100 offset1:101
	ds_read2st64_b32 v[12:13], v2 offset0:6 offset1:7
	ds_read2st64_b32 v[14:15], v2 offset0:38 offset1:39
	ds_read2st64_b32 v[116:117], v2 offset0:70 offset1:71
	ds_read2st64_b32 v[118:119], v2 offset0:102 offset1:103
	s_waitcnt lgkmcnt(0)
	s_nop 0
	v_pk_add_f32 v[4:5], v[4:5], v[6:7]
	s_lshl_b32 s4, s4, 6
	v_pk_add_f32 v[6:7], v[12:13], v[14:15]
	v_pk_add_f32 v[4:5], v[4:5], v[8:9]
	v_pk_add_f32 v[6:7], v[6:7], v[116:117]
	v_pk_add_f32 v[12:13], v[4:5], v[10:11]
	v_pk_add_f32 v[14:15], v[6:7], v[118:119]
	ds_read2st64_b32 v[4:5], v2 offset0:8 offset1:9
	s_nop 0
	ds_read2st64_b32 v[6:7], v2 offset0:40 offset1:41
	ds_read2st64_b32 v[8:9], v2 offset0:72 offset1:73
	ds_read2st64_b32 v[10:11], v2 offset0:104 offset1:105
	ds_read2st64_b32 v[116:117], v2 offset0:10 offset1:11
	ds_read2st64_b32 v[118:119], v2 offset0:42 offset1:43
	ds_read2st64_b32 v[120:121], v2 offset0:74 offset1:75
	ds_read2st64_b32 v[122:123], v2 offset0:106 offset1:107
	s_waitcnt lgkmcnt(0)
	s_nop 0
	v_pk_add_f32 v[4:5], v[4:5], v[6:7]
	s_and_b32 s4, s4, 0xc0
	v_pk_add_f32 v[6:7], v[116:117], v[118:119]
	v_pk_add_f32 v[4:5], v[4:5], v[8:9]
	v_pk_add_f32 v[6:7], v[6:7], v[120:121]
	v_or_b32_e32 v101, s4, v106
	v_pk_add_f32 v[8:9], v[4:5], v[10:11]
	v_pk_add_f32 v[10:11], v[6:7], v[122:123]
	s_nop 0
	ds_read2st64_b32 v[4:5], v2 offset0:12 offset1:13
	ds_read2st64_b32 v[6:7], v2 offset0:44 offset1:45
	ds_read2st64_b32 v[116:117], v2 offset0:76 offset1:77
	ds_read2st64_b32 v[118:119], v2 offset0:108 offset1:109
	ds_read2st64_b32 v[120:121], v2 offset0:14 offset1:15
	ds_read2st64_b32 v[122:123], v2 offset0:46 offset1:47
	ds_read2st64_b32 v[124:125], v2 offset0:78 offset1:79
	ds_read2st64_b32 v[126:127], v2 offset0:110 offset1:111
	v_lshl_or_b32 v102, s36, 5, v111
	s_waitcnt lgkmcnt(0)
	v_pk_add_f32 v[4:5], v[4:5], v[6:7]
	v_lshlrev_b32_e32 v2, 12, v101
	v_pk_add_f32 v[4:5], v[4:5], v[116:117]
	v_ashrrev_i32_e32 v103, 31, v102
	v_lshl_add_u64 v[116:117], s[0:1], 0, v[2:3]
	v_lshl_add_u64 v[116:117], v[102:103], 1, v[116:117]
	s_mov_b64 s[4:5], 0x4000000
	s_nop 0
	v_lshl_add_u64 v[102:103], v[116:117], 0, s[4:5]
	v_add_co_u32_e32 v116, vcc, s8, v116
	v_pk_add_f32 v[4:5], v[4:5], v[118:119]
	s_nop 0
	v_addc_co_u32_e32 v117, vcc, 0, v117, vcc
	global_load_dwordx2 v[118:119], v[116:117], off
	v_pk_add_f32 v[6:7], v[120:121], v[122:123]
	s_waitcnt vmcnt(0)
	v_lshlrev_b32_e32 v120, 16, v118
	v_and_b32_e32 v121, 0xffff0000, v118
	s_nop 0
	v_pk_add_f32 v[16:17], v[16:17], v[120:121]
	v_lshlrev_b32_e32 v118, 16, v119
	v_and_b32_e32 v119, 0xffff0000, v119
	v_cvt_pk_bf16_f32 v16, v16, v17
	v_pk_add_f32 v[18:19], v[18:19], v[118:119]
	v_lshlrev_b32_e32 v2, 16, v16
	v_cvt_pk_bf16_f32 v17, v18, v19
	global_store_dwordx2 v[116:117], v[16:17], off
	v_and_b32_e32 v16, 0xffff0000, v16
	v_lshlrev_b32_e32 v18, 16, v17
	v_and_b32_e32 v17, 0xffff0000, v17
	v_mul_f32_e32 v16, v16, v16
	v_fmac_f32_e32 v16, v2, v2
	v_mul_f32_e32 v2, v17, v17
	v_fmac_f32_e32 v2, v18, v18
	v_add_f32_e32 v2, v16, v2
	global_load_dwordx2 v[16:17], v[102:103], off offset:16
	v_pk_add_f32 v[6:7], v[6:7], v[124:125]
	s_waitcnt vmcnt(0)
	v_lshlrev_b32_e32 v18, 16, v16
	v_and_b32_e32 v19, 0xffff0000, v16
	v_lshlrev_b32_e32 v16, 16, v17
	v_and_b32_e32 v17, 0xffff0000, v17
	v_pk_add_f32 v[12:13], v[12:13], v[18:19]
	v_pk_add_f32 v[14:15], v[14:15], v[16:17]
	v_cvt_pk_bf16_f32 v12, v12, v13
	v_pk_add_f32 v[6:7], v[6:7], v[126:127]
	v_cvt_pk_bf16_f32 v13, v14, v15
	global_store_dwordx2 v[102:103], v[12:13], off offset:16
	v_lshlrev_b32_e32 v14, 16, v12
	v_and_b32_e32 v12, 0xffff0000, v12
	v_lshlrev_b32_e32 v15, 16, v13
	v_and_b32_e32 v13, 0xffff0000, v13
	v_mul_f32_e32 v12, v12, v12
	v_mul_f32_e32 v13, v13, v13
	v_fmac_f32_e32 v12, v14, v14
	v_fmac_f32_e32 v13, v15, v15
	v_add_f32_e32 v12, v12, v13
	v_add_f32_e32 v2, v2, v12
	global_load_dwordx2 v[12:13], v[102:103], off offset:32
	s_waitcnt vmcnt(0)
	v_lshlrev_b32_e32 v14, 16, v12
	s_nop 0
	v_and_b32_e32 v15, 0xffff0000, v12
	v_lshlrev_b32_e32 v12, 16, v13
	v_and_b32_e32 v13, 0xffff0000, v13
	v_pk_add_f32 v[8:9], v[8:9], v[14:15]
	v_pk_add_f32 v[10:11], v[10:11], v[12:13]
	v_cvt_pk_bf16_f32 v8, v8, v9
	s_nop 0
	v_cvt_pk_bf16_f32 v9, v10, v11
	global_store_dwordx2 v[102:103], v[8:9], off offset:32
	v_lshlrev_b32_e32 v10, 16, v8
	v_and_b32_e32 v8, 0xffff0000, v8
	v_lshlrev_b32_e32 v11, 16, v9
	v_and_b32_e32 v9, 0xffff0000, v9
	v_mul_f32_e32 v8, v8, v8
	v_mul_f32_e32 v9, v9, v9
	v_fmac_f32_e32 v8, v10, v10
	v_fmac_f32_e32 v9, v11, v11
	v_add_f32_e32 v8, v8, v9
	v_add_f32_e32 v2, v2, v8
	global_load_dwordx2 v[8:9], v[102:103], off offset:48
	s_waitcnt vmcnt(0)
	v_lshlrev_b32_e32 v10, 16, v8
	v_and_b32_e32 v11, 0xffff0000, v8
	v_lshlrev_b32_e32 v8, 16, v9
	v_and_b32_e32 v9, 0xffff0000, v9
	v_pk_add_f32 v[4:5], v[4:5], v[10:11]
	v_pk_add_f32 v[6:7], v[6:7], v[8:9]
	v_cvt_pk_bf16_f32 v4, v4, v5
	s_nop 0
	v_cvt_pk_bf16_f32 v5, v6, v7
	global_store_dwordx2 v[102:103], v[4:5], off offset:48
	v_lshlrev_b32_e32 v6, 16, v4
	v_and_b32_e32 v4, 0xffff0000, v4
	v_lshlrev_b32_e32 v7, 16, v5
	v_and_b32_e32 v5, 0xffff0000, v5
	v_mul_f32_e32 v4, v4, v4
	v_mul_f32_e32 v5, v5, v5
	v_fmac_f32_e32 v4, v6, v6
	v_fmac_f32_e32 v5, v7, v7
	v_add_f32_e32 v4, v4, v5
	v_and_b32_e32 v5, 64, v204
	v_add_f32_e32 v4, v2, v4
	v_xor_b32_e32 v2, 32, v204
	v_add_u32_e32 v5, 64, v5
	v_cmp_lt_i32_e32 vcc, v2, v5
	s_nop 1
	v_cndmask_b32_e32 v2, v204, v2, vcc
	v_lshlrev_b32_e32 v2, 2, v2
	ds_bpermute_b32 v5, v2, v4
	s_and_saveexec_b64 s[40:41], s[38:39]
	s_cbranch_execz .LBB0_2576
	v_lshlrev_b32_e32 v2, 8, v101
	v_lshl_add_u64 v[6:7], s[2:3], 0, v[2:3]
	s_ashr_i32 s37, s36, 31
	v_lshl_add_u64 v[6:7], s[36:37], 2, v[6:7]
	s_waitcnt lgkmcnt(0)
	v_add_f32_e32 v2, v4, v5
	s_nop 0
	global_store_dword v[6:7], v2, off
	s_branch .LBB0_2576

; #define SK_LOAD3() do { SK_LOAD(0, 0); if (1 < nsc) SK_LOAD(1, 1); if (2 < nsc) SK_LOAD(2, 2); } while (0)
; #define SK_WRITE(s_, b) do { LAS unsigned char* bb = lds + (b) * BUF; _Pragma("unroll") for (int i = 0; i < 4; ++i) *(LAS bf16x8*)(bb + st0 + i * 8192) = ra[s_][i]; \
;         _Pragma("unroll") for (int i = 0; i < NW2; ++i) *(LAS bf16x8*)(bb + 32768 + st0 + i * 8192) = rw[s_][i]; } while (0)
; template <class Epi, int NC>
; __device__ __forceinline__ void skinny_phase(const bf16* __restrict__ A, int lda, int a_goff, const bf16* __restrict__ Bt, int ldb, int K, int ncg, int vcu, int G, const Epi& E, LAS float* rs_tab, LAS unsigned char* lds) {
;     ...
;     int u = vcu;
;     if (u < NU) { SK_PTRS(u); SK_LOAD3(); }
; #pragma unroll 1
;     while (u < NU) {
;         const int cg = (u >> 2) * NC, rb = u & 3;
;         f32x16 acc[NC] = {};
;         SK_WRITE(0, 0);
;         asm volatile("s_waitcnt lgkmcnt(0)" ::: "memory"); __builtin_amdgcn_s_barrier(); asm volatile("" ::: "memory");
; #pragma unroll 1
;         for (int c3 = 0; c3 < nsc; c3 += 3) { SK_STEP(0); SK_STEP(1); SK_STEP(2); }
.LBB0_2674:
	v_add_u32_e32 v2, 0, v184
	s_waitcnt vmcnt(8) lgkmcnt(0)
	ds_write_b128 v2, v[36:39]
	ds_write_b128 v2, v[40:43] offset:8192
	ds_write_b128 v2, v[48:51] offset:16384
	ds_write_b128 v2, v[44:47] offset:24576
	s_nop 0
	ds_write_b128 v2, v[56:59] offset:32768
	ds_write_b128 v2, v[60:63] offset:40960
	ds_write_b128 v2, v[68:71] offset:49152
	ds_write_b128 v2, v[72:75] offset:57344
	s_waitcnt lgkmcnt(0)
	s_barrier
	v_mov_b32_e32 v4, 0
	s_mov_b32 s10, s62
	s_mov_b64 s[12:13], 0
	s_mov_b32 s4, 0
	s_mov_b32 s5, 0
	v_mov_b32_e32 v5, v4
	v_mov_b32_e32 v6, v4
	v_mov_b32_e32 v7, v4
	v_mov_b32_e32 v8, v4
	v_mov_b32_e32 v9, v4
	v_mov_b32_e32 v10, v4
	v_mov_b32_e32 v11, v4
	v_mov_b32_e32 v12, v4
	v_mov_b32_e32 v13, v4
	v_mov_b32_e32 v14, v4
	v_mov_b32_e32 v15, v4
	v_mov_b32_e32 v16, v4
	v_mov_b32_e32 v17, v4
	v_mov_b32_e32 v18, v4
	v_mov_b32_e32 v19, v4
	v_mov_b32_e32 v20, v4
	v_mov_b32_e32 v21, v4
	v_mov_b32_e32 v22, v4
	v_mov_b32_e32 v23, v4
	v_mov_b32_e32 v24, v4
	v_mov_b32_e32 v25, v4
	v_mov_b32_e32 v26, v4
	v_mov_b32_e32 v27, v4
	v_mov_b32_e32 v28, v4
	v_mov_b32_e32 v29, v4
	v_mov_b32_e32 v30, v4
	v_mov_b32_e32 v31, v4
	v_mov_b32_e32 v32, v4
	v_mov_b32_e32 v33, v4
	v_mov_b32_e32 v34, v4
	v_mov_b32_e32 v35, v4
	s_branch .LBB0_2677
.LBB0_2675:
	v_add_u32_e32 v156, s7, v188
	v_add_u32_e32 v157, s7, v189
	v_add_u32_e32 v158, v156, v191
	ds_read_b128 v[216:219], v158
	v_add_u32_e32 v159, v157, v191
	ds_read_b128 v[232:235], v159 offset:32768
	ds_read_b128 v[244:247], v159 offset:49152
	v_add_u32_e32 v164, v156, v192
	ds_read_b128 v[220:223], v164
	v_add_u32_e32 v165, v157, v192
	ds_read_b128 v[236:239], v165 offset:32768
	s_nop 0
	ds_read_b128 v[248:251], v165 offset:49152
	v_add_u32_e32 v180, v156, v193
	ds_read_b128 v[224:227], v180
	v_add_u32_e32 v181, v157, v193
	ds_read_b128 v[240:243], v181 offset:32768
	ds_read_b128 v[176:179], v181 offset:49152
	v_add_u32_e32 v200, v156, v194
	ds_read_b128 v[228:231], v200
	v_add_u32_e32 v201, v157, v194
	s_waitcnt lgkmcnt(8)
	s_nop 0
	v_mfma_f32_32x32x16_bf16 v[4:19], v[232:235], v[216:219], v[4:19]
	s_waitcnt lgkmcnt(7)
	v_mfma_f32_32x32x16_bf16 v[20:35], v[244:247], v[216:219], v[20:35]
	ds_read_b128 v[232:235], v201 offset:32768
	ds_read_b128 v[244:247], v201 offset:49152
	s_waitcnt lgkmcnt(7)
	v_mfma_f32_32x32x16_bf16 v[4:19], v[236:239], v[220:223], v[4:19]
	s_waitcnt lgkmcnt(6)
	v_mfma_f32_32x32x16_bf16 v[20:35], v[248:251], v[220:223], v[20:35]
	s_waitcnt lgkmcnt(4)
	v_mfma_f32_32x32x16_bf16 v[4:19], v[240:243], v[224:227], v[4:19]
	s_waitcnt lgkmcnt(3)
	v_mfma_f32_32x32x16_bf16 v[20:35], v[176:179], v[224:227], v[20:35]
	s_waitcnt lgkmcnt(1)
	v_mfma_f32_32x32x16_bf16 v[4:19], v[232:235], v[228:231], v[4:19]
	s_waitcnt lgkmcnt(0)
	s_barrier
	v_mfma_f32_32x32x16_bf16 v[20:35], v[244:247], v[228:231], v[20:35]

.Lsk2674_a:
	s_waitcnt vmcnt(6)
	s_cmp_gt_u32 s5, 4
	s_cselect_b64 s[18:19], -1, 0
	v_add_u32_e32 v2, s6, v184
	s_and_b64 vcc, exec, s[18:19]
	ds_write_b128 v2, v[52:55]
	ds_write_b128 v2, v[64:67] offset:8192
	ds_write_b128 v2, v[80:83] offset:16384
	ds_write_b128 v2, v[76:79] offset:24576
	ds_write_b128 v2, v[88:91] offset:32768
	ds_write_b128 v2, v[92:95] offset:40960
	ds_write_b128 v2, v[100:103] offset:49152
	s_nop 0
	ds_write_b128 v2, v[104:107] offset:57344
	s_cbranch_vccnz .LBB0_2679
	v_lshl_add_u64 v[44:45], v[142:143], 0, s[12:13]
	v_add_co_u32_e32 v40, vcc, 0x10000, v44
	v_lshl_add_u64 v[56:57], v[134:135], 0, s[12:13]
	s_nop 0
	v_addc_co_u32_e32 v41, vcc, 0, v45, vcc
	v_add_co_u32_e32 v46, vcc, 0x20000, v44
	global_load_dwordx4 v[36:39], v[44:45], off offset:1536
	s_nop 0
	global_load_dwordx4 v[40:43], v[40:41], off offset:1536
	v_addc_co_u32_e32 v47, vcc, 0, v45, vcc
	v_add_co_u32_e32 v44, vcc, 0x30000, v44
	v_lshl_add_u64 v[60:61], v[136:137], 0, s[12:13]
	s_nop 0
	v_addc_co_u32_e32 v45, vcc, 0, v45, vcc
	v_lshl_add_u64 v[68:69], v[138:139], 0, s[12:13]
	v_lshl_add_u64 v[72:73], v[140:141], 0, s[12:13]
	global_load_dwordx4 v[48:51], v[46:47], off offset:1536
	s_nop 0
	global_load_dwordx4 v[44:47], v[44:45], off offset:1536
	s_nop 0
	global_load_dwordx4 v[56:59], v[56:57], off offset:1536
	s_nop 0
	global_load_dwordx4 v[60:63], v[60:61], off offset:1536
	s_nop 0
	global_load_dwordx4 v[68:71], v[68:69], off offset:1536
	s_nop 0
	global_load_dwordx4 v[72:75], v[72:73], off offset:1536

.LBB0_2681:
	s_cmp_gt_u32 s5, 3
	s_cbranch_scc1 .LBB0_2683
	v_lshl_add_u64 v[76:77], v[142:143], 0, s[12:13]
	v_add_co_u32_e32 v64, vcc, 0x10000, v76
	v_lshl_add_u64 v[88:89], v[134:135], 0, s[12:13]
	s_nop 0
	v_addc_co_u32_e32 v65, vcc, 0, v77, vcc
	v_add_co_u32_e32 v78, vcc, 0x20000, v76
	global_load_dwordx4 v[52:55], v[76:77], off offset:2048
	s_nop 0
	s_nop 0
	global_load_dwordx4 v[64:67], v[64:65], off offset:2048
	v_addc_co_u32_e32 v79, vcc, 0, v77, vcc
	v_add_co_u32_e32 v76, vcc, 0x30000, v76
	v_lshl_add_u64 v[92:93], v[136:137], 0, s[12:13]
	s_nop 0
	v_addc_co_u32_e32 v77, vcc, 0, v77, vcc
	v_lshl_add_u64 v[100:101], v[138:139], 0, s[12:13]
	v_lshl_add_u64 v[104:105], v[140:141], 0, s[12:13]
	global_load_dwordx4 v[80:83], v[78:79], off offset:2048
	s_nop 0
	global_load_dwordx4 v[76:79], v[76:77], off offset:2048
	s_nop 0
	global_load_dwordx4 v[88:91], v[88:89], off offset:2048
	s_nop 0
	global_load_dwordx4 v[92:95], v[92:93], off offset:2048
	s_nop 0
	global_load_dwordx4 v[100:103], v[100:101], off offset:2048
	s_nop 0
	global_load_dwordx4 v[104:107], v[104:105], off offset:2048
.LBB0_2683:
	v_add_u32_e32 v155, s6, v188
	v_add_u32_e32 v156, s6, v189
	s_andn2_b64 vcc, exec, s[20:21]
	v_add_u32_e32 v158, v155, v191
	ds_read_b128 v[216:219], v158
	v_add_u32_e32 v159, v156, v191
	ds_read_b128 v[232:235], v159 offset:32768
	ds_read_b128 v[244:247], v159 offset:49152
	v_add_u32_e32 v164, v155, v192
	ds_read_b128 v[220:223], v164
	v_add_u32_e32 v165, v156, v192
	ds_read_b128 v[236:239], v165 offset:32768
	s_nop 0
	ds_read_b128 v[248:251], v165 offset:49152
	v_add_u32_e32 v180, v155, v193
	ds_read_b128 v[224:227], v180
	v_add_u32_e32 v181, v156, v193
	ds_read_b128 v[240:243], v181 offset:32768
	ds_read_b128 v[176:179], v181 offset:49152
	v_add_u32_e32 v200, v155, v194
	ds_read_b128 v[228:231], v200
	v_add_u32_e32 v201, v156, v194
	s_waitcnt lgkmcnt(8)
	s_nop 0
	v_mfma_f32_32x32x16_bf16 v[4:19], v[232:235], v[216:219], v[4:19]
	s_waitcnt lgkmcnt(7)
	v_mfma_f32_32x32x16_bf16 v[20:35], v[244:247], v[216:219], v[20:35]
	ds_read_b128 v[232:235], v201 offset:32768
	ds_read_b128 v[244:247], v201 offset:49152
	s_waitcnt lgkmcnt(7)
	v_mfma_f32_32x32x16_bf16 v[4:19], v[236:239], v[220:223], v[4:19]
	s_waitcnt lgkmcnt(6)
	v_mfma_f32_32x32x16_bf16 v[20:35], v[248:251], v[220:223], v[20:35]
	s_waitcnt lgkmcnt(4)
	v_mfma_f32_32x32x16_bf16 v[4:19], v[240:243], v[224:227], v[4:19]
	s_waitcnt lgkmcnt(3)
	v_mfma_f32_32x32x16_bf16 v[20:35], v[176:179], v[224:227], v[20:35]
	s_waitcnt lgkmcnt(1)
	v_mfma_f32_32x32x16_bf16 v[4:19], v[232:235], v[228:231], v[4:19]
	s_waitcnt lgkmcnt(0)
	s_barrier
	v_mfma_f32_32x32x16_bf16 v[20:35], v[244:247], v[228:231], v[20:35]
	s_cbranch_vccnz .LBB0_2676
	s_cmpk_eq_i32 s12, 0xa00
	s_cbranch_scc1 .LBB0_2686
	s_waitcnt vmcnt(8)
	ds_write_b128 v2, v[36:39]
	ds_write_b128 v2, v[40:43] offset:8192
	ds_write_b128 v2, v[48:51] offset:16384
	ds_write_b128 v2, v[44:47] offset:24576
	ds_write_b128 v2, v[56:59] offset:32768
	ds_write_b128 v2, v[60:63] offset:40960
	ds_write_b128 v2, v[68:71] offset:49152
	ds_write_b128 v2, v[72:75] offset:57344

; #define LAS __attribute__((address_space(3)))
; #define SK_LOAD3() do { SK_LOAD(0, 0); if (1 < nsc) SK_LOAD(1, 1); if (2 < nsc) SK_LOAD(2, 2); } while (0)
; template <class Epi, int NC>
; __device__ __forceinline__ void skinny_phase(const bf16* __restrict__ A, int lda, int a_goff, const bf16* __restrict__ Bt, int ldb, int K, int ncg, int vcu, int G, const Epi& E, LAS float* rs_tab, LAS unsigned char* lds) {
;     ...
;         const int un = u + G;
;         if (un < NU) { SK_PTRS(un); SK_LOAD3(); }
;         LAS float* pb = (LAS float*)lds + (w * NC) * 1024 + lane;
;         asm volatile("" : "+v"(pb));
; #pragma unroll
;         for (int g = 0; g < NC; ++g)
; #pragma unroll
;             for (int r = 0; r < 16; ++r) pb[(g * 16 + r) * 64] = acc[g][r];
;         asm volatile("s_waitcnt lgkmcnt(0)" ::: "memory"); __builtin_amdgcn_s_barrier(); asm volatile("" ::: "memory");
;         if (kq == 0) {
;             const int row = 64 * rb + rrow; const float rs = Epi::NEEDS_RS ? rs_tab[row] : 1.f;
; #pragma unroll
;             for (int g = 0; g < NC; ++g) {
; #pragma unroll
;                 for (int r = 0; r < 16; ++r) { const int o_ = (g * 16 + r) * 64; acc[g][r] = ((pb[o_] + pb[o_ + 2 * NC * 1024]) + pb[o_ + 4 * NC * 1024]) + pb[o_ + 6 * NC * 1024]; }
.LBB0_2688:
	s_add_i32 s62, s10, s59
	s_cmpk_gt_i32 s62, 0x2bf
	s_cselect_b64 s[12:13], -1, 0
	s_cmpk_lt_i32 s62, 0x2c0
	s_cbranch_scc0 .LBB0_2690
	s_lshl_b32 s5, s62, 6
	s_ashr_i32 s4, s62, 1
	s_and_b32 s5, s5, 0xc0
	s_waitcnt vmcnt(0)
	v_add_u32_e32 v36, s5, v182
	s_lshl_b32 s5, s4, 5
	s_lshl_b32 s4, s4, 4
	s_and_b32 s5, s5, 0xffffff00
	s_nop 0
	s_and_b32 s4, s4, 0x60
	s_or_b32 s4, s4, s5
	v_or_b32_e32 v2, s4, v183
	v_add_u32_e32 v38, v2, v186
	v_ashrrev_i32_e32 v39, 31, v38
	v_lshlrev_b64 v[38:39], 12, v[38:39]
	v_lshl_add_u64 v[134:135], v[132:133], 0, v[38:39]
	v_add_u32_e32 v38, v2, v187
	v_ashrrev_i32_e32 v37, 31, v36
	v_ashrrev_i32_e32 v39, 31, v38
	v_lshlrev_b64 v[36:37], 12, v[36:37]
	s_nop 0
	v_lshlrev_b64 v[38:39], 12, v[38:39]
	v_or_b32_e32 v2, 16, v2
	v_lshl_add_u64 v[136:137], v[132:133], 0, v[38:39]
	v_add_u32_e32 v38, v2, v186
	v_lshl_add_u64 v[142:143], v[144:145], 0, v[36:37]
	v_ashrrev_i32_e32 v39, 31, v38
	v_lshlrev_b64 v[38:39], 12, v[38:39]
	v_add_co_u32_e32 v80, vcc, s71, v142
	v_lshl_add_u64 v[138:139], v[132:133], 0, v[38:39]
	s_nop 0
	v_addc_co_u32_e32 v81, vcc, 0, v143, vcc
	v_add_u32_e32 v38, v2, v187
	v_add_co_u32_e32 v108, vcc, s81, v142
	v_ashrrev_i32_e32 v39, 31, v38
	s_nop 0
	v_addc_co_u32_e32 v109, vcc, 0, v143, vcc
	s_mov_b32 s4, 0x30000
	v_lshlrev_b64 v[38:39], 12, v[38:39]
	v_add_co_u32_e32 v112, vcc, s4, v142
	v_lshl_add_u64 v[140:141], v[132:133], 0, v[38:39]
	s_nop 0
	v_addc_co_u32_e32 v113, vcc, 0, v143, vcc
	global_load_dwordx4 v[36:39], v[142:143], off
	global_load_dwordx4 v[52:55], v[142:143], off offset:512
	global_load_dwordx4 v[40:43], v[80:81], off
	global_load_dwordx4 v[64:67], v[80:81], off offset:512
	global_load_dwordx4 v[44:47], v[112:113], off
	global_load_dwordx4 v[76:79], v[112:113], off offset:512
	global_load_dwordx4 v[56:59], v[134:135], off
	global_load_dwordx4 v[88:91], v[134:135], off offset:512
	global_load_dwordx4 v[60:63], v[136:137], off
	global_load_dwordx4 v[92:95], v[136:137], off offset:512
	global_load_dwordx4 v[68:71], v[138:139], off
	global_load_dwordx4 v[100:103], v[138:139], off offset:512
	global_load_dwordx4 v[72:75], v[140:141], off
	global_load_dwordx4 v[104:107], v[140:141], off offset:512
	global_load_dwordx4 v[84:87], v[142:143], off offset:1024
	global_load_dwordx4 v[48:51], v[108:109], off
	global_load_dwordx4 v[96:99], v[80:81], off offset:1024
	s_nop 0
	global_load_dwordx4 v[80:83], v[108:109], off offset:512
	s_nop 0
	global_load_dwordx4 v[108:111], v[108:109], off offset:1024
	s_nop 0
	global_load_dwordx4 v[112:115], v[112:113], off offset:1024
	s_nop 0
	global_load_dwordx4 v[116:119], v[134:135], off offset:1024
	global_load_dwordx4 v[120:123], v[136:137], off offset:1024
	global_load_dwordx4 v[124:127], v[138:139], off offset:1024
	global_load_dwordx4 v[128:131], v[140:141], off offset:1024
.LBB0_2690:
	v_mov_b32_e32 v195, v190
	ds_write2st64_b32 v195, v4, v5 offset1:1
	ds_write2st64_b32 v195, v6, v7 offset0:2 offset1:3
	ds_write2st64_b32 v195, v8, v9 offset0:4 offset1:5
	ds_write2st64_b32 v195, v10, v11 offset0:6 offset1:7
	ds_write2st64_b32 v195, v12, v13 offset0:8 offset1:9
	ds_write2st64_b32 v195, v14, v15 offset0:10 offset1:11
	s_nop 0
	ds_write2st64_b32 v195, v16, v17 offset0:12 offset1:13
	ds_write2st64_b32 v195, v18, v19 offset0:14 offset1:15
	ds_write2st64_b32 v195, v20, v21 offset0:16 offset1:17
	ds_write2st64_b32 v195, v22, v23 offset0:18 offset1:19
	ds_write2st64_b32 v195, v24, v25 offset0:20 offset1:21
	ds_write2st64_b32 v195, v26, v27 offset0:22 offset1:23
	ds_write2st64_b32 v195, v28, v29 offset0:24 offset1:25
	ds_write2st64_b32 v195, v30, v31 offset0:26 offset1:27
	ds_write2st64_b32 v195, v32, v33 offset0:28 offset1:29
	ds_write2st64_b32 v195, v34, v35 offset0:30 offset1:31
	s_waitcnt lgkmcnt(0)
	s_barrier
	s_andn2_b64 vcc, exec, s[2:3]
	s_cbranch_vccnz .LBB0_2673
	s_lshl_b32 s4, s10, 6
	s_and_b32 s4, s4, 0xc0
	v_or_b32_e32 v2, s4, v185
	v_lshl_add_u32 v4, v2, 2, 0
	v_add_u32_e32 v4, 0x20000, v4
	ds_read_b32 v4, v4
	ds_read2st64_b32 v[154:155], v195 offset1:1
	ds_read2st64_b32 v[152:153], v195 offset0:64 offset1:65
	ds_read2st64_b32 v[150:151], v195 offset0:128 offset1:129
	ds_read2st64_b32 v[34:35], v195 offset0:192 offset1:193
	ds_read2st64_b32 v[32:33], v195 offset0:2 offset1:3
	ds_read2st64_b32 v[30:31], v195 offset0:66 offset1:67
	ds_read2st64_b32 v[28:29], v195 offset0:130 offset1:131
	ds_read2st64_b32 v[26:27], v195 offset0:194 offset1:195
	ds_read2st64_b32 v[22:23], v195 offset0:4 offset1:5
	ds_read2st64_b32 v[20:21], v195 offset0:68 offset1:69
	ds_read2st64_b32 v[18:19], v195 offset0:132 offset1:133
	ds_read2st64_b32 v[16:17], v195 offset0:196 offset1:197
	ds_read2st64_b32 v[10:11], v195 offset0:6 offset1:7
	ds_read2st64_b32 v[12:13], v195 offset0:70 offset1:71
	ds_read2st64_b32 v[14:15], v195 offset0:134 offset1:135
	ds_read2st64_b32 v[24:25], v195 offset0:198 offset1:199
	ds_read2st64_b32 v[156:157], v195 offset0:8 offset1:9
	ds_read2st64_b32 v[158:159], v195 offset0:72 offset1:73
	ds_read2st64_b32 v[164:165], v195 offset0:136 offset1:137
	ds_read2st64_b32 v[172:173], v195 offset0:200 offset1:201
	ds_read2st64_b32 v[174:175], v195 offset0:10 offset1:11
	ds_read2st64_b32 v[176:177], v195 offset0:74 offset1:75
	ds_read2st64_b32 v[178:179], v195 offset0:138 offset1:139
	ds_read2st64_b32 v[180:181], v195 offset0:202 offset1:203
	ds_read2st64_b32 v[196:197], v195 offset0:12 offset1:13
	ds_read2st64_b32 v[200:201], v195 offset0:76 offset1:77
	ds_read2st64_b32 v[208:209], v195 offset0:140 offset1:141
	ds_read2st64_b32 v[210:211], v195 offset0:204 offset1:205
	ds_read2st64_b32 v[148:149], v195 offset0:14 offset1:15
	ds_read2st64_b32 v[212:213], v195 offset0:78 offset1:79
	ds_read2st64_b32 v[214:215], v195 offset0:142 offset1:143
	s_waitcnt lgkmcnt(0)
; __device__ __forceinline__ float sigmoidf_(float x) { return __builtin_amdgcn_rcpf(1.0f + fast_exp(-x)); }
; __device__ __forceinline__ u32x2 pack4(float a, float b, float c, float d) { u32x2 w; w.x = cvt_pk_bf16(a, b); w.y = cvt_pk_bf16(c, d); return w; }
; template <class Epi, int NC>
; __device__ __forceinline__ void skinny_phase(const bf16* __restrict__ A, int lda, int a_goff, const bf16* __restrict__ Bt, int ldb, int K, int ncg, int vcu, int G, const Epi& E, LAS float* rs_tab, LAS unsigned char* lds) {
;     ...
;             const int row = 64 * rb + rrow; const float rs = Epi::NEEDS_RS ? rs_tab[row] : 1.f;
; #pragma unroll
;             for (int g = 0; g < NC; ++g) {
; #pragma unroll
;                 for (int r = 0; r < 16; ++r) { const int o_ = (g * 16 + r) * 64; acc[g][r] = ((pb[o_] + pb[o_ + 2 * NC * 1024]) + pb[o_ + 4 * NC * 1024]) + pb[o_ + 6 * NC * 1024]; }
;                 E(acc[g], cg + g, row, hi, rs); }
;     __device__ __forceinline__ void operator()(const f32x16& acc, int u, int row, int hi, float rs) const {
; #pragma unroll
;         for (int q = 0; q < 2; ++q) { float o[4];
; #pragma unroll
;             for (int i = 0; i < 4; ++i) { const float gt = acc[4 * q + i] * rs, up = acc[4 * q + i + 8] * rs; o[i] = gt * sigmoidf_(gt) * up; }
;             *(u32x2*)(H + (size_t)(MP + row) * FF + 16 * u + 8 * q + 4 * hi) = pack4(o[0], o[1], o[2], o[3]); }
;     }
	v_mov_b32_e32 v216, v154
	v_mov_b32_e32 v217, v156
	v_mov_b32_e32 v218, v152
	v_mov_b32_e32 v219, v158
	v_mov_b32_e32 v156, v155
	v_mov_b32_e32 v158, v153
	v_pk_add_f32 v[216:217], v[216:217], v[218:219]
	v_mov_b32_e32 v218, v150
	v_mov_b32_e32 v219, v164
	v_pk_add_f32 v[152:153], v[156:157], v[158:159]
	v_mov_b32_e32 v164, v151
	v_pk_add_f32 v[216:217], v[216:217], v[218:219]
	v_mov_b32_e32 v219, v172
	v_pk_add_f32 v[150:151], v[152:153], v[164:165]
	v_mov_b32_e32 v172, v35
	v_mov_b32_e32 v218, v34
	v_pk_add_f32 v[34:35], v[150:151], v[172:173]
	v_pk_add_f32 v[216:217], v[216:217], v[218:219]
	v_pk_mul_f32 v[34:35], v[4:5], v[34:35] op_sel_hi:[0,1]
	v_pk_mul_f32 v[216:217], v[4:5], v[216:217] op_sel_hi:[0,1]
	v_mul_f32_e32 v5, 0xbfb8aa3b, v34
	v_exp_f32_e32 v5, v5
	v_mov_b32_e32 v150, v32
	v_mov_b32_e32 v151, v174
	v_mov_b32_e32 v152, v30
	v_add_f32_e32 v5, 1.0, v5
	v_rcp_f32_e32 v5, v5
	v_mov_b32_e32 v153, v176
	v_pk_add_f32 v[150:151], v[150:151], v[152:153]
	v_mov_b32_e32 v152, v28
	v_mov_b32_e32 v153, v178
	v_pk_add_f32 v[150:151], v[150:151], v[152:153]
	v_mov_b32_e32 v152, v26
	v_mov_b32_e32 v153, v180
	v_pk_add_f32 v[150:151], v[150:151], v[152:153]
	v_mov_b32_e32 v174, v33
	v_mov_b32_e32 v176, v31
	v_pk_mul_f32 v[150:151], v[4:5], v[150:151] op_sel_hi:[0,1]
	v_pk_add_f32 v[30:31], v[174:175], v[176:177]
	v_mov_b32_e32 v178, v29
	v_mul_f32_e32 v26, 0xbfb8aa3b, v150
	v_pk_add_f32 v[28:29], v[30:31], v[178:179]
	v_mov_b32_e32 v180, v27
	v_mul_u32_u24_e32 v2, 0x1600, v2
	v_exp_f32_e32 v32, v26
	s_nop 0
	v_pk_add_f32 v[26:27], v[28:29], v[180:181]
	v_lshlrev_b32_e32 v2, 1, v2
	v_pk_mul_f32 v[26:27], v[4:5], v[26:27] op_sel_hi:[0,1]
	v_lshl_add_u64 v[8:9], s[0:1], 0, v[2:3]
	v_mul_f32_e32 v2, 0xbfb8aa3b, v216
	v_mul_f32_e32 v28, 0xbfb8aa3b, v26
	v_exp_f32_e32 v2, v2
	v_exp_f32_e32 v28, v28
	v_add_f32_e32 v29, 1.0, v32
	v_mov_b32_e32 v30, v22
	v_add_f32_e32 v2, 1.0, v2
	v_add_f32_e32 v28, 1.0, v28
	v_rcp_f32_e32 v2, v2
	v_rcp_f32_e32 v28, v28
	v_mov_b32_e32 v31, v196
	v_mov_b32_e32 v32, v20
	v_mov_b32_e32 v33, v200
	v_mov_b32_e32 v196, v23
	v_mov_b32_e32 v200, v21
	v_pk_add_f32 v[30:31], v[30:31], v[32:33]
	v_mov_b32_e32 v32, v18
	v_mov_b32_e32 v33, v208
	v_pk_add_f32 v[20:21], v[196:197], v[200:201]
	v_mov_b32_e32 v208, v19
	v_mul_f32_e32 v5, v34, v5
	v_pk_add_f32 v[30:31], v[30:31], v[32:33]
	v_mov_b32_e32 v33, v210
	v_pk_add_f32 v[18:19], v[20:21], v[208:209]
	v_mov_b32_e32 v210, v17
	v_mul_f32_e32 v5, v5, v35
	v_mov_b32_e32 v32, v16
	v_pk_add_f32 v[16:17], v[18:19], v[210:211]
	v_mul_f32_e32 v2, v216, v2
	v_mul_f32_e32 v26, v26, v28
	v_pk_add_f32 v[30:31], v[30:31], v[32:33]
	v_pk_mul_f32 v[16:17], v[4:5], v[16:17] op_sel_hi:[0,1]
	ds_read2st64_b32 v[218:219], v195 offset0:206 offset1:207
	v_mul_f32_e32 v2, v2, v217
	v_mul_f32_e32 v27, v26, v27
	v_cvt_pk_bf16_f32 v26, v2, v5
	v_pk_mul_f32 v[30:31], v[4:5], v[30:31] op_sel_hi:[0,1]
	v_mul_f32_e32 v5, 0xbfb8aa3b, v16
	v_exp_f32_e32 v5, v5
	v_mov_b32_e32 v18, v10
	v_mov_b32_e32 v19, v148
	v_mov_b32_e32 v20, v12
	v_add_f32_e32 v5, 1.0, v5
	v_rcp_f32_e32 v5, v5
	v_mov_b32_e32 v21, v212
	v_pk_add_f32 v[18:19], v[18:19], v[20:21]
	v_mov_b32_e32 v20, v14
	v_mov_b32_e32 v21, v214
	v_pk_add_f32 v[18:19], v[18:19], v[20:21]
	v_mov_b32_e32 v20, v24
	s_waitcnt lgkmcnt(0)
	v_mov_b32_e32 v21, v218
	v_pk_add_f32 v[18:19], v[18:19], v[20:21]
	v_mov_b32_e32 v148, v11
	v_pk_mul_f32 v[18:19], v[4:5], v[18:19] op_sel_hi:[0,1]
	s_nop 0
	v_mul_f32_e32 v10, 0xbfb8aa3b, v18
	v_mov_b32_e32 v212, v13
	v_exp_f32_e32 v12, v10
	v_pk_add_f32 v[10:11], v[148:149], v[212:213]
	v_mov_b32_e32 v214, v15
	v_pk_add_f32 v[10:11], v[10:11], v[214:215]
	v_mov_b32_e32 v218, v25
	v_pk_add_f32 v[10:11], v[10:11], v[218:219]
	v_rcp_f32_e32 v29, v29
	v_pk_mul_f32 v[10:11], v[4:5], v[10:11] op_sel_hi:[0,1]
	s_nop 0
	v_mul_f32_e32 v13, 0xbfb8aa3b, v10
	v_mul_f32_e32 v2, 0xbfb8aa3b, v30
	v_exp_f32_e32 v13, v13
	s_lshl_b32 s4, s10, 3
	v_exp_f32_e32 v2, v2
	s_andn2_b32 s4, s4, 31
	v_mov_b32_e32 v147, v3
	s_ashr_i32 s5, s4, 31
	v_mul_f32_e32 v29, v150, v29
	v_lshl_add_u64 v[6:7], v[8:9], 0, v[146:147]
	v_mul_f32_e32 v29, v29, v151
	s_lshl_b64 s[18:19], s[4:5], 1
	v_add_f32_e32 v13, 1.0, v13
	v_cvt_pk_bf16_f32 v27, v29, v27
	v_lshl_add_u64 v[28:29], v[6:7], 0, s[18:19]
	s_mov_b64 s[4:5], 0xb000000
	v_add_f32_e32 v2, 1.0, v2
	v_add_f32_e32 v12, 1.0, v12
	v_rcp_f32_e32 v13, v13
	v_lshl_add_u64 v[6:7], v[28:29], 0, s[4:5]
	s_mov_b32 s4, 0xb000000
	v_rcp_f32_e32 v2, v2
	v_rcp_f32_e32 v12, v12
	v_add_co_u32_e32 v28, vcc, s4, v28
	v_lshl_add_u64 v[8:9], v[8:9], 0, s[18:19]
	s_nop 0
	v_addc_co_u32_e32 v29, vcc, 0, v29, vcc
	v_lshl_add_u64 v[8:9], v[8:9], 0, v[146:147]
	v_mul_f32_e32 v10, v10, v13
	v_add_co_u32_e32 v8, vcc, s4, v8
	v_mul_f32_e32 v2, v30, v2
	v_mul_f32_e32 v5, v16, v5
	v_mul_f32_e32 v12, v18, v12
	v_mul_f32_e32 v11, v10, v11
	v_addc_co_u32_e32 v9, vcc, 0, v9, vcc
	global_store_dwordx2 v[28:29], v[26:27], off
	v_mul_f32_e32 v2, v2, v31
	v_mul_f32_e32 v5, v5, v17
	v_mul_f32_e32 v12, v12, v19
	v_cvt_pk_bf16_f32 v10, v2, v5
	v_cvt_pk_bf16_f32 v11, v12, v11
	global_store_dwordx2 v[8:9], v[10:11], off offset:16
	ds_read2st64_b32 v[156:157], v195 offset0:16 offset1:17
	ds_read2st64_b32 v[158:159], v195 offset0:80 offset1:81
	ds_read2st64_b32 v[164:165], v195 offset0:144 offset1:145
	ds_read2st64_b32 v[196:197], v195 offset0:208 offset1:209
	ds_read2st64_b32 v[32:33], v195 offset0:18 offset1:19
	ds_read2st64_b32 v[30:31], v195 offset0:82 offset1:83
	ds_read2st64_b32 v[28:29], v195 offset0:146 offset1:147
	ds_read2st64_b32 v[26:27], v195 offset0:210 offset1:211
	ds_read2st64_b32 v[22:23], v195 offset0:20 offset1:21
	ds_read2st64_b32 v[20:21], v195 offset0:84 offset1:85
	ds_read2st64_b32 v[18:19], v195 offset0:148 offset1:149
	ds_read2st64_b32 v[16:17], v195 offset0:212 offset1:213
	ds_read2st64_b32 v[10:11], v195 offset0:22 offset1:23
	ds_read2st64_b32 v[12:13], v195 offset0:86 offset1:87
	ds_read2st64_b32 v[14:15], v195 offset0:150 offset1:151
	ds_read2st64_b32 v[24:25], v195 offset0:214 offset1:215
	ds_read2st64_b32 v[200:201], v195 offset0:24 offset1:25
	ds_read2st64_b32 v[208:209], v195 offset0:88 offset1:89
	ds_read2st64_b32 v[210:211], v195 offset0:152 offset1:153
	ds_read2st64_b32 v[212:213], v195 offset0:216 offset1:217
	ds_read2st64_b32 v[174:175], v195 offset0:26 offset1:27
	ds_read2st64_b32 v[176:177], v195 offset0:90 offset1:91
	ds_read2st64_b32 v[172:173], v195 offset0:154 offset1:155
	ds_read2st64_b32 v[154:155], v195 offset0:218 offset1:219
	ds_read2st64_b32 v[150:151], v195 offset0:28 offset1:29
	ds_read2st64_b32 v[152:153], v195 offset0:92 offset1:93
	ds_read2st64_b32 v[148:149], v195 offset0:156 offset1:157
	ds_read2st64_b32 v[34:35], v195 offset0:220 offset1:221
	s_waitcnt lgkmcnt(0)
; __device__ __forceinline__ float sigmoidf_(float x) { return __builtin_amdgcn_rcpf(1.0f + fast_exp(-x)); }
; __device__ __forceinline__ u32x2 pack4(float a, float b, float c, float d) { u32x2 w; w.x = cvt_pk_bf16(a, b); w.y = cvt_pk_bf16(c, d); return w; }
; template <class Epi, int NC>
; __device__ __forceinline__ void skinny_phase(const bf16* __restrict__ A, int lda, int a_goff, const bf16* __restrict__ Bt, int ldb, int K, int ncg, int vcu, int G, const Epi& E, LAS float* rs_tab, LAS unsigned char* lds) {
;     ...
;             const int row = 64 * rb + rrow; const float rs = Epi::NEEDS_RS ? rs_tab[row] : 1.f;
; #pragma unroll
;             for (int g = 0; g < NC; ++g) {
; #pragma unroll
;                 for (int r = 0; r < 16; ++r) { const int o_ = (g * 16 + r) * 64; acc[g][r] = ((pb[o_] + pb[o_ + 2 * NC * 1024]) + pb[o_ + 4 * NC * 1024]) + pb[o_ + 6 * NC * 1024]; }
;                 E(acc[g], cg + g, row, hi, rs); }
;     __device__ __forceinline__ void operator()(const f32x16& acc, int u, int row, int hi, float rs) const {
; #pragma unroll
;         for (int q = 0; q < 2; ++q) { float o[4];
; #pragma unroll
;             for (int i = 0; i < 4; ++i) { const float gt = acc[4 * q + i] * rs, up = acc[4 * q + i + 8] * rs; o[i] = gt * sigmoidf_(gt) * up; }
;             *(u32x2*)(H + (size_t)(MP + row) * FF + 16 * u + 8 * q + 4 * hi) = pack4(o[0], o[1], o[2], o[3]); }
;     }
	v_mov_b32_e32 v178, v156
	v_mov_b32_e32 v179, v200
	v_mov_b32_e32 v180, v158
	v_mov_b32_e32 v181, v208
	v_mov_b32_e32 v200, v157
	v_mov_b32_e32 v208, v159
	v_pk_add_f32 v[178:179], v[178:179], v[180:181]
	v_mov_b32_e32 v180, v164
	v_mov_b32_e32 v181, v210
	v_pk_add_f32 v[156:157], v[200:201], v[208:209]
	v_mov_b32_e32 v210, v165
	v_pk_add_f32 v[178:179], v[178:179], v[180:181]
	v_mov_b32_e32 v181, v212
	v_pk_add_f32 v[156:157], v[156:157], v[210:211]
	v_mov_b32_e32 v212, v197
	v_mov_b32_e32 v180, v196
	v_pk_add_f32 v[156:157], v[156:157], v[212:213]
	v_pk_add_f32 v[178:179], v[178:179], v[180:181]
	v_pk_mul_f32 v[156:157], v[4:5], v[156:157] op_sel_hi:[0,1]
	v_pk_mul_f32 v[214:215], v[4:5], v[178:179] op_sel_hi:[0,1]
	v_mul_f32_e32 v5, 0xbfb8aa3b, v156
	v_exp_f32_e32 v5, v5
	v_mov_b32_e32 v164, v32
	v_mov_b32_e32 v165, v174
	v_mov_b32_e32 v196, v30
	v_add_f32_e32 v5, 1.0, v5
	v_rcp_f32_e32 v5, v5
	v_mov_b32_e32 v197, v176
	v_pk_add_f32 v[164:165], v[164:165], v[196:197]
	v_mov_b32_e32 v196, v28
	v_mov_b32_e32 v197, v172
	v_pk_add_f32 v[164:165], v[164:165], v[196:197]
	v_mov_b32_e32 v196, v26
	v_mov_b32_e32 v197, v154
	v_pk_add_f32 v[164:165], v[164:165], v[196:197]
	v_mov_b32_e32 v174, v33
	v_mov_b32_e32 v176, v31
	v_pk_mul_f32 v[164:165], v[4:5], v[164:165] op_sel_hi:[0,1]
	v_pk_add_f32 v[30:31], v[174:175], v[176:177]
	v_mov_b32_e32 v172, v29
	v_mul_f32_e32 v26, 0xbfb8aa3b, v164
	v_pk_add_f32 v[28:29], v[30:31], v[172:173]
	v_mov_b32_e32 v154, v27
	v_exp_f32_e32 v32, v26
	v_pk_add_f32 v[26:27], v[28:29], v[154:155]
	s_nop 0
	v_mul_f32_e32 v2, 0xbfb8aa3b, v214
	v_pk_mul_f32 v[26:27], v[4:5], v[26:27] op_sel_hi:[0,1]
	v_mul_f32_e32 v28, 0xbfb8aa3b, v26
	v_exp_f32_e32 v28, v28
	v_add_f32_e32 v29, 1.0, v32
	v_rcp_f32_e32 v29, v29
	v_exp_f32_e32 v2, v2
	v_add_f32_e32 v28, 1.0, v28
	v_rcp_f32_e32 v28, v28
	v_mul_f32_e32 v29, v164, v29
	v_mul_f32_e32 v32, v29, v165
	v_mov_b32_e32 v29, v150
	v_mul_f32_e32 v26, v26, v28
	v_mov_b32_e32 v28, v22
	v_mov_b32_e32 v30, v20
	v_mov_b32_e32 v31, v152
	v_pk_add_f32 v[28:29], v[28:29], v[30:31]
	v_mov_b32_e32 v30, v18
	v_mov_b32_e32 v31, v148
	v_mul_f32_e32 v5, v156, v5
	v_pk_add_f32 v[28:29], v[28:29], v[30:31]
	v_mov_b32_e32 v30, v16
	v_mov_b32_e32 v31, v34
	v_add_f32_e32 v2, 1.0, v2
	v_mul_f32_e32 v5, v5, v157
	v_pk_add_f32 v[28:29], v[28:29], v[30:31]
	v_rcp_f32_e32 v2, v2
	v_pk_mul_f32 v[28:29], v[4:5], v[28:29] op_sel_hi:[0,1]
	v_mul_f32_e32 v16, 0xbfb8aa3b, v28
	v_exp_f32_e32 v16, v16
	v_mov_b32_e32 v150, v23
	v_mov_b32_e32 v152, v21
	v_mul_f32_e32 v2, v214, v2
	v_mul_f32_e32 v18, v26, v27
	v_pk_add_f32 v[20:21], v[150:151], v[152:153]
	v_mov_b32_e32 v148, v19
	ds_read2st64_b32 v[178:179], v195 offset0:30 offset1:31
	s_nop 0
	ds_read2st64_b32 v[180:181], v195 offset0:94 offset1:95
	ds_read2st64_b32 v[216:217], v195 offset0:158 offset1:159
	ds_read2st64_b32 v[158:159], v195 offset0:222 offset1:223
	v_mul_f32_e32 v2, v2, v215
	v_cvt_pk_bf16_f32 v26, v2, v5
	v_cvt_pk_bf16_f32 v27, v32, v18
	v_pk_add_f32 v[18:19], v[20:21], v[148:149]
	v_mov_b32_e32 v34, v17
	v_add_f32_e32 v2, 1.0, v16
	s_nop 0
	v_pk_add_f32 v[16:17], v[18:19], v[34:35]
	global_store_dwordx2 v[6:7], v[26:27], off offset:32
	v_pk_mul_f32 v[16:17], v[4:5], v[16:17] op_sel_hi:[0,1]
	v_mul_f32_e32 v5, 0xbfb8aa3b, v16
	v_exp_f32_e32 v5, v5
	v_mov_b32_e32 v6, v10
	s_waitcnt lgkmcnt(0)
	v_mov_b32_e32 v7, v178
	v_mov_b32_e32 v18, v12
	v_mov_b32_e32 v19, v180
	v_pk_add_f32 v[6:7], v[6:7], v[18:19]
	v_mov_b32_e32 v18, v14
	v_mov_b32_e32 v19, v216
	v_pk_add_f32 v[6:7], v[6:7], v[18:19]
	v_mov_b32_e32 v18, v24
	v_mov_b32_e32 v19, v158
	v_mov_b32_e32 v178, v11
	v_mov_b32_e32 v180, v13
	v_add_f32_e32 v5, 1.0, v5
	v_pk_add_f32 v[6:7], v[6:7], v[18:19]
	v_pk_add_f32 v[10:11], v[178:179], v[180:181]
	v_mov_b32_e32 v216, v15
	v_pk_mul_f32 v[6:7], v[4:5], v[6:7] op_sel_hi:[0,1]
	v_pk_add_f32 v[10:11], v[10:11], v[216:217]
	v_mov_b32_e32 v158, v25
	v_rcp_f32_e32 v20, v5
	v_mul_f32_e32 v5, 0xbfb8aa3b, v6
	v_pk_add_f32 v[10:11], v[10:11], v[158:159]
	v_exp_f32_e32 v12, v5
	v_pk_mul_f32 v[4:5], v[4:5], v[10:11] op_sel_hi:[0,1]
	v_mul_f32_e32 v10, 0xbfb8aa3b, v4
	v_exp_f32_e32 v10, v10
	v_add_f32_e32 v12, 1.0, v12
	v_rcp_f32_e32 v2, v2
	v_rcp_f32_e32 v12, v12
	v_add_f32_e32 v10, 1.0, v10
	v_rcp_f32_e32 v10, v10
	v_mul_f32_e32 v2, v28, v2
	v_mul_f32_e32 v11, v16, v20
	v_mul_f32_e32 v6, v6, v12
	v_mul_f32_e32 v4, v4, v10
	v_mul_f32_e32 v5, v4, v5
	v_mul_f32_e32 v2, v2, v29
	v_mul_f32_e32 v11, v11, v17
	v_mul_f32_e32 v6, v6, v7
	v_cvt_pk_bf16_f32 v4, v2, v11
	v_cvt_pk_bf16_f32 v5, v6, v5
	s_nop 0
	global_store_dwordx2 v[8:9], v[4:5], off offset:48
	s_branch .LBB0_2673

.LBB0_2804:
	s_cmp_lt_u32 s5, 19
	s_cselect_b64 s[40:41], -1, 0
	s_cmp_gt_u32 s5, 18
	s_cselect_b64 s[36:37], -1, 0
	s_and_b64 vcc, exec, s[36:37]
	s_cbranch_vccnz .LBB0_2806
	s_waitcnt vmcnt(12)
	v_lshl_add_u64 v[48:49], v[94:95], 0, s[20:21]
	v_add_co_u32_e32 v32, vcc, 0x2c000, v48
	s_nop 0
	v_lshl_add_u64 v[72:73], v[96:97], 0, s[20:21]
	s_nop 0
	v_addc_co_u32_e32 v33, vcc, 0, v49, vcc
	v_add_co_u32_e32 v50, vcc, 0x58000, v48
	global_load_dwordx4 v[20:23], v[48:49], off offset:1536
	s_nop 0
	global_load_dwordx4 v[32:35], v[32:33], off offset:1536
	v_addc_co_u32_e32 v51, vcc, 0, v49, vcc
	v_add_co_u32_e32 v48, vcc, 0x84000, v48
	v_lshl_add_u64 v[80:81], v[92:93], 0, s[20:21]
	s_nop 0
	v_addc_co_u32_e32 v49, vcc, 0, v49, vcc
	global_load_dwordx4 v[60:63], v[50:51], off offset:1536
	s_nop 0
	global_load_dwordx4 v[48:51], v[48:49], off offset:1536
	s_nop 0
	global_load_dwordx4 v[72:75], v[72:73], off offset:1536
	s_nop 0
	global_load_dwordx4 v[80:83], v[80:81], off offset:1536

; template <class Epi, int NC>
; __device__ __forceinline__ void skinny_phase(const bf16* __restrict__ A, int lda, int a_goff, const bf16* __restrict__ Bt, int ldb, int K, int ncg, int vcu, int G, const Epi& E, LAS float* rs_tab, LAS unsigned char* lds) {
;     ...
;         for (int c3 = 0; c3 < nsc; c3 += 3) { SK_STEP(0); SK_STEP(1); SK_STEP(2); }
.LBB0_2809:
	s_cmp_gt_u32 s5, 17
	s_cbranch_scc1 .LBB0_2811
	s_waitcnt vmcnt(12)
	v_lshl_add_u64 v[44:45], v[94:95], 0, s[20:21]
	s_nop 0
	v_add_co_u32_e32 v28, vcc, 0x2c000, v44
	v_lshl_add_u64 v[68:69], v[96:97], 0, s[20:21]
	s_nop 0
	v_addc_co_u32_e32 v29, vcc, 0, v45, vcc
	v_add_co_u32_e32 v46, vcc, 0x58000, v44
	global_load_dwordx4 v[24:27], v[44:45], off offset:2048
	s_nop 0
	global_load_dwordx4 v[28:31], v[28:29], off offset:2048
	v_addc_co_u32_e32 v47, vcc, 0, v45, vcc
	v_add_co_u32_e32 v44, vcc, 0x84000, v44
	v_lshl_add_u64 v[76:77], v[92:93], 0, s[20:21]
	s_nop 0
	v_addc_co_u32_e32 v45, vcc, 0, v45, vcc
	global_load_dwordx4 v[56:59], v[46:47], off offset:2048
	s_nop 0
	global_load_dwordx4 v[44:47], v[44:45], off offset:2048
	s_nop 0
	global_load_dwordx4 v[68:71], v[68:69], off offset:2048
	s_nop 0
	global_load_dwordx4 v[76:79], v[76:77], off offset:2048
.LBB0_2811:
	s_bitcmp1_b32 s6, 0
	s_cselect_b32 s6, 0xc000, 0
	s_add_i32 s6, s6, 0
	v_add_u32_e32 v212, s6, v108
	v_add_u32_e32 v213, s6, v109
	v_add_u32_e32 v208, v212, v112
	ds_read_b128 v[216:219], v208
	v_add_u32_e32 v209, v213, v112
	ds_read_b128 v[232:235], v209 offset:32768
	v_add_u32_e32 v208, v212, v113
	ds_read_b128 v[220:223], v208
	v_add_u32_e32 v209, v213, v113
	s_nop 0
	ds_read_b128 v[236:239], v209 offset:32768
	v_add_u32_e32 v208, v212, v114
	ds_read_b128 v[224:227], v208
	v_add_u32_e32 v209, v213, v114
	ds_read_b128 v[240:243], v209 offset:32768
	v_add_u32_e32 v208, v212, v115
	ds_read_b128 v[228:231], v208
	v_add_u32_e32 v209, v213, v115
	ds_read_b128 v[244:247], v209 offset:32768
	s_waitcnt lgkmcnt(6)
	s_nop 0
	v_mfma_f32_32x32x16_bf16 v[4:19], v[232:235], v[216:219], v[4:19]
	s_waitcnt lgkmcnt(4)
	v_mfma_f32_32x32x16_bf16 v[4:19], v[236:239], v[220:223], v[4:19]
	s_waitcnt lgkmcnt(2)
	v_mfma_f32_32x32x16_bf16 v[4:19], v[240:243], v[224:227], v[4:19]
	s_waitcnt lgkmcnt(0)
	s_barrier
	v_mfma_f32_32x32x16_bf16 v[4:19], v[244:247], v[228:231], v[4:19]
	s_add_i32 s6, s5, 3
	s_cmp_gt_u32 s5, 19
	s_cbranch_scc0 .LBB0_2814
.LBB0_2812:
	s_nop 0
	s_add_u32 s20, s20, 0x600
	s_addc_u32 s21, s21, 0
	s_and_b64 vcc, exec, s[36:37]
	s_cbranch_vccz .LBB0_2819
	s_branch .LBB0_2820

; template <class Epi, int NC>
; __device__ __forceinline__ void skinny_phase(const bf16* __restrict__ A, int lda, int a_goff, const bf16* __restrict__ Bt, int ldb, int K, int ncg, int vcu, int G, const Epi& E, LAS float* rs_tab, LAS unsigned char* lds) {
;     ...
;         for (int c3 = 0; c3 < nsc; c3 += 3) { SK_STEP(0); SK_STEP(1); SK_STEP(2); }
.LBB0_2818:
	v_add_u32_e32 v208, v210, v112
	ds_read_b128 v[216:219], v208
	v_add_u32_e32 v209, v211, v112
	ds_read_b128 v[232:235], v209 offset:32768
	v_add_u32_e32 v208, v210, v113
	ds_read_b128 v[220:223], v208
	v_add_u32_e32 v209, v211, v113
	ds_read_b128 v[236:239], v209 offset:32768
	v_add_u32_e32 v208, v210, v114
	ds_read_b128 v[224:227], v208
	v_add_u32_e32 v209, v211, v114
	ds_read_b128 v[240:243], v209 offset:32768
	v_add_u32_e32 v208, v210, v115
	ds_read_b128 v[228:231], v208
	v_add_u32_e32 v209, v211, v115
	ds_read_b128 v[244:247], v209 offset:32768
	s_waitcnt lgkmcnt(6)
	v_mfma_f32_32x32x16_bf16 v[4:19], v[232:235], v[216:219], v[4:19]
	s_waitcnt lgkmcnt(4)
	s_nop 0
	v_mfma_f32_32x32x16_bf16 v[4:19], v[236:239], v[220:223], v[4:19]
	s_waitcnt lgkmcnt(2)
	v_mfma_f32_32x32x16_bf16 v[4:19], v[240:243], v[224:227], v[4:19]
	s_waitcnt lgkmcnt(0)
	s_barrier
	v_mfma_f32_32x32x16_bf16 v[4:19], v[244:247], v[228:231], v[4:19]
	s_add_u32 s20, s20, 0x600
	s_addc_u32 s21, s21, 0
	s_and_b64 vcc, exec, s[36:37]
	s_cbranch_vccnz .LBB0_2820

; #define LAS __attribute__((address_space(3)))
; #define SK_LOAD3() do { SK_LOAD(0, 0); if (1 < nsc) SK_LOAD(1, 1); if (2 < nsc) SK_LOAD(2, 2); } while (0)
; template <class Epi, int NC>
; __device__ __forceinline__ void skinny_phase(const bf16* __restrict__ A, int lda, int a_goff, const bf16* __restrict__ Bt, int ldb, int K, int ncg, int vcu, int G, const Epi& E, LAS float* rs_tab, LAS unsigned char* lds) {
;     ...
;         const int un = u + G;
;         if (un < NU) { SK_PTRS(un); SK_LOAD3(); }
;         LAS float* pb = (LAS float*)lds + (w * NC) * 1024 + lane;
;         asm volatile("" : "+v"(pb));
; #pragma unroll
;         for (int g = 0; g < NC; ++g)
; #pragma unroll
;             for (int r = 0; r < 16; ++r) pb[(g * 16 + r) * 64] = acc[g][r];
;         asm volatile("s_waitcnt lgkmcnt(0)" ::: "memory"); __builtin_amdgcn_s_barrier(); asm volatile("" ::: "memory");
.LBB0_2820:
	s_add_i32 s62, s4, s59
	s_cmpk_gt_i32 s62, 0xff
	s_cselect_b64 s[20:21], -1, 0
	s_cmpk_lt_i32 s62, 0x100
	s_cbranch_scc0 .LBB0_2822
	s_lshl_b32 s5, s62, 6
	s_and_b32 s5, s5, 0xc0
	v_add_u32_e32 v2, s5, v104
	s_waitcnt vmcnt(0)
	v_mov_b64_e32 v[20:21], s[18:19]
	s_movk_i32 s9, 0x2c00
	v_mad_i64_i32 v[20:21], s[6:7], v2, s9, v[20:21]
	v_mov_b32_e32 v101, v3
	s_lshl_b32 s5, s62, 3
	v_lshl_add_u64 v[94:95], v[20:21], 0, v[100:101]
	s_andn2_b32 s5, s5, 31
	v_add_u32_e32 v2, s5, v104
	v_add_co_u32_e32 v40, vcc, s10, v94
	s_mov_b32 s5, 0x58000
	s_nop 0
	v_addc_co_u32_e32 v41, vcc, 0, v95, vcc
	v_add_co_u32_e32 v52, vcc, s5, v94
	s_mov_b32 s5, 0x84000
	s_nop 0
	v_addc_co_u32_e32 v53, vcc, 0, v95, vcc
	v_mad_i64_i32 v[96:97], s[6:7], v2, s9, v[98:99]
	v_add_u32_e32 v2, 16, v2
	v_add_co_u32_e32 v64, vcc, s5, v94
	v_mad_i64_i32 v[92:93], s[6:7], v2, s9, v[98:99]
	s_nop 0
	v_addc_co_u32_e32 v65, vcc, 0, v95, vcc
	global_load_dwordx4 v[20:23], v[94:95], off
	global_load_dwordx4 v[24:27], v[94:95], off offset:512
	global_load_dwordx4 v[32:35], v[40:41], off
	global_load_dwordx4 v[28:31], v[40:41], off offset:512
	global_load_dwordx4 v[48:51], v[64:65], off
	global_load_dwordx4 v[44:47], v[64:65], off offset:512
	global_load_dwordx4 v[72:75], v[96:97], off
	global_load_dwordx4 v[68:71], v[96:97], off offset:512
	global_load_dwordx4 v[80:83], v[92:93], off
	global_load_dwordx4 v[76:79], v[92:93], off offset:512
	global_load_dwordx4 v[36:39], v[94:95], off offset:1024
	global_load_dwordx4 v[60:63], v[52:53], off
	s_nop 0
	s_nop 0
	global_load_dwordx4 v[40:43], v[40:41], off offset:1024
	s_nop 0
	global_load_dwordx4 v[56:59], v[52:53], off offset:512
	s_nop 0
	global_load_dwordx4 v[52:55], v[52:53], off offset:1024
	s_nop 0
	global_load_dwordx4 v[64:67], v[64:65], off offset:1024
	s_nop 0
	global_load_dwordx4 v[84:87], v[96:97], off offset:1024
	global_load_dwordx4 v[88:91], v[92:93], off offset:1024
.LBB0_2822:
	v_mov_b32_e32 v2, v110
	s_nop 1
	ds_write2st64_b32 v2, v4, v5 offset1:1
	ds_write2st64_b32 v2, v6, v7 offset0:2 offset1:3
	ds_write2st64_b32 v2, v8, v9 offset0:4 offset1:5
	ds_write2st64_b32 v2, v10, v11 offset0:6 offset1:7
	ds_write2st64_b32 v2, v12, v13 offset0:8 offset1:9
	ds_write2st64_b32 v2, v14, v15 offset0:10 offset1:11
	ds_write2st64_b32 v2, v16, v17 offset0:12 offset1:13
	ds_write2st64_b32 v2, v18, v19 offset0:14 offset1:15
	s_waitcnt lgkmcnt(0)
	s_barrier
	s_andn2_b64 vcc, exec, s[12:13]
	s_cbranch_vccnz .LBB0_2800
; __device__ __forceinline__ u32x2 pack4(float a, float b, float c, float d) { u32x2 w; w.x = cvt_pk_bf16(a, b); w.y = cvt_pk_bf16(c, d); return w; }
; template <class Epi, int NC>
; __device__ __forceinline__ void skinny_phase(const bf16* __restrict__ A, int lda, int a_goff, const bf16* __restrict__ Bt, int ldb, int K, int ncg, int vcu, int G, const Epi& E, LAS float* rs_tab, LAS unsigned char* lds) {
;     ...
;         if (kq == 0) {
;             const int row = 64 * rb + rrow; const float rs = Epi::NEEDS_RS ? rs_tab[row] : 1.f;
; #pragma unroll
;             for (int g = 0; g < NC; ++g) {
; #pragma unroll
;                 for (int r = 0; r < 16; ++r) { const int o_ = (g * 16 + r) * 64; acc[g][r] = ((pb[o_] + pb[o_ + 2 * NC * 1024]) + pb[o_ + 4 * NC * 1024]) + pb[o_ + 6 * NC * 1024]; }
;                 E(acc[g], cg + g, row, hi, rs); }
;         }
;         asm volatile("s_waitcnt lgkmcnt(0)" ::: "memory"); __builtin_amdgcn_s_barrier(); asm volatile("" ::: "memory");
;     __device__ __forceinline__ void operator()(const f32x16& acc, int u, int row, int hi, float) const {
;         float ss = 0.f;
; #pragma unroll
;         for (int q = 0; q < 4; ++q) { const int c = 32 * u + 8 * q + 4 * hi; bf16* xp = XB + (size_t)(MP + row) * D + c;
;             const u32x2 w0 = *(const u32x2*)xp; f32x4 xv = {__uint_as_float(w0.x << 16), __uint_as_float(w0.x & 0xffff0000u), __uint_as_float(w0.y << 16), __uint_as_float(w0.y & 0xffff0000u)};
;             f32x4 av = {acc[4 * q], acc[4 * q + 1], acc[4 * q + 2], acc[4 * q + 3]};
;             if (cs) av *= *(const f32x4*)(cs + c);
;             xv += av; const u32x2 w1 = pack4(xv[0], xv[1], xv[2], xv[3]); *(u32x2*)xp = w1;
;             xv = (f32x4){__uint_as_float(w1.x << 16), __uint_as_float(w1.x & 0xffff0000u), __uint_as_float(w1.y << 16), __uint_as_float(w1.y & 0xffff0000u)};
;             ss += (xv[0] * xv[0] + xv[1] * xv[1]) + (xv[2] * xv[2] + xv[3] * xv[3]); }
;         ss += __shfl_xor(ss, 32);
;         if (hi == 0) ssqS[(size_t)row * 64 + u] = ss;
;     }
	ds_read2st64_b32 v[4:5], v2 offset1:1
	ds_read2st64_b32 v[6:7], v2 offset0:32 offset1:33
	ds_read2st64_b32 v[8:9], v2 offset0:64 offset1:65
	ds_read2st64_b32 v[10:11], v2 offset0:96 offset1:97
	ds_read2st64_b32 v[12:13], v2 offset0:2 offset1:3
	ds_read2st64_b32 v[14:15], v2 offset0:34 offset1:35
	ds_read2st64_b32 v[16:17], v2 offset0:66 offset1:67
	ds_read2st64_b32 v[18:19], v2 offset0:98 offset1:99
	s_waitcnt lgkmcnt(0)
	v_pk_add_f32 v[4:5], v[4:5], v[6:7]
	s_ashr_i32 s36, s4, 2
	v_pk_add_f32 v[6:7], v[12:13], v[14:15]
	v_pk_add_f32 v[4:5], v[4:5], v[8:9]
	v_pk_add_f32 v[6:7], v[6:7], v[16:17]
	v_pk_add_f32 v[16:17], v[4:5], v[10:11]
	v_pk_add_f32 v[18:19], v[6:7], v[18:19]
	ds_read2st64_b32 v[4:5], v2 offset0:4 offset1:5
	ds_read2st64_b32 v[6:7], v2 offset0:36 offset1:37
	ds_read2st64_b32 v[8:9], v2 offset0:68 offset1:69
	ds_read2st64_b32 v[10:11], v2 offset0:100 offset1:101
	ds_read2st64_b32 v[12:13], v2 offset0:6 offset1:7
	ds_read2st64_b32 v[14:15], v2 offset0:38 offset1:39
	ds_read2st64_b32 v[116:117], v2 offset0:70 offset1:71
	ds_read2st64_b32 v[118:119], v2 offset0:102 offset1:103
	s_waitcnt lgkmcnt(0)
	v_pk_add_f32 v[4:5], v[4:5], v[6:7]
	s_lshl_b32 s4, s4, 6
	v_pk_add_f32 v[6:7], v[12:13], v[14:15]
	v_pk_add_f32 v[4:5], v[4:5], v[8:9]
	v_pk_add_f32 v[6:7], v[6:7], v[116:117]
	v_pk_add_f32 v[12:13], v[4:5], v[10:11]
	v_pk_add_f32 v[14:15], v[6:7], v[118:119]
	ds_read2st64_b32 v[4:5], v2 offset0:8 offset1:9
	ds_read2st64_b32 v[6:7], v2 offset0:40 offset1:41
	ds_read2st64_b32 v[8:9], v2 offset0:72 offset1:73
	ds_read2st64_b32 v[10:11], v2 offset0:104 offset1:105
	ds_read2st64_b32 v[116:117], v2 offset0:10 offset1:11
	ds_read2st64_b32 v[118:119], v2 offset0:42 offset1:43
	ds_read2st64_b32 v[120:121], v2 offset0:74 offset1:75
	ds_read2st64_b32 v[122:123], v2 offset0:106 offset1:107
	s_waitcnt lgkmcnt(0)
	v_pk_add_f32 v[4:5], v[4:5], v[6:7]
	s_and_b32 s4, s4, 0xc0
	v_pk_add_f32 v[6:7], v[116:117], v[118:119]
	v_pk_add_f32 v[4:5], v[4:5], v[8:9]
	v_pk_add_f32 v[6:7], v[6:7], v[120:121]
	v_or_b32_e32 v101, s4, v106
	v_pk_add_f32 v[8:9], v[4:5], v[10:11]
	v_pk_add_f32 v[10:11], v[6:7], v[122:123]
	ds_read2st64_b32 v[4:5], v2 offset0:12 offset1:13
	ds_read2st64_b32 v[6:7], v2 offset0:44 offset1:45
	ds_read2st64_b32 v[116:117], v2 offset0:76 offset1:77
	ds_read2st64_b32 v[118:119], v2 offset0:108 offset1:109
	ds_read2st64_b32 v[120:121], v2 offset0:14 offset1:15
	ds_read2st64_b32 v[122:123], v2 offset0:46 offset1:47
	ds_read2st64_b32 v[124:125], v2 offset0:78 offset1:79
	ds_read2st64_b32 v[126:127], v2 offset0:110 offset1:111
	v_lshl_or_b32 v102, s36, 5, v111
	s_waitcnt lgkmcnt(0)
	v_pk_add_f32 v[4:5], v[4:5], v[6:7]
	v_lshlrev_b32_e32 v2, 12, v101
	v_pk_add_f32 v[4:5], v[4:5], v[116:117]
	v_ashrrev_i32_e32 v103, 31, v102
	v_lshl_add_u64 v[116:117], s[0:1], 0, v[2:3]
	v_lshl_add_u64 v[116:117], v[102:103], 1, v[116:117]
	s_nop 0
	s_mov_b64 s[4:5], 0x4000000
	v_lshl_add_u64 v[102:103], v[116:117], 0, s[4:5]
	v_add_co_u32_e32 v116, vcc, s8, v116
	v_pk_add_f32 v[4:5], v[4:5], v[118:119]
	s_nop 0
	v_addc_co_u32_e32 v117, vcc, 0, v117, vcc
	global_load_dwordx2 v[118:119], v[116:117], off
	v_pk_add_f32 v[6:7], v[120:121], v[122:123]
	s_waitcnt vmcnt(0)
	v_lshlrev_b32_e32 v120, 16, v118
	s_nop 0
	v_and_b32_e32 v121, 0xffff0000, v118
	v_pk_add_f32 v[16:17], v[16:17], v[120:121]
	v_lshlrev_b32_e32 v118, 16, v119
	v_and_b32_e32 v119, 0xffff0000, v119
	v_cvt_pk_bf16_f32 v16, v16, v17
	v_pk_add_f32 v[18:19], v[18:19], v[118:119]
	v_lshlrev_b32_e32 v2, 16, v16
	v_cvt_pk_bf16_f32 v17, v18, v19
	global_store_dwordx2 v[116:117], v[16:17], off
	v_and_b32_e32 v16, 0xffff0000, v16
	v_lshlrev_b32_e32 v18, 16, v17
	v_and_b32_e32 v17, 0xffff0000, v17
	v_mul_f32_e32 v16, v16, v16
	v_fmac_f32_e32 v16, v2, v2
	v_mul_f32_e32 v2, v17, v17
	v_fmac_f32_e32 v2, v18, v18
	v_add_f32_e32 v2, v16, v2
	global_load_dwordx2 v[16:17], v[102:103], off offset:16
	v_pk_add_f32 v[6:7], v[6:7], v[124:125]
	s_waitcnt vmcnt(0)
	v_lshlrev_b32_e32 v18, 16, v16
	v_and_b32_e32 v19, 0xffff0000, v16
	v_lshlrev_b32_e32 v16, 16, v17
	v_and_b32_e32 v17, 0xffff0000, v17
	v_pk_add_f32 v[12:13], v[12:13], v[18:19]
	v_pk_add_f32 v[14:15], v[14:15], v[16:17]
	v_cvt_pk_bf16_f32 v12, v12, v13
	v_pk_add_f32 v[6:7], v[6:7], v[126:127]
	v_cvt_pk_bf16_f32 v13, v14, v15
	s_nop 0
	global_store_dwordx2 v[102:103], v[12:13], off offset:16
	v_lshlrev_b32_e32 v14, 16, v12
	v_and_b32_e32 v12, 0xffff0000, v12
	v_lshlrev_b32_e32 v15, 16, v13
	v_and_b32_e32 v13, 0xffff0000, v13
	v_mul_f32_e32 v12, v12, v12
	v_mul_f32_e32 v13, v13, v13
	v_fmac_f32_e32 v12, v14, v14
	v_fmac_f32_e32 v13, v15, v15
	v_add_f32_e32 v12, v12, v13
	v_add_f32_e32 v2, v2, v12
	global_load_dwordx2 v[12:13], v[102:103], off offset:32
	s_waitcnt vmcnt(0)
	v_lshlrev_b32_e32 v14, 16, v12
	v_and_b32_e32 v15, 0xffff0000, v12
	v_lshlrev_b32_e32 v12, 16, v13
	v_and_b32_e32 v13, 0xffff0000, v13
	v_pk_add_f32 v[8:9], v[8:9], v[14:15]
	v_pk_add_f32 v[10:11], v[10:11], v[12:13]
	v_cvt_pk_bf16_f32 v8, v8, v9
	s_nop 0
	v_cvt_pk_bf16_f32 v9, v10, v11
	global_store_dwordx2 v[102:103], v[8:9], off offset:32
	v_lshlrev_b32_e32 v10, 16, v8
	v_and_b32_e32 v8, 0xffff0000, v8
	v_lshlrev_b32_e32 v11, 16, v9
	v_and_b32_e32 v9, 0xffff0000, v9
	v_mul_f32_e32 v8, v8, v8
	v_mul_f32_e32 v9, v9, v9
	v_fmac_f32_e32 v8, v10, v10
	v_fmac_f32_e32 v9, v11, v11
	v_add_f32_e32 v8, v8, v9
	v_add_f32_e32 v2, v2, v8
	global_load_dwordx2 v[8:9], v[102:103], off offset:48
	s_waitcnt vmcnt(0)
	v_lshlrev_b32_e32 v10, 16, v8
	v_and_b32_e32 v11, 0xffff0000, v8
	v_lshlrev_b32_e32 v8, 16, v9
	v_and_b32_e32 v9, 0xffff0000, v9
	v_pk_add_f32 v[4:5], v[4:5], v[10:11]
	v_pk_add_f32 v[6:7], v[6:7], v[8:9]
	v_cvt_pk_bf16_f32 v4, v4, v5
	s_nop 0
	v_cvt_pk_bf16_f32 v5, v6, v7
	global_store_dwordx2 v[102:103], v[4:5], off offset:48
	v_lshlrev_b32_e32 v6, 16, v4
	v_and_b32_e32 v4, 0xffff0000, v4
	v_lshlrev_b32_e32 v7, 16, v5
	v_and_b32_e32 v5, 0xffff0000, v5
	v_mul_f32_e32 v4, v4, v4
	v_mul_f32_e32 v5, v5, v5
	v_fmac_f32_e32 v4, v6, v6
	v_fmac_f32_e32 v5, v7, v7
	v_add_f32_e32 v4, v4, v5
	v_and_b32_e32 v5, 64, v204
	v_add_f32_e32 v4, v2, v4
	v_xor_b32_e32 v2, 32, v204
	v_add_u32_e32 v5, 64, v5
	v_cmp_lt_i32_e32 vcc, v2, v5
	s_nop 1
	v_cndmask_b32_e32 v2, v204, v2, vcc
	v_lshlrev_b32_e32 v2, 2, v2
	ds_bpermute_b32 v5, v2, v4
	s_and_saveexec_b64 s[40:41], s[38:39]
	s_cbranch_execz .LBB0_2799
	v_lshlrev_b32_e32 v2, 8, v101
	v_lshl_add_u64 v[6:7], s[2:3], 0, v[2:3]
	s_ashr_i32 s37, s36, 31
	v_lshl_add_u64 v[6:7], s[36:37], 2, v[6:7]
	s_waitcnt lgkmcnt(0)
	v_add_f32_e32 v2, v4, v5
	global_store_dword v[6:7], v2, off
	s_branch .LBB0_2799

; __device__ __forceinline__ unsigned xb_ld(unsigned* p)              { return __hip_atomic_load(p, __ATOMIC_RELAXED, __HIP_MEMORY_SCOPE_AGENT); }
; __device__ __forceinline__ void xcd_barrier_complete(unsigned* bar, unsigned x, unsigned& nloc, unsigned& nx) {
;     const unsigned G = gridDim.x * gridDim.y * gridDim.z;
;     unsigned sum, cnt, mine, sp = 0u;
;     for (;;) {
;         sum = 0u; cnt = 0u; mine = 0u;
; #pragma unroll
;         for (unsigned j = 0; j < 16; ++j) { const unsigned c = xb_ld(&bar[XB_XCNT(j)]); sum += c; cnt += (c > 0u) ? 1u : 0u; mine = (j == x) ? c : mine; }
;         if (sum == G) break;
;         __builtin_amdgcn_s_sleep(1);
;         if ((++sp & 255u) == 0u) { if (xb_ld(&bar[XB_TMO])) break; if (sp > XB_SPIN_CAP) { atomicAdd(&bar[XB_TMO], 1u); break; } }
;     }
.LBB0_2831:
	v_readlane_b32 s2, v254, 6
	v_readlane_b32 s3, v254, 7
	global_load_dword v2, v17, s[82:83] sc1
	global_load_dword v1, v17, s[84:85] sc1
	s_mov_b64 s[10:11], -1
	s_waitcnt vmcnt(0)
	v_add_u32_e32 v18, v1, v2
	global_load_dword v3, v17, s[2:3] sc1
	v_readlane_b32 s2, v254, 8
	v_readlane_b32 s3, v254, 9
	s_waitcnt vmcnt(0)
	v_add_u32_e32 v18, v18, v3
	s_nop 2
	global_load_dword v4, v17, s[2:3] sc1
	v_readlane_b32 s2, v254, 10
	v_readlane_b32 s3, v254, 11
	s_waitcnt vmcnt(0)
	v_add_u32_e32 v18, v18, v4
	s_nop 2
	global_load_dword v5, v17, s[2:3] sc1
	v_readlane_b32 s2, v254, 12
	v_readlane_b32 s3, v254, 13
	s_waitcnt vmcnt(0)
	v_add_u32_e32 v18, v18, v5
	s_nop 2
	global_load_dword v6, v17, s[2:3] sc1
	v_readlane_b32 s2, v254, 14
	v_readlane_b32 s3, v254, 15
	s_waitcnt vmcnt(0)
	v_add_u32_e32 v18, v18, v6
	s_nop 2
	global_load_dword v7, v17, s[2:3] sc1
	v_readlane_b32 s2, v254, 16
	v_readlane_b32 s3, v254, 17
	s_waitcnt vmcnt(0)
	v_add_u32_e32 v18, v18, v7
	s_nop 2
	global_load_dword v8, v17, s[2:3] sc1
	v_readlane_b32 s2, v254, 18
	v_readlane_b32 s3, v254, 19
	s_waitcnt vmcnt(0)
	v_add_u32_e32 v18, v18, v8
	s_nop 2
	global_load_dword v9, v17, s[2:3] sc1
	v_readlane_b32 s2, v254, 20
	v_readlane_b32 s3, v254, 21
	s_waitcnt vmcnt(0)
	v_add_u32_e32 v18, v18, v9
	s_nop 2
	global_load_dword v10, v17, s[2:3] sc1
	v_readlane_b32 s2, v254, 22
	v_readlane_b32 s3, v254, 23
	s_waitcnt vmcnt(0)
	v_add_u32_e32 v18, v18, v10
	s_nop 2
	global_load_dword v11, v17, s[2:3] sc1
	v_readlane_b32 s2, v254, 24
	s_nop 0
	v_readlane_b32 s3, v254, 25
	s_waitcnt vmcnt(0)
	v_add_u32_e32 v18, v18, v11
	s_nop 2
	global_load_dword v12, v17, s[2:3] sc1
	v_readlane_b32 s2, v254, 26
	v_readlane_b32 s3, v254, 27
	s_waitcnt vmcnt(0)
	v_add_u32_e32 v18, v18, v12
	s_nop 2
	global_load_dword v13, v17, s[2:3] sc1
	v_readlane_b32 s2, v254, 28
	v_readlane_b32 s3, v254, 29
	s_waitcnt vmcnt(0)
	v_add_u32_e32 v18, v18, v13
	s_nop 2
	global_load_dword v14, v17, s[2:3] sc1
	v_readlane_b32 s2, v254, 30
	v_readlane_b32 s3, v254, 31
	s_waitcnt vmcnt(0)
	v_add_u32_e32 v18, v18, v14
	s_nop 2
	global_load_dword v15, v17, s[2:3] sc1
	v_readlane_b32 s2, v254, 32
	v_readlane_b32 s3, v254, 33
	s_waitcnt vmcnt(0)
	v_add_u32_e32 v18, v18, v15
	s_nop 2
	global_load_dword v16, v17, s[2:3] sc1
	s_mov_b64 s[2:3], -1
	s_waitcnt vmcnt(0)
	v_add_u32_e32 v18, v18, v16
	v_cmp_eq_u32_e32 vcc, s5, v18
	s_cbranch_vccnz .LBB0_2830
	s_and_b32 s2, s4, 0xff
	s_cmp_eq_u32 s2, 0
	s_mov_b64 s[2:3], -1
	s_mov_b64 s[12:13], -1
	s_sleep 1
	s_cbranch_scc1 .LBB0_2835
	s_and_b64 vcc, exec, s[12:13]
	s_cbranch_vccz .LBB0_2830
